# plus: V rows stored in plain key order in LDS so packed P fragments need no half-wave swaps (8 permlane32_swap per softmax removed)
# speedup vs baseline: 1.0015x; 1.0015x over previous
; __device__ __forceinline__ int lane_id_v() { int l; asm volatile("v_mbcnt_lo_u32_b32 %0, -1, 0\n\tv_mbcnt_hi_u32_b32 %0, -1, %0" : "=v"(l)); return l; }
; __device__ __forceinline__ int v_st(int k, int c) { const int kk = (k & ~0xC) | ((k & 4) << 1) | ((k & 8) >> 1); return ((kk >> 3) * 4 + (c >> 5)) * 512 + ((kk & 7) * 32 + (c & 31)) * 2; }
; __device__ __forceinline__ int v_rd_base(int lane) { return ((lane & 3) << 3) | (((lane >> 2) & 3) << 6) | (((lane >> 4) & 1) << 5) | (((lane >> 5) & 1) << 8); }
; #define SLOAD2(k0) do { vs0 = *reinterpret_cast<const bf16x8*>(&Vh[(long)((k0) + sr) * ldv + sc]); vs1 = *reinterpret_cast<const bf16x8*>(&Vh[(long)((k0) + 32 + sr) * ldv + sc]); \
;     ks0 = *reinterpret_cast<const bf16x8*>(&Kh[(long)((k0) + sr) * ldk + sc]); ks1 = *reinterpret_cast<const bf16x8*>(&Kh[(long)((k0) + 32 + sr) * ldk + sc]); } while (0)
; __device__ __forceinline__ void attn_unit_A2(const bf16_t* __restrict__ Qb, int ldq, const bf16_t* __restrict__ Kh, int ldk, const bf16_t* __restrict__ Vh, int ldv, int nkeys, int q0, ...
;     ...
;   int tid_ = wave0 * 64 + lane_id_v();
;   const int tid = tid_, wid = tid >> 6, lane = tid & 63, r32 = lane & 31, hi = lane >> 5;
;   char* V_lds = lds; char* K_lds = lds + LDS_K_OFF;
;   float* ws = (float*)(lds + LDS_WS_OFF) + wid * 64; float* sl0 = ws; float* sl1 = ws + 32;
;   float* tbl_l = (float*)(lds + LDS_TBL_OFF);
;   char* qls = lds + LDS_Q_OFF + wid * 8192 + lane * 16;
;   __syncthreads();
;   for (int i = tid; i < TBLN; i += 512) tbl_l[i] = tblg[i];
;   { const bf16_t* Qw = Qb + (long)(wid * QBLK + r32) * ldq + hi * 8;
; #pragma unroll
;     for (int i = 0; i < 8; ++i) *reinterpret_cast<bf16x8*>(qls + i * 1024) = *reinterpret_cast<const bf16x8*>(Qw + i * 16); }
;   float m0 = -1e30f, m1 = -1e30f, l0 = 0.f, l1 = 0.f; f32x16 oa[4] = {}, ob[4] = {};
;   const int sr = tid >> 4, sc = (tid & 15) * 8, vst0 = v_st(sr, sc), vst1 = v_st(32 + sr, sc);
;   const int vb0 = (int)(uintptr_t)V_lds + v_rd_base(lane);
;   const int qlane = q0 + wid * QBLK + r32;
;   bf16x8 vs0, vs1, ks0, ks1;
;     ...
;   const int NT = nkeys / KVBLK;
;   const int kbA = (int)(uintptr_t)K_lds + r32 * 256 + (((r32 & 15) << 4) ^ (hi << 4)), qaA = (int)(uintptr_t)qls;
;   SLOAD2(0); asm volatile("s_waitcnt vmcnt(0)" ::: "memory"); SWRITE2(0); __syncthreads();
.LBB0_334:
	s_or_b64 exec, exec, s[4:5]
	s_lshl_b32 s4, s57, 8
	s_and_b32 s7, s4, 0x2000
	s_lshl_b32 s4, s59, 3
	s_ashr_i32 s23, s59, 3
	s_and_b32 s4, s4, 32
	s_add_i32 s4, s4, s23
	s_lshl_b32 s6, s20, 8
	s_lshl_b32 s20, s4, 8
	s_ashr_i32 s21, s20, 31
	s_mul_i32 s4, s4, 0x280000
	s_mul_hi_i32 s5, s20, 0x2800
	s_add_u32 s4, s24, s4
	s_addc_u32 s5, s25, s5
	s_lshl_b32 s10, s22, 7
	s_lshl_b32 s8, s22, 8
	v_ashrrev_i32_e32 v3, 6, v2
	s_add_u32 s4, s4, s8
	s_addc_u32 s5, s5, 0
	v_and_b32_e32 v46, 31, v6
	v_lshlrev_b32_e32 v196, 5, v3
	v_or_b32_e32 v0, v196, v46
	v_mov_b64_e32 v[4:5], s[4:5]
	v_mad_i64_i32 v[4:5], s[4:5], v0, s55, v[4:5]
	v_and_b32_e32 v9, 63, v6
	s_add_u32 s4, s26, s8
	v_lshrrev_b32_e32 v47, 5, v9
	s_addc_u32 s5, s27, 0
	v_lshlrev_b32_e32 v0, 4, v47
	s_add_u32 s8, s45, s8
	v_lshl_add_u64 v[4:5], v[4:5], 0, v[0:1]
	s_addc_u32 s9, s46, 0
	v_lshlrev_b32_e32 v49, 3, v6
	global_load_dwordx4 v[10:13], v[4:5], off
	global_load_dwordx4 v[14:17], v[4:5], off offset:32
	global_load_dwordx4 v[18:21], v[4:5], off offset:64
	global_load_dwordx4 v[22:25], v[4:5], off offset:96
	global_load_dwordx4 v[26:29], v[4:5], off offset:128
	global_load_dwordx4 v[30:33], v[4:5], off offset:160
	global_load_dwordx4 v[34:37], v[4:5], off offset:192
	global_load_dwordx4 v[38:41], v[4:5], off offset:224
	v_ashrrev_i32_e32 v48, 4, v2
	v_and_b32_e32 v4, 0x78, v49
	v_mov_b64_e32 v[42:43], s[8:9]
	v_lshlrev_b32_e32 v4, 1, v4
	v_add_u32_e32 v50, 32, v48
	v_mad_i64_i32 v[44:45], s[8:9], v48, s55, v[42:43]
	v_mov_b32_e32 v5, v1
	v_lshl_add_u64 v[44:45], v[44:45], 0, v[4:5]
	v_mad_i64_i32 v[42:43], s[8:9], v50, s55, v[42:43]
	global_load_dwordx4 v[176:179], v[44:45], off
	v_lshl_add_u64 v[42:43], v[42:43], 0, v[4:5]
	global_load_dwordx4 v[180:183], v[42:43], off
	v_mov_b64_e32 v[42:43], s[4:5]
	v_mad_i64_i32 v[44:45], s[4:5], v48, s55, v[42:43]
	v_lshl_add_u64 v[44:45], v[44:45], 0, v[4:5]
	global_load_dwordx4 v[184:187], v[44:45], off
	v_mad_i64_i32 v[42:43], s[4:5], v50, s55, v[42:43]
	v_lshl_add_u64 v[42:43], v[42:43], 0, v[4:5]
	global_load_dwordx4 v[188:191], v[42:43], off
	s_waitcnt vmcnt(13)
	v_mul_f32_e32 v197, 0x3fb8aa3b, v7
	s_waitcnt vmcnt(12)
	v_mul_f32_e32 v207, 0x3fb8aa3b, v8
	v_lshlrev_b32_e32 v3, 13, v3
	v_lshlrev_b32_e32 v7, 4, v9
	v_and_b32_e32 v8, 0xfffff0, v48
	v_lshlrev_b32_e32 v42, 1, v48
	v_readlane_b32 s4, v254, 58
	v_lshrrev_b32_e32 v43, 1, v48
	v_bfe_u32 v44, v49, 5, 2
	v_add3_u32 v208, s4, v3, v7
	v_and_or_b32 v3, v48, 8, v8
	v_and_b32_e32 v45, 3, v48
	v_lshrrev_b32_e32 v3, 1, v3
	v_and_or_b32 v8, v48, 4, v45
	v_or_b32_e32 v3, v3, v44
	v_and_b32_e32 v5, 0x3fffffc0, v2
	v_lshlrev_b32_e32 v8, 6, v8
	v_and_b32_e32 v42, 48, v4
	v_lshlrev_b32_e32 v3, 9, v3
	s_add_i32 s37, 0, 0x14000
	v_or3_b32 v209, v3, v8, v42
	v_lshl_add_u32 v201, v5, 2, s37
	v_and_b32_e32 v3, 0xfffff0, v50
	v_lshlrev_b32_e32 v5, 1, v50
	v_and_or_b32 v3, v50, 8, v3
	v_lshrrev_b32_e32 v3, 1, v3
	v_or_b32_e32 v3, v3, v44
	v_lshlrev_b32_e32 v3, 9, v3
	v_or3_b32 v210, v3, v8, v42
	v_and_b32_e32 v2, 0xf0, v2
	s_add_i32 s44, 0, 0x8000
	v_and_b32_e32 v8, 0xc0, v7
	v_lshlrev_b32_e32 v7, 1, v9
	s_cmp_lg_u32 s44, -1
	s_cselect_b32 s4, s44, 0
	s_add_i32 s60, s20, 0x4ff
	s_waitcnt vmcnt(11)
	ds_write_b128 v208, v[10:13]
	s_waitcnt vmcnt(10)
	ds_write_b128 v208, v[14:17] offset:1024
	s_waitcnt vmcnt(9)
	ds_write_b128 v208, v[18:21] offset:2048
	s_waitcnt vmcnt(8)
	ds_write_b128 v208, v[22:25] offset:3072
	s_waitcnt vmcnt(7)
	ds_write_b128 v208, v[26:29] offset:4096
	s_waitcnt vmcnt(6)
	ds_write_b128 v208, v[30:33] offset:5120
	s_waitcnt vmcnt(5)
	ds_write_b128 v208, v[34:37] offset:6144
	s_waitcnt vmcnt(4)
	ds_write_b128 v208, v[38:41] offset:7168
	v_add_u32_e32 v12, 0, v209
	s_waitcnt vmcnt(0)
; __device__ __forceinline__ int v_st(int k, int c) { const int kk = (k & ~0xC) | ((k & 4) << 1) | ((k & 8) >> 1); return ((kk >> 3) * 4 + (c >> 5)) * 512 + ((kk & 7) * 32 + (c & 31)) * 2; }
; __device__ __forceinline__ int v_rd_base(int lane) { return ((lane & 3) << 3) | (((lane >> 2) & 3) << 6) | (((lane >> 4) & 1) << 5) | (((lane >> 5) & 1) << 8); }
; #define SLOAD2(k0) do { vs0 = *reinterpret_cast<const bf16x8*>(&Vh[(long)((k0) + sr) * ldv + sc]); vs1 = *reinterpret_cast<const bf16x8*>(&Vh[(long)((k0) + 32 + sr) * ldv + sc]); \
;     ks0 = *reinterpret_cast<const bf16x8*>(&Kh[(long)((k0) + sr) * ldk + sc]); ks1 = *reinterpret_cast<const bf16x8*>(&Kh[(long)((k0) + 32 + sr) * ldk + sc]); } while (0)
; #define SWRITE2(b) do { *(bf16x8*)(V_lds + (b) * SHM_V + vst0) = vs0; *(bf16x8*)(V_lds + (b) * SHM_V + vst1) = vs1; \
;     *(bf16x8*)(K_lds + (b) * SHM_K + KSWZ(sr, sc * 2)) = ks0; *(bf16x8*)(K_lds + (b) * SHM_K + KSWZ(32 + sr, sc * 2)) = ks1; } while (0)
; __device__ __forceinline__ void attn_unit_A2(const bf16_t* __restrict__ Qb, int ldq, const bf16_t* __restrict__ Kh, int ldk, const bf16_t* __restrict__ Vh, int ldv, int nkeys, int q0, ...
;     ...
;   float m0 = -1e30f, m1 = -1e30f, l0 = 0.f, l1 = 0.f; f32x16 oa[4] = {}, ob[4] = {};
;   const int sr = tid >> 4, sc = (tid & 15) * 8, vst0 = v_st(sr, sc), vst1 = v_st(32 + sr, sc);
;   const int vb0 = (int)(uintptr_t)V_lds + v_rd_base(lane);
;   const int qlane = q0 + wid * QBLK + r32;
;   bf16x8 vs0, vs1, ks0, ks1;
;     ...
;   const int NT = nkeys / KVBLK;
;   const int kbA = (int)(uintptr_t)K_lds + r32 * 256 + (((r32 & 15) << 4) ^ (hi << 4)), qaA = (int)(uintptr_t)qls;
;   SLOAD2(0); asm volatile("s_waitcnt vmcnt(0)" ::: "memory"); SWRITE2(0); __syncthreads();
	v_and_b32_e32 v11, 15, v6
	v_bitop3_b32 v6, v47, v6, 15 bitop3:0x78
	v_and_b32_e32 v10, 32, v7
	v_lshlrev_b32_e32 v7, 8, v46
	v_lshlrev_b32_e32 v6, 4, v6
	v_lshlrev_b32_e32 v3, 3, v9
	v_add3_u32 v211, v7, s4, v6
	v_mad_i64_i32 v[6:7], s[4:5], v48, s55, 0
	s_waitcnt vmcnt(3)
	ds_write_b128 v12, v[176:179]
	v_add_u32_e32 v12, 0, v210
	s_waitcnt vmcnt(2)
	ds_write_b128 v12, v[180:183]
	v_lshlrev_b32_e32 v12, 8, v48
	v_bitop3_b32 v212, v4, v12, v2 bitop3:0xde
	v_add_u32_e32 v12, 0, v212
	s_cmp_lg_u32 0, -1
	s_waitcnt vmcnt(1)
	ds_write_b128 v12, v[184:187] offset:32768
	v_lshlrev_b32_e32 v12, 8, v50
	v_bitop3_b32 v213, v12, v4, v2 bitop3:0xf6
	v_and_b32_e32 v5, 24, v3
	v_add_u32_e32 v2, 0, v213
	s_cselect_b32 s4, 0, 0
	s_lshl_b32 s8, s23, 8
	v_and_b32_e32 v3, 0x100, v3
	s_waitcnt vmcnt(0)
	ds_write_b128 v2, v[188:191] offset:32768
	v_add3_u32 v2, v8, s4, v5
	s_add_i32 s7, s7, s8
	v_add3_u32 v214, v2, v10, v3
	v_add_u32_e32 v2, s7, v196
	v_or_b32_e32 v2, v2, v46
	v_lshlrev_b32_e32 v2, 2, v2
	v_add_u32_e32 v216, v201, v0
	v_sub_u32_e32 v0, v0, v2
	v_add_u32_e32 v217, 0, v0
	v_lshlrev_b32_e32 v0, 4, v11
	v_or3_b32 v6, v6, s6, v0
	v_mov_b32_e32 v14, v1
	v_mov_b32_e32 v15, v1
	v_cmp_gt_u32_e64 s[4:5], 32, v9
	v_lshl_add_u32 v215, v46, 2, v201
	v_lshl_add_u64 v[198:199], s[18:19], 0, v[6:7]
	v_mov_b32_e32 v0, v1
	v_mov_b32_e32 v2, v1
	v_mov_b32_e32 v3, v1
	v_mov_b32_e32 v4, v1
	v_mov_b32_e32 v5, v1
	v_mov_b32_e32 v6, v1
	v_mov_b32_e32 v7, v1
	v_mov_b32_e32 v8, v1
	v_mov_b32_e32 v9, v1
	v_mov_b32_e32 v10, v1
	v_mov_b32_e32 v11, v1
	v_mov_b32_e32 v12, v1
	v_mov_b32_e32 v13, v1
	v_mov_b64_e32 v[46:47], v[14:15]
	v_mov_b64_e32 v[30:31], v[14:15]
	v_mov_b64_e32 v[78:79], v[14:15]
	v_mov_b64_e32 v[126:127], v[14:15]
	v_mov_b64_e32 v[142:143], v[14:15]
	v_mov_b64_e32 v[110:111], v[14:15]
	v_mov_b64_e32 v[62:63], v[14:15]
	v_mov_b64_e32 v[94:95], v[14:15]
	s_mov_b32 s11, 0
	s_sub_i32 s61, 0, s7
	v_mov_b32_e32 v218, 0xf149f2ca
	v_mov_b32_e32 v219, 0
	s_mov_b32 s62, 0
	s_mov_b32 s63, 0
	v_mov_b64_e32 v[44:45], v[12:13]
	v_mov_b64_e32 v[42:43], v[10:11]
	v_mov_b64_e32 v[40:41], v[8:9]
	v_mov_b64_e32 v[38:39], v[6:7]
	v_mov_b64_e32 v[36:37], v[4:5]
	v_mov_b64_e32 v[34:35], v[2:3]
	v_mov_b64_e32 v[32:33], v[0:1]
	v_mov_b64_e32 v[28:29], v[12:13]
	v_mov_b64_e32 v[26:27], v[10:11]
	v_mov_b64_e32 v[24:25], v[8:9]
	v_mov_b64_e32 v[22:23], v[6:7]
	v_mov_b64_e32 v[20:21], v[4:5]
	v_mov_b64_e32 v[18:19], v[2:3]
	v_mov_b64_e32 v[16:17], v[0:1]
	v_mov_b64_e32 v[76:77], v[12:13]
	v_mov_b64_e32 v[74:75], v[10:11]
	v_mov_b64_e32 v[72:73], v[8:9]
	v_mov_b64_e32 v[70:71], v[6:7]
	v_mov_b64_e32 v[68:69], v[4:5]
	v_mov_b64_e32 v[66:67], v[2:3]
	v_mov_b64_e32 v[64:65], v[0:1]
	v_mov_b64_e32 v[124:125], v[12:13]
	v_mov_b64_e32 v[122:123], v[10:11]
	v_mov_b64_e32 v[120:121], v[8:9]
	v_mov_b64_e32 v[118:119], v[6:7]
	v_mov_b64_e32 v[116:117], v[4:5]
	v_mov_b64_e32 v[114:115], v[2:3]
	v_mov_b64_e32 v[112:113], v[0:1]
	v_mov_b64_e32 v[140:141], v[12:13]
	v_mov_b64_e32 v[138:139], v[10:11]
	v_mov_b64_e32 v[136:137], v[8:9]
	v_mov_b64_e32 v[134:135], v[6:7]
	v_mov_b64_e32 v[132:133], v[4:5]
	v_mov_b64_e32 v[130:131], v[2:3]
	v_mov_b64_e32 v[128:129], v[0:1]
	v_mov_b64_e32 v[108:109], v[12:13]
	v_mov_b64_e32 v[106:107], v[10:11]
	v_mov_b64_e32 v[104:105], v[8:9]
	v_mov_b64_e32 v[102:103], v[6:7]
	v_mov_b64_e32 v[100:101], v[4:5]
	v_mov_b64_e32 v[98:99], v[2:3]
	v_mov_b64_e32 v[96:97], v[0:1]
	v_mov_b64_e32 v[60:61], v[12:13]
	v_mov_b64_e32 v[58:59], v[10:11]
	v_mov_b64_e32 v[56:57], v[8:9]
	v_mov_b64_e32 v[54:55], v[6:7]
	v_mov_b64_e32 v[52:53], v[4:5]
	v_mov_b64_e32 v[50:51], v[2:3]
	v_mov_b64_e32 v[48:49], v[0:1]
	v_mov_b64_e32 v[92:93], v[12:13]
	v_mov_b64_e32 v[90:91], v[10:11]
	v_mov_b64_e32 v[88:89], v[8:9]
	v_mov_b64_e32 v[86:87], v[6:7]
	v_mov_b64_e32 v[84:85], v[4:5]
	v_mov_b64_e32 v[82:83], v[2:3]
	v_mov_b64_e32 v[80:81], v[0:1]
	v_mov_b32_e32 v14, 0
	v_mov_b32_e32 v0, 0xf149f2ca
	s_waitcnt lgkmcnt(0)
	s_barrier

; #define RESC2(O, SL, a) do { if (__any((a) < 1.f)) { if (hi == 0) SL[r32] = (a); asm volatile("s_waitcnt lgkmcnt(0)" ::: "memory"); \
;     _Pragma("unroll") for (int d = 0; d < 4; ++d) _Pragma("unroll") for (int r = 0; r < 16; ++r) O[d][r] *= SL[crow(r, hi)]; } } while (0)
; __device__ __forceinline__ void softmax_tile(f32x16& p0, f32x16& p1, float& m, float& l, float& alpha, float cb, bf16x8& pa0, bf16x8& pa1, bf16x8& pa2, bf16x8& pa3) {
;   float mx_[4] = {p0[0], p0[1], p0[2], p0[3]};
; #pragma unroll
;   for (int r = 4; r < 16; ++r) mx_[r & 3] = fmaxf(mx_[r & 3], p0[r]);
; #pragma unroll
;   for (int r = 0; r < 16; ++r) mx_[r & 3] = fmaxf(mx_[r & 3], p1[r]);
;   float pmax = fmaxf(fmaxf(mx_[0], mx_[1]), fmaxf(mx_[2], mx_[3]));
;   { auto rr = __builtin_amdgcn_permlane32_swap(__float_as_uint(pmax), __float_as_uint(pmax), false, false);
;     pmax = fmaxf(__uint_as_float(rr[0]), __uint_as_float(rr[1])); }
;   pmax += cb;
;   float mn;
;   if (__builtin_expect(__all(pmax - m <= THR2), 1)) { mn = m; alpha = 1.f; }
;   else { mn = fmaxf(m, pmax); alpha = __builtin_amdgcn_exp2f(m - mn); m = mn; }
;   const float off = cb - mn;
; #pragma unroll
;   for (int r = 0; r < 16; ++r) p0[r] = __builtin_amdgcn_exp2f(p0[r] + off);
; #pragma unroll
;   for (int r = 0; r < 16; ++r) p1[r] = __builtin_amdgcn_exp2f(p1[r] + off);
;   float sm_[4] = {p0[0], p0[1], p0[2], p0[3]};
; #pragma unroll
;   for (int r = 4; r < 16; ++r) sm_[r & 3] += p0[r];
; #pragma unroll
;   for (int r = 0; r < 16; ++r) sm_[r & 3] += p1[r];
;   float ps = (sm_[0] + sm_[1]) + (sm_[2] + sm_[3]);
;   { auto rr = __builtin_amdgcn_permlane32_swap(__float_as_uint(ps), __float_as_uint(ps), false, false);
;     ps = __uint_as_float(rr[0]) + __uint_as_float(rr[1]); }
;   l = l * alpha + ps;
;     ...
;   PK4(p0, 0, pa0); PK4(p0, 8, pa1); PK4(p1, 0, pa2); PK4(p1, 8, pa3);
;     ...
; }
; __device__ __forceinline__ void attn_unit_A2(const bf16_t* __restrict__ Qb, int ldq, const bf16_t* __restrict__ Kh, int ldk, const bf16_t* __restrict__ Vh, int ldv, int nkeys, int q0, ...
;     ...
;     softmax_tile(s0, s1, m0, l0, al0, cb, pa0, pa1, pa2, pa3);
;     RESC2(oa, sl0, al0);
.LBB0_337:
	s_nop 4
	v_cndmask_b32_e64 v2, v197, 0, s[22:23]
	v_cndmask_b32_e64 v227, v207, v2, s[8:9]
	v_max_f32_e32 v2, v160, v164
	v_max_f32_e32 v3, v161, v165
	v_max_f32_e32 v4, v163, v167
	v_max3_f32 v5, v162, v166, v170
	v_max3_f32 v4, v4, v171, v175
	v_max3_f32 v2, v2, v168, v172
	v_max3_f32 v3, v3, v169, v173
	v_max3_f32 v5, v5, v174, v146
	v_max3_f32 v4, v4, v147, v151
	v_max3_f32 v2, v2, v144, v148
	v_max3_f32 v3, v3, v145, v149
	v_max3_f32 v5, v5, v150, v154
	v_max3_f32 v4, v4, v155, v159
	v_max3_f32 v2, v2, v152, v156
	v_max3_f32 v3, v3, v153, v157
	v_max3_f32 v4, v5, v158, v4
	v_max3_f32 v2, v2, v3, v4
	v_mov_b32_e32 v3, v2
	s_nop 1
	v_permlane32_swap_b32_e32 v2, v3
	v_max_f32_e32 v2, v2, v3
	v_add_f32_e32 v2, v227, v2
	v_sub_f32_e32 v3, v2, v0
	v_cmp_ge_f32_e32 vcc, s48, v3
	v_max_f32_e32 v2, v0, v2
	v_sub_f32_e32 v3, v0, v2
	v_exp_f32_e32 v3, v3
	s_cmp_eq_u64 vcc, exec
	s_cselect_b64 vcc, -1, 0
	v_cndmask_b32_e32 v0, v2, v0, vcc
	v_sub_f32_e32 v2, v227, v0
	v_cndmask_b32_e64 v15, v3, 1.0, vcc
	v_add_f32_e32 v3, v160, v2
	v_add_f32_e32 v4, v161, v2
	v_add_f32_e32 v5, v162, v2
	v_add_f32_e32 v6, v163, v2
	v_add_f32_e32 v7, v164, v2
	v_add_f32_e32 v8, v165, v2
	v_add_f32_e32 v9, v166, v2
	v_add_f32_e32 v10, v167, v2
	v_exp_f32_e32 v3, v3
	v_exp_f32_e32 v4, v4
	v_exp_f32_e32 v5, v5
	v_exp_f32_e32 v6, v6
	v_exp_f32_e32 v7, v7
	v_exp_f32_e32 v8, v8
	v_exp_f32_e32 v9, v9
	v_exp_f32_e32 v10, v10
	v_add_f32_e32 v11, v168, v2
	v_add_f32_e32 v12, v169, v2
	v_add_f32_e32 v13, v170, v2
	v_add_f32_e32 v160, v171, v2
	v_exp_f32_e32 v11, v11
	v_exp_f32_e32 v12, v12
	v_exp_f32_e32 v13, v13
	v_exp_f32_e32 v160, v160
	v_add_f32_e32 v161, v172, v2
	v_add_f32_e32 v162, v173, v2
	v_add_f32_e32 v163, v174, v2
	v_add_f32_e32 v164, v175, v2
	v_exp_f32_e32 v161, v161
	v_exp_f32_e32 v162, v162
	v_exp_f32_e32 v163, v163
	v_exp_f32_e32 v164, v164
	v_add_f32_e32 v144, v144, v2
	v_add_f32_e32 v145, v145, v2
	v_add_f32_e32 v146, v146, v2
	v_add_f32_e32 v147, v147, v2
	v_exp_f32_e32 v144, v144
	v_exp_f32_e32 v145, v145
	v_exp_f32_e32 v146, v146
	v_exp_f32_e32 v147, v147
	v_add_f32_e32 v148, v148, v2
	v_add_f32_e32 v149, v149, v2
	v_add_f32_e32 v150, v150, v2
	v_add_f32_e32 v151, v151, v2
	v_add_f32_e32 v152, v152, v2
	v_add_f32_e32 v153, v153, v2
	v_add_f32_e32 v154, v154, v2
	v_add_f32_e32 v155, v155, v2
	v_add_f32_e32 v156, v156, v2
	v_add_f32_e32 v157, v157, v2
	v_add_f32_e32 v158, v158, v2
	v_add_f32_e32 v2, v159, v2
	v_exp_f32_e32 v148, v148
	v_exp_f32_e32 v149, v149
	v_exp_f32_e32 v150, v150
	v_exp_f32_e32 v151, v151
	v_exp_f32_e32 v159, v2
	v_add_f32_e32 v2, v7, v3
	v_add_f32_e32 v165, v8, v4
	v_add_f32_e32 v166, v9, v5
	v_add_f32_e32 v167, v10, v6
	v_exp_f32_e32 v152, v152
	v_exp_f32_e32 v153, v153
	v_exp_f32_e32 v154, v154
	v_exp_f32_e32 v155, v155
	v_add_f32_e32 v2, v11, v2
	v_add_f32_e32 v165, v12, v165
	v_add_f32_e32 v166, v13, v166
	v_add_f32_e32 v167, v160, v167
	v_exp_f32_e32 v156, v156
	v_exp_f32_e32 v157, v157
	v_exp_f32_e32 v158, v158
	v_add_f32_e32 v2, v161, v2
	v_add_f32_e32 v165, v162, v165
	v_add_f32_e32 v166, v163, v166
	v_add_f32_e32 v167, v164, v167
	v_add_f32_e32 v2, v144, v2
	v_add_f32_e32 v165, v145, v165
	v_add_f32_e32 v166, v146, v166
	v_add_f32_e32 v167, v147, v167
	v_add_f32_e32 v2, v148, v2
	v_add_f32_e32 v165, v149, v165
	v_add_f32_e32 v166, v150, v166
	v_add_f32_e32 v167, v151, v167
	v_add_f32_e32 v2, v152, v2
	v_add_f32_e32 v165, v153, v165
	v_add_f32_e32 v166, v154, v166
	v_add_f32_e32 v167, v155, v167
	v_add_f32_e32 v2, v156, v2
	v_add_f32_e32 v165, v157, v165
	v_add_f32_e32 v166, v158, v166
	v_add_f32_e32 v167, v159, v167
	v_add_f32_e32 v2, v2, v165
	v_add_f32_e32 v165, v166, v167
	v_add_f32_e32 v220, v2, v165
	v_mov_b32_e32 v221, v220
	v_cvt_pk_bf16_f32 v2, v3, v4
	v_cvt_pk_bf16_f32 v3, v5, v6
	v_cvt_pk_bf16_f32 v4, v7, v8
	v_cvt_pk_bf16_f32 v5, v9, v10
	v_cvt_pk_bf16_f32 v6, v11, v12
	v_cvt_pk_bf16_f32 v7, v13, v160
	v_cvt_pk_bf16_f32 v8, v161, v162
	v_cvt_pk_bf16_f32 v9, v163, v164
	v_cvt_pk_bf16_f32 v10, v144, v145
	v_cvt_pk_bf16_f32 v11, v146, v147
	v_cvt_pk_bf16_f32 v12, v148, v149
	v_cvt_pk_bf16_f32 v13, v150, v151
	v_cvt_pk_bf16_f32 v144, v152, v153
	v_cvt_pk_bf16_f32 v145, v154, v155
	v_cvt_pk_bf16_f32 v146, v156, v157
	v_cvt_pk_bf16_f32 v147, v158, v159
	s_nop 1
	v_permlane32_swap_b32_e32 v220, v221
	v_cmp_gt_f32_e32 vcc, 1.0, v15
	s_cbranch_vccz .LBB0_341
	s_and_saveexec_b64 s[8:9], s[4:5]
	ds_write_b32 v215, v15
	s_or_b64 exec, exec, s[8:9]
	s_waitcnt lgkmcnt(0)
	ds_read_b128 v[148:151], v216 offset:96
	ds_read_b128 v[152:155], v216 offset:64
	ds_read_b128 v[156:159], v216 offset:32
	ds_read_b128 v[160:163], v216
	s_waitcnt lgkmcnt(3)
	v_pk_mul_f32 v[142:143], v[142:143], v[150:151]
	s_waitcnt lgkmcnt(2)
	v_pk_mul_f32 v[138:139], v[138:139], v[154:155]
	s_waitcnt lgkmcnt(1)
	v_pk_mul_f32 v[134:135], v[134:135], v[158:159]
	s_waitcnt lgkmcnt(0)
	v_pk_mul_f32 v[130:131], v[130:131], v[162:163]
	v_pk_mul_f32 v[140:141], v[140:141], v[148:149]
	v_pk_mul_f32 v[136:137], v[136:137], v[152:153]
	v_pk_mul_f32 v[132:133], v[132:133], v[156:157]
	v_pk_mul_f32 v[128:129], v[128:129], v[160:161]
	v_pk_mul_f32 v[110:111], v[110:111], v[150:151]
	v_pk_mul_f32 v[106:107], v[106:107], v[154:155]
	v_pk_mul_f32 v[102:103], v[102:103], v[158:159]
	v_pk_mul_f32 v[98:99], v[98:99], v[162:163]
	v_pk_mul_f32 v[108:109], v[108:109], v[148:149]
	v_pk_mul_f32 v[104:105], v[104:105], v[152:153]
	v_pk_mul_f32 v[100:101], v[100:101], v[156:157]
	v_pk_mul_f32 v[96:97], v[96:97], v[160:161]
	v_pk_mul_f32 v[62:63], v[62:63], v[150:151]
	v_pk_mul_f32 v[58:59], v[58:59], v[154:155]
	v_pk_mul_f32 v[54:55], v[54:55], v[158:159]
	v_pk_mul_f32 v[50:51], v[50:51], v[162:163]
	v_pk_mul_f32 v[60:61], v[60:61], v[148:149]
	v_pk_mul_f32 v[56:57], v[56:57], v[152:153]
	v_pk_mul_f32 v[52:53], v[52:53], v[156:157]
	v_pk_mul_f32 v[48:49], v[48:49], v[160:161]
	v_pk_mul_f32 v[94:95], v[94:95], v[150:151]
	v_pk_mul_f32 v[90:91], v[90:91], v[154:155]
	v_pk_mul_f32 v[86:87], v[86:87], v[158:159]
	v_pk_mul_f32 v[82:83], v[82:83], v[162:163]
	v_pk_mul_f32 v[92:93], v[92:93], v[148:149]
	v_pk_mul_f32 v[88:89], v[88:89], v[152:153]
	v_pk_mul_f32 v[84:85], v[84:85], v[156:157]
	v_pk_mul_f32 v[80:81], v[80:81], v[160:161]

; #define RESC2(O, SL, a) do { if (__any((a) < 1.f)) { if (hi == 0) SL[r32] = (a); asm volatile("s_waitcnt lgkmcnt(0)" ::: "memory"); \
;     _Pragma("unroll") for (int d = 0; d < 4; ++d) _Pragma("unroll") for (int r = 0; r < 16; ++r) O[d][r] *= SL[crow(r, hi)]; } } while (0)
; __device__ __forceinline__ void softmax_tile(f32x16& p0, f32x16& p1, float& m, float& l, float& alpha, float cb, bf16x8& pa0, bf16x8& pa1, bf16x8& pa2, bf16x8& pa3) {
;   float mx_[4] = {p0[0], p0[1], p0[2], p0[3]};
; #pragma unroll
;   for (int r = 4; r < 16; ++r) mx_[r & 3] = fmaxf(mx_[r & 3], p0[r]);
; #pragma unroll
;   for (int r = 0; r < 16; ++r) mx_[r & 3] = fmaxf(mx_[r & 3], p1[r]);
;   float pmax = fmaxf(fmaxf(mx_[0], mx_[1]), fmaxf(mx_[2], mx_[3]));
;   { auto rr = __builtin_amdgcn_permlane32_swap(__float_as_uint(pmax), __float_as_uint(pmax), false, false);
;     pmax = fmaxf(__uint_as_float(rr[0]), __uint_as_float(rr[1])); }
;   pmax += cb;
;   float mn;
;   if (__builtin_expect(__all(pmax - m <= THR2), 1)) { mn = m; alpha = 1.f; }
;   else { mn = fmaxf(m, pmax); alpha = __builtin_amdgcn_exp2f(m - mn); m = mn; }
;   const float off = cb - mn;
; #pragma unroll
;   for (int r = 0; r < 16; ++r) p0[r] = __builtin_amdgcn_exp2f(p0[r] + off);
; #pragma unroll
;   for (int r = 0; r < 16; ++r) p1[r] = __builtin_amdgcn_exp2f(p1[r] + off);
;   float sm_[4] = {p0[0], p0[1], p0[2], p0[3]};
; #pragma unroll
;   for (int r = 4; r < 16; ++r) sm_[r & 3] += p0[r];
; #pragma unroll
;   for (int r = 0; r < 16; ++r) sm_[r & 3] += p1[r];
;   float ps = (sm_[0] + sm_[1]) + (sm_[2] + sm_[3]);
;   { auto rr = __builtin_amdgcn_permlane32_swap(__float_as_uint(ps), __float_as_uint(ps), false, false);
;     ps = __uint_as_float(rr[0]) + __uint_as_float(rr[1]); }
;   l = l * alpha + ps;
;     ...
;   PK4(p0, 0, pa0); PK4(p0, 8, pa1); PK4(p1, 0, pa2); PK4(p1, 8, pa3);
;     ...
; }
; __device__ __forceinline__ void attn_unit_A2(const bf16_t* __restrict__ Qb, int ldq, const bf16_t* __restrict__ Kh, int ldk, const bf16_t* __restrict__ Vh, int ldv, int nkeys, int q0, ...
;     ...
;     softmax_tile(s0, s1, m1, l1, al1, cb, pa0, pa1, pa2, pa3);
;     RESC2(ob, sl1, al1);
.LBB0_343:
	s_nop 8
	v_max_f32_e32 v2, v160, v164
	v_max_f32_e32 v3, v161, v165
	v_max_f32_e32 v4, v163, v167
	v_max3_f32 v5, v162, v166, v170
	v_max3_f32 v4, v4, v171, v175
	v_max3_f32 v2, v2, v168, v172
	v_max3_f32 v3, v3, v169, v173
	v_max3_f32 v5, v5, v174, v146
	v_max3_f32 v4, v4, v147, v151
	v_max3_f32 v2, v2, v144, v148
	v_max3_f32 v3, v3, v145, v149
	v_max3_f32 v5, v5, v150, v154
	v_max3_f32 v4, v4, v155, v159
	v_max3_f32 v2, v2, v152, v156
	v_max3_f32 v3, v3, v153, v157
	v_max3_f32 v4, v5, v158, v4
	v_max3_f32 v2, v2, v3, v4
	v_mov_b32_e32 v3, v2
	s_nop 1
	v_permlane32_swap_b32_e32 v2, v3
	v_max_f32_e32 v2, v2, v3
	v_add_f32_e32 v2, v227, v2
	v_sub_f32_e32 v3, v2, v218
	v_cmp_ge_f32_e32 vcc, s48, v3
	s_cmp_eq_u64 vcc, exec
	v_max_f32_e32 v2, v218, v2
	s_cselect_b64 vcc, -1, 0
	v_sub_f32_e32 v3, v218, v2
	v_cndmask_b32_e32 v218, v2, v218, vcc
	v_sub_f32_e32 v2, v227, v218
	v_add_f32_e32 v148, v148, v2
	v_add_f32_e32 v8, v165, v2
	v_exp_f32_e32 v165, v148
	v_add_f32_e32 v148, v149, v2
	v_exp_f32_e32 v3, v3
	v_add_f32_e32 v9, v166, v2
	v_exp_f32_e32 v166, v148
	v_add_f32_e32 v148, v150, v2
	v_exp_f32_e32 v150, v148
	v_add_f32_e32 v148, v151, v2
	v_exp_f32_e32 v151, v148
	v_add_f32_e32 v148, v152, v2
	v_exp_f32_e32 v152, v148
	v_add_f32_e32 v148, v153, v2
	v_cndmask_b32_e64 v223, v3, 1.0, vcc
	v_add_f32_e32 v3, v160, v2
	v_add_f32_e32 v4, v161, v2
	v_add_f32_e32 v5, v162, v2
	v_add_f32_e32 v6, v163, v2
	v_add_f32_e32 v7, v164, v2
	v_add_f32_e32 v10, v167, v2
	v_exp_f32_e32 v153, v148
	v_add_f32_e32 v148, v154, v2
	v_exp_f32_e32 v3, v3
	v_exp_f32_e32 v4, v4
	v_exp_f32_e32 v5, v5
	v_exp_f32_e32 v6, v6
	v_exp_f32_e32 v7, v7
	v_exp_f32_e32 v8, v8
	v_exp_f32_e32 v9, v9
	v_exp_f32_e32 v10, v10
	v_add_f32_e32 v11, v168, v2
	v_add_f32_e32 v12, v169, v2
	v_add_f32_e32 v13, v170, v2
	v_add_f32_e32 v160, v171, v2
	v_exp_f32_e32 v154, v148
	v_add_f32_e32 v148, v155, v2
	v_exp_f32_e32 v11, v11
	v_exp_f32_e32 v12, v12
	v_exp_f32_e32 v13, v13
	v_exp_f32_e32 v160, v160
	v_add_f32_e32 v161, v172, v2
	v_add_f32_e32 v162, v173, v2
	v_add_f32_e32 v163, v174, v2
	v_add_f32_e32 v164, v175, v2
	v_exp_f32_e32 v155, v148
	v_add_f32_e32 v148, v156, v2
	v_exp_f32_e32 v161, v161
	v_exp_f32_e32 v162, v162
	v_exp_f32_e32 v163, v163
	v_exp_f32_e32 v164, v164
	v_add_f32_e32 v144, v144, v2
	v_add_f32_e32 v145, v145, v2
	v_add_f32_e32 v146, v146, v2
	v_add_f32_e32 v147, v147, v2
	v_exp_f32_e32 v156, v148
	v_add_f32_e32 v148, v157, v2
	v_exp_f32_e32 v144, v144
	v_exp_f32_e32 v145, v145
	v_exp_f32_e32 v146, v146
	v_exp_f32_e32 v147, v147
	v_exp_f32_e32 v157, v148
	v_add_f32_e32 v148, v158, v2
	v_add_f32_e32 v2, v159, v2
	v_exp_f32_e32 v158, v148
	v_exp_f32_e32 v159, v2
	v_add_f32_e32 v2, v7, v3
	v_add_f32_e32 v148, v8, v4
	v_add_f32_e32 v149, v9, v5
	v_add_f32_e32 v167, v10, v6
	v_add_f32_e32 v2, v11, v2
	v_add_f32_e32 v148, v12, v148
	v_add_f32_e32 v149, v13, v149
	v_add_f32_e32 v167, v160, v167
	v_add_f32_e32 v2, v161, v2
	v_add_f32_e32 v148, v162, v148
	v_add_f32_e32 v149, v163, v149
	v_add_f32_e32 v167, v164, v167
	v_add_f32_e32 v2, v144, v2
	v_add_f32_e32 v148, v145, v148
	v_add_f32_e32 v149, v146, v149
	v_add_f32_e32 v167, v147, v167
	v_add_f32_e32 v2, v165, v2
	v_add_f32_e32 v148, v166, v148
	v_add_f32_e32 v149, v150, v149
	v_add_f32_e32 v167, v151, v167
	v_add_f32_e32 v2, v152, v2
	v_add_f32_e32 v148, v153, v148
	v_add_f32_e32 v149, v154, v149
	v_add_f32_e32 v167, v155, v167
	v_add_f32_e32 v2, v156, v2
	v_add_f32_e32 v148, v157, v148
	v_add_f32_e32 v149, v158, v149
	v_add_f32_e32 v167, v159, v167
	v_add_f32_e32 v2, v2, v148
	v_add_f32_e32 v148, v149, v167
	v_add_f32_e32 v148, v2, v148
	v_mov_b32_e32 v149, v148
	v_cvt_pk_bf16_f32 v2, v3, v4
	v_cvt_pk_bf16_f32 v3, v5, v6
	v_cvt_pk_bf16_f32 v4, v7, v8
	v_cvt_pk_bf16_f32 v5, v9, v10
	v_cvt_pk_bf16_f32 v6, v11, v12
	v_cvt_pk_bf16_f32 v7, v13, v160
	v_cvt_pk_bf16_f32 v8, v161, v162
	v_cvt_pk_bf16_f32 v9, v163, v164
	v_cvt_pk_bf16_f32 v10, v144, v145
	v_cvt_pk_bf16_f32 v11, v146, v147
	v_cvt_pk_bf16_f32 v12, v165, v166
	v_cvt_pk_bf16_f32 v13, v150, v151
	v_cvt_pk_bf16_f32 v144, v152, v153
	v_cvt_pk_bf16_f32 v145, v154, v155
	v_cvt_pk_bf16_f32 v146, v156, v157
	v_cvt_pk_bf16_f32 v147, v158, v159
	s_nop 1
	v_permlane32_swap_b32_e32 v148, v149
	v_cmp_gt_f32_e32 vcc, 1.0, v223
	s_cbranch_vccz .LBB0_347
	s_and_saveexec_b64 s[6:7], s[4:5]
	ds_write_b32 v215, v223 offset:128
	s_or_b64 exec, exec, s[6:7]
	s_waitcnt lgkmcnt(0)
	ds_read_b128 v[150:153], v216 offset:224
	ds_read_b128 v[154:157], v216 offset:192
	ds_read_b128 v[158:161], v216 offset:160
	ds_read_b128 v[162:165], v216 offset:128
	s_waitcnt lgkmcnt(3)
	v_pk_mul_f32 v[126:127], v[126:127], v[152:153]
	s_waitcnt lgkmcnt(2)
	v_pk_mul_f32 v[122:123], v[122:123], v[156:157]
	s_waitcnt lgkmcnt(1)
	v_pk_mul_f32 v[118:119], v[118:119], v[160:161]
	s_waitcnt lgkmcnt(0)
	v_pk_mul_f32 v[114:115], v[114:115], v[164:165]
	v_pk_mul_f32 v[124:125], v[124:125], v[150:151]
	v_pk_mul_f32 v[120:121], v[120:121], v[154:155]
	v_pk_mul_f32 v[116:117], v[116:117], v[158:159]
	v_pk_mul_f32 v[112:113], v[112:113], v[162:163]
	v_pk_mul_f32 v[78:79], v[78:79], v[152:153]
	v_pk_mul_f32 v[74:75], v[74:75], v[156:157]
	v_pk_mul_f32 v[70:71], v[70:71], v[160:161]
	v_pk_mul_f32 v[66:67], v[66:67], v[164:165]
	v_pk_mul_f32 v[76:77], v[76:77], v[150:151]
	v_pk_mul_f32 v[72:73], v[72:73], v[154:155]
	v_pk_mul_f32 v[68:69], v[68:69], v[158:159]
	v_pk_mul_f32 v[64:65], v[64:65], v[162:163]
	v_pk_mul_f32 v[30:31], v[30:31], v[152:153]
	v_pk_mul_f32 v[26:27], v[26:27], v[156:157]
	v_pk_mul_f32 v[22:23], v[22:23], v[160:161]
	v_pk_mul_f32 v[18:19], v[18:19], v[164:165]
	v_pk_mul_f32 v[28:29], v[28:29], v[150:151]
	v_pk_mul_f32 v[24:25], v[24:25], v[154:155]
	v_pk_mul_f32 v[20:21], v[20:21], v[158:159]
	v_pk_mul_f32 v[16:17], v[16:17], v[162:163]
	v_pk_mul_f32 v[46:47], v[46:47], v[152:153]
	v_pk_mul_f32 v[42:43], v[42:43], v[156:157]
	v_pk_mul_f32 v[38:39], v[38:39], v[160:161]
	v_pk_mul_f32 v[34:35], v[34:35], v[164:165]
	v_pk_mul_f32 v[44:45], v[44:45], v[150:151]
	v_pk_mul_f32 v[40:41], v[40:41], v[154:155]
	v_pk_mul_f32 v[36:37], v[36:37], v[158:159]
	v_pk_mul_f32 v[32:33], v[32:33], v[162:163]

; __device__ __forceinline__ float bf2f(unsigned short b) { return __uint_as_float(((unsigned)b) << 16); }
;     ...
;   int tid_ = wave0 * 64 + lane_id_v();
;   const int tid = tid_, wid = tid >> 6, lane = tid & 63, r32 = lane & 31, hi = lane >> 5;
;   char* V_lds = lds; char* K_lds = lds + LDS_K_OFF;
;   float* ws = (float*)(lds + LDS_WS_OFF) + wid * 64; float* li_l = ws; float* al_l = ws + 32;
;   float* tbl_l = (float*)(lds + LDS_TBL_OFF);
;   __syncthreads();
;   if constexpr (BIAS) { for (int i = tid; i < TBLN; i += 512) tbl_l[i] = tblg[i]; }
;   float mC = 0.f, l_reg = 0, nm_cur = 0.f; f32x16 o[4] = {}; f32x16 negm = {}; bf16x8 qr[NDQ - NQL];
;   const bf16_t* Qw = Qb + (long)(wid * QBLK + r32) * ldq + hi * 8;
;   char* qls = lds + LDS_Q_OFF + wid * 8192 + lane * 16;
; #pragma unroll
;   for (int d0 = 0; d0 < NDQ - NQL; ++d0) qr[d0] = *reinterpret_cast<const bf16x8*>(Qw + d0 * 16);
;   if constexpr (ROPEQ) {
;     static_assert(NDQ == 12 && NQL >= 4, "ROPEQ: MLA layout");
; #pragma unroll
;     for (int d0 = NDQ - NQL; d0 < 8; ++d0) *reinterpret_cast<bf16x8*>(qls + (d0 - (NDQ - NQL)) * 1024) = *reinterpret_cast<const bf16x8*>(Qw + d0 * 16);
;     const int qrow = q0 + wid * QBLK + r32;
; #pragma unroll
;     for (int pr = 0; pr < 2; ++pr) {
;       const bf16x8 xa = *reinterpret_cast<const bf16x8*>(Qw + (8 + pr) * 16), xb = *reinterpret_cast<const bf16x8*>(Qw + (10 + pr) * 16);
;       const float* cp = cosp + (size_t)qrow * 32 + pr * 16 + hi * 8; const float* sp = sinp + (size_t)qrow * 32 + pr * 16 + hi * 8;
;       const f32x4 c0 = *(const f32x4*)cp, c1 = *(const f32x4*)(cp + 4), s0 = *(const f32x4*)sp, s1 = *(const f32x4*)(sp + 4);
;       float ya[8], yb[8];
; #pragma unroll
;       for (int t = 0; t < 8; ++t) { const float x1 = bf2f((unsigned short)xa[t]), x2 = bf2f((unsigned short)xb[t]); const float c = t < 4 ? c0[t & 3] : c1[t & 3], sn = t < 4 ? s0[t & 3] : s1[t & 3];
;         ya[t] = x1 * c - x2 * sn; yb[t] = x2 * c + x1 * sn; }
;       u32x4 wa = {pk2(ya[0], ya[1]), pk2(ya[2], ya[3]), pk2(ya[4], ya[5]), pk2(ya[6], ya[7])}, wb = {pk2(yb[0], yb[1]), pk2(yb[2], yb[3]), pk2(yb[4], yb[5]), pk2(yb[6], yb[7])};
;       *reinterpret_cast<u32x4*>(qls + (8 + pr - (NDQ - NQL)) * 1024) = wa; *reinterpret_cast<u32x4*>(qls + (10 + pr - (NDQ - NQL)) * 1024) = wb; }
.LBB0_358:
	s_and_b32 s4, s63, 3
	s_lshl_b32 s5, s82, 3
	s_lshl_b32 s59, s4, 9
	s_lshr_b32 s4, s82, 3
	s_and_b32 s5, s5, 32
	s_add_i32 s4, s5, s4
	s_and_b32 s83, s82, 3
	s_lshl_b32 s58, s4, 8
	s_mul_i32 s4, s4, 0x60000
	s_mul_hi_i32 s5, s58, 0x600
	s_add_u32 s4, s45, s4
	s_addc_u32 s5, s46, s5
	s_mul_i32 s6, s83, 0x180
	s_add_u32 s64, s4, s6
	s_addc_u32 s65, s5, 0
	s_lshl_b32 s4, s83, 9
	v_readlane_b32 s6, v254, 19
	s_add_u32 s60, s47, s4
	v_readlane_b32 s7, v254, 20
	s_addc_u32 s61, s62, 0
	s_mov_b64 s[4:5], -1
	s_and_b64 vcc, exec, s[6:7]
	s_cbranch_vccz .LBB0_384
	v_readlane_b32 s4, v254, 8
	v_mbcnt_lo_u32_b32 v56, -1, 0
	v_mbcnt_hi_u32_b32 v56, -1, v56
	v_mov_b32_e32 v185, v1
	v_and_b32_e32 v0, 31, v56
	v_add_u32_e32 v30, s4, v56
	v_ashrrev_i32_e32 v4, 6, v30
	v_and_b32_e32 v2, 0x3fffffc0, v30
	v_lshlrev_b32_e32 v182, 5, v4
	v_bfe_u32 v198, v56, 5, 1
	v_lshl_add_u32 v183, v2, 2, s37
	v_or_b32_e32 v5, v182, v0
	v_mov_b64_e32 v[2:3], s[64:65]
	v_and_b32_e32 v57, 63, v56
	v_mad_i64_i32 v[2:3], s[4:5], v5, s1, v[2:3]
	v_lshlrev_b32_e32 v184, 4, v198
	v_lshl_add_u64 v[22:23], v[2:3], 0, v[184:185]
	v_lshlrev_b32_e32 v2, 13, v4
	v_lshlrev_b32_e32 v28, 4, v57
	v_readlane_b32 s4, v254, 58
	v_and_b32_e32 v6, 32, v56
	v_mov_b32_e32 v7, v1
	v_add3_u32 v199, s4, v2, v28
	v_or_b32_e32 v2, s58, v0
	v_add_u32_e32 v2, v2, v182
	v_ashrrev_i32_e32 v3, 31, v2
	v_lshlrev_b64 v[2:3], 7, v[2:3]
	v_lshl_add_u64 v[4:5], s[50:51], 0, v[2:3]
	v_lshl_add_u64 v[32:33], v[4:5], 0, v[6:7]
	v_lshl_add_u64 v[2:3], s[56:57], 0, v[2:3]
	s_waitcnt vmcnt(63) expcnt(7) lgkmcnt(15)
	s_barrier
	global_load_dwordx4 v[142:145], v[22:23], off
	global_load_dwordx4 v[138:141], v[22:23], off offset:32
	global_load_dwordx4 v[134:137], v[22:23], off offset:64
	global_load_dwordx4 v[130:133], v[22:23], off offset:96
	global_load_dwordx4 v[126:129], v[22:23], off offset:128
	global_load_dwordx4 v[122:125], v[22:23], off offset:160
	global_load_dwordx4 v[118:121], v[22:23], off offset:192
	global_load_dwordx4 v[114:117], v[22:23], off offset:224
	v_lshl_add_u64 v[34:35], v[2:3], 0, v[6:7]
	global_load_dwordx4 v[2:5], v[32:33], off offset:16
	global_load_dwordx4 v[6:9], v[32:33], off
	global_load_dwordx4 v[10:13], v[34:35], off offset:16
	global_load_dwordx4 v[14:17], v[34:35], off
	global_load_dwordx4 v[18:21], v[22:23], off offset:256
	global_load_dwordx4 v[24:27], v[22:23], off offset:320
	s_cmp_lg_u32 0, -1
	s_cselect_b32 s6, 0, 0
	s_cmp_lg_u32 s44, -1
	s_cselect_b32 s4, s44, 0
	v_mov_b32_e32 v29, v1
	s_movk_i32 s5, 0x70
	s_mov_b32 s96, -1
	v_and_b32_e32 v58, 7, v56
	s_waitcnt vmcnt(4)
	v_mov_b32_e32 v40, v6
	v_mov_b32_e32 v41, v8
	s_waitcnt vmcnt(2)
	v_mov_b32_e32 v42, v14
	s_waitcnt vmcnt(1)
	v_lshlrev_b32_e32 v37, 16, v19
	v_lshlrev_b32_e32 v36, 16, v18
	s_waitcnt vmcnt(0)
	v_lshlrev_b32_e32 v39, 16, v25
	v_lshlrev_b32_e32 v38, 16, v24
	v_and_b32_e32 v19, 0xffff0000, v19
	v_and_b32_e32 v18, 0xffff0000, v18
	v_and_b32_e32 v25, 0xffff0000, v25
	v_and_b32_e32 v24, 0xffff0000, v24
	v_mov_b32_e32 v43, v16
	v_mov_b32_e32 v16, v15
	v_mov_b32_e32 v8, v7
	v_pk_mul_f32 v[6:7], v[16:17], v[18:19]
	v_pk_mul_f32 v[14:15], v[42:43], v[38:39]
	v_pk_mul_f32 v[16:17], v[16:17], v[24:25]
	v_pk_mul_f32 v[44:45], v[42:43], v[36:37]
	v_pk_fma_f32 v[6:7], v[8:9], v[24:25], v[6:7]
	v_pk_fma_f32 v[14:15], v[40:41], v[36:37], v[14:15] neg_lo:[0,0,1] neg_hi:[0,0,1]
	v_pk_fma_f32 v[8:9], v[8:9], v[18:19], v[16:17] neg_lo:[0,0,1] neg_hi:[0,0,1]
	v_lshlrev_b32_e32 v17, 16, v21
	v_lshlrev_b32_e32 v16, 16, v20
	v_and_b32_e32 v21, 0xffff0000, v21
	v_and_b32_e32 v20, 0xffff0000, v20
	v_and_b32_e32 v25, 0xffff0000, v27
	v_and_b32_e32 v24, 0xffff0000, v26
	v_mov_b32_e32 v37, v12
	v_mov_b32_e32 v12, v11
	v_lshlrev_b32_e32 v19, 16, v27
	v_lshlrev_b32_e32 v18, 16, v26
	v_mov_b32_e32 v26, v2
	v_mov_b32_e32 v27, v4
	v_mov_b32_e32 v36, v10
	v_mov_b32_e32 v4, v3
	v_pk_mul_f32 v[2:3], v[12:13], v[20:21]
	v_pk_mul_f32 v[12:13], v[12:13], v[24:25]
	v_pk_fma_f32 v[10:11], v[4:5], v[24:25], v[2:3]
	v_pk_mul_f32 v[2:3], v[36:37], v[18:19]
	v_pk_fma_f32 v[4:5], v[4:5], v[20:21], v[12:13] neg_lo:[0,0,1] neg_hi:[0,0,1]
	v_pk_fma_f32 v[44:45], v[40:41], v[38:39], v[44:45]
	v_pk_mul_f32 v[38:39], v[36:37], v[16:17]
	v_pk_fma_f32 v[2:3], v[26:27], v[16:17], v[2:3] neg_lo:[0,0,1] neg_hi:[0,0,1]
	v_bfe_u32 v12, v5, 16, 1
	v_bfe_u32 v13, v4, 16, 1
	v_bfe_u32 v16, v9, 16, 1
	v_bfe_u32 v17, v8, 16, 1
	v_add3_u32 v8, v8, v17, s0
	v_add3_u32 v9, v9, v16, s0
	v_add3_u32 v4, v4, v13, s0
	v_add3_u32 v5, v5, v12, s0
	v_bfe_u32 v12, v14, 16, 1
	v_bfe_u32 v13, v15, 16, 1
	v_bfe_u32 v16, v2, 16, 1
	v_bfe_u32 v17, v3, 16, 1
	v_add3_u32 v3, v3, v17, s0
	v_add3_u32 v2, v2, v16, s0
	v_add3_u32 v13, v15, v13, s0
	v_add3_u32 v12, v14, v12, s0
	v_lshrrev_b32_e32 v12, 16, v12
	v_lshrrev_b32_e32 v13, 16, v13
	v_lshrrev_b32_e32 v2, 16, v2
	v_lshrrev_b32_e32 v3, 16, v3
	v_pk_fma_f32 v[38:39], v[26:27], v[18:19], v[38:39]
	v_and_or_b32 v5, v5, s34, v3
	v_and_or_b32 v4, v4, s34, v2
	v_and_or_b32 v3, v9, s34, v13
	v_and_or_b32 v2, v8, s34, v12
	v_bfe_u32 v8, v11, 16, 1
	v_bfe_u32 v9, v10, 16, 1
	v_bfe_u32 v12, v7, 16, 1
	v_bfe_u32 v13, v6, 16, 1
	v_add3_u32 v6, v6, v13, s0
	v_add3_u32 v7, v7, v12, s0
	v_add3_u32 v10, v10, v9, s0
	v_add3_u32 v8, v11, v8, s0
	v_bfe_u32 v9, v44, 16, 1
	v_bfe_u32 v11, v45, 16, 1
	v_bfe_u32 v12, v38, 16, 1
	v_bfe_u32 v13, v39, 16, 1
	v_add3_u32 v13, v39, v13, s0
	v_add3_u32 v12, v38, v12, s0
	v_add3_u32 v11, v45, v11, s0
	v_add3_u32 v9, v44, v9, s0
	v_lshrrev_b32_e32 v14, 16, v9
	v_lshrrev_b32_e32 v11, 16, v11
	v_lshrrev_b32_e32 v12, 16, v12
	v_lshrrev_b32_e32 v9, 16, v13
	v_and_or_b32 v9, v8, s34, v9
	v_and_or_b32 v8, v10, s34, v12
	v_and_or_b32 v7, v7, s34, v11
	v_and_or_b32 v6, v6, s34, v14
	ds_write_b128 v199, v[2:5]
	ds_write_b128 v199, v[6:9] offset:2048
	global_load_dwordx4 v[2:5], v[32:33], off offset:80
	global_load_dwordx4 v[10:13], v[32:33], off offset:64
	global_load_dwordx4 v[6:9], v[34:35], off offset:80
	global_load_dwordx4 v[14:17], v[34:35], off offset:64
	global_load_dwordx4 v[18:21], v[22:23], off offset:288
	s_waitcnt vmcnt(3)
; __device__ __forceinline__ float bf2f(unsigned short b) { return __uint_as_float(((unsigned)b) << 16); }
; __device__ __forceinline__ unsigned pk2(float lo, float hi) { return f2bf(lo) | (f2bf(hi) << 16); }
; __device__ __forceinline__ int v_st(int k, int c) { const int kk = (k & ~0xC) | ((k & 4) << 1) | ((k & 8) >> 1); return ((kk >> 3) * 4 + (c >> 5)) * 512 + ((kk & 7) * 32 + (c & 31)) * 2; }
;     ...
;       const bf16x8 xa = *reinterpret_cast<const bf16x8*>(Qw + (8 + pr) * 16), xb = *reinterpret_cast<const bf16x8*>(Qw + (10 + pr) * 16);
;       const float* cp = cosp + (size_t)qrow * 32 + pr * 16 + hi * 8; const float* sp = sinp + (size_t)qrow * 32 + pr * 16 + hi * 8;
;       const f32x4 c0 = *(const f32x4*)cp, c1 = *(const f32x4*)(cp + 4), s0 = *(const f32x4*)sp, s1 = *(const f32x4*)(sp + 4);
;       float ya[8], yb[8];
; #pragma unroll
;       for (int t = 0; t < 8; ++t) { const float x1 = bf2f((unsigned short)xa[t]), x2 = bf2f((unsigned short)xb[t]); const float c = t < 4 ? c0[t & 3] : c1[t & 3], sn = t < 4 ? s0[t & 3] : s1[t & 3];
;         ya[t] = x1 * c - x2 * sn; yb[t] = x2 * c + x1 * sn; }
;       u32x4 wa = {pk2(ya[0], ya[1]), pk2(ya[2], ya[3]), pk2(ya[4], ya[5]), pk2(ya[6], ya[7])}, wb = {pk2(yb[0], yb[1]), pk2(yb[2], yb[3]), pk2(yb[4], yb[5]), pk2(yb[6], yb[7])};
;       *reinterpret_cast<u32x4*>(qls + (8 + pr - (NDQ - NQL)) * 1024) = wa; *reinterpret_cast<u32x4*>(qls + (10 + pr - (NDQ - NQL)) * 1024) = wb; }
;   } else {
; #pragma unroll
;   for (int d0 = NDQ - NQL; d0 < NDQ; ++d0) *reinterpret_cast<bf16x8*>(qls + (d0 - (NDQ - NQL)) * 1024) = *reinterpret_cast<const bf16x8*>(Qw + d0 * 16);
;   }
;   const int sr = tid >> 4, sc = (tid & 15) * 8, vst0 = v_st(sr, sc), vst1 = v_st(32 + sr, sc);
;   const int sr8 = tid >> 3, sc8 = (tid & 7) * 8;
;   const int vb0 = (int)(uintptr_t)V_lds + v_rd_base(lane);
;   const int qlane = q0 + wid * QBLK + r32;
;   struct { bf16x8 vs0, vs1, ks0, ks1, ks2; } sr_[SDEPTH];
;   constexpr int SWM = (NDQ == 8) ? 15 : 7;
;     ...
;   f32x16 pA0, pA1, pB0, pB1; float alA, alB; bf16x8 pa0, pa1, pa2, pa3; const int NT = nkeys / KVBLK;
;   const int kb0 = (int)(uintptr_t)K_lds + r32 * ROWB + (((r32 & SWM) << 4) ^ (hi << 4));
;   const int qa0 = (int)(uintptr_t)qls;
;     ...
;   constexpr int SE = 0, SO = SDEPTH - 1;
;   SLOAD(SE, kbeg); asm volatile("s_waitcnt vmcnt(0)" ::: "memory"); SWRITE(0, SE); __syncthreads();
	v_mov_b32_e32 v34, v10
	global_load_dwordx4 v[22:25], v[22:23], off offset:352
	s_waitcnt vmcnt(2)
	v_mov_b32_e32 v36, v14
	s_waitcnt vmcnt(1)
	v_lshlrev_b32_e32 v27, 16, v19
	v_lshlrev_b32_e32 v26, 16, v18
	v_and_b32_e32 v19, 0xffff0000, v19
	v_and_b32_e32 v18, 0xffff0000, v18
	v_mov_b32_e32 v37, v16
	v_mov_b32_e32 v16, v15
	v_mov_b32_e32 v35, v12
	v_mov_b32_e32 v12, v11
	v_pk_mul_f32 v[10:11], v[16:17], v[18:19]
	v_pk_mul_f32 v[38:39], v[36:37], v[26:27]
	s_waitcnt vmcnt(0)
	v_lshlrev_b32_e32 v33, 16, v23
	v_lshlrev_b32_e32 v32, 16, v22
	v_and_b32_e32 v23, 0xffff0000, v23
	v_and_b32_e32 v22, 0xffff0000, v22
	v_pk_mul_f32 v[14:15], v[36:37], v[32:33]
	v_pk_mul_f32 v[16:17], v[16:17], v[22:23]
	v_pk_fma_f32 v[10:11], v[12:13], v[22:23], v[10:11]
	v_pk_fma_f32 v[14:15], v[34:35], v[26:27], v[14:15] neg_lo:[0,0,1] neg_hi:[0,0,1]
	v_pk_fma_f32 v[12:13], v[12:13], v[18:19], v[16:17] neg_lo:[0,0,1] neg_hi:[0,0,1]
	v_lshlrev_b32_e32 v17, 16, v21
	v_lshlrev_b32_e32 v16, 16, v20
	v_and_b32_e32 v21, 0xffff0000, v21
	v_and_b32_e32 v20, 0xffff0000, v20
	v_and_b32_e32 v23, 0xffff0000, v25
	v_and_b32_e32 v22, 0xffff0000, v24
	v_mov_b32_e32 v27, v8
	v_mov_b32_e32 v8, v7
	v_lshlrev_b32_e32 v19, 16, v25
	v_lshlrev_b32_e32 v18, 16, v24
	v_mov_b32_e32 v24, v2
	v_mov_b32_e32 v25, v4
	v_mov_b32_e32 v26, v6
	v_mov_b32_e32 v4, v3
	v_pk_mul_f32 v[2:3], v[8:9], v[20:21]
	v_pk_mul_f32 v[8:9], v[8:9], v[22:23]
	v_pk_fma_f32 v[6:7], v[4:5], v[22:23], v[2:3]
	v_pk_mul_f32 v[2:3], v[26:27], v[18:19]
	v_pk_fma_f32 v[4:5], v[4:5], v[20:21], v[8:9] neg_lo:[0,0,1] neg_hi:[0,0,1]
	v_pk_fma_f32 v[38:39], v[34:35], v[32:33], v[38:39]
	v_pk_mul_f32 v[32:33], v[26:27], v[16:17]
	v_pk_fma_f32 v[2:3], v[24:25], v[16:17], v[2:3] neg_lo:[0,0,1] neg_hi:[0,0,1]
	v_bfe_u32 v8, v5, 16, 1
	v_bfe_u32 v9, v4, 16, 1
	v_bfe_u32 v16, v13, 16, 1
	v_bfe_u32 v17, v12, 16, 1
	v_add3_u32 v12, v12, v17, s0
	v_add3_u32 v13, v13, v16, s0
	v_add3_u32 v4, v4, v9, s0
	v_add3_u32 v5, v5, v8, s0
	v_bfe_u32 v8, v14, 16, 1
	v_bfe_u32 v9, v15, 16, 1
	v_bfe_u32 v16, v2, 16, 1
	v_bfe_u32 v17, v3, 16, 1
	v_add3_u32 v3, v3, v17, s0
	v_add3_u32 v2, v2, v16, s0
	v_add3_u32 v9, v15, v9, s0
	v_add3_u32 v8, v14, v8, s0
	v_lshrrev_b32_e32 v8, 16, v8
	v_lshrrev_b32_e32 v9, 16, v9
	v_lshrrev_b32_e32 v2, 16, v2
	v_lshrrev_b32_e32 v3, 16, v3
	v_pk_fma_f32 v[32:33], v[24:25], v[18:19], v[32:33]
	v_and_or_b32 v5, v5, s34, v3
	v_and_or_b32 v4, v4, s34, v2
	v_and_or_b32 v3, v13, s34, v9
	v_and_or_b32 v2, v12, s34, v8
	v_bfe_u32 v8, v7, 16, 1
	v_bfe_u32 v9, v6, 16, 1
	v_bfe_u32 v12, v11, 16, 1
	v_bfe_u32 v13, v10, 16, 1
	v_add3_u32 v10, v10, v13, s0
	v_add3_u32 v11, v11, v12, s0
	v_add3_u32 v6, v6, v9, s0
	v_add3_u32 v7, v7, v8, s0
	v_bfe_u32 v8, v38, 16, 1
	v_bfe_u32 v9, v39, 16, 1
	v_bfe_u32 v12, v32, 16, 1
	v_bfe_u32 v13, v33, 16, 1
	v_add3_u32 v13, v33, v13, s0
	v_add3_u32 v12, v32, v12, s0
	v_add3_u32 v9, v39, v9, s0
	v_add3_u32 v8, v38, v8, s0
	v_lshrrev_b32_e32 v14, 16, v8
	v_lshrrev_b32_e32 v15, 16, v9
	v_lshrrev_b32_e32 v8, 16, v12
	v_lshrrev_b32_e32 v9, 16, v13
	v_ashrrev_i32_e32 v22, 4, v30
	v_and_or_b32 v9, v7, s34, v9
	v_and_or_b32 v8, v6, s34, v8
	v_and_or_b32 v7, v11, s34, v15
	v_and_or_b32 v6, v10, s34, v14
	ds_write_b128 v199, v[2:5] offset:1024
	ds_write_b128 v199, v[6:9] offset:3072
	v_and_b32_e32 v4, 0xfffff0, v22
	v_lshlrev_b32_e32 v5, 1, v22
	v_lshlrev_b32_e32 v2, 3, v56
	v_and_or_b32 v4, v22, 8, v4
	v_and_b32_e32 v3, 0x78, v2
	v_lshrrev_b32_e32 v5, 1, v22
	v_lshrrev_b32_e32 v4, 1, v4
	v_bfe_u32 v2, v2, 5, 2
	v_and_b32_e32 v6, 3, v22
	v_or_b32_e32 v4, v4, v2
	v_and_or_b32 v5, v22, 4, v6
	v_lshlrev_b32_e32 v24, 1, v3
	v_lshlrev_b32_e32 v4, 9, v4
	v_lshlrev_b32_e32 v5, 6, v5
	v_and_b32_e32 v3, 48, v24
	v_add_u32_e32 v6, 32, v22
	v_or3_b32 v31, v4, v5, v3
	v_and_b32_e32 v4, 0xfffff0, v6
	v_lshlrev_b32_e32 v7, 1, v6
	v_and_or_b32 v4, v6, 8, v4
	v_lshrrev_b32_e32 v4, 1, v4
	v_or_b32_e32 v2, v4, v2
	v_lshlrev_b32_e32 v2, 9, v2
	v_or3_b32 v32, v2, v5, v3
	v_lshlrev_b32_e32 v2, 3, v57
	v_and_b32_e32 v3, 0xc0, v28
	v_lshlrev_b32_e32 v4, 1, v56
	v_and_or_b32 v3, v2, 24, v3
	v_and_b32_e32 v4, 32, v4
	v_and_b32_e32 v2, 0x100, v2
	v_or3_b32 v59, v3, v4, v2
	v_bitop3_b32 v3, v198, v56, 7 bitop3:0x78
	v_ashrrev_i32_e32 v23, 31, v22
	v_mul_u32_u24_e32 v2, 0x180, v0
	v_lshlrev_b32_e32 v3, 4, v3
	v_lshlrev_b64 v[50:51], 11, v[22:23]
	v_add3_u32 v209, v2, s4, v3
	v_lshl_add_u64 v[2:3], s[60:61], 0, v[50:51]
	v_mov_b32_e32 v25, v1
	v_ashrrev_i32_e32 v26, 3, v30
	v_lshl_add_u64 v[52:53], v[2:3], 0, v[24:25]
	global_load_dwordx4 v[2:5], v[52:53], off offset:256
	v_ashrrev_i32_e32 v7, 31, v6
	v_ashrrev_i32_e32 v27, 31, v26
	v_lshlrev_b64 v[6:7], 11, v[6:7]
	v_lshlrev_b64 v[186:187], 7, v[26:27]
	v_lshlrev_b32_e32 v20, 4, v56
	v_lshl_add_u64 v[6:7], s[60:61], 0, v[6:7]
	v_lshl_add_u64 v[18:19], s[8:9], 0, v[186:187]
	v_and_b32_e32 v28, 0x70, v20
	v_lshl_add_u64 v[10:11], v[6:7], 0, v[24:25]
	v_lshl_add_u64 v[54:55], v[18:19], 0, v[28:29]
	global_load_dwordx4 v[6:9], v[10:11], off offset:256
	global_load_dwordx4 v[14:17], v[52:53], off
	s_nop 0
	global_load_dwordx4 v[10:13], v[10:11], off
	v_add_u32_e32 v210, 0, v31
	global_load_dwordx4 v[18:21], v[54:55], off
	s_movk_i32 s4, 0x180
	s_waitcnt vmcnt(0)
	v_add_u32_e32 v211, 0, v32
	v_xor_b32_e32 v215, 32, v209
	v_add_u32_e32 v201, s6, v59
	s_waitcnt vmcnt(4)
	ds_write_b128 v210, v[2:5]
	v_mul_lo_u32 v2, v22, s4
	v_bitop3_b32 v3, v24, v30, s5 bitop3:0x78
	v_lshlrev_b32_e32 v4, 4, v26
	v_add3_u32 v212, v3, v2, 0
	v_mul_lo_u32 v2, v26, s4
	v_or_b32_e32 v3, 0x100, v28
	v_and_b32_e32 v4, 0x70, v4
	v_xad_u32 v2, v3, v4, v2
	v_add_u32_e32 v214, 0, v2
	s_waitcnt vmcnt(3)
	ds_write_b128 v211, v[6:9]
	s_waitcnt vmcnt(2)
	ds_write_b128 v212, v[14:17] offset:32768
	s_waitcnt vmcnt(1)
	ds_write_b128 v212, v[10:13] offset:45056
	s_waitcnt vmcnt(0)
	ds_write_b128 v214, v[18:21] offset:32768
	s_waitcnt lgkmcnt(0)
	s_barrier
; __device__ __forceinline__ void qkt12_roll(f32x16& p0, f32x16& p1, const f32x16& negm, int kb, int qa, const bf16x8* qr) {
;   const int a0 = kb ^ (0 << 5); const bf16x8 x0 = lds_rd128<0>(a0), y0 = lds_rd128<12288>(a0);
;   const int a1 = kb ^ (1 << 5); const bf16x8 x1 = lds_rd128<0>(a1), y1 = lds_rd128<12288>(a1);
;   asm volatile("s_waitcnt lgkmcnt(2)" ::: "memory"); SBAR();
;   p0 = __builtin_amdgcn_mfma_f32_32x32x16_bf16(x0, qr[0], negm, 0, 0, 0); p1 = __builtin_amdgcn_mfma_f32_32x32x16_bf16(y0, qr[0], negm, 0, 0, 0);
;   const int a2 = kb ^ (2 << 5); const bf16x8 x2 = lds_rd128<0>(a2), y2 = lds_rd128<12288>(a2);
;   asm volatile("s_waitcnt lgkmcnt(2)" ::: "memory"); SBAR();
;   p0 = __builtin_amdgcn_mfma_f32_32x32x16_bf16(x1, qr[1], p0, 0, 0, 0); p1 = __builtin_amdgcn_mfma_f32_32x32x16_bf16(y1, qr[1], p1, 0, 0, 0);
;   const int a3 = kb ^ (3 << 5); const bf16x8 x3 = lds_rd128<0>(a3), y3 = lds_rd128<12288>(a3);
;   asm volatile("s_waitcnt lgkmcnt(2)" ::: "memory"); SBAR();
;   p0 = __builtin_amdgcn_mfma_f32_32x32x16_bf16(x2, qr[2], p0, 0, 0, 0); p1 = __builtin_amdgcn_mfma_f32_32x32x16_bf16(y2, qr[2], p1, 0, 0, 0);
;   const int a4 = kb ^ (0 << 5); const bf16x8 x4 = lds_rd128<128>(a4), y4 = lds_rd128<12416>(a4);
;   asm volatile("s_waitcnt lgkmcnt(2)" ::: "memory"); SBAR();
;   p0 = __builtin_amdgcn_mfma_f32_32x32x16_bf16(x3, qr[3], p0, 0, 0, 0); p1 = __builtin_amdgcn_mfma_f32_32x32x16_bf16(y3, qr[3], p1, 0, 0, 0);
;   const int a5 = kb ^ (1 << 5); const bf16x8 x5 = lds_rd128<128>(a5), y5 = lds_rd128<12416>(a5);
;   asm volatile("s_waitcnt lgkmcnt(2)" ::: "memory"); SBAR();
;   p0 = __builtin_amdgcn_mfma_f32_32x32x16_bf16(x4, qr[4], p0, 0, 0, 0); p1 = __builtin_amdgcn_mfma_f32_32x32x16_bf16(y4, qr[4], p1, 0, 0, 0);
;   const int a6 = kb ^ (2 << 5); const bf16x8 x6 = lds_rd128<128>(a6), y6 = lds_rd128<12416>(a6);
;   asm volatile("s_waitcnt lgkmcnt(2)" ::: "memory"); SBAR();
;   p0 = __builtin_amdgcn_mfma_f32_32x32x16_bf16(x5, qr[5], p0, 0, 0, 0); p1 = __builtin_amdgcn_mfma_f32_32x32x16_bf16(y5, qr[5], p1, 0, 0, 0);
;   const int a7 = kb ^ (3 << 5); const bf16x8 x7 = lds_rd128<128>(a7), y7 = lds_rd128<12416>(a7);
;   asm volatile("s_waitcnt lgkmcnt(2)" ::: "memory"); SBAR();
;   p0 = __builtin_amdgcn_mfma_f32_32x32x16_bf16(x6, qr[6], p0, 0, 0, 0); p1 = __builtin_amdgcn_mfma_f32_32x32x16_bf16(y6, qr[6], p1, 0, 0, 0);
	ds_read_b128 v[2:5], v209 offset:0
	ds_read_b128 v[18:21], v209 offset:0x3000
	ds_read_b128 v[60:63], v215 offset:0
	ds_read_b128 v[64:67], v215 offset:0x3000
	s_waitcnt lgkmcnt(2)
	v_add_u32_e32 v213, 0x3000, v212
	v_mfma_f32_32x32x16_bf16 v[34:49], v[2:5], v[142:145], 0
	v_xor_b32_e32 v216, 64, v209
	ds_read_b128 v[68:71], v216 offset:0
	ds_read_b128 v[72:75], v216 offset:0x3000
	s_mov_b32 s13, s12
	s_waitcnt lgkmcnt(2)
	s_mov_b32 s14, s12
	s_mov_b32 s15, s12
	v_mfma_f32_32x32x16_bf16 v[18:33], v[18:21], v[142:145], 0
	s_mov_b32 s16, s12
	s_mov_b32 s17, s12
	s_mov_b32 s18, s12
	s_mov_b32 s19, s12
	s_mov_b32 s20, s12
	s_mov_b32 s21, s12
	s_mov_b32 s22, s12
	s_mov_b32 s23, s12
	s_mov_b32 s24, s12
	s_mov_b32 s25, s12
	s_mov_b32 s26, s12
	s_mov_b32 s27, s12
	v_mov_b64_e32 v[2:3], s[12:13]
	v_mov_b64_e32 v[4:5], s[14:15]
	v_mov_b64_e32 v[6:7], s[16:17]
	v_mov_b64_e32 v[8:9], s[18:19]
	v_mov_b64_e32 v[10:11], s[20:21]
	v_mov_b64_e32 v[12:13], s[22:23]
	v_mov_b64_e32 v[14:15], s[24:25]
	v_mov_b64_e32 v[16:17], s[26:27]
	v_mfma_f32_32x32x16_bf16 v[34:49], v[60:63], v[138:141], v[34:49]
	v_xor_b32_e32 v217, 0x60, v209
	ds_read_b128 v[60:63], v217 offset:0
	v_mfma_f32_32x32x16_bf16 v[18:33], v[64:67], v[138:141], v[18:33]
	ds_read_b128 v[64:67], v217 offset:0x3000
	s_waitcnt lgkmcnt(2)
	v_mfma_f32_32x32x16_bf16 v[34:49], v[68:71], v[134:137], v[34:49]
	ds_read_b128 v[68:71], v209 offset:0x80
	v_mfma_f32_32x32x16_bf16 v[18:33], v[72:75], v[134:137], v[18:33]
	ds_read_b128 v[72:75], v209 offset:0x3080
	s_waitcnt lgkmcnt(2)
	v_mfma_f32_32x32x16_bf16 v[34:49], v[60:63], v[130:133], v[34:49]
	ds_read_b128 v[60:63], v215 offset:0x80
	v_mfma_f32_32x32x16_bf16 v[18:33], v[64:67], v[130:133], v[18:33]
	ds_read_b128 v[64:67], v215 offset:0x3080
	s_waitcnt lgkmcnt(2)
	v_mfma_f32_32x32x16_bf16 v[34:49], v[68:71], v[126:129], v[34:49]
	ds_read_b128 v[68:71], v216 offset:0x80
	v_mfma_f32_32x32x16_bf16 v[18:33], v[72:75], v[126:129], v[18:33]
	ds_read_b128 v[72:75], v216 offset:0x3080
	s_waitcnt lgkmcnt(2)
	v_mfma_f32_32x32x16_bf16 v[34:49], v[60:63], v[122:125], v[34:49]
	ds_read_b128 v[60:63], v217 offset:0x80
	v_mfma_f32_32x32x16_bf16 v[18:33], v[64:67], v[122:125], v[18:33]
	ds_read_b128 v[64:67], v217 offset:0x3080
	s_waitcnt lgkmcnt(2)
	v_mfma_f32_32x32x16_bf16 v[34:49], v[68:71], v[118:121], v[34:49]
	ds_read_b128 v[68:71], v209 offset:0x100
	v_mfma_f32_32x32x16_bf16 v[18:33], v[72:75], v[118:121], v[18:33]
	ds_read_b128 v[72:75], v209 offset:0x3100
	ds_read_b128 v[76:79], v199 offset:0
	s_waitcnt lgkmcnt(3)
	v_mfma_f32_32x32x16_bf16 v[34:49], v[60:63], v[114:117], v[34:49]
	ds_read_b128 v[60:63], v215 offset:0x100
	v_mfma_f32_32x32x16_bf16 v[18:33], v[64:67], v[114:117], v[18:33]
	ds_read_b128 v[64:67], v215 offset:0x3100
	ds_read_b128 v[80:83], v199 offset:0x400
	s_waitcnt lgkmcnt(3)
	v_mfma_f32_32x32x16_bf16 v[34:49], v[68:71], v[76:79], v[34:49]
	ds_read_b128 v[68:71], v216 offset:0x100
	v_mfma_f32_32x32x16_bf16 v[18:33], v[72:75], v[76:79], v[18:33]
	ds_read_b128 v[72:75], v216 offset:0x3100
	ds_read_b128 v[76:79], v199 offset:0x800
	s_waitcnt lgkmcnt(3)
	v_mfma_f32_32x32x16_bf16 v[34:49], v[60:63], v[80:83], v[34:49]
	ds_read_b128 v[60:63], v217 offset:0x100
	v_mfma_f32_32x32x16_bf16 v[18:33], v[64:67], v[80:83], v[18:33]
	ds_read_b128 v[64:67], v217 offset:0x3100
	ds_read_b128 v[80:83], v199 offset:0xc00
	s_waitcnt lgkmcnt(3)
	v_mfma_f32_32x32x16_bf16 v[34:49], v[68:71], v[76:79], v[34:49]
	s_waitcnt lgkmcnt(0)
	v_mfma_f32_32x32x16_bf16 v[18:33], v[72:75], v[76:79], v[18:33]
	v_mfma_f32_32x32x16_bf16 v[34:49], v[60:63], v[80:83], v[34:49]
	v_mfma_f32_32x32x16_bf16 v[18:33], v[64:67], v[80:83], v[18:33]
	s_mov_b64 s[4:5], 0x20000
	v_lshl_add_u64 v[60:61], v[52:53], 0, s[4:5]
	s_mov_b64 s[4:5], 0x30000
	v_lshl_add_u64 v[64:65], v[52:53], 0, s[4:5]
	s_mov_b32 s4, 0x20000
	global_load_dwordx4 v[60:63], v[60:61], off offset:256
	s_nop 0
	global_load_dwordx4 v[82:85], v[64:65], off offset:256
	v_add_co_u32_e32 v64, vcc, s4, v52
	s_mov_b32 s4, 0x30000
	s_nop 0
	v_addc_co_u32_e32 v65, vcc, 0, v53, vcc
	v_add_co_u32_e32 v52, vcc, s4, v52
	s_movk_i32 s4, 0x2000
	s_nop 0
	v_addc_co_u32_e32 v53, vcc, 0, v53, vcc
	global_load_dwordx4 v[86:89], v[64:65], off
	global_load_dwordx4 v[90:93], v[52:53], off
	v_add_co_u32_e32 v52, vcc, s4, v54
	v_max_f32_e32 v66, v38, v38
	s_nop 0
	v_addc_co_u32_e32 v53, vcc, 0, v55, vcc
	global_load_dwordx4 v[52:55], v[52:53], off
	v_max_f32_e32 v67, v34, v34
	v_max_f32_e32 v64, v67, v66
	v_max_f32_e32 v65, v39, v39
	v_max_f32_e32 v66, v35, v35
	v_max_f32_e32 v65, v66, v65
	v_max_f32_e32 v66, v41, v41
	v_max_f32_e32 v67, v37, v37
	v_max_f32_e32 v66, v67, v66
	v_max3_f32 v67, v36, v40, v44
	v_max3_f32 v66, v66, v45, v49
	v_max3_f32 v64, v64, v42, v46
	v_max3_f32 v65, v65, v43, v47
	v_max3_f32 v67, v67, v48, v20
	v_max3_f32 v66, v66, v21, v25
	v_max3_f32 v64, v64, v18, v22
	v_max3_f32 v65, v65, v19, v23
	v_max3_f32 v67, v67, v24, v28
	v_max3_f32 v66, v66, v29, v33
	v_max3_f32 v64, v64, v26, v30
	v_max3_f32 v65, v65, v27, v31
	v_max3_f32 v66, v67, v32, v66
	v_max3_f32 v64, v64, v65, v66
	v_mov_b32_e32 v65, v64
	s_nop 1
	v_permlane32_swap_b32_e32 v64, v65
	s_mov_b32 s4, 0xc3480000
	v_max3_f32 v64, v64, v65, s4
	v_sub_f32_e32 v34, v34, v64
	v_sub_f32_e32 v35, v35, v64
	v_sub_f32_e32 v36, v36, v64
	v_sub_f32_e32 v37, v37, v64
	v_sub_f32_e32 v38, v38, v64
	v_sub_f32_e32 v39, v39, v64
	v_sub_f32_e32 v40, v40, v64
	v_sub_f32_e32 v41, v41, v64
	v_sub_f32_e32 v42, v42, v64
	v_sub_f32_e32 v43, v43, v64
	v_sub_f32_e32 v44, v44, v64
	v_sub_f32_e32 v45, v45, v64
	v_sub_f32_e32 v46, v46, v64
	v_sub_f32_e32 v47, v47, v64
	v_sub_f32_e32 v48, v48, v64
	v_sub_f32_e32 v49, v49, v64
	v_sub_f32_e32 v66, v18, v64
	v_exp_f32_e32 v146, v34
	v_exp_f32_e32 v161, v35
	v_exp_f32_e32 v147, v36
	v_exp_f32_e32 v160, v37
	v_exp_f32_e32 v148, v38
	v_exp_f32_e32 v159, v39
	v_exp_f32_e32 v149, v40
	v_exp_f32_e32 v158, v41
	v_exp_f32_e32 v150, v42
	v_exp_f32_e32 v157, v43
	v_exp_f32_e32 v151, v44
	v_exp_f32_e32 v156, v45
	v_exp_f32_e32 v152, v46
	v_exp_f32_e32 v155, v47
	v_exp_f32_e32 v153, v48
	v_exp_f32_e32 v154, v49
	v_and_b32_e32 v18, 15, v56
	v_sub_f32_e32 v67, v19, v64
	s_waitcnt vmcnt(0)
; #define SWAIT() do { if constexpr (SDEPTH == 2) { if constexpr (NDQ == 4) asm volatile("s_waitcnt vmcnt(3)" ::: "memory"); else if constexpr (NDQ == 8) asm volatile("s_waitcnt vmcnt(4)" ::: "memory"); else asm volatile("s_waitcnt vmcnt(5)" ::: "memory"); } \
;     else asm volatile("s_waitcnt vmcnt(0)" ::: "memory"); } while (0)
; template <bool FIRST>
; __device__ __forceinline__ void partialSM(f32x16& p0, f32x16& p1, float& mC, float& alpha) {
;     ...
;   else { const float delta = FIRST ? fmaxf(pmax, -200.f) : fmaxf(pmax, 0.f); alpha = FIRST ? 1.f : __builtin_amdgcn_exp2f(-delta); mC += delta;
; #pragma unroll
;     for (int r = 0; r < 16; ++r) p0[r] -= delta;
; #pragma unroll
;     for (int r = 0; r < 16; ++r) p1[r] -= delta; }
;     ...
;   SLOAD(SO, kbeg + KVBLK); if constexpr (SDEPTH == 2) { if (2 < NT) SLOAD(SE, kbeg + 2 * KVBLK); }
;   SWAIT(); SWRITE(1, SO); __syncthreads();
	s_addk_i32 s6, 0x4000
	v_or_b32_e32 v50, s59, v50
	v_lshlrev_b32_e32 v18, 4, v18
	v_mov_b32_e32 v19, v1
	v_add_f32_e32 v226, 0, v64
	v_sub_f32_e32 v81, v33, v64
	v_sub_f32_e32 v80, v32, v64
	v_sub_f32_e32 v79, v31, v64
	v_sub_f32_e32 v78, v30, v64
	v_sub_f32_e32 v77, v29, v64
	v_sub_f32_e32 v76, v28, v64
	v_sub_f32_e32 v75, v27, v64
	v_sub_f32_e32 v74, v26, v64
	v_sub_f32_e32 v73, v25, v64
	v_sub_f32_e32 v72, v24, v64
	v_sub_f32_e32 v71, v23, v64
	v_sub_f32_e32 v70, v22, v64
	v_sub_f32_e32 v69, v21, v64
	v_sub_f32_e32 v68, v20, v64
	s_waitcnt vmcnt(4)
	ds_write_b128 v210, v[60:63] offset:16384
	s_waitcnt vmcnt(3)
	ds_write_b128 v211, v[82:85] offset:16384
	s_waitcnt vmcnt(2)
	ds_write_b128 v212, v[86:89] offset:57344
	s_waitcnt vmcnt(1)
	ds_write_b128 v213, v[90:93] offset:57344
	s_waitcnt vmcnt(0)
	ds_write_b128 v214, v[52:55] offset:57344
	v_add_u32_e32 v221, 0x6000, v209
	v_cmp_gt_u32_e64 s[4:5], 32, v57
	v_add_u32_e32 v208, s6, v59
	v_lshl_add_u64 v[188:189], v[50:51], 0, v[18:19]
	v_lshl_or_b32 v186, v58, 4, v186
	v_mov_b32_e32 v229, 0
	v_mov_b64_e32 v[64:65], v[16:17]
	v_mov_b64_e32 v[48:49], v[16:17]
	v_mov_b64_e32 v[32:33], v[16:17]
	v_xor_b32_e32 v220, 32, v221
	v_xor_b32_e32 v219, 64, v221
	v_xor_b32_e32 v218, 0x60, v221
	v_lshl_add_u32 v200, v0, 2, v183
	v_add_u32_e32 v185, v183, v184
	v_mov_b32_e32 v222, 1.0
	v_mov_b64_e32 v[62:63], v[14:15]
	v_mov_b64_e32 v[60:61], v[12:13]
	v_mov_b64_e32 v[58:59], v[10:11]
	v_mov_b64_e32 v[56:57], v[8:9]
	v_mov_b64_e32 v[54:55], v[6:7]
	v_mov_b64_e32 v[52:53], v[4:5]
	v_mov_b64_e32 v[50:51], v[2:3]
	v_mov_b64_e32 v[46:47], v[14:15]
	v_mov_b64_e32 v[44:45], v[12:13]
	v_mov_b64_e32 v[42:43], v[10:11]
	v_mov_b64_e32 v[40:41], v[8:9]
	v_mov_b64_e32 v[38:39], v[6:7]
	v_mov_b64_e32 v[36:37], v[4:5]
	v_mov_b64_e32 v[34:35], v[2:3]
	v_mov_b64_e32 v[30:31], v[14:15]
	v_mov_b64_e32 v[28:29], v[12:13]
	v_mov_b64_e32 v[26:27], v[10:11]
	v_mov_b64_e32 v[24:25], v[8:9]
	v_mov_b64_e32 v[22:23], v[6:7]
	v_mov_b64_e32 v[20:21], v[4:5]
	v_mov_b64_e32 v[18:19], v[2:3]
	v_mov_b32_e32 v207, 0
	v_mov_b32_e32 v82, 0
	v_mov_b32_e32 v83, v229
	v_mov_b32_e32 v84, v229
	v_mov_b32_e32 v85, v229
	v_mov_b32_e32 v86, v229
	v_mov_b32_e32 v87, v229
	v_mov_b32_e32 v88, v229
	v_mov_b32_e32 v89, v229
	v_mov_b32_e32 v90, v229
	v_mov_b32_e32 v91, v229
	v_mov_b32_e32 v92, v229
	v_mov_b32_e32 v93, v229
	v_mov_b32_e32 v94, v229
	v_mov_b32_e32 v95, v229
	v_mov_b32_e32 v96, v229
	v_mov_b32_e32 v97, v229
	s_waitcnt lgkmcnt(0)
	s_barrier
; __device__ __forceinline__ void qkt12_roll(f32x16& p0, f32x16& p1, const f32x16& negm, int kb, int qa, const bf16x8* qr) {
;   const int a0 = kb ^ (0 << 5); const bf16x8 x0 = lds_rd128<0>(a0), y0 = lds_rd128<12288>(a0);
;   const int a1 = kb ^ (1 << 5); const bf16x8 x1 = lds_rd128<0>(a1), y1 = lds_rd128<12288>(a1);
;   asm volatile("s_waitcnt lgkmcnt(2)" ::: "memory"); SBAR();
;   p0 = __builtin_amdgcn_mfma_f32_32x32x16_bf16(x0, qr[0], negm, 0, 0, 0); p1 = __builtin_amdgcn_mfma_f32_32x32x16_bf16(y0, qr[0], negm, 0, 0, 0);
;   const int a2 = kb ^ (2 << 5); const bf16x8 x2 = lds_rd128<0>(a2), y2 = lds_rd128<12288>(a2);
;   asm volatile("s_waitcnt lgkmcnt(2)" ::: "memory"); SBAR();
;   p0 = __builtin_amdgcn_mfma_f32_32x32x16_bf16(x1, qr[1], p0, 0, 0, 0); p1 = __builtin_amdgcn_mfma_f32_32x32x16_bf16(y1, qr[1], p1, 0, 0, 0);
;   const int a3 = kb ^ (3 << 5); const bf16x8 x3 = lds_rd128<0>(a3), y3 = lds_rd128<12288>(a3);
;   asm volatile("s_waitcnt lgkmcnt(2)" ::: "memory"); SBAR();
;   p0 = __builtin_amdgcn_mfma_f32_32x32x16_bf16(x2, qr[2], p0, 0, 0, 0); p1 = __builtin_amdgcn_mfma_f32_32x32x16_bf16(y2, qr[2], p1, 0, 0, 0);
;   const int a4 = kb ^ (0 << 5); const bf16x8 x4 = lds_rd128<128>(a4), y4 = lds_rd128<12416>(a4);
;   asm volatile("s_waitcnt lgkmcnt(2)" ::: "memory"); SBAR();
;   p0 = __builtin_amdgcn_mfma_f32_32x32x16_bf16(x3, qr[3], p0, 0, 0, 0); p1 = __builtin_amdgcn_mfma_f32_32x32x16_bf16(y3, qr[3], p1, 0, 0, 0);
;   const int a5 = kb ^ (1 << 5); const bf16x8 x5 = lds_rd128<128>(a5), y5 = lds_rd128<12416>(a5);
;   asm volatile("s_waitcnt lgkmcnt(2)" ::: "memory"); SBAR();
;   p0 = __builtin_amdgcn_mfma_f32_32x32x16_bf16(x4, qr[4], p0, 0, 0, 0); p1 = __builtin_amdgcn_mfma_f32_32x32x16_bf16(y4, qr[4], p1, 0, 0, 0);
;   const int a6 = kb ^ (2 << 5); const bf16x8 x6 = lds_rd128<128>(a6), y6 = lds_rd128<12416>(a6);
;   asm volatile("s_waitcnt lgkmcnt(2)" ::: "memory"); SBAR();
;   p0 = __builtin_amdgcn_mfma_f32_32x32x16_bf16(x5, qr[5], p0, 0, 0, 0); p1 = __builtin_amdgcn_mfma_f32_32x32x16_bf16(y5, qr[5], p1, 0, 0, 0);
;   const int a7 = kb ^ (3 << 5); const bf16x8 x7 = lds_rd128<128>(a7), y7 = lds_rd128<12416>(a7);
;   asm volatile("s_waitcnt lgkmcnt(2)" ::: "memory"); SBAR();
;   p0 = __builtin_amdgcn_mfma_f32_32x32x16_bf16(x6, qr[6], p0, 0, 0, 0); p1 = __builtin_amdgcn_mfma_f32_32x32x16_bf16(y6, qr[6], p1, 0, 0, 0);
.LBB0_360:
	v_exp_f32_e32 v66, v66
	v_exp_f32_e32 v67, v67
	v_exp_f32_e32 v68, v68
	v_exp_f32_e32 v69, v69
	v_exp_f32_e32 v70, v70
	v_exp_f32_e32 v71, v71
	v_exp_f32_e32 v72, v72
	v_exp_f32_e32 v73, v73
	v_add_f32_e32 v98, v148, v146
	v_add_f32_e32 v99, v159, v161
	v_add_f32_e32 v100, v149, v147
	v_add_f32_e32 v101, v158, v160
	v_exp_f32_e32 v74, v74
	v_exp_f32_e32 v75, v75
	v_exp_f32_e32 v76, v76
	v_exp_f32_e32 v77, v77
	v_add_f32_e32 v98, v150, v98
	v_add_f32_e32 v99, v157, v99
	v_add_f32_e32 v100, v151, v100
	v_add_f32_e32 v101, v156, v101
	v_exp_f32_e32 v78, v78
	v_exp_f32_e32 v79, v79
	v_exp_f32_e32 v80, v80
	v_exp_f32_e32 v81, v81
	v_add_f32_e32 v98, v152, v98
	v_add_f32_e32 v99, v155, v99
	v_add_f32_e32 v100, v153, v100
	v_add_f32_e32 v101, v154, v101
	v_add_f32_e32 v98, v66, v98
	v_add_f32_e32 v99, v67, v99
	v_add_f32_e32 v100, v68, v100
	v_add_f32_e32 v101, v69, v101
	v_add_f32_e32 v98, v70, v98
	v_add_f32_e32 v99, v71, v99
	v_add_f32_e32 v100, v72, v100
	v_add_f32_e32 v101, v73, v101
	v_add_f32_e32 v98, v74, v98
	v_add_f32_e32 v99, v75, v99
	v_add_f32_e32 v100, v76, v100
	v_add_f32_e32 v101, v77, v101
	v_add_f32_e32 v98, v78, v98
	v_add_f32_e32 v99, v79, v99
	v_add_f32_e32 v100, v80, v100
	v_add_f32_e32 v101, v81, v101
	v_add_f32_e32 v98, v98, v99
	v_add_f32_e32 v99, v100, v101
	v_add_f32_e32 v224, v98, v99
	v_mov_b32_e32 v225, v224
	v_cvt_pk_bf16_f32 v146, v146, v161
	v_cvt_pk_bf16_f32 v147, v147, v160
	v_cvt_pk_bf16_f32 v148, v148, v159
	v_cvt_pk_bf16_f32 v149, v149, v158
	v_cvt_pk_bf16_f32 v150, v150, v157
	v_cvt_pk_bf16_f32 v151, v151, v156
	v_cvt_pk_bf16_f32 v152, v152, v155
	v_cvt_pk_bf16_f32 v153, v153, v154
	v_cvt_pk_bf16_f32 v158, v66, v67
	v_cvt_pk_bf16_f32 v159, v68, v69
	v_cvt_pk_bf16_f32 v160, v70, v71
	v_cvt_pk_bf16_f32 v161, v72, v73
	v_cvt_pk_bf16_f32 v154, v74, v75
	v_cvt_pk_bf16_f32 v155, v76, v77
	v_cvt_pk_bf16_f32 v156, v78, v79
	v_cvt_pk_bf16_f32 v157, v80, v81
	s_nop 1
	v_permlane32_swap_b32_e32 v224, v225
	v_cmp_neq_f32_e64 s[6:7], v229, -v226
	s_cmp_eq_u64 s[6:7], 0
	s_cselect_b64 s[6:7], -1, 0
	v_cndmask_b32_e64 v81, -v226, v97, s[6:7]
	v_cndmask_b32_e64 v80, -v226, v96, s[6:7]
	v_cndmask_b32_e64 v79, -v226, v95, s[6:7]
	v_cndmask_b32_e64 v78, -v226, v94, s[6:7]
	v_cndmask_b32_e64 v77, -v226, v93, s[6:7]
	v_cndmask_b32_e64 v76, -v226, v92, s[6:7]
	v_cndmask_b32_e64 v75, -v226, v91, s[6:7]
	v_cndmask_b32_e64 v74, -v226, v90, s[6:7]
	v_cndmask_b32_e64 v73, -v226, v89, s[6:7]
	v_cndmask_b32_e64 v72, -v226, v88, s[6:7]
	v_cndmask_b32_e64 v71, -v226, v87, s[6:7]
	v_cndmask_b32_e64 v70, -v226, v86, s[6:7]
	v_cndmask_b32_e64 v69, -v226, v85, s[6:7]
	v_cndmask_b32_e64 v68, -v226, v84, s[6:7]
	v_cndmask_b32_e64 v67, -v226, v83, s[6:7]
	v_cndmask_b32_e64 v66, -v226, v82, s[6:7]
	ds_read_b128 v[82:85], v221 offset:0
	ds_read_b128 v[162:165], v221 offset:0x3000
	ds_read_b128 v[166:169], v220 offset:0
	ds_read_b128 v[170:173], v220 offset:0x3000
	s_waitcnt lgkmcnt(2)
	s_nop 1
	v_mfma_f32_32x32x16_bf16 v[98:113], v[82:85], v[142:145], v[66:81]
	v_mfma_f32_32x32x16_bf16 v[82:97], v[162:165], v[142:145], v[66:81]
	ds_read_b128 v[162:165], v219 offset:0
	ds_read_b128 v[174:177], v219 offset:0x3000
	s_waitcnt lgkmcnt(2)
	v_mfma_f32_32x32x16_bf16 v[98:113], v[166:169], v[138:141], v[98:113]
	ds_read_b128 v[166:169], v218 offset:0
	v_mfma_f32_32x32x16_bf16 v[82:97], v[170:173], v[138:141], v[82:97]
	ds_read_b128 v[170:173], v218 offset:0x3000
	s_waitcnt lgkmcnt(2)
	v_mfma_f32_32x32x16_bf16 v[98:113], v[162:165], v[134:137], v[98:113]
	ds_read_b128 v[162:165], v221 offset:0x80
	v_mfma_f32_32x32x16_bf16 v[82:97], v[174:177], v[134:137], v[82:97]
	ds_read_b128 v[174:177], v221 offset:0x3080
	s_waitcnt lgkmcnt(2)
	v_mfma_f32_32x32x16_bf16 v[98:113], v[166:169], v[130:133], v[98:113]
	ds_read_b128 v[166:169], v220 offset:0x80
	v_mfma_f32_32x32x16_bf16 v[82:97], v[170:173], v[130:133], v[82:97]
	ds_read_b128 v[170:173], v220 offset:0x3080
	s_waitcnt lgkmcnt(2)
	v_mfma_f32_32x32x16_bf16 v[98:113], v[162:165], v[126:129], v[98:113]
	ds_read_b128 v[162:165], v219 offset:0x80
	v_mfma_f32_32x32x16_bf16 v[82:97], v[174:177], v[126:129], v[82:97]
	ds_read_b128 v[174:177], v219 offset:0x3080
	s_waitcnt lgkmcnt(2)
	v_mfma_f32_32x32x16_bf16 v[98:113], v[166:169], v[122:125], v[98:113]
	ds_read_b128 v[166:169], v218 offset:0x80
	v_mfma_f32_32x32x16_bf16 v[82:97], v[170:173], v[122:125], v[82:97]
	ds_read_b128 v[170:173], v218 offset:0x3080
	s_waitcnt lgkmcnt(2)
	v_mfma_f32_32x32x16_bf16 v[98:113], v[162:165], v[118:121], v[98:113]
	ds_read_b128 v[162:165], v221 offset:0x100
	v_mfma_f32_32x32x16_bf16 v[82:97], v[174:177], v[118:121], v[82:97]
	ds_read_b128 v[174:177], v221 offset:0x3100
	ds_read_b128 v[178:181], v199 offset:0
	s_waitcnt lgkmcnt(3)
	v_mfma_f32_32x32x16_bf16 v[98:113], v[166:169], v[114:117], v[98:113]
	ds_read_b128 v[166:169], v220 offset:0x100
	v_mfma_f32_32x32x16_bf16 v[82:97], v[170:173], v[114:117], v[82:97]
	ds_read_b128 v[170:173], v220 offset:0x3100
	ds_read_b128 v[230:233], v199 offset:0x400
	s_waitcnt lgkmcnt(3)
	v_mfma_f32_32x32x16_bf16 v[98:113], v[162:165], v[178:181], v[98:113]
	ds_read_b128 v[162:165], v219 offset:0x100
	v_mfma_f32_32x32x16_bf16 v[82:97], v[174:177], v[178:181], v[82:97]
	ds_read_b128 v[174:177], v219 offset:0x3100
	ds_read_b128 v[178:181], v199 offset:0x800
	s_waitcnt lgkmcnt(3)
	v_mfma_f32_32x32x16_bf16 v[98:113], v[166:169], v[230:233], v[98:113]
	ds_read_b128 v[166:169], v218 offset:0x100
	v_mfma_f32_32x32x16_bf16 v[82:97], v[170:173], v[230:233], v[82:97]
	ds_read_b128 v[170:173], v218 offset:0x3100
	ds_read_b128 v[230:233], v199 offset:0xc00
	s_waitcnt lgkmcnt(3)
	v_mfma_f32_32x32x16_bf16 v[98:113], v[162:165], v[178:181], v[98:113]
	s_waitcnt lgkmcnt(0)
	v_mfma_f32_32x32x16_bf16 v[82:97], v[174:177], v[178:181], v[82:97]
	v_mfma_f32_32x32x16_bf16 v[98:113], v[166:169], v[230:233], v[98:113]
	v_mfma_f32_32x32x16_bf16 v[82:97], v[170:173], v[230:233], v[82:97]
	s_nop 10
	v_max_f32_e32 v162, v102, v102
	v_max_f32_e32 v163, v98, v98
	v_max_f32_e32 v162, v163, v162
	v_max_f32_e32 v163, v103, v103
	v_max_f32_e32 v164, v99, v99
	v_max_f32_e32 v163, v164, v163
	v_max_f32_e32 v164, v105, v105
	v_max_f32_e32 v165, v101, v101
	v_max_f32_e32 v164, v165, v164
	v_max3_f32 v165, v100, v104, v108
	v_max3_f32 v164, v164, v109, v113
	v_max3_f32 v162, v162, v106, v110
	v_max3_f32 v163, v163, v107, v111
	v_max3_f32 v165, v165, v112, v84
	v_max3_f32 v164, v164, v85, v89
	v_max3_f32 v162, v162, v82, v86
	v_max3_f32 v163, v163, v83, v87
	v_max3_f32 v165, v165, v88, v92
	v_max3_f32 v164, v164, v93, v97
	v_max3_f32 v162, v162, v90, v94
	v_max3_f32 v163, v163, v91, v95
	v_max3_f32 v164, v165, v96, v164
	v_max3_f32 v162, v162, v163, v164
	v_mov_b32_e32 v163, v162
	s_nop 1
	v_permlane32_swap_b32_e32 v162, v163
	v_max_f32_e32 v163, v163, v163
	v_max_f32_e32 v162, v162, v162
	v_max_f32_e32 v162, v162, v163
	v_cmp_ge_f32_e32 vcc, s48, v162
	s_cmp_eq_u64 vcc, exec
	s_cbranch_scc0 .LBB0_374
	v_mov_b32_e32 v228, v226
	v_mov_b32_e32 v227, 1.0

; template <bool FIRST>
; __device__ __forceinline__ void partialSM(f32x16& p0, f32x16& p1, float& mC, float& alpha) {
;     ...
;   for (int r = 0; r < 16; ++r) p0[r] = __builtin_amdgcn_exp2f(p0[r]);
; }
; template <bool EXP1 = true>
; __device__ __forceinline__ void finishSM(f32x16& p0, f32x16& p1, float alpha, float& l_reg, bf16x8& pa0, bf16x8& pa1, bf16x8& pa2, bf16x8& pa3) {
;   if constexpr (EXP1) {
; #pragma unroll
;   for (int r = 0; r < 16; ++r) p1[r] = __builtin_amdgcn_exp2f(p1[r]);
;   }
;   float sm_[4] = {p0[0], p0[1], p0[2], p0[3]};
; #pragma unroll
;   for (int r = 4; r < 16; ++r) sm_[r & 3] += p0[r];
; #pragma unroll
;   for (int r = 0; r < 16; ++r) sm_[r & 3] += p1[r];
;   float ps = (sm_[0] + sm_[1]) + (sm_[2] + sm_[3]);
;   { auto rr = __builtin_amdgcn_permlane32_swap(__float_as_uint(ps), __float_as_uint(ps), false, false);
;     ps = __uint_as_float(rr[0]) + __uint_as_float(rr[1]); }
;   l_reg = l_reg * alpha + ps;
.LBB0_366:
	v_exp_f32_e32 v146, v98
	v_exp_f32_e32 v153, v99
	v_exp_f32_e32 v147, v100
	v_exp_f32_e32 v152, v101
	v_exp_f32_e32 v148, v102
	v_exp_f32_e32 v151, v103
	v_exp_f32_e32 v149, v104
	v_exp_f32_e32 v150, v105
	v_exp_f32_e32 v103, v106
	v_exp_f32_e32 v105, v107
	v_exp_f32_e32 v101, v108
	v_exp_f32_e32 v104, v109
	v_exp_f32_e32 v99, v110
	v_exp_f32_e32 v102, v111
	v_exp_f32_e32 v98, v112
	v_exp_f32_e32 v100, v113
	v_xor_b32_e32 v106, 0x80000000, v226
	v_exp_f32_e32 v82, v82
	v_exp_f32_e32 v83, v83
	v_exp_f32_e32 v84, v84
	v_exp_f32_e32 v85, v85
	v_cndmask_b32_e64 v229, v106, v229, s[6:7]
	v_exp_f32_e32 v86, v86
	v_exp_f32_e32 v87, v87
	v_exp_f32_e32 v88, v88
	v_exp_f32_e32 v89, v89
	v_add_f32_e32 v106, v148, v146
	v_add_f32_e32 v107, v151, v153
	v_add_f32_e32 v108, v149, v147
	v_add_f32_e32 v109, v150, v152
	v_exp_f32_e32 v90, v90
	v_exp_f32_e32 v91, v91
	v_exp_f32_e32 v92, v92
	v_exp_f32_e32 v93, v93
	v_add_f32_e32 v106, v103, v106
	v_add_f32_e32 v107, v105, v107
	v_add_f32_e32 v108, v101, v108
	v_add_f32_e32 v109, v104, v109
	v_exp_f32_e32 v94, v94
	v_exp_f32_e32 v95, v95
	v_exp_f32_e32 v96, v96
	v_exp_f32_e32 v97, v97
	v_add_f32_e32 v106, v99, v106
	v_add_f32_e32 v107, v102, v107
	v_add_f32_e32 v108, v98, v108
	v_add_f32_e32 v109, v100, v109
	v_add_f32_e32 v106, v82, v106
	v_add_f32_e32 v107, v107, v83
	v_add_f32_e32 v108, v108, v84
	v_add_f32_e32 v109, v109, v85
	v_add_f32_e32 v106, v86, v106
	v_add_f32_e32 v107, v87, v107
	v_add_f32_e32 v108, v88, v108
	v_add_f32_e32 v109, v89, v109
	v_add_f32_e32 v106, v90, v106
	v_add_f32_e32 v107, v91, v107
	v_add_f32_e32 v108, v92, v108
	v_add_f32_e32 v109, v93, v109
	v_add_f32_e32 v106, v94, v106
	v_add_f32_e32 v107, v95, v107
	v_add_f32_e32 v108, v96, v108
	v_add_f32_e32 v109, v97, v109
	v_add_f32_e32 v106, v106, v107
	v_add_f32_e32 v107, v108, v109
	v_add_f32_e32 v230, v106, v107
	s_waitcnt lgkmcnt(0)
	s_barrier
; __device__ __forceinline__ void qkt12_roll(f32x16& p0, f32x16& p1, const f32x16& negm, int kb, int qa, const bf16x8* qr) {
;   const int a0 = kb ^ (0 << 5); const bf16x8 x0 = lds_rd128<0>(a0), y0 = lds_rd128<12288>(a0);
;   const int a1 = kb ^ (1 << 5); const bf16x8 x1 = lds_rd128<0>(a1), y1 = lds_rd128<12288>(a1);
;   asm volatile("s_waitcnt lgkmcnt(2)" ::: "memory"); SBAR();
;   p0 = __builtin_amdgcn_mfma_f32_32x32x16_bf16(x0, qr[0], negm, 0, 0, 0); p1 = __builtin_amdgcn_mfma_f32_32x32x16_bf16(y0, qr[0], negm, 0, 0, 0);
;   const int a2 = kb ^ (2 << 5); const bf16x8 x2 = lds_rd128<0>(a2), y2 = lds_rd128<12288>(a2);
;   asm volatile("s_waitcnt lgkmcnt(2)" ::: "memory"); SBAR();
;   p0 = __builtin_amdgcn_mfma_f32_32x32x16_bf16(x1, qr[1], p0, 0, 0, 0); p1 = __builtin_amdgcn_mfma_f32_32x32x16_bf16(y1, qr[1], p1, 0, 0, 0);
;   const int a3 = kb ^ (3 << 5); const bf16x8 x3 = lds_rd128<0>(a3), y3 = lds_rd128<12288>(a3);
;   asm volatile("s_waitcnt lgkmcnt(2)" ::: "memory"); SBAR();
;   p0 = __builtin_amdgcn_mfma_f32_32x32x16_bf16(x2, qr[2], p0, 0, 0, 0); p1 = __builtin_amdgcn_mfma_f32_32x32x16_bf16(y2, qr[2], p1, 0, 0, 0);
;   const int a4 = kb ^ (0 << 5); const bf16x8 x4 = lds_rd128<128>(a4), y4 = lds_rd128<12416>(a4);
;   asm volatile("s_waitcnt lgkmcnt(2)" ::: "memory"); SBAR();
;   p0 = __builtin_amdgcn_mfma_f32_32x32x16_bf16(x3, qr[3], p0, 0, 0, 0); p1 = __builtin_amdgcn_mfma_f32_32x32x16_bf16(y3, qr[3], p1, 0, 0, 0);
;   const int a5 = kb ^ (1 << 5); const bf16x8 x5 = lds_rd128<128>(a5), y5 = lds_rd128<12416>(a5);
;   asm volatile("s_waitcnt lgkmcnt(2)" ::: "memory"); SBAR();
;   p0 = __builtin_amdgcn_mfma_f32_32x32x16_bf16(x4, qr[4], p0, 0, 0, 0); p1 = __builtin_amdgcn_mfma_f32_32x32x16_bf16(y4, qr[4], p1, 0, 0, 0);
;   const int a6 = kb ^ (2 << 5); const bf16x8 x6 = lds_rd128<128>(a6), y6 = lds_rd128<12416>(a6);
;   asm volatile("s_waitcnt lgkmcnt(2)" ::: "memory"); SBAR();
;   p0 = __builtin_amdgcn_mfma_f32_32x32x16_bf16(x5, qr[5], p0, 0, 0, 0); p1 = __builtin_amdgcn_mfma_f32_32x32x16_bf16(y5, qr[5], p1, 0, 0, 0);
;   const int a7 = kb ^ (3 << 5); const bf16x8 x7 = lds_rd128<128>(a7), y7 = lds_rd128<12416>(a7);
;   asm volatile("s_waitcnt lgkmcnt(2)" ::: "memory"); SBAR();
;   p0 = __builtin_amdgcn_mfma_f32_32x32x16_bf16(x6, qr[6], p0, 0, 0, 0); p1 = __builtin_amdgcn_mfma_f32_32x32x16_bf16(y6, qr[6], p1, 0, 0, 0);
	v_mov_b32_e32 v231, v230
	v_cvt_pk_bf16_f32 v146, v146, v153
	v_cvt_pk_bf16_f32 v147, v147, v152
	v_cvt_pk_bf16_f32 v148, v148, v151
	v_cvt_pk_bf16_f32 v149, v149, v150
	v_cvt_pk_bf16_f32 v150, v103, v105
	v_cvt_pk_bf16_f32 v151, v101, v104
	v_cvt_pk_bf16_f32 v152, v99, v102
	v_cvt_pk_bf16_f32 v153, v98, v100
	v_cvt_pk_bf16_f32 v158, v82, v83
	v_cvt_pk_bf16_f32 v159, v84, v85
	v_cvt_pk_bf16_f32 v160, v86, v87
	v_cvt_pk_bf16_f32 v161, v88, v89
	v_cvt_pk_bf16_f32 v154, v90, v91
	v_cvt_pk_bf16_f32 v155, v92, v93
	v_cvt_pk_bf16_f32 v156, v94, v95
	v_cvt_pk_bf16_f32 v157, v96, v97
	s_nop 1
	v_permlane32_swap_b32_e32 v230, v231
	v_cmp_neq_f32_e64 s[6:7], v229, -v228
	s_cmp_eq_u64 s[6:7], 0
	s_cselect_b64 s[6:7], -1, 0
	v_cndmask_b32_e64 v97, -v228, v81, s[6:7]
	v_cndmask_b32_e64 v96, -v228, v80, s[6:7]
	v_cndmask_b32_e64 v95, -v228, v79, s[6:7]
	v_cndmask_b32_e64 v94, -v228, v78, s[6:7]
	v_cndmask_b32_e64 v93, -v228, v77, s[6:7]
	v_cndmask_b32_e64 v92, -v228, v76, s[6:7]
	v_cndmask_b32_e64 v91, -v228, v75, s[6:7]
	v_cndmask_b32_e64 v90, -v228, v74, s[6:7]
	v_cndmask_b32_e64 v89, -v228, v73, s[6:7]
	v_cndmask_b32_e64 v88, -v228, v72, s[6:7]
	v_cndmask_b32_e64 v87, -v228, v71, s[6:7]
	v_cndmask_b32_e64 v86, -v228, v70, s[6:7]
	v_cndmask_b32_e64 v85, -v228, v69, s[6:7]
	v_cndmask_b32_e64 v84, -v228, v68, s[6:7]
	v_cndmask_b32_e64 v83, -v228, v67, s[6:7]
	v_cndmask_b32_e64 v82, -v228, v66, s[6:7]
	ds_read_b128 v[66:69], v209 offset:0
	ds_read_b128 v[162:165], v209 offset:0x3000
	ds_read_b128 v[166:169], v215 offset:0
	ds_read_b128 v[170:173], v215 offset:0x3000
	s_waitcnt lgkmcnt(2)
	s_nop 1
	v_mfma_f32_32x32x16_bf16 v[98:113], v[66:69], v[142:145], v[82:97]
	v_mfma_f32_32x32x16_bf16 v[66:81], v[162:165], v[142:145], v[82:97]
	ds_read_b128 v[162:165], v216 offset:0
	ds_read_b128 v[174:177], v216 offset:0x3000
	s_waitcnt lgkmcnt(2)
	v_mfma_f32_32x32x16_bf16 v[98:113], v[166:169], v[138:141], v[98:113]
	ds_read_b128 v[166:169], v217 offset:0
	v_mfma_f32_32x32x16_bf16 v[66:81], v[170:173], v[138:141], v[66:81]
	ds_read_b128 v[170:173], v217 offset:0x3000
	s_waitcnt lgkmcnt(2)
	v_mfma_f32_32x32x16_bf16 v[98:113], v[162:165], v[134:137], v[98:113]
	ds_read_b128 v[162:165], v209 offset:0x80
	v_mfma_f32_32x32x16_bf16 v[66:81], v[174:177], v[134:137], v[66:81]
	ds_read_b128 v[174:177], v209 offset:0x3080
	s_waitcnt lgkmcnt(2)
	v_mfma_f32_32x32x16_bf16 v[98:113], v[166:169], v[130:133], v[98:113]
	ds_read_b128 v[166:169], v215 offset:0x80
	v_mfma_f32_32x32x16_bf16 v[66:81], v[170:173], v[130:133], v[66:81]
	ds_read_b128 v[170:173], v215 offset:0x3080
	s_waitcnt lgkmcnt(2)
	v_mfma_f32_32x32x16_bf16 v[98:113], v[162:165], v[126:129], v[98:113]
	ds_read_b128 v[162:165], v216 offset:0x80
	v_mfma_f32_32x32x16_bf16 v[66:81], v[174:177], v[126:129], v[66:81]
	ds_read_b128 v[174:177], v216 offset:0x3080
	s_waitcnt lgkmcnt(2)
	v_mfma_f32_32x32x16_bf16 v[98:113], v[166:169], v[122:125], v[98:113]
	ds_read_b128 v[166:169], v217 offset:0x80
	v_mfma_f32_32x32x16_bf16 v[66:81], v[170:173], v[122:125], v[66:81]
	ds_read_b128 v[170:173], v217 offset:0x3080
	s_waitcnt lgkmcnt(2)
	v_mfma_f32_32x32x16_bf16 v[98:113], v[162:165], v[118:121], v[98:113]
	ds_read_b128 v[162:165], v209 offset:0x100
	v_mfma_f32_32x32x16_bf16 v[66:81], v[174:177], v[118:121], v[66:81]
	ds_read_b128 v[174:177], v209 offset:0x3100
	ds_read_b128 v[178:181], v199 offset:0
	s_waitcnt lgkmcnt(3)
	v_mfma_f32_32x32x16_bf16 v[98:113], v[166:169], v[114:117], v[98:113]
	ds_read_b128 v[166:169], v215 offset:0x100
	v_mfma_f32_32x32x16_bf16 v[66:81], v[170:173], v[114:117], v[66:81]
	ds_read_b128 v[170:173], v215 offset:0x3100
	ds_read_b128 v[232:235], v199 offset:0x400
	s_waitcnt lgkmcnt(3)
	v_mfma_f32_32x32x16_bf16 v[98:113], v[162:165], v[178:181], v[98:113]
	ds_read_b128 v[162:165], v216 offset:0x100
	v_mfma_f32_32x32x16_bf16 v[66:81], v[174:177], v[178:181], v[66:81]
	ds_read_b128 v[174:177], v216 offset:0x3100
	ds_read_b128 v[178:181], v199 offset:0x800
	s_waitcnt lgkmcnt(3)
	v_mfma_f32_32x32x16_bf16 v[98:113], v[166:169], v[232:235], v[98:113]
	ds_read_b128 v[166:169], v217 offset:0x100
	v_mfma_f32_32x32x16_bf16 v[66:81], v[170:173], v[232:235], v[66:81]
	ds_read_b128 v[170:173], v217 offset:0x3100
	ds_read_b128 v[232:235], v199 offset:0xc00
	s_waitcnt lgkmcnt(3)
	v_mfma_f32_32x32x16_bf16 v[98:113], v[162:165], v[178:181], v[98:113]
	s_waitcnt lgkmcnt(0)
	v_mfma_f32_32x32x16_bf16 v[66:81], v[174:177], v[178:181], v[66:81]
	v_mfma_f32_32x32x16_bf16 v[98:113], v[166:169], v[232:235], v[98:113]
	v_mfma_f32_32x32x16_bf16 v[66:81], v[170:173], v[232:235], v[66:81]
	s_nop 10
	v_max_f32_e32 v162, v102, v102
	v_max_f32_e32 v163, v98, v98
	v_max_f32_e32 v162, v163, v162
	v_max_f32_e32 v163, v103, v103
	v_max_f32_e32 v164, v99, v99
	v_max_f32_e32 v163, v164, v163
	v_max_f32_e32 v164, v105, v105
	v_max_f32_e32 v165, v101, v101
	v_max_f32_e32 v164, v165, v164
	v_max3_f32 v165, v100, v104, v108
	v_max3_f32 v164, v164, v109, v113
	v_max3_f32 v162, v162, v106, v110
	v_max3_f32 v163, v163, v107, v111
	v_max3_f32 v165, v165, v112, v68
	v_max3_f32 v164, v164, v69, v73
	v_max3_f32 v162, v162, v66, v70
	v_max3_f32 v163, v163, v67, v71
	v_max3_f32 v165, v165, v72, v76
	v_max3_f32 v164, v164, v77, v81
	v_max3_f32 v162, v162, v74, v78
	v_max3_f32 v163, v163, v75, v79
	v_max3_f32 v164, v165, v80, v164
	v_max3_f32 v162, v162, v163, v164
	v_mov_b32_e32 v163, v162
	s_nop 1
	v_permlane32_swap_b32_e32 v162, v163
	v_max_f32_e32 v163, v163, v163
	v_max_f32_e32 v162, v162, v162
	v_max_f32_e32 v162, v162, v163
	v_cmp_ge_f32_e32 vcc, s48, v162
	s_cmp_eq_u64 vcc, exec
	v_mov_b32_e32 v223, 1.0
	s_cbranch_scc0 .LBB0_375
	v_mov_b32_e32 v226, v228

; #define SBAR() __builtin_amdgcn_sched_barrier(0)
; __device__ __forceinline__ void qkt12_roll(f32x16& p0, f32x16& p1, const f32x16& negm, int kb, int qa, const bf16x8* qr) {
;   const int a0 = kb ^ (0 << 5); const bf16x8 x0 = lds_rd128<0>(a0), y0 = lds_rd128<12288>(a0);
;   const int a1 = kb ^ (1 << 5); const bf16x8 x1 = lds_rd128<0>(a1), y1 = lds_rd128<12288>(a1);
;   asm volatile("s_waitcnt lgkmcnt(2)" ::: "memory"); SBAR();
;   p0 = __builtin_amdgcn_mfma_f32_32x32x16_bf16(x0, qr[0], negm, 0, 0, 0); p1 = __builtin_amdgcn_mfma_f32_32x32x16_bf16(y0, qr[0], negm, 0, 0, 0);
;   const int a2 = kb ^ (2 << 5); const bf16x8 x2 = lds_rd128<0>(a2), y2 = lds_rd128<12288>(a2);
;   asm volatile("s_waitcnt lgkmcnt(2)" ::: "memory"); SBAR();
;   p0 = __builtin_amdgcn_mfma_f32_32x32x16_bf16(x1, qr[1], p0, 0, 0, 0); p1 = __builtin_amdgcn_mfma_f32_32x32x16_bf16(y1, qr[1], p1, 0, 0, 0);
;   const int a3 = kb ^ (3 << 5); const bf16x8 x3 = lds_rd128<0>(a3), y3 = lds_rd128<12288>(a3);
;   asm volatile("s_waitcnt lgkmcnt(2)" ::: "memory"); SBAR();
;   p0 = __builtin_amdgcn_mfma_f32_32x32x16_bf16(x2, qr[2], p0, 0, 0, 0); p1 = __builtin_amdgcn_mfma_f32_32x32x16_bf16(y2, qr[2], p1, 0, 0, 0);
;   const int a4 = kb ^ (0 << 5); const bf16x8 x4 = lds_rd128<128>(a4), y4 = lds_rd128<12416>(a4);
;   asm volatile("s_waitcnt lgkmcnt(2)" ::: "memory"); SBAR();
;   p0 = __builtin_amdgcn_mfma_f32_32x32x16_bf16(x3, qr[3], p0, 0, 0, 0); p1 = __builtin_amdgcn_mfma_f32_32x32x16_bf16(y3, qr[3], p1, 0, 0, 0);
;   const int a5 = kb ^ (1 << 5); const bf16x8 x5 = lds_rd128<128>(a5), y5 = lds_rd128<12416>(a5);
;   asm volatile("s_waitcnt lgkmcnt(2)" ::: "memory"); SBAR();
;   p0 = __builtin_amdgcn_mfma_f32_32x32x16_bf16(x4, qr[4], p0, 0, 0, 0); p1 = __builtin_amdgcn_mfma_f32_32x32x16_bf16(y4, qr[4], p1, 0, 0, 0);
;   const int a6 = kb ^ (2 << 5); const bf16x8 x6 = lds_rd128<128>(a6), y6 = lds_rd128<12416>(a6);
;   asm volatile("s_waitcnt lgkmcnt(2)" ::: "memory"); SBAR();
;   p0 = __builtin_amdgcn_mfma_f32_32x32x16_bf16(x5, qr[5], p0, 0, 0, 0); p1 = __builtin_amdgcn_mfma_f32_32x32x16_bf16(y5, qr[5], p1, 0, 0, 0);
;   const int a7 = kb ^ (3 << 5); const bf16x8 x7 = lds_rd128<128>(a7), y7 = lds_rd128<12416>(a7);
;   asm volatile("s_waitcnt lgkmcnt(2)" ::: "memory"); SBAR();
;     ...
;   NEGM_UPD(kbeg + (NT - 1) * KVBLK); SBAR(); QKT(pB0, pB1, SHM_K);
.LBB0_376:
	v_cmp_neq_f32_e64 s[6:7], v229, -v226
	s_cmp_eq_u64 s[6:7], 0
	s_cselect_b64 s[6:7], -1, 0
	v_cndmask_b32_e64 v97, -v226, v97, s[6:7]
	v_cndmask_b32_e64 v96, -v226, v96, s[6:7]
	v_cndmask_b32_e64 v95, -v226, v95, s[6:7]
	v_cndmask_b32_e64 v94, -v226, v94, s[6:7]
	v_cndmask_b32_e64 v93, -v226, v93, s[6:7]
	v_cndmask_b32_e64 v92, -v226, v92, s[6:7]
	v_cndmask_b32_e64 v91, -v226, v91, s[6:7]
	v_cndmask_b32_e64 v90, -v226, v90, s[6:7]
	v_cndmask_b32_e64 v89, -v226, v89, s[6:7]
	v_cndmask_b32_e64 v88, -v226, v88, s[6:7]
	v_cndmask_b32_e64 v87, -v226, v87, s[6:7]
	v_cndmask_b32_e64 v86, -v226, v86, s[6:7]
	v_cndmask_b32_e64 v85, -v226, v85, s[6:7]
	v_cndmask_b32_e64 v84, -v226, v84, s[6:7]
	v_cndmask_b32_e64 v83, -v226, v83, s[6:7]
	v_cndmask_b32_e64 v82, -v226, v82, s[6:7]
	ds_read_b128 v[162:165], v221 offset:0
	ds_read_b128 v[166:169], v221 offset:0x3000
	ds_read_b128 v[170:173], v220 offset:0
	ds_read_b128 v[174:177], v220 offset:0x3000
	s_waitcnt lgkmcnt(2)
	s_nop 1
	v_mfma_f32_32x32x16_bf16 v[98:113], v[162:165], v[142:145], v[82:97]
	v_mfma_f32_32x32x16_bf16 v[82:97], v[166:169], v[142:145], v[82:97]
	ds_read_b128 v[142:145], v219 offset:0
	ds_read_b128 v[162:165], v219 offset:0x3000
	s_waitcnt lgkmcnt(2)
	v_mfma_f32_32x32x16_bf16 v[98:113], v[170:173], v[138:141], v[98:113]
	v_mfma_f32_32x32x16_bf16 v[82:97], v[174:177], v[138:141], v[82:97]
	ds_read_b128 v[138:141], v218 offset:0
	ds_read_b128 v[166:169], v218 offset:0x3000
	s_waitcnt lgkmcnt(2)
	v_mfma_f32_32x32x16_bf16 v[98:113], v[142:145], v[134:137], v[98:113]
	v_mfma_f32_32x32x16_bf16 v[82:97], v[162:165], v[134:137], v[82:97]
	ds_read_b128 v[134:137], v221 offset:0x80
	ds_read_b128 v[142:145], v221 offset:0x3080
	s_waitcnt lgkmcnt(2)
	v_mfma_f32_32x32x16_bf16 v[98:113], v[138:141], v[130:133], v[98:113]
	v_mfma_f32_32x32x16_bf16 v[82:97], v[166:169], v[130:133], v[82:97]
	ds_read_b128 v[130:133], v220 offset:0x80
	ds_read_b128 v[138:141], v220 offset:0x3080
	s_waitcnt lgkmcnt(2)
	v_mfma_f32_32x32x16_bf16 v[98:113], v[134:137], v[126:129], v[98:113]
	v_mfma_f32_32x32x16_bf16 v[82:97], v[142:145], v[126:129], v[82:97]
	ds_read_b128 v[126:129], v219 offset:0x80
	ds_read_b128 v[134:137], v219 offset:0x3080
	s_waitcnt lgkmcnt(2)
	v_mfma_f32_32x32x16_bf16 v[98:113], v[130:133], v[122:125], v[98:113]
	v_mfma_f32_32x32x16_bf16 v[82:97], v[138:141], v[122:125], v[82:97]
	ds_read_b128 v[122:125], v218 offset:0x80
	ds_read_b128 v[130:133], v218 offset:0x3080
	s_waitcnt lgkmcnt(2)
	v_mfma_f32_32x32x16_bf16 v[98:113], v[126:129], v[118:121], v[98:113]
	v_mfma_f32_32x32x16_bf16 v[82:97], v[134:137], v[118:121], v[82:97]
	ds_read_b128 v[118:121], v221 offset:0x100
	ds_read_b128 v[126:129], v221 offset:0x3100
	ds_read_b128 v[134:137], v199 offset:0
	s_waitcnt lgkmcnt(3)
	v_mfma_f32_32x32x16_bf16 v[98:113], v[122:125], v[114:117], v[98:113]
	v_mfma_f32_32x32x16_bf16 v[82:97], v[130:133], v[114:117], v[82:97]
	ds_read_b128 v[114:117], v220 offset:0x100
	ds_read_b128 v[122:125], v220 offset:0x3100
	ds_read_b128 v[130:133], v199 offset:0x400
	s_waitcnt lgkmcnt(3)
	v_mfma_f32_32x32x16_bf16 v[98:113], v[118:121], v[134:137], v[98:113]
	ds_read_b128 v[118:121], v219 offset:0x100
	v_mfma_f32_32x32x16_bf16 v[82:97], v[126:129], v[134:137], v[82:97]
	ds_read_b128 v[126:129], v219 offset:0x3100
	ds_read_b128 v[134:137], v199 offset:0x800
	s_waitcnt lgkmcnt(3)
	v_mfma_f32_32x32x16_bf16 v[98:113], v[114:117], v[130:133], v[98:113]
	ds_read_b128 v[114:117], v218 offset:0x100
	v_mfma_f32_32x32x16_bf16 v[82:97], v[122:125], v[130:133], v[82:97]
	ds_read_b128 v[122:125], v218 offset:0x3100
	ds_read_b128 v[130:133], v199 offset:0xc00
	s_waitcnt lgkmcnt(3)
	v_mfma_f32_32x32x16_bf16 v[98:113], v[118:121], v[134:137], v[98:113]
	s_waitcnt lgkmcnt(0)
; __device__ __forceinline__ void pv_d0(f32x16* o, int vb, bf16x8 pa0, bf16x8 pa1, bf16x8 pa2, bf16x8 pa3) {
;     ...
;   const s16x4 l0 = tr_read<v_rd_off(0, 0, 0)>(vb), h0 = tr_read<v_rd_off(0, 0, 1)>(vb);
;   const s16x4 l1 = tr_read<v_rd_off(0, 1, 0)>(vb), h1 = tr_read<v_rd_off(0, 1, 1)>(vb);
;   const s16x4 l2 = tr_read<v_rd_off(0, 2, 0)>(vb), h2 = tr_read<v_rd_off(0, 2, 1)>(vb);
;   const s16x4 l3 = tr_read<v_rd_off(0, 3, 0)>(vb), h3 = tr_read<v_rd_off(0, 3, 1)>(vb);
;   const s16x4 l4 = tr_read<v_rd_off(1, 0, 0)>(vb), h4 = tr_read<v_rd_off(1, 0, 1)>(vb);
;   asm volatile("s_waitcnt lgkmcnt(8)" ::: "memory"); SBAR();
;   o[0] = __builtin_amdgcn_mfma_f32_32x32x16_bf16(pa0, PK(l0, h0), o[0], 0, 0, 0);
;   const s16x4 l5 = tr_read<v_rd_off(1, 1, 0)>(vb), h5 = tr_read<v_rd_off(1, 1, 1)>(vb);
;   asm volatile("s_waitcnt lgkmcnt(8)" ::: "memory"); SBAR();
;   o[0] = __builtin_amdgcn_mfma_f32_32x32x16_bf16(pa1, PK(l1, h1), o[0], 0, 0, 0);
;   const s16x4 l6 = tr_read<v_rd_off(1, 2, 0)>(vb), h6 = tr_read<v_rd_off(1, 2, 1)>(vb);
;   asm volatile("s_waitcnt lgkmcnt(8)" ::: "memory"); SBAR();
;   o[0] = __builtin_amdgcn_mfma_f32_32x32x16_bf16(pa2, PK(l2, h2), o[0], 0, 0, 0);
;   const s16x4 l7 = tr_read<v_rd_off(1, 3, 0)>(vb), h7 = tr_read<v_rd_off(1, 3, 1)>(vb);
;   asm volatile("s_waitcnt lgkmcnt(8)" ::: "memory"); SBAR();
;   o[0] = __builtin_amdgcn_mfma_f32_32x32x16_bf16(pa3, PK(l3, h3), o[0], 0, 0, 0);
;   const s16x4 l8 = tr_read<v_rd_off(2, 0, 0)>(vb), h8 = tr_read<v_rd_off(2, 0, 1)>(vb);
;   asm volatile("s_waitcnt lgkmcnt(8)" ::: "memory"); SBAR();
;   o[1] = __builtin_amdgcn_mfma_f32_32x32x16_bf16(pa0, PK(l4, h4), o[1], 0, 0, 0);
;   const s16x4 l9 = tr_read<v_rd_off(2, 1, 0)>(vb), h9 = tr_read<v_rd_off(2, 1, 1)>(vb);
;   asm volatile("s_waitcnt lgkmcnt(8)" ::: "memory"); SBAR();
;   o[1] = __builtin_amdgcn_mfma_f32_32x32x16_bf16(pa1, PK(l5, h5), o[1], 0, 0, 0);
;   const s16x4 l10 = tr_read<v_rd_off(2, 2, 0)>(vb), h10 = tr_read<v_rd_off(2, 2, 1)>(vb);
;   asm volatile("s_waitcnt lgkmcnt(8)" ::: "memory"); SBAR();
;   o[1] = __builtin_amdgcn_mfma_f32_32x32x16_bf16(pa2, PK(l6, h6), o[1], 0, 0, 0);
;   const s16x4 l11 = tr_read<v_rd_off(2, 3, 0)>(vb), h11 = tr_read<v_rd_off(2, 3, 1)>(vb);
;   asm volatile("s_waitcnt lgkmcnt(8)" ::: "memory"); SBAR();
;   o[1] = __builtin_amdgcn_mfma_f32_32x32x16_bf16(pa3, PK(l7, h7), o[1], 0, 0, 0);
	v_mfma_f32_32x32x16_bf16 v[82:97], v[126:129], v[134:137], v[82:97]
	v_mfma_f32_32x32x16_bf16 v[98:113], v[114:117], v[130:133], v[98:113]
	v_mfma_f32_32x32x16_bf16 v[82:97], v[122:125], v[130:133], v[82:97]
	v_exp_f32_e32 v116, v66
	v_exp_f32_e32 v117, v67
	v_exp_f32_e32 v118, v68
	v_exp_f32_e32 v119, v69
	v_exp_f32_e32 v120, v70
	v_exp_f32_e32 v121, v71
	v_exp_f32_e32 v122, v72
	v_exp_f32_e32 v123, v73
	v_add_f32_e32 v66, v148, v146
	v_add_f32_e32 v67, v159, v161
	v_add_f32_e32 v68, v149, v147
	v_add_f32_e32 v69, v158, v160
	v_exp_f32_e32 v124, v74
	v_exp_f32_e32 v125, v75
	v_exp_f32_e32 v126, v76
	v_exp_f32_e32 v127, v77
	v_add_f32_e32 v66, v150, v66
	v_add_f32_e32 v67, v157, v67
	v_add_f32_e32 v68, v151, v68
	v_add_f32_e32 v69, v156, v69
	v_exp_f32_e32 v128, v78
	v_exp_f32_e32 v129, v79
	v_exp_f32_e32 v130, v80
	v_exp_f32_e32 v81, v81
	v_add_f32_e32 v66, v152, v66
	v_add_f32_e32 v67, v155, v67
	v_add_f32_e32 v68, v153, v68
	v_add_f32_e32 v69, v154, v69
	v_add_f32_e32 v66, v66, v116
	v_add_f32_e32 v67, v67, v117
	v_add_f32_e32 v68, v68, v118
	v_add_f32_e32 v69, v69, v119
	v_add_f32_e32 v66, v120, v66
	v_add_f32_e32 v67, v121, v67
	v_add_f32_e32 v68, v122, v68
	v_add_f32_e32 v69, v123, v69
	v_add_f32_e32 v66, v124, v66
	v_add_f32_e32 v67, v125, v67
	v_add_f32_e32 v68, v126, v68
	v_add_f32_e32 v69, v127, v69
	v_add_f32_e32 v66, v128, v66
	v_add_f32_e32 v67, v129, v67
	v_add_f32_e32 v68, v130, v68
	v_add_f32_e32 v69, v81, v69
	v_add_f32_e32 v66, v66, v67
	v_add_f32_e32 v67, v68, v69
	v_add_f32_e32 v114, v66, v67
	v_mov_b32_e32 v115, v114
	v_cvt_pk_bf16_f32 v66, v146, v161
	v_cvt_pk_bf16_f32 v67, v147, v160
	v_cvt_pk_bf16_f32 v68, v148, v159
	s_nop 1
	v_permlane32_swap_b32_e32 v114, v115
	v_cvt_pk_bf16_f32 v69, v149, v158
	v_cvt_pk_bf16_f32 v70, v150, v157
	v_cvt_pk_bf16_f32 v71, v151, v156
	v_cvt_pk_bf16_f32 v72, v152, v155
	v_cvt_pk_bf16_f32 v73, v153, v154
	v_cvt_pk_bf16_f32 v74, v116, v117
	v_cvt_pk_bf16_f32 v75, v118, v119
	v_cvt_pk_bf16_f32 v76, v120, v121
	v_cvt_pk_bf16_f32 v77, v122, v123
	v_cvt_pk_bf16_f32 v78, v124, v125
	v_cvt_pk_bf16_f32 v79, v126, v127
	v_cvt_pk_bf16_f32 v80, v128, v129
	v_cvt_pk_bf16_f32 v81, v130, v81
	ds_read_b64_tr_b16 v[116:117], v201 offset:0
	ds_read_b64_tr_b16 v[118:119], v201 offset:0x800
	ds_read_b64_tr_b16 v[120:121], v201 offset:0x1000
	ds_read_b64_tr_b16 v[122:123], v201 offset:0x1800
	ds_read_b64_tr_b16 v[124:125], v201 offset:0x2000
	ds_read_b64_tr_b16 v[126:127], v201 offset:0x2800
	ds_read_b64_tr_b16 v[128:129], v201 offset:0x3000
	ds_read_b64_tr_b16 v[130:131], v201 offset:0x3800
	ds_read_b64_tr_b16 v[132:133], v201 offset:0x200
	ds_read_b64_tr_b16 v[134:135], v201 offset:0xa00
	s_waitcnt lgkmcnt(8)
	s_nop 0
	v_mfma_f32_32x32x16_bf16 v[2:17], v[66:69], v[116:119], v[2:17]
	ds_read_b64_tr_b16 v[116:117], v201 offset:0x1200
	ds_read_b64_tr_b16 v[118:119], v201 offset:0x1a00
	s_waitcnt lgkmcnt(8)
	v_mfma_f32_32x32x16_bf16 v[2:17], v[70:73], v[120:123], v[2:17]
	ds_read_b64_tr_b16 v[120:121], v201 offset:0x2200
	ds_read_b64_tr_b16 v[122:123], v201 offset:0x2a00
	s_waitcnt lgkmcnt(8)
	v_mfma_f32_32x32x16_bf16 v[2:17], v[74:77], v[124:127], v[2:17]
	ds_read_b64_tr_b16 v[124:125], v201 offset:0x3200
	ds_read_b64_tr_b16 v[126:127], v201 offset:0x3a00
	s_waitcnt lgkmcnt(8)
	v_mfma_f32_32x32x16_bf16 v[2:17], v[78:81], v[128:131], v[2:17]
	ds_read_b64_tr_b16 v[128:129], v201 offset:0x400
	ds_read_b64_tr_b16 v[130:131], v201 offset:0xc00
	s_waitcnt lgkmcnt(8)
	v_mfma_f32_32x32x16_bf16 v[50:65], v[66:69], v[132:135], v[50:65]
	ds_read_b64_tr_b16 v[132:133], v201 offset:0x1400
	ds_read_b64_tr_b16 v[134:135], v201 offset:0x1c00
	s_waitcnt lgkmcnt(8)
	v_mfma_f32_32x32x16_bf16 v[50:65], v[70:73], v[116:119], v[50:65]
	ds_read_b64_tr_b16 v[116:117], v201 offset:0x2400
	ds_read_b64_tr_b16 v[118:119], v201 offset:0x2c00
	s_waitcnt lgkmcnt(8)
	v_mfma_f32_32x32x16_bf16 v[50:65], v[74:77], v[120:123], v[50:65]
	ds_read_b64_tr_b16 v[120:121], v201 offset:0x3400
	ds_read_b64_tr_b16 v[122:123], v201 offset:0x3c00
	s_waitcnt lgkmcnt(8)
	v_mfma_f32_32x32x16_bf16 v[50:65], v[78:81], v[124:127], v[50:65]
	ds_read_b64_tr_b16 v[124:125], v201 offset:0x600
	ds_read_b64_tr_b16 v[126:127], v201 offset:0xe00
	s_waitcnt lgkmcnt(8)
	v_mfma_f32_32x32x16_bf16 v[34:49], v[66:69], v[128:131], v[34:49]
	ds_read_b64_tr_b16 v[128:129], v201 offset:0x1600
	ds_read_b64_tr_b16 v[130:131], v201 offset:0x1e00
	s_waitcnt lgkmcnt(8)
	v_mfma_f32_32x32x16_bf16 v[34:49], v[70:73], v[132:135], v[34:49]
	ds_read_b64_tr_b16 v[132:133], v201 offset:0x2600
	ds_read_b64_tr_b16 v[134:135], v201 offset:0x2e00
	s_waitcnt lgkmcnt(8)
	v_mfma_f32_32x32x16_bf16 v[34:49], v[74:77], v[116:119], v[34:49]
	ds_read_b64_tr_b16 v[116:117], v201 offset:0x3600
	ds_read_b64_tr_b16 v[118:119], v201 offset:0x3e00
	s_waitcnt lgkmcnt(8)
	v_mfma_f32_32x32x16_bf16 v[34:49], v[78:81], v[120:123], v[34:49]
	s_waitcnt lgkmcnt(6)
	v_mfma_f32_32x32x16_bf16 v[18:33], v[66:69], v[124:127], v[18:33]
	s_waitcnt lgkmcnt(4)
	v_mfma_f32_32x32x16_bf16 v[18:33], v[70:73], v[128:131], v[18:33]
	s_waitcnt lgkmcnt(2)
	v_mfma_f32_32x32x16_bf16 v[18:33], v[74:77], v[132:135], v[18:33]
	s_waitcnt lgkmcnt(0)
	v_max_f32_e32 v66, v102, v102
	v_max_f32_e32 v67, v98, v98
	v_max_f32_e32 v66, v67, v66
	v_max_f32_e32 v67, v103, v103
	v_max_f32_e32 v68, v99, v99
	v_max_f32_e32 v67, v68, v67
	v_max_f32_e32 v68, v105, v105
	v_max_f32_e32 v69, v101, v101
	v_max_f32_e32 v68, v69, v68
	v_max3_f32 v69, v100, v104, v108
	v_max3_f32 v68, v68, v109, v113
	v_max3_f32 v66, v66, v106, v110
	v_max3_f32 v67, v67, v107, v111
	v_max3_f32 v69, v69, v112, v84
	v_max3_f32 v68, v68, v85, v89
	v_max3_f32 v66, v66, v82, v86
	v_max3_f32 v67, v67, v83, v87
	v_max3_f32 v69, v69, v88, v92
	v_max3_f32 v68, v68, v93, v97
	v_mfma_f32_32x32x16_bf16 v[18:33], v[78:81], v[116:119], v[18:33]
	v_max3_f32 v66, v66, v90, v94
	v_max3_f32 v67, v67, v91, v95
	v_max3_f32 v68, v69, v96, v68
	v_max3_f32 v66, v66, v67, v68
	v_mov_b32_e32 v67, v66
	s_nop 1
	v_permlane32_swap_b32_e32 v66, v67
	v_max_f32_e32 v67, v67, v67
	v_max_f32_e32 v66, v66, v66
	v_max_f32_e32 v66, v66, v67
	v_cmp_ge_f32_e32 vcc, s48, v66
	s_cmp_lg_u64 vcc, exec
	v_mov_b32_e32 v116, 1.0
	s_cbranch_scc1 .LBB0_409

; __device__ __forceinline__ void pv_d0(f32x16* o, int vb, bf16x8 pa0, bf16x8 pa1, bf16x8 pa2, bf16x8 pa3) {
;     ...
;   const s16x4 l0 = tr_read<v_rd_off(0, 0, 0)>(vb), h0 = tr_read<v_rd_off(0, 0, 1)>(vb);
;   const s16x4 l1 = tr_read<v_rd_off(0, 1, 0)>(vb), h1 = tr_read<v_rd_off(0, 1, 1)>(vb);
;   const s16x4 l2 = tr_read<v_rd_off(0, 2, 0)>(vb), h2 = tr_read<v_rd_off(0, 2, 1)>(vb);
;   const s16x4 l3 = tr_read<v_rd_off(0, 3, 0)>(vb), h3 = tr_read<v_rd_off(0, 3, 1)>(vb);
;   const s16x4 l4 = tr_read<v_rd_off(1, 0, 0)>(vb), h4 = tr_read<v_rd_off(1, 0, 1)>(vb);
;   asm volatile("s_waitcnt lgkmcnt(8)" ::: "memory"); SBAR();
;   o[0] = __builtin_amdgcn_mfma_f32_32x32x16_bf16(pa0, PK(l0, h0), o[0], 0, 0, 0);
;   const s16x4 l5 = tr_read<v_rd_off(1, 1, 0)>(vb), h5 = tr_read<v_rd_off(1, 1, 1)>(vb);
;   asm volatile("s_waitcnt lgkmcnt(8)" ::: "memory"); SBAR();
;   o[0] = __builtin_amdgcn_mfma_f32_32x32x16_bf16(pa1, PK(l1, h1), o[0], 0, 0, 0);
;   const s16x4 l6 = tr_read<v_rd_off(1, 2, 0)>(vb), h6 = tr_read<v_rd_off(1, 2, 1)>(vb);
;   asm volatile("s_waitcnt lgkmcnt(8)" ::: "memory"); SBAR();
;   o[0] = __builtin_amdgcn_mfma_f32_32x32x16_bf16(pa2, PK(l2, h2), o[0], 0, 0, 0);
;   const s16x4 l7 = tr_read<v_rd_off(1, 3, 0)>(vb), h7 = tr_read<v_rd_off(1, 3, 1)>(vb);
;   asm volatile("s_waitcnt lgkmcnt(8)" ::: "memory"); SBAR();
;   o[0] = __builtin_amdgcn_mfma_f32_32x32x16_bf16(pa3, PK(l3, h3), o[0], 0, 0, 0);
;   const s16x4 l8 = tr_read<v_rd_off(2, 0, 0)>(vb), h8 = tr_read<v_rd_off(2, 0, 1)>(vb);
;   asm volatile("s_waitcnt lgkmcnt(8)" ::: "memory"); SBAR();
;   o[1] = __builtin_amdgcn_mfma_f32_32x32x16_bf16(pa0, PK(l4, h4), o[1], 0, 0, 0);
;   const s16x4 l9 = tr_read<v_rd_off(2, 1, 0)>(vb), h9 = tr_read<v_rd_off(2, 1, 1)>(vb);
;   asm volatile("s_waitcnt lgkmcnt(8)" ::: "memory"); SBAR();
;   o[1] = __builtin_amdgcn_mfma_f32_32x32x16_bf16(pa1, PK(l5, h5), o[1], 0, 0, 0);
;   const s16x4 l10 = tr_read<v_rd_off(2, 2, 0)>(vb), h10 = tr_read<v_rd_off(2, 2, 1)>(vb);
;   asm volatile("s_waitcnt lgkmcnt(8)" ::: "memory"); SBAR();
;   o[1] = __builtin_amdgcn_mfma_f32_32x32x16_bf16(pa2, PK(l6, h6), o[1], 0, 0, 0);
;   const s16x4 l11 = tr_read<v_rd_off(2, 3, 0)>(vb), h11 = tr_read<v_rd_off(2, 3, 1)>(vb);
;   asm volatile("s_waitcnt lgkmcnt(8)" ::: "memory"); SBAR();
;   o[1] = __builtin_amdgcn_mfma_f32_32x32x16_bf16(pa3, PK(l7, h7), o[1], 0, 0, 0);
.LBB0_381:
	v_exp_f32_e32 v66, v98
	v_exp_f32_e32 v81, v99
	v_exp_f32_e32 v67, v100
	v_exp_f32_e32 v80, v101
	v_exp_f32_e32 v68, v102
	v_exp_f32_e32 v79, v103
	v_exp_f32_e32 v69, v104
	v_exp_f32_e32 v78, v105
	v_exp_f32_e32 v70, v106
	v_exp_f32_e32 v77, v107
	v_exp_f32_e32 v71, v108
	v_exp_f32_e32 v76, v109
	v_exp_f32_e32 v72, v110
	v_exp_f32_e32 v75, v111
	v_exp_f32_e32 v73, v112
	v_exp_f32_e32 v74, v113
	v_exp_f32_e32 v98, v82
	v_exp_f32_e32 v99, v83
	v_exp_f32_e32 v84, v84
	v_exp_f32_e32 v85, v85
	v_exp_f32_e32 v86, v86
	v_exp_f32_e32 v87, v87
	v_exp_f32_e32 v88, v88
	v_exp_f32_e32 v89, v89
	v_add_f32_e32 v82, v68, v66
	v_add_f32_e32 v83, v79, v81
	v_add_f32_e32 v100, v69, v67
	v_add_f32_e32 v101, v78, v80
	v_exp_f32_e32 v90, v90
	v_exp_f32_e32 v91, v91
	v_exp_f32_e32 v92, v92
	v_exp_f32_e32 v93, v93
	v_add_f32_e32 v82, v70, v82
	v_add_f32_e32 v83, v77, v83
	v_add_f32_e32 v100, v71, v100
	v_add_f32_e32 v101, v76, v101
	v_exp_f32_e32 v94, v94
	v_exp_f32_e32 v95, v95
	v_exp_f32_e32 v96, v96
	v_exp_f32_e32 v97, v97
	v_add_f32_e32 v82, v72, v82
	v_add_f32_e32 v83, v75, v83
	v_add_f32_e32 v100, v73, v100
	v_add_f32_e32 v101, v74, v101
	v_add_f32_e32 v82, v98, v82
	v_add_f32_e32 v83, v99, v83
	v_add_f32_e32 v100, v100, v84
	v_add_f32_e32 v101, v101, v85
	v_add_f32_e32 v82, v86, v82
	v_add_f32_e32 v83, v87, v83
	v_add_f32_e32 v100, v88, v100
	v_add_f32_e32 v101, v89, v101
	v_add_f32_e32 v82, v90, v82
	v_add_f32_e32 v83, v91, v83
	v_add_f32_e32 v100, v92, v100
	v_add_f32_e32 v101, v93, v101
	v_add_f32_e32 v82, v94, v82
	v_add_f32_e32 v83, v95, v83
	v_add_f32_e32 v100, v96, v100
	v_add_f32_e32 v101, v97, v101
	v_add_f32_e32 v82, v83, v82
	v_add_f32_e32 v83, v100, v101
	v_add_f32_e32 v82, v83, v82
	v_mov_b32_e32 v83, v82
	s_nop 1
	v_permlane32_swap_b32_e32 v82, v83
	v_cvt_pk_bf16_f32 v66, v66, v81
	v_cvt_pk_bf16_f32 v67, v67, v80
	v_cvt_pk_bf16_f32 v68, v68, v79
	v_cvt_pk_bf16_f32 v69, v69, v78
	v_cvt_pk_bf16_f32 v70, v70, v77
	v_cvt_pk_bf16_f32 v71, v71, v76
	v_cvt_pk_bf16_f32 v72, v72, v75
	v_cvt_pk_bf16_f32 v73, v73, v74
	v_cvt_pk_bf16_f32 v74, v98, v99
	v_cvt_pk_bf16_f32 v75, v84, v85
	v_cvt_pk_bf16_f32 v76, v86, v87
	v_cvt_pk_bf16_f32 v77, v88, v89
	v_cvt_pk_bf16_f32 v78, v90, v91
	v_cvt_pk_bf16_f32 v79, v92, v93
	v_cvt_pk_bf16_f32 v80, v94, v95
	v_cvt_pk_bf16_f32 v81, v96, v97
	s_nop 0
	ds_read_b64_tr_b16 v[84:85], v208 offset:0
	ds_read_b64_tr_b16 v[86:87], v208 offset:0x800
	ds_read_b64_tr_b16 v[88:89], v208 offset:0x1000
	ds_read_b64_tr_b16 v[90:91], v208 offset:0x1800
	ds_read_b64_tr_b16 v[92:93], v208 offset:0x2000
	ds_read_b64_tr_b16 v[94:95], v208 offset:0x2800
	ds_read_b64_tr_b16 v[96:97], v208 offset:0x3000
	ds_read_b64_tr_b16 v[98:99], v208 offset:0x3800
	ds_read_b64_tr_b16 v[100:101], v208 offset:0x200
	ds_read_b64_tr_b16 v[102:103], v208 offset:0xa00
	s_waitcnt lgkmcnt(8)
	s_nop 0
	v_mfma_f32_32x32x16_bf16 v[2:17], v[66:69], v[84:87], v[2:17]
	ds_read_b64_tr_b16 v[84:85], v208 offset:0x1200
	ds_read_b64_tr_b16 v[86:87], v208 offset:0x1a00
	s_waitcnt lgkmcnt(8)
	v_mfma_f32_32x32x16_bf16 v[2:17], v[70:73], v[88:91], v[2:17]
	ds_read_b64_tr_b16 v[88:89], v208 offset:0x2200
	ds_read_b64_tr_b16 v[90:91], v208 offset:0x2a00
	s_waitcnt lgkmcnt(8)
	v_mfma_f32_32x32x16_bf16 v[2:17], v[74:77], v[92:95], v[2:17]
	ds_read_b64_tr_b16 v[92:93], v208 offset:0x3200
	ds_read_b64_tr_b16 v[94:95], v208 offset:0x3a00
	s_waitcnt lgkmcnt(8)
	v_mfma_f32_32x32x16_bf16 v[2:17], v[78:81], v[96:99], v[2:17]
	ds_read_b64_tr_b16 v[96:97], v208 offset:0x400
	ds_read_b64_tr_b16 v[98:99], v208 offset:0xc00
	s_waitcnt lgkmcnt(8)
	v_mfma_f32_32x32x16_bf16 v[50:65], v[66:69], v[100:103], v[50:65]
	ds_read_b64_tr_b16 v[100:101], v208 offset:0x1400
	ds_read_b64_tr_b16 v[102:103], v208 offset:0x1c00
	s_waitcnt lgkmcnt(8)
	v_mfma_f32_32x32x16_bf16 v[50:65], v[70:73], v[84:87], v[50:65]
	ds_read_b64_tr_b16 v[84:85], v208 offset:0x2400
	ds_read_b64_tr_b16 v[86:87], v208 offset:0x2c00
	s_waitcnt lgkmcnt(8)
	v_mfma_f32_32x32x16_bf16 v[50:65], v[74:77], v[88:91], v[50:65]
	ds_read_b64_tr_b16 v[88:89], v208 offset:0x3400
	ds_read_b64_tr_b16 v[90:91], v208 offset:0x3c00
	s_waitcnt lgkmcnt(8)
	v_mfma_f32_32x32x16_bf16 v[50:65], v[78:81], v[92:95], v[50:65]
	ds_read_b64_tr_b16 v[92:93], v208 offset:0x600
	ds_read_b64_tr_b16 v[94:95], v208 offset:0xe00
	s_waitcnt lgkmcnt(8)
	v_mfma_f32_32x32x16_bf16 v[34:49], v[66:69], v[96:99], v[34:49]
	ds_read_b64_tr_b16 v[96:97], v208 offset:0x1600
	ds_read_b64_tr_b16 v[98:99], v208 offset:0x1e00
	s_waitcnt lgkmcnt(8)
	v_mfma_f32_32x32x16_bf16 v[34:49], v[70:73], v[100:103], v[34:49]
	ds_read_b64_tr_b16 v[100:101], v208 offset:0x2600
	ds_read_b64_tr_b16 v[102:103], v208 offset:0x2e00
	s_waitcnt lgkmcnt(8)
	v_mfma_f32_32x32x16_bf16 v[34:49], v[74:77], v[84:87], v[34:49]
	ds_read_b64_tr_b16 v[84:85], v208 offset:0x3600
	ds_read_b64_tr_b16 v[86:87], v208 offset:0x3e00
	s_waitcnt lgkmcnt(8)
	v_mfma_f32_32x32x16_bf16 v[34:49], v[78:81], v[88:91], v[34:49]
	s_waitcnt lgkmcnt(6)
	v_mfma_f32_32x32x16_bf16 v[18:33], v[66:69], v[92:95], v[18:33]
	s_waitcnt lgkmcnt(4)
	v_mfma_f32_32x32x16_bf16 v[18:33], v[70:73], v[96:99], v[18:33]
	s_waitcnt lgkmcnt(2)
	v_mfma_f32_32x32x16_bf16 v[18:33], v[74:77], v[100:103], v[18:33]
	s_waitcnt lgkmcnt(0)
	v_mfma_f32_32x32x16_bf16 v[18:33], v[78:81], v[84:87], v[18:33]
	s_and_saveexec_b64 s[6:7], s[4:5]
	v_add_f32_e32 v66, v114, v115
	v_fmac_f32_e32 v66, v207, v223
	v_add_f32_e32 v67, v82, v83
	v_fmac_f32_e32 v67, v66, v116
	ds_write_b32 v200, v67
	s_or_b64 exec, exec, s[6:7]
	s_waitcnt lgkmcnt(0)
	s_mov_b64 s[4:5], 0
; __device__ __forceinline__ float bf2f(unsigned short b) { return __uint_as_float(((unsigned)b) << 16); }
;     ...
;   int tid_ = wave0 * 64 + lane_id_v();
;   const int tid = tid_, wid = tid >> 6, lane = tid & 63, r32 = lane & 31, hi = lane >> 5;
;   char* V_lds = lds; char* K_lds = lds + LDS_K_OFF;
;   float* ws = (float*)(lds + LDS_WS_OFF) + wid * 64; float* li_l = ws; float* al_l = ws + 32;
;   float* tbl_l = (float*)(lds + LDS_TBL_OFF);
;   __syncthreads();
;   if constexpr (BIAS) { for (int i = tid; i < TBLN; i += 512) tbl_l[i] = tblg[i]; }
;   float mC = 0.f, l_reg = 0, nm_cur = 0.f; f32x16 o[4] = {}; f32x16 negm = {}; bf16x8 qr[NDQ - NQL];
;   const bf16_t* Qw = Qb + (long)(wid * QBLK + r32) * ldq + hi * 8;
;   char* qls = lds + LDS_Q_OFF + wid * 8192 + lane * 16;
; #pragma unroll
;   for (int d0 = 0; d0 < NDQ - NQL; ++d0) qr[d0] = *reinterpret_cast<const bf16x8*>(Qw + d0 * 16);
;   if constexpr (ROPEQ) {
;     static_assert(NDQ == 12 && NQL >= 4, "ROPEQ: MLA layout");
; #pragma unroll
;     for (int d0 = NDQ - NQL; d0 < 8; ++d0) *reinterpret_cast<bf16x8*>(qls + (d0 - (NDQ - NQL)) * 1024) = *reinterpret_cast<const bf16x8*>(Qw + d0 * 16);
;     const int qrow = q0 + wid * QBLK + r32;
; #pragma unroll
;     for (int pr = 0; pr < 2; ++pr) {
;       const bf16x8 xa = *reinterpret_cast<const bf16x8*>(Qw + (8 + pr) * 16), xb = *reinterpret_cast<const bf16x8*>(Qw + (10 + pr) * 16);
;       const float* cp = cosp + (size_t)qrow * 32 + pr * 16 + hi * 8; const float* sp = sinp + (size_t)qrow * 32 + pr * 16 + hi * 8;
;       const f32x4 c0 = *(const f32x4*)cp, c1 = *(const f32x4*)(cp + 4), s0 = *(const f32x4*)sp, s1 = *(const f32x4*)(sp + 4);
;       float ya[8], yb[8];
; #pragma unroll
;       for (int t = 0; t < 8; ++t) { const float x1 = bf2f((unsigned short)xa[t]), x2 = bf2f((unsigned short)xb[t]); const float c = t < 4 ? c0[t & 3] : c1[t & 3], sn = t < 4 ? s0[t & 3] : s1[t & 3];
;         ya[t] = x1 * c - x2 * sn; yb[t] = x2 * c + x1 * sn; }
;       u32x4 wa = {pk2(ya[0], ya[1]), pk2(ya[2], ya[3]), pk2(ya[4], ya[5]), pk2(ya[6], ya[7])}, wb = {pk2(yb[0], yb[1]), pk2(yb[2], yb[3]), pk2(yb[4], yb[5]), pk2(yb[6], yb[7])};
;       *reinterpret_cast<u32x4*>(qls + (8 + pr - (NDQ - NQL)) * 1024) = wa; *reinterpret_cast<u32x4*>(qls + (10 + pr - (NDQ - NQL)) * 1024) = wb; }
.LBB0_384:
	s_and_b64 vcc, exec, s[4:5]
	s_cbranch_vccz .LBB0_357
	v_readlane_b32 s4, v254, 21
	v_mbcnt_lo_u32_b32 v56, -1, 0
	v_mbcnt_hi_u32_b32 v56, -1, v56
	v_mov_b32_e32 v185, v1
	v_and_b32_e32 v0, 31, v56
	v_add_u32_e32 v30, s4, v56
	v_ashrrev_i32_e32 v4, 6, v30
	v_and_b32_e32 v2, 0x3fffffc0, v30
	v_lshlrev_b32_e32 v182, 5, v4
	v_bfe_u32 v198, v56, 5, 1
	v_lshl_add_u32 v183, v2, 2, s37
	v_or_b32_e32 v5, v182, v0
	v_mov_b64_e32 v[2:3], s[64:65]
	v_and_b32_e32 v57, 63, v56
	v_mad_i64_i32 v[2:3], s[4:5], v5, s1, v[2:3]
	v_lshlrev_b32_e32 v184, 4, v198
	v_lshl_add_u64 v[22:23], v[2:3], 0, v[184:185]
	v_lshlrev_b32_e32 v2, 13, v4
	v_lshlrev_b32_e32 v28, 4, v57
	v_readlane_b32 s4, v254, 58
	v_and_b32_e32 v6, 32, v56
	v_mov_b32_e32 v7, v1
	v_add3_u32 v199, s4, v2, v28
	v_or_b32_e32 v2, s58, v0
	v_add_u32_e32 v2, v2, v182
	v_ashrrev_i32_e32 v3, 31, v2
	v_lshlrev_b64 v[2:3], 7, v[2:3]
	v_lshl_add_u64 v[4:5], s[50:51], 0, v[2:3]
	v_lshl_add_u64 v[32:33], v[4:5], 0, v[6:7]
	v_lshl_add_u64 v[2:3], s[56:57], 0, v[2:3]
	s_waitcnt lgkmcnt(0)
	s_barrier
	global_load_dwordx4 v[158:161], v[22:23], off
	global_load_dwordx4 v[154:157], v[22:23], off offset:32
	global_load_dwordx4 v[150:153], v[22:23], off offset:64
	global_load_dwordx4 v[146:149], v[22:23], off offset:96
	global_load_dwordx4 v[142:145], v[22:23], off offset:128
	global_load_dwordx4 v[138:141], v[22:23], off offset:160
	global_load_dwordx4 v[134:137], v[22:23], off offset:192
	global_load_dwordx4 v[130:133], v[22:23], off offset:224
	v_lshl_add_u64 v[34:35], v[2:3], 0, v[6:7]
	global_load_dwordx4 v[2:5], v[32:33], off offset:16
	global_load_dwordx4 v[6:9], v[32:33], off
	global_load_dwordx4 v[10:13], v[34:35], off offset:16
	global_load_dwordx4 v[14:17], v[34:35], off
	global_load_dwordx4 v[18:21], v[22:23], off offset:256
	global_load_dwordx4 v[24:27], v[22:23], off offset:320
	s_cmp_lg_u32 0, -1
	s_cselect_b32 s6, 0, 0
	s_cmp_lg_u32 s44, -1
	s_cselect_b32 s4, s44, 0
	v_mov_b32_e32 v29, v1
	s_movk_i32 s5, 0x70
	s_mov_b32 s64, -1
	v_and_b32_e32 v58, 7, v56
	s_waitcnt vmcnt(4)
	v_mov_b32_e32 v40, v6
	v_mov_b32_e32 v41, v8
	s_waitcnt vmcnt(2)
	v_mov_b32_e32 v42, v14
	s_waitcnt vmcnt(1)
	v_lshlrev_b32_e32 v37, 16, v19
	v_lshlrev_b32_e32 v36, 16, v18
	s_waitcnt vmcnt(0)
	v_lshlrev_b32_e32 v39, 16, v25
	v_lshlrev_b32_e32 v38, 16, v24
	v_and_b32_e32 v19, 0xffff0000, v19
	v_and_b32_e32 v18, 0xffff0000, v18
	v_and_b32_e32 v25, 0xffff0000, v25
	v_and_b32_e32 v24, 0xffff0000, v24
	v_mov_b32_e32 v43, v16
	v_mov_b32_e32 v16, v15
	v_mov_b32_e32 v8, v7
	v_pk_mul_f32 v[6:7], v[16:17], v[18:19]
	v_pk_mul_f32 v[14:15], v[42:43], v[38:39]
	v_pk_mul_f32 v[16:17], v[16:17], v[24:25]
	v_pk_mul_f32 v[44:45], v[42:43], v[36:37]
	v_pk_fma_f32 v[6:7], v[8:9], v[24:25], v[6:7]
	v_pk_fma_f32 v[14:15], v[40:41], v[36:37], v[14:15] neg_lo:[0,0,1] neg_hi:[0,0,1]
	v_pk_fma_f32 v[8:9], v[8:9], v[18:19], v[16:17] neg_lo:[0,0,1] neg_hi:[0,0,1]
	v_lshlrev_b32_e32 v17, 16, v21
	v_lshlrev_b32_e32 v16, 16, v20
	v_and_b32_e32 v21, 0xffff0000, v21
	v_and_b32_e32 v20, 0xffff0000, v20
	v_and_b32_e32 v25, 0xffff0000, v27
	v_and_b32_e32 v24, 0xffff0000, v26
	v_mov_b32_e32 v37, v12
	v_mov_b32_e32 v12, v11
	v_lshlrev_b32_e32 v19, 16, v27
	v_lshlrev_b32_e32 v18, 16, v26
	v_mov_b32_e32 v26, v2
	v_mov_b32_e32 v27, v4
	v_mov_b32_e32 v36, v10
	v_mov_b32_e32 v4, v3
	v_pk_mul_f32 v[2:3], v[12:13], v[20:21]
	v_pk_mul_f32 v[12:13], v[12:13], v[24:25]
	v_pk_fma_f32 v[10:11], v[4:5], v[24:25], v[2:3]
	v_pk_mul_f32 v[2:3], v[36:37], v[18:19]
	v_pk_fma_f32 v[4:5], v[4:5], v[20:21], v[12:13] neg_lo:[0,0,1] neg_hi:[0,0,1]
	v_pk_fma_f32 v[44:45], v[40:41], v[38:39], v[44:45]
	v_pk_mul_f32 v[38:39], v[36:37], v[16:17]
	v_pk_fma_f32 v[2:3], v[26:27], v[16:17], v[2:3] neg_lo:[0,0,1] neg_hi:[0,0,1]
	v_bfe_u32 v12, v5, 16, 1
	v_bfe_u32 v13, v4, 16, 1
	v_bfe_u32 v16, v9, 16, 1
	v_bfe_u32 v17, v8, 16, 1
	v_add3_u32 v8, v8, v17, s0
	v_add3_u32 v9, v9, v16, s0
	v_add3_u32 v4, v4, v13, s0
	v_add3_u32 v5, v5, v12, s0
	v_bfe_u32 v12, v14, 16, 1
	v_bfe_u32 v13, v15, 16, 1
	v_bfe_u32 v16, v2, 16, 1
	v_bfe_u32 v17, v3, 16, 1
	v_add3_u32 v3, v3, v17, s0
	v_add3_u32 v2, v2, v16, s0
	v_add3_u32 v13, v15, v13, s0
	v_add3_u32 v12, v14, v12, s0
	v_lshrrev_b32_e32 v12, 16, v12
	v_lshrrev_b32_e32 v13, 16, v13
	v_lshrrev_b32_e32 v2, 16, v2
	v_lshrrev_b32_e32 v3, 16, v3
	v_pk_fma_f32 v[38:39], v[26:27], v[18:19], v[38:39]
	v_and_or_b32 v5, v5, s34, v3
	v_and_or_b32 v4, v4, s34, v2
	v_and_or_b32 v3, v9, s34, v13
	v_and_or_b32 v2, v8, s34, v12
	v_bfe_u32 v8, v11, 16, 1
	v_bfe_u32 v9, v10, 16, 1
	v_bfe_u32 v12, v7, 16, 1
	v_bfe_u32 v13, v6, 16, 1
	v_add3_u32 v6, v6, v13, s0
	v_add3_u32 v7, v7, v12, s0
	v_add3_u32 v10, v10, v9, s0
	v_add3_u32 v8, v11, v8, s0
	v_bfe_u32 v9, v44, 16, 1
	v_bfe_u32 v11, v45, 16, 1
	v_bfe_u32 v12, v38, 16, 1
	v_bfe_u32 v13, v39, 16, 1
	v_add3_u32 v13, v39, v13, s0
	v_add3_u32 v12, v38, v12, s0
	v_add3_u32 v11, v45, v11, s0
	v_add3_u32 v9, v44, v9, s0
	v_lshrrev_b32_e32 v14, 16, v9
	v_lshrrev_b32_e32 v11, 16, v11
	v_lshrrev_b32_e32 v12, 16, v12
	v_lshrrev_b32_e32 v9, 16, v13
	v_and_or_b32 v9, v8, s34, v9
	v_and_or_b32 v8, v10, s34, v12
	v_and_or_b32 v7, v7, s34, v11
	v_and_or_b32 v6, v6, s34, v14
	ds_write_b128 v199, v[2:5]
	ds_write_b128 v199, v[6:9] offset:2048
	global_load_dwordx4 v[2:5], v[32:33], off offset:80
	global_load_dwordx4 v[10:13], v[32:33], off offset:64
	global_load_dwordx4 v[6:9], v[34:35], off offset:80
	global_load_dwordx4 v[14:17], v[34:35], off offset:64
	global_load_dwordx4 v[18:21], v[22:23], off offset:288
	s_waitcnt vmcnt(3)
	v_mov_b32_e32 v34, v10
	global_load_dwordx4 v[22:25], v[22:23], off offset:352
	s_waitcnt vmcnt(2)
; __device__ __forceinline__ float bf2f(unsigned short b) { return __uint_as_float(((unsigned)b) << 16); }
; __device__ __forceinline__ unsigned pk2(float lo, float hi) { return f2bf(lo) | (f2bf(hi) << 16); }
; __device__ __forceinline__ int v_st(int k, int c) { const int kk = (k & ~0xC) | ((k & 4) << 1) | ((k & 8) >> 1); return ((kk >> 3) * 4 + (c >> 5)) * 512 + ((kk & 7) * 32 + (c & 31)) * 2; }
;     ...
;       const bf16x8 xa = *reinterpret_cast<const bf16x8*>(Qw + (8 + pr) * 16), xb = *reinterpret_cast<const bf16x8*>(Qw + (10 + pr) * 16);
;       const float* cp = cosp + (size_t)qrow * 32 + pr * 16 + hi * 8; const float* sp = sinp + (size_t)qrow * 32 + pr * 16 + hi * 8;
;       const f32x4 c0 = *(const f32x4*)cp, c1 = *(const f32x4*)(cp + 4), s0 = *(const f32x4*)sp, s1 = *(const f32x4*)(sp + 4);
;       float ya[8], yb[8];
; #pragma unroll
;       for (int t = 0; t < 8; ++t) { const float x1 = bf2f((unsigned short)xa[t]), x2 = bf2f((unsigned short)xb[t]); const float c = t < 4 ? c0[t & 3] : c1[t & 3], sn = t < 4 ? s0[t & 3] : s1[t & 3];
;         ya[t] = x1 * c - x2 * sn; yb[t] = x2 * c + x1 * sn; }
;       u32x4 wa = {pk2(ya[0], ya[1]), pk2(ya[2], ya[3]), pk2(ya[4], ya[5]), pk2(ya[6], ya[7])}, wb = {pk2(yb[0], yb[1]), pk2(yb[2], yb[3]), pk2(yb[4], yb[5]), pk2(yb[6], yb[7])};
;       *reinterpret_cast<u32x4*>(qls + (8 + pr - (NDQ - NQL)) * 1024) = wa; *reinterpret_cast<u32x4*>(qls + (10 + pr - (NDQ - NQL)) * 1024) = wb; }
;   } else {
; #pragma unroll
;   for (int d0 = NDQ - NQL; d0 < NDQ; ++d0) *reinterpret_cast<bf16x8*>(qls + (d0 - (NDQ - NQL)) * 1024) = *reinterpret_cast<const bf16x8*>(Qw + d0 * 16);
;   }
;   const int sr = tid >> 4, sc = (tid & 15) * 8, vst0 = v_st(sr, sc), vst1 = v_st(32 + sr, sc);
;   const int sr8 = tid >> 3, sc8 = (tid & 7) * 8;
;   const int vb0 = (int)(uintptr_t)V_lds + v_rd_base(lane);
;   const int qlane = q0 + wid * QBLK + r32;
;   struct { bf16x8 vs0, vs1, ks0, ks1, ks2; } sr_[SDEPTH];
;   constexpr int SWM = (NDQ == 8) ? 15 : 7;
;     ...
;   f32x16 pA0, pA1, pB0, pB1; float alA, alB; bf16x8 pa0, pa1, pa2, pa3; const int NT = nkeys / KVBLK;
;   const int kb0 = (int)(uintptr_t)K_lds + r32 * ROWB + (((r32 & SWM) << 4) ^ (hi << 4));
;   const int qa0 = (int)(uintptr_t)qls;
;     ...
;   constexpr int SE = 0, SO = SDEPTH - 1;
;   SLOAD(SE, kbeg); asm volatile("s_waitcnt vmcnt(0)" ::: "memory"); SWRITE(0, SE); __syncthreads();
	v_mov_b32_e32 v36, v14
	s_waitcnt vmcnt(1)
	v_lshlrev_b32_e32 v27, 16, v19
	v_lshlrev_b32_e32 v26, 16, v18
	v_and_b32_e32 v19, 0xffff0000, v19
	v_and_b32_e32 v18, 0xffff0000, v18
	v_mov_b32_e32 v37, v16
	v_mov_b32_e32 v16, v15
	v_mov_b32_e32 v35, v12
	v_mov_b32_e32 v12, v11
	v_pk_mul_f32 v[10:11], v[16:17], v[18:19]
	v_pk_mul_f32 v[38:39], v[36:37], v[26:27]
	s_waitcnt vmcnt(0)
	v_lshlrev_b32_e32 v33, 16, v23
	v_lshlrev_b32_e32 v32, 16, v22
	v_and_b32_e32 v23, 0xffff0000, v23
	v_and_b32_e32 v22, 0xffff0000, v22
	v_pk_mul_f32 v[14:15], v[36:37], v[32:33]
	v_pk_mul_f32 v[16:17], v[16:17], v[22:23]
	v_pk_fma_f32 v[10:11], v[12:13], v[22:23], v[10:11]
	v_pk_fma_f32 v[14:15], v[34:35], v[26:27], v[14:15] neg_lo:[0,0,1] neg_hi:[0,0,1]
	v_pk_fma_f32 v[12:13], v[12:13], v[18:19], v[16:17] neg_lo:[0,0,1] neg_hi:[0,0,1]
	v_lshlrev_b32_e32 v17, 16, v21
	v_lshlrev_b32_e32 v16, 16, v20
	v_and_b32_e32 v21, 0xffff0000, v21
	v_and_b32_e32 v20, 0xffff0000, v20
	v_and_b32_e32 v23, 0xffff0000, v25
	v_and_b32_e32 v22, 0xffff0000, v24
	v_mov_b32_e32 v27, v8
	v_mov_b32_e32 v8, v7
	v_lshlrev_b32_e32 v19, 16, v25
	v_lshlrev_b32_e32 v18, 16, v24
	v_mov_b32_e32 v24, v2
	v_mov_b32_e32 v25, v4
	v_mov_b32_e32 v26, v6
	v_mov_b32_e32 v4, v3
	v_pk_mul_f32 v[2:3], v[8:9], v[20:21]
	v_pk_mul_f32 v[8:9], v[8:9], v[22:23]
	v_pk_fma_f32 v[6:7], v[4:5], v[22:23], v[2:3]
	v_pk_mul_f32 v[2:3], v[26:27], v[18:19]
	v_pk_fma_f32 v[4:5], v[4:5], v[20:21], v[8:9] neg_lo:[0,0,1] neg_hi:[0,0,1]
	v_pk_fma_f32 v[38:39], v[34:35], v[32:33], v[38:39]
	v_pk_mul_f32 v[32:33], v[26:27], v[16:17]
	v_pk_fma_f32 v[2:3], v[24:25], v[16:17], v[2:3] neg_lo:[0,0,1] neg_hi:[0,0,1]
	v_bfe_u32 v8, v5, 16, 1
	v_bfe_u32 v9, v4, 16, 1
	v_bfe_u32 v16, v13, 16, 1
	v_bfe_u32 v17, v12, 16, 1
	v_add3_u32 v12, v12, v17, s0
	v_add3_u32 v13, v13, v16, s0
	v_add3_u32 v4, v4, v9, s0
	v_add3_u32 v5, v5, v8, s0
	v_bfe_u32 v8, v14, 16, 1
	v_bfe_u32 v9, v15, 16, 1
	v_bfe_u32 v16, v2, 16, 1
	v_bfe_u32 v17, v3, 16, 1
	v_add3_u32 v3, v3, v17, s0
	v_add3_u32 v2, v2, v16, s0
	v_add3_u32 v9, v15, v9, s0
	v_add3_u32 v8, v14, v8, s0
	v_lshrrev_b32_e32 v8, 16, v8
	v_lshrrev_b32_e32 v9, 16, v9
	v_lshrrev_b32_e32 v2, 16, v2
	v_lshrrev_b32_e32 v3, 16, v3
	v_pk_fma_f32 v[32:33], v[24:25], v[18:19], v[32:33]
	v_and_or_b32 v5, v5, s34, v3
	v_and_or_b32 v4, v4, s34, v2
	v_and_or_b32 v3, v13, s34, v9
	v_and_or_b32 v2, v12, s34, v8
	v_bfe_u32 v8, v7, 16, 1
	v_bfe_u32 v9, v6, 16, 1
	v_bfe_u32 v12, v11, 16, 1
	v_bfe_u32 v13, v10, 16, 1
	v_add3_u32 v10, v10, v13, s0
	v_add3_u32 v11, v11, v12, s0
	v_add3_u32 v6, v6, v9, s0
	v_add3_u32 v7, v7, v8, s0
	v_bfe_u32 v8, v38, 16, 1
	v_bfe_u32 v9, v39, 16, 1
	v_bfe_u32 v12, v32, 16, 1
	v_bfe_u32 v13, v33, 16, 1
	v_add3_u32 v13, v33, v13, s0
	v_add3_u32 v12, v32, v12, s0
	v_add3_u32 v9, v39, v9, s0
	v_add3_u32 v8, v38, v8, s0
	v_lshrrev_b32_e32 v14, 16, v8
	v_lshrrev_b32_e32 v15, 16, v9
	v_lshrrev_b32_e32 v8, 16, v12
	v_lshrrev_b32_e32 v9, 16, v13
	v_ashrrev_i32_e32 v22, 4, v30
	v_and_or_b32 v9, v7, s34, v9
	v_and_or_b32 v8, v6, s34, v8
	v_and_or_b32 v7, v11, s34, v15
	v_and_or_b32 v6, v10, s34, v14
	ds_write_b128 v199, v[2:5] offset:1024
	ds_write_b128 v199, v[6:9] offset:3072
	v_and_b32_e32 v4, 0xfffff0, v22
	v_lshlrev_b32_e32 v5, 1, v22
	v_lshlrev_b32_e32 v2, 3, v56
	v_and_or_b32 v4, v22, 8, v4
	v_and_b32_e32 v3, 0x78, v2
	v_lshrrev_b32_e32 v5, 1, v22
	v_lshrrev_b32_e32 v4, 1, v4
	v_bfe_u32 v2, v2, 5, 2
	v_and_b32_e32 v6, 3, v22
	v_or_b32_e32 v4, v4, v2
	v_and_or_b32 v5, v22, 4, v6
	v_lshlrev_b32_e32 v24, 1, v3
	v_lshlrev_b32_e32 v4, 9, v4
	v_lshlrev_b32_e32 v5, 6, v5
	v_and_b32_e32 v3, 48, v24
	v_add_u32_e32 v6, 32, v22
	v_or3_b32 v31, v4, v5, v3
	v_and_b32_e32 v4, 0xfffff0, v6
	v_lshlrev_b32_e32 v7, 1, v6
	v_and_or_b32 v4, v6, 8, v4
	v_lshrrev_b32_e32 v4, 1, v4
	v_or_b32_e32 v2, v4, v2
	v_lshlrev_b32_e32 v2, 9, v2
	v_or3_b32 v32, v2, v5, v3
	v_lshlrev_b32_e32 v2, 3, v57
	v_and_b32_e32 v3, 0xc0, v28
	v_lshlrev_b32_e32 v4, 1, v56
	v_and_or_b32 v3, v2, 24, v3
	v_and_b32_e32 v4, 32, v4
	v_and_b32_e32 v2, 0x100, v2
	v_or3_b32 v59, v3, v4, v2
	v_bitop3_b32 v3, v198, v56, 7 bitop3:0x78
	v_ashrrev_i32_e32 v23, 31, v22
	v_mul_u32_u24_e32 v2, 0x180, v0
	v_lshlrev_b32_e32 v3, 4, v3
	v_lshlrev_b64 v[50:51], 11, v[22:23]
	v_add3_u32 v209, v2, s4, v3
	v_lshl_add_u64 v[2:3], s[60:61], 0, v[50:51]
	v_mov_b32_e32 v25, v1
	v_ashrrev_i32_e32 v26, 3, v30
	v_lshl_add_u64 v[52:53], v[2:3], 0, v[24:25]
	global_load_dwordx4 v[2:5], v[52:53], off offset:256
	v_ashrrev_i32_e32 v7, 31, v6
	v_ashrrev_i32_e32 v27, 31, v26
	v_lshlrev_b64 v[6:7], 11, v[6:7]
	v_lshlrev_b64 v[186:187], 7, v[26:27]
	v_lshlrev_b32_e32 v20, 4, v56
	v_lshl_add_u64 v[6:7], s[60:61], 0, v[6:7]
	v_lshl_add_u64 v[18:19], s[8:9], 0, v[186:187]
	v_and_b32_e32 v28, 0x70, v20
	v_lshl_add_u64 v[10:11], v[6:7], 0, v[24:25]
	v_lshl_add_u64 v[54:55], v[18:19], 0, v[28:29]
	global_load_dwordx4 v[6:9], v[10:11], off offset:256
	global_load_dwordx4 v[14:17], v[52:53], off
	s_nop 0
	global_load_dwordx4 v[10:13], v[10:11], off
	v_add_u32_e32 v210, 0, v31
	global_load_dwordx4 v[18:21], v[54:55], off
	s_movk_i32 s4, 0x180
	s_waitcnt vmcnt(0)
	v_add_u32_e32 v211, 0, v32
	v_xor_b32_e32 v215, 32, v209
	v_add_u32_e32 v201, s6, v59
	s_waitcnt vmcnt(4)
	ds_write_b128 v210, v[2:5]
	v_mul_lo_u32 v2, v22, s4
	v_bitop3_b32 v3, v24, v30, s5 bitop3:0x78
	v_lshlrev_b32_e32 v4, 4, v26
	v_add3_u32 v212, v3, v2, 0
	v_mul_lo_u32 v2, v26, s4
	v_or_b32_e32 v3, 0x100, v28
	v_and_b32_e32 v4, 0x70, v4
	v_xad_u32 v2, v3, v4, v2
	v_add_u32_e32 v214, 0, v2
	s_waitcnt vmcnt(3)
	ds_write_b128 v211, v[6:9]
	s_waitcnt vmcnt(2)
	ds_write_b128 v212, v[14:17] offset:32768
	s_waitcnt vmcnt(1)
	ds_write_b128 v212, v[10:13] offset:45056
	s_waitcnt vmcnt(0)
	ds_write_b128 v214, v[18:21] offset:32768
	s_waitcnt lgkmcnt(0)
	s_barrier
; __device__ __forceinline__ void qkt12_roll(f32x16& p0, f32x16& p1, const f32x16& negm, int kb, int qa, const bf16x8* qr) {
;   const int a0 = kb ^ (0 << 5); const bf16x8 x0 = lds_rd128<0>(a0), y0 = lds_rd128<12288>(a0);
;   const int a1 = kb ^ (1 << 5); const bf16x8 x1 = lds_rd128<0>(a1), y1 = lds_rd128<12288>(a1);
;   asm volatile("s_waitcnt lgkmcnt(2)" ::: "memory"); SBAR();
;   p0 = __builtin_amdgcn_mfma_f32_32x32x16_bf16(x0, qr[0], negm, 0, 0, 0); p1 = __builtin_amdgcn_mfma_f32_32x32x16_bf16(y0, qr[0], negm, 0, 0, 0);
;   const int a2 = kb ^ (2 << 5); const bf16x8 x2 = lds_rd128<0>(a2), y2 = lds_rd128<12288>(a2);
;   asm volatile("s_waitcnt lgkmcnt(2)" ::: "memory"); SBAR();
;   p0 = __builtin_amdgcn_mfma_f32_32x32x16_bf16(x1, qr[1], p0, 0, 0, 0); p1 = __builtin_amdgcn_mfma_f32_32x32x16_bf16(y1, qr[1], p1, 0, 0, 0);
;   const int a3 = kb ^ (3 << 5); const bf16x8 x3 = lds_rd128<0>(a3), y3 = lds_rd128<12288>(a3);
;   asm volatile("s_waitcnt lgkmcnt(2)" ::: "memory"); SBAR();
;   p0 = __builtin_amdgcn_mfma_f32_32x32x16_bf16(x2, qr[2], p0, 0, 0, 0); p1 = __builtin_amdgcn_mfma_f32_32x32x16_bf16(y2, qr[2], p1, 0, 0, 0);
;   const int a4 = kb ^ (0 << 5); const bf16x8 x4 = lds_rd128<128>(a4), y4 = lds_rd128<12416>(a4);
;   asm volatile("s_waitcnt lgkmcnt(2)" ::: "memory"); SBAR();
;   p0 = __builtin_amdgcn_mfma_f32_32x32x16_bf16(x3, qr[3], p0, 0, 0, 0); p1 = __builtin_amdgcn_mfma_f32_32x32x16_bf16(y3, qr[3], p1, 0, 0, 0);
;   const int a5 = kb ^ (1 << 5); const bf16x8 x5 = lds_rd128<128>(a5), y5 = lds_rd128<12416>(a5);
;   asm volatile("s_waitcnt lgkmcnt(2)" ::: "memory"); SBAR();
;   p0 = __builtin_amdgcn_mfma_f32_32x32x16_bf16(x4, qr[4], p0, 0, 0, 0); p1 = __builtin_amdgcn_mfma_f32_32x32x16_bf16(y4, qr[4], p1, 0, 0, 0);
;   const int a6 = kb ^ (2 << 5); const bf16x8 x6 = lds_rd128<128>(a6), y6 = lds_rd128<12416>(a6);
;   asm volatile("s_waitcnt lgkmcnt(2)" ::: "memory"); SBAR();
;   p0 = __builtin_amdgcn_mfma_f32_32x32x16_bf16(x5, qr[5], p0, 0, 0, 0); p1 = __builtin_amdgcn_mfma_f32_32x32x16_bf16(y5, qr[5], p1, 0, 0, 0);
;   const int a7 = kb ^ (3 << 5); const bf16x8 x7 = lds_rd128<128>(a7), y7 = lds_rd128<12416>(a7);
;   asm volatile("s_waitcnt lgkmcnt(2)" ::: "memory"); SBAR();
;   p0 = __builtin_amdgcn_mfma_f32_32x32x16_bf16(x6, qr[6], p0, 0, 0, 0); p1 = __builtin_amdgcn_mfma_f32_32x32x16_bf16(y6, qr[6], p1, 0, 0, 0);
	ds_read_b128 v[2:5], v209 offset:0
	ds_read_b128 v[18:21], v209 offset:0x3000
	ds_read_b128 v[60:63], v215 offset:0
	ds_read_b128 v[64:67], v215 offset:0x3000
	s_waitcnt lgkmcnt(2)
	v_add_u32_e32 v213, 0x3000, v212
	v_mfma_f32_32x32x16_bf16 v[34:49], v[2:5], v[158:161], 0
	v_xor_b32_e32 v216, 64, v209
	ds_read_b128 v[68:71], v216 offset:0
	ds_read_b128 v[72:75], v216 offset:0x3000
	s_mov_b32 s13, s12
	s_waitcnt lgkmcnt(2)
	s_mov_b32 s14, s12
	s_mov_b32 s15, s12
	v_mfma_f32_32x32x16_bf16 v[18:33], v[18:21], v[158:161], 0
	s_mov_b32 s16, s12
	s_mov_b32 s17, s12
	s_mov_b32 s18, s12
	s_mov_b32 s19, s12
	s_mov_b32 s20, s12
	s_mov_b32 s21, s12
	s_mov_b32 s22, s12
	s_mov_b32 s23, s12
	s_mov_b32 s24, s12
	s_mov_b32 s25, s12
	s_mov_b32 s26, s12
	s_mov_b32 s27, s12
	v_mov_b64_e32 v[2:3], s[12:13]
	v_mov_b64_e32 v[4:5], s[14:15]
	v_mov_b64_e32 v[6:7], s[16:17]
	v_mov_b64_e32 v[8:9], s[18:19]
	v_mov_b64_e32 v[10:11], s[20:21]
	v_mov_b64_e32 v[12:13], s[22:23]
	v_mov_b64_e32 v[14:15], s[24:25]
	v_mov_b64_e32 v[16:17], s[26:27]
	v_mfma_f32_32x32x16_bf16 v[34:49], v[60:63], v[154:157], v[34:49]
	v_xor_b32_e32 v217, 0x60, v209
	ds_read_b128 v[60:63], v217 offset:0
	v_mfma_f32_32x32x16_bf16 v[18:33], v[64:67], v[154:157], v[18:33]
	ds_read_b128 v[64:67], v217 offset:0x3000
	s_waitcnt lgkmcnt(2)
	v_mfma_f32_32x32x16_bf16 v[34:49], v[68:71], v[150:153], v[34:49]
	ds_read_b128 v[68:71], v209 offset:0x80
	v_mfma_f32_32x32x16_bf16 v[18:33], v[72:75], v[150:153], v[18:33]
	ds_read_b128 v[72:75], v209 offset:0x3080
	s_waitcnt lgkmcnt(2)
	v_mfma_f32_32x32x16_bf16 v[34:49], v[60:63], v[146:149], v[34:49]
	ds_read_b128 v[60:63], v215 offset:0x80
	v_mfma_f32_32x32x16_bf16 v[18:33], v[64:67], v[146:149], v[18:33]
	ds_read_b128 v[64:67], v215 offset:0x3080
	s_waitcnt lgkmcnt(2)
	v_mfma_f32_32x32x16_bf16 v[34:49], v[68:71], v[142:145], v[34:49]
	ds_read_b128 v[68:71], v216 offset:0x80
	v_mfma_f32_32x32x16_bf16 v[18:33], v[72:75], v[142:145], v[18:33]
	ds_read_b128 v[72:75], v216 offset:0x3080
	s_waitcnt lgkmcnt(2)
	v_mfma_f32_32x32x16_bf16 v[34:49], v[60:63], v[138:141], v[34:49]
	ds_read_b128 v[60:63], v217 offset:0x80
	v_mfma_f32_32x32x16_bf16 v[18:33], v[64:67], v[138:141], v[18:33]
	ds_read_b128 v[64:67], v217 offset:0x3080
	s_waitcnt lgkmcnt(2)
	v_mfma_f32_32x32x16_bf16 v[34:49], v[68:71], v[134:137], v[34:49]
	ds_read_b128 v[68:71], v209 offset:0x100
	v_mfma_f32_32x32x16_bf16 v[18:33], v[72:75], v[134:137], v[18:33]
	ds_read_b128 v[72:75], v209 offset:0x3100
	ds_read_b128 v[76:79], v199 offset:0
	s_waitcnt lgkmcnt(3)
	v_mfma_f32_32x32x16_bf16 v[34:49], v[60:63], v[130:133], v[34:49]
	ds_read_b128 v[60:63], v215 offset:0x100
	v_mfma_f32_32x32x16_bf16 v[18:33], v[64:67], v[130:133], v[18:33]
	ds_read_b128 v[64:67], v215 offset:0x3100
	ds_read_b128 v[80:83], v199 offset:0x400
	s_waitcnt lgkmcnt(3)
	v_mfma_f32_32x32x16_bf16 v[34:49], v[68:71], v[76:79], v[34:49]
	ds_read_b128 v[68:71], v216 offset:0x100
	v_mfma_f32_32x32x16_bf16 v[18:33], v[72:75], v[76:79], v[18:33]
	ds_read_b128 v[72:75], v216 offset:0x3100
	ds_read_b128 v[76:79], v199 offset:0x800
	s_waitcnt lgkmcnt(3)
	v_mfma_f32_32x32x16_bf16 v[34:49], v[60:63], v[80:83], v[34:49]
	ds_read_b128 v[60:63], v217 offset:0x100
	v_mfma_f32_32x32x16_bf16 v[18:33], v[64:67], v[80:83], v[18:33]
	ds_read_b128 v[64:67], v217 offset:0x3100
	ds_read_b128 v[80:83], v199 offset:0xc00
	s_waitcnt lgkmcnt(3)
	v_mfma_f32_32x32x16_bf16 v[34:49], v[68:71], v[76:79], v[34:49]
	s_waitcnt lgkmcnt(0)
	v_mfma_f32_32x32x16_bf16 v[18:33], v[72:75], v[76:79], v[18:33]
	v_mfma_f32_32x32x16_bf16 v[34:49], v[60:63], v[80:83], v[34:49]
	v_mfma_f32_32x32x16_bf16 v[18:33], v[64:67], v[80:83], v[18:33]
	s_mov_b64 s[4:5], 0x20000
	v_lshl_add_u64 v[60:61], v[52:53], 0, s[4:5]
	s_mov_b64 s[4:5], 0x30000
	v_lshl_add_u64 v[64:65], v[52:53], 0, s[4:5]
	s_mov_b32 s4, 0x20000
	global_load_dwordx4 v[60:63], v[60:61], off offset:256
	s_nop 0
	global_load_dwordx4 v[82:85], v[64:65], off offset:256
	v_add_co_u32_e32 v64, vcc, s4, v52
	s_mov_b32 s4, 0x30000
	s_nop 0
	v_addc_co_u32_e32 v65, vcc, 0, v53, vcc
	v_add_co_u32_e32 v52, vcc, s4, v52
	s_movk_i32 s4, 0x2000
	s_nop 0
	v_addc_co_u32_e32 v53, vcc, 0, v53, vcc
	global_load_dwordx4 v[86:89], v[64:65], off
	global_load_dwordx4 v[90:93], v[52:53], off
	v_add_co_u32_e32 v52, vcc, s4, v54
	v_max_f32_e32 v66, v38, v38
	s_nop 0
	v_addc_co_u32_e32 v53, vcc, 0, v55, vcc
	global_load_dwordx4 v[52:55], v[52:53], off
	v_max_f32_e32 v67, v34, v34
	v_max_f32_e32 v64, v67, v66
	v_max_f32_e32 v65, v39, v39
	v_max_f32_e32 v66, v35, v35
	v_max_f32_e32 v65, v66, v65
	v_max_f32_e32 v66, v41, v41
	v_max_f32_e32 v67, v37, v37
	v_max_f32_e32 v66, v67, v66
	v_max3_f32 v67, v36, v40, v44
	v_max3_f32 v66, v66, v45, v49
	v_max3_f32 v64, v64, v42, v46
	v_max3_f32 v65, v65, v43, v47
	v_max3_f32 v67, v67, v48, v20
	v_max3_f32 v66, v66, v21, v25
	v_max3_f32 v64, v64, v18, v22
	v_max3_f32 v65, v65, v19, v23
	v_max3_f32 v67, v67, v24, v28
	v_max3_f32 v66, v66, v29, v33
	v_max3_f32 v64, v64, v26, v30
	v_max3_f32 v65, v65, v27, v31
	v_max3_f32 v66, v67, v32, v66
	v_max3_f32 v64, v64, v65, v66
	v_mov_b32_e32 v65, v64
	s_nop 1
	v_permlane32_swap_b32_e32 v64, v65
	s_mov_b32 s4, 0xc3480000
	v_max3_f32 v64, v64, v65, s4
	v_sub_f32_e32 v34, v34, v64
	v_sub_f32_e32 v35, v35, v64
	v_sub_f32_e32 v36, v36, v64
	v_sub_f32_e32 v37, v37, v64
	v_sub_f32_e32 v38, v38, v64
	v_sub_f32_e32 v39, v39, v64
	v_sub_f32_e32 v40, v40, v64
	v_sub_f32_e32 v41, v41, v64
	v_sub_f32_e32 v42, v42, v64
	v_sub_f32_e32 v43, v43, v64
	v_sub_f32_e32 v44, v44, v64
	v_sub_f32_e32 v45, v45, v64
	v_sub_f32_e32 v46, v46, v64
	v_sub_f32_e32 v47, v47, v64
	v_sub_f32_e32 v48, v48, v64
	v_sub_f32_e32 v49, v49, v64
	v_sub_f32_e32 v66, v18, v64
	v_exp_f32_e32 v176, v34
	v_exp_f32_e32 v178, v35
	v_exp_f32_e32 v167, v36
	v_exp_f32_e32 v177, v37
	v_exp_f32_e32 v168, v38
	v_exp_f32_e32 v175, v39
	v_exp_f32_e32 v169, v40
	v_exp_f32_e32 v174, v41
	v_exp_f32_e32 v170, v42
	v_exp_f32_e32 v173, v43
	v_exp_f32_e32 v165, v44
	v_exp_f32_e32 v171, v45
	v_exp_f32_e32 v163, v46
	v_exp_f32_e32 v172, v47
	v_exp_f32_e32 v162, v48
	v_exp_f32_e32 v164, v49
	v_and_b32_e32 v18, 15, v56
	v_sub_f32_e32 v67, v19, v64
	s_waitcnt vmcnt(0)
; __device__ __forceinline__ void qkt12_roll(f32x16& p0, f32x16& p1, const f32x16& negm, int kb, int qa, const bf16x8* qr) {
;   const int a0 = kb ^ (0 << 5); const bf16x8 x0 = lds_rd128<0>(a0), y0 = lds_rd128<12288>(a0);
;   const int a1 = kb ^ (1 << 5); const bf16x8 x1 = lds_rd128<0>(a1), y1 = lds_rd128<12288>(a1);
;   asm volatile("s_waitcnt lgkmcnt(2)" ::: "memory"); SBAR();
;   p0 = __builtin_amdgcn_mfma_f32_32x32x16_bf16(x0, qr[0], negm, 0, 0, 0); p1 = __builtin_amdgcn_mfma_f32_32x32x16_bf16(y0, qr[0], negm, 0, 0, 0);
;   const int a2 = kb ^ (2 << 5); const bf16x8 x2 = lds_rd128<0>(a2), y2 = lds_rd128<12288>(a2);
;   asm volatile("s_waitcnt lgkmcnt(2)" ::: "memory"); SBAR();
;   p0 = __builtin_amdgcn_mfma_f32_32x32x16_bf16(x1, qr[1], p0, 0, 0, 0); p1 = __builtin_amdgcn_mfma_f32_32x32x16_bf16(y1, qr[1], p1, 0, 0, 0);
;   const int a3 = kb ^ (3 << 5); const bf16x8 x3 = lds_rd128<0>(a3), y3 = lds_rd128<12288>(a3);
;   asm volatile("s_waitcnt lgkmcnt(2)" ::: "memory"); SBAR();
;   p0 = __builtin_amdgcn_mfma_f32_32x32x16_bf16(x2, qr[2], p0, 0, 0, 0); p1 = __builtin_amdgcn_mfma_f32_32x32x16_bf16(y2, qr[2], p1, 0, 0, 0);
;   const int a4 = kb ^ (0 << 5); const bf16x8 x4 = lds_rd128<128>(a4), y4 = lds_rd128<12416>(a4);
;   asm volatile("s_waitcnt lgkmcnt(2)" ::: "memory"); SBAR();
;   p0 = __builtin_amdgcn_mfma_f32_32x32x16_bf16(x3, qr[3], p0, 0, 0, 0); p1 = __builtin_amdgcn_mfma_f32_32x32x16_bf16(y3, qr[3], p1, 0, 0, 0);
;   const int a5 = kb ^ (1 << 5); const bf16x8 x5 = lds_rd128<128>(a5), y5 = lds_rd128<12416>(a5);
;   asm volatile("s_waitcnt lgkmcnt(2)" ::: "memory"); SBAR();
;   p0 = __builtin_amdgcn_mfma_f32_32x32x16_bf16(x4, qr[4], p0, 0, 0, 0); p1 = __builtin_amdgcn_mfma_f32_32x32x16_bf16(y4, qr[4], p1, 0, 0, 0);
;   const int a6 = kb ^ (2 << 5); const bf16x8 x6 = lds_rd128<128>(a6), y6 = lds_rd128<12416>(a6);
;   asm volatile("s_waitcnt lgkmcnt(2)" ::: "memory"); SBAR();
;   p0 = __builtin_amdgcn_mfma_f32_32x32x16_bf16(x5, qr[5], p0, 0, 0, 0); p1 = __builtin_amdgcn_mfma_f32_32x32x16_bf16(y5, qr[5], p1, 0, 0, 0);
;   const int a7 = kb ^ (3 << 5); const bf16x8 x7 = lds_rd128<128>(a7), y7 = lds_rd128<12416>(a7);
;   asm volatile("s_waitcnt lgkmcnt(2)" ::: "memory"); SBAR();
;   p0 = __builtin_amdgcn_mfma_f32_32x32x16_bf16(x6, qr[6], p0, 0, 0, 0); p1 = __builtin_amdgcn_mfma_f32_32x32x16_bf16(y6, qr[6], p1, 0, 0, 0);
	s_addk_i32 s6, 0x4000
	v_or_b32_e32 v50, s59, v50
	v_lshlrev_b32_e32 v18, 4, v18
	v_mov_b32_e32 v19, v1
	v_add_f32_e32 v225, 0, v64
	v_sub_f32_e32 v81, v33, v64
	v_sub_f32_e32 v80, v32, v64
	v_sub_f32_e32 v79, v31, v64
	v_sub_f32_e32 v78, v30, v64
	v_sub_f32_e32 v77, v29, v64
	v_sub_f32_e32 v76, v28, v64
	v_sub_f32_e32 v75, v27, v64
	v_sub_f32_e32 v74, v26, v64
	v_sub_f32_e32 v73, v25, v64
	v_sub_f32_e32 v72, v24, v64
	v_sub_f32_e32 v71, v23, v64
	v_sub_f32_e32 v70, v22, v64
	v_sub_f32_e32 v69, v21, v64
	v_sub_f32_e32 v68, v20, v64
	s_waitcnt vmcnt(4)
	ds_write_b128 v210, v[60:63] offset:16384
	s_waitcnt vmcnt(3)
	ds_write_b128 v211, v[82:85] offset:16384
	s_waitcnt vmcnt(2)
	ds_write_b128 v212, v[86:89] offset:57344
	s_waitcnt vmcnt(1)
	ds_write_b128 v213, v[90:93] offset:57344
	s_waitcnt vmcnt(0)
	ds_write_b128 v214, v[52:55] offset:57344
	v_add_u32_e32 v221, 0x6000, v209
	v_cmp_gt_u32_e64 s[4:5], 32, v57
	v_add_u32_e32 v208, s6, v59
	v_lshl_add_u64 v[188:189], v[50:51], 0, v[18:19]
	v_lshl_or_b32 v186, v58, 4, v186
	v_mov_b32_e32 v228, 0
	v_mov_b64_e32 v[64:65], v[16:17]
	v_mov_b64_e32 v[48:49], v[16:17]
	v_mov_b64_e32 v[32:33], v[16:17]
	v_xor_b32_e32 v220, 32, v221
	v_xor_b32_e32 v219, 64, v221
	v_xor_b32_e32 v218, 0x60, v221
	v_lshl_add_u32 v200, v0, 2, v183
	v_add_u32_e32 v185, v183, v184
	v_mov_b32_e32 v222, 1.0
	v_mov_b64_e32 v[62:63], v[14:15]
	v_mov_b64_e32 v[60:61], v[12:13]
	v_mov_b64_e32 v[58:59], v[10:11]
	v_mov_b64_e32 v[56:57], v[8:9]
	v_mov_b64_e32 v[54:55], v[6:7]
	v_mov_b64_e32 v[52:53], v[4:5]
	v_mov_b64_e32 v[50:51], v[2:3]
	v_mov_b64_e32 v[46:47], v[14:15]
	v_mov_b64_e32 v[44:45], v[12:13]
	v_mov_b64_e32 v[42:43], v[10:11]
	v_mov_b64_e32 v[40:41], v[8:9]
	v_mov_b64_e32 v[38:39], v[6:7]
	v_mov_b64_e32 v[36:37], v[4:5]
	v_mov_b64_e32 v[34:35], v[2:3]
	v_mov_b64_e32 v[30:31], v[14:15]
	v_mov_b64_e32 v[28:29], v[12:13]
	v_mov_b64_e32 v[26:27], v[10:11]
	v_mov_b64_e32 v[24:25], v[8:9]
	v_mov_b64_e32 v[22:23], v[6:7]
	v_mov_b64_e32 v[20:21], v[4:5]
	v_mov_b64_e32 v[18:19], v[2:3]
	v_mov_b32_e32 v207, 0
	v_mov_b32_e32 v98, 0
	v_mov_b32_e32 v99, v228
	v_mov_b32_e32 v100, v228
	v_mov_b32_e32 v101, v228
	v_mov_b32_e32 v102, v228
	v_mov_b32_e32 v103, v228
	v_mov_b32_e32 v104, v228
	v_mov_b32_e32 v105, v228
	v_mov_b32_e32 v106, v228
	v_mov_b32_e32 v107, v228
	v_mov_b32_e32 v108, v228
	v_mov_b32_e32 v109, v228
	v_mov_b32_e32 v110, v228
	v_mov_b32_e32 v111, v228
	v_mov_b32_e32 v112, v228
	v_mov_b32_e32 v113, v228
	s_waitcnt lgkmcnt(0)
	s_barrier
.LBB0_386:
	v_cmp_neq_f32_e64 s[6:7], v228, -v225
	s_cmp_eq_u64 s[6:7], 0
	s_cselect_b64 s[6:7], -1, 0
	v_cndmask_b32_e64 v113, -v225, v113, s[6:7]
	v_cndmask_b32_e64 v112, -v225, v112, s[6:7]
	v_cndmask_b32_e64 v111, -v225, v111, s[6:7]
	v_cndmask_b32_e64 v110, -v225, v110, s[6:7]
	v_cndmask_b32_e64 v109, -v225, v109, s[6:7]
	v_cndmask_b32_e64 v108, -v225, v108, s[6:7]
	v_cndmask_b32_e64 v107, -v225, v107, s[6:7]
	v_cndmask_b32_e64 v106, -v225, v106, s[6:7]
	v_cndmask_b32_e64 v105, -v225, v105, s[6:7]
	v_cndmask_b32_e64 v104, -v225, v104, s[6:7]
	v_cndmask_b32_e64 v103, -v225, v103, s[6:7]
	v_cndmask_b32_e64 v102, -v225, v102, s[6:7]
	v_cndmask_b32_e64 v101, -v225, v101, s[6:7]
	v_cndmask_b32_e64 v100, -v225, v100, s[6:7]
	v_cndmask_b32_e64 v99, -v225, v99, s[6:7]
	v_cndmask_b32_e64 v98, -v225, v98, s[6:7]
	ds_read_b128 v[82:85], v221 offset:0
	ds_read_b128 v[230:233], v221 offset:0x3000
	ds_read_b128 v[234:237], v220 offset:0
	ds_read_b128 v[238:241], v220 offset:0x3000
	s_waitcnt lgkmcnt(2)
	s_nop 1
	v_mfma_f32_32x32x16_bf16 v[114:129], v[82:85], v[158:161], v[98:113]
	v_mfma_f32_32x32x16_bf16 v[82:97], v[230:233], v[158:161], v[98:113]
	ds_read_b128 v[230:233], v219 offset:0
	ds_read_b128 v[242:245], v219 offset:0x3000
	s_waitcnt lgkmcnt(2)
	v_mfma_f32_32x32x16_bf16 v[114:129], v[234:237], v[154:157], v[114:129]
	ds_read_b128 v[234:237], v218 offset:0
	v_mfma_f32_32x32x16_bf16 v[82:97], v[238:241], v[154:157], v[82:97]
	ds_read_b128 v[238:241], v218 offset:0x3000
	s_waitcnt lgkmcnt(2)
	v_mfma_f32_32x32x16_bf16 v[114:129], v[230:233], v[150:153], v[114:129]
	ds_read_b128 v[230:233], v221 offset:0x80
	v_mfma_f32_32x32x16_bf16 v[82:97], v[242:245], v[150:153], v[82:97]
	ds_read_b128 v[242:245], v221 offset:0x3080
	s_waitcnt lgkmcnt(2)
	v_mfma_f32_32x32x16_bf16 v[114:129], v[234:237], v[146:149], v[114:129]
	ds_read_b128 v[234:237], v220 offset:0x80
	v_mfma_f32_32x32x16_bf16 v[82:97], v[238:241], v[146:149], v[82:97]
	ds_read_b128 v[238:241], v220 offset:0x3080
	s_waitcnt lgkmcnt(2)
	v_mfma_f32_32x32x16_bf16 v[114:129], v[230:233], v[142:145], v[114:129]
	ds_read_b128 v[230:233], v219 offset:0x80
	v_mfma_f32_32x32x16_bf16 v[82:97], v[242:245], v[142:145], v[82:97]
	ds_read_b128 v[242:245], v219 offset:0x3080
	s_waitcnt lgkmcnt(2)
	v_mfma_f32_32x32x16_bf16 v[114:129], v[234:237], v[138:141], v[114:129]
	ds_read_b128 v[234:237], v218 offset:0x80
	v_mfma_f32_32x32x16_bf16 v[82:97], v[238:241], v[138:141], v[82:97]
	ds_read_b128 v[238:241], v218 offset:0x3080
	s_waitcnt lgkmcnt(2)
	v_mfma_f32_32x32x16_bf16 v[114:129], v[230:233], v[134:137], v[114:129]
	ds_read_b128 v[230:233], v221 offset:0x100
	v_mfma_f32_32x32x16_bf16 v[82:97], v[242:245], v[134:137], v[82:97]
	ds_read_b128 v[242:245], v221 offset:0x3100
	ds_read_b128 v[246:249], v199 offset:0
	s_waitcnt lgkmcnt(3)
	v_mfma_f32_32x32x16_bf16 v[114:129], v[234:237], v[130:133], v[114:129]
	ds_read_b128 v[234:237], v220 offset:0x100
	v_mfma_f32_32x32x16_bf16 v[82:97], v[238:241], v[130:133], v[82:97]
	ds_read_b128 v[238:241], v220 offset:0x3100
	ds_read_b128 v[250:253], v199 offset:0x400
	s_waitcnt lgkmcnt(3)
; #define SBAR() __builtin_amdgcn_sched_barrier(0)
; #define BIASADD(P0, P1, kt0) do { if constexpr (BIAS) { const int dlo_ = (kt0) - q0 - 255, dhi_ = (kt0) + 63 - q0; \
;     if (!(dlo_ >= 1024) && !(dhi_ <= -1024)) { const float* tb_ = tbl_l + ((kt0) - qlane + TOFF + 4 * hi); \
;       _Pragma("unroll") for (int r = 0; r < 16; ++r) { P0[r] += tb_[(r & 3) + 8 * (r >> 2)]; P1[r] += tb_[32 + (r & 3) + 8 * (r >> 2)]; } } } } while (0)
; #define NEGM_UPD(kt0) do { float nmj_ = -mC; if constexpr (BIAS) { const int dlo_ = (kt0) - q0 - 255, dhi_ = (kt0) + 63 - q0; if (dlo_ >= 1024) nmj_ += cb_hi; else if (dhi_ <= -1024) nmj_ += cb_lo; } \
;     if (__any(nmj_ != nm_cur)) { nm_cur = nmj_; _Pragma("unroll") for (int r = 0; r < 16; ++r) negm[r] = nmj_; } } while (0)
; #define QKT(P0, P1, KOFF) do { if constexpr (NDQ == 8 && NQL == 0) qkt8_roll(P0, P1, negm, kb0 + (KOFF), qr); \
;     else if constexpr (NDQ == 12 && NQL == 4) qkt12_roll(P0, P1, negm, kb0 + (KOFF), qa0, qr); else qkt<NDQ, NQL>(P0, P1, negm, K_lds + (KOFF), qr, qls, r32, hi); } while (0)
; template <bool EXP1 = true>
; __device__ __forceinline__ void finishSM(f32x16& p0, f32x16& p1, float alpha, float& l_reg, bf16x8& pa0, bf16x8& pa1, bf16x8& pa2, bf16x8& pa3) {
;   if constexpr (EXP1) {
; #pragma unroll
;   for (int r = 0; r < 16; ++r) p1[r] = __builtin_amdgcn_exp2f(p1[r]);
;   }
;   float sm_[4] = {p0[0], p0[1], p0[2], p0[3]};
; #pragma unroll
;   for (int r = 4; r < 16; ++r) sm_[r & 3] += p0[r];
; #pragma unroll
;   for (int r = 0; r < 16; ++r) sm_[r & 3] += p1[r];
;   float ps = (sm_[0] + sm_[1]) + (sm_[2] + sm_[3]);
;   { auto rr = __builtin_amdgcn_permlane32_swap(__float_as_uint(ps), __float_as_uint(ps), false, false);
;     ps = __uint_as_float(rr[0]) + __uint_as_float(rr[1]); }
;   l_reg = l_reg * alpha + ps;
;     ...
;   PK4(p0, 0, pa0); PK4(p0, 8, pa1); PK4(p1, 0, pa2); PK4(p1, 8, pa3);
;     ...
; }
;     ...
;     NEGM_UPD(kbeg + j * KVBLK); SBAR(); QKT(pB0, pB1, SHM_K);
;     finishSM(pA0, pA1, alA, l_reg, pa0, pa1, pa2, pa3); SBAR();
;     SLOAD(SO, kbeg + (j + SDEPTH) * KVBLK); SBAR();
;     pv_d0(o, vb0, pa0, pa1, pa2, pa3); BIASADD(pB0, pB1, kbeg + j * KVBLK); partialSM<false>(pB0, pB1, mC, alB);
	v_mfma_f32_32x32x16_bf16 v[114:129], v[230:233], v[246:249], v[114:129]
	ds_read_b128 v[230:233], v219 offset:0x100
	v_mfma_f32_32x32x16_bf16 v[82:97], v[242:245], v[246:249], v[82:97]
	ds_read_b128 v[242:245], v219 offset:0x3100
	ds_read_b128 v[246:249], v199 offset:0x800
	s_waitcnt lgkmcnt(3)
	v_mfma_f32_32x32x16_bf16 v[114:129], v[234:237], v[250:253], v[114:129]
	ds_read_b128 v[234:237], v218 offset:0x100
	v_mfma_f32_32x32x16_bf16 v[82:97], v[238:241], v[250:253], v[82:97]
	ds_read_b128 v[238:241], v218 offset:0x3100
	ds_read_b128 v[250:253], v199 offset:0xc00
	s_waitcnt lgkmcnt(3)
	v_mfma_f32_32x32x16_bf16 v[114:129], v[230:233], v[246:249], v[114:129]
	s_waitcnt lgkmcnt(0)
	v_mfma_f32_32x32x16_bf16 v[82:97], v[242:245], v[246:249], v[82:97]
	v_mfma_f32_32x32x16_bf16 v[114:129], v[234:237], v[250:253], v[114:129]
	v_mfma_f32_32x32x16_bf16 v[82:97], v[238:241], v[250:253], v[82:97]
	v_exp_f32_e32 v66, v66
	v_exp_f32_e32 v67, v67
	v_exp_f32_e32 v68, v68
	v_exp_f32_e32 v69, v69
	v_exp_f32_e32 v70, v70
	v_exp_f32_e32 v71, v71
	v_exp_f32_e32 v72, v72
	v_exp_f32_e32 v73, v73
	v_add_f32_e32 v166, v168, v176
	v_add_f32_e32 v179, v175, v178
	v_add_f32_e32 v180, v169, v167
	v_add_f32_e32 v181, v174, v177
	v_exp_f32_e32 v74, v74
	v_exp_f32_e32 v75, v75
	v_exp_f32_e32 v76, v76
	v_exp_f32_e32 v77, v77
	v_add_f32_e32 v166, v170, v166
	v_add_f32_e32 v179, v173, v179
	v_add_f32_e32 v180, v165, v180
	v_add_f32_e32 v181, v171, v181
	v_exp_f32_e32 v78, v78
	v_exp_f32_e32 v79, v79
	v_exp_f32_e32 v80, v80
	v_exp_f32_e32 v81, v81
	v_add_f32_e32 v166, v163, v166
	v_add_f32_e32 v179, v172, v179
	v_add_f32_e32 v180, v162, v180
	v_add_f32_e32 v181, v164, v181
	v_add_f32_e32 v166, v66, v166
	v_add_f32_e32 v179, v67, v179
	v_add_f32_e32 v180, v68, v180
	v_add_f32_e32 v181, v69, v181
	v_add_f32_e32 v166, v70, v166
	v_add_f32_e32 v179, v71, v179
	v_add_f32_e32 v180, v72, v180
	v_add_f32_e32 v181, v73, v181
	v_add_f32_e32 v166, v74, v166
	v_add_f32_e32 v179, v75, v179
	v_add_f32_e32 v180, v76, v180
	v_add_f32_e32 v181, v77, v181
	v_add_f32_e32 v166, v78, v166
	v_add_f32_e32 v179, v79, v179
	v_add_f32_e32 v180, v80, v180
	v_add_f32_e32 v181, v81, v181
	v_add_f32_e32 v166, v166, v179
	v_add_f32_e32 v179, v180, v181
	v_add_f32_e32 v223, v166, v179
	v_mov_b32_e32 v224, v223
	v_cvt_pk_bf16_f32 v166, v176, v178
	v_cvt_pk_bf16_f32 v167, v167, v177
	v_cvt_pk_bf16_f32 v168, v168, v175
	s_nop 1
	v_permlane32_swap_b32_e32 v223, v224
	v_cvt_pk_bf16_f32 v169, v169, v174
	v_cvt_pk_bf16_f32 v170, v170, v173
	v_cvt_pk_bf16_f32 v171, v165, v171
	v_cvt_pk_bf16_f32 v172, v163, v172
	v_cvt_pk_bf16_f32 v173, v162, v164
	v_cvt_pk_bf16_f32 v174, v66, v67
	v_cvt_pk_bf16_f32 v175, v68, v69
	v_cvt_pk_bf16_f32 v176, v70, v71
	v_cvt_pk_bf16_f32 v177, v72, v73
	v_cvt_pk_bf16_f32 v178, v74, v75
	v_cvt_pk_bf16_f32 v179, v76, v77
	v_cvt_pk_bf16_f32 v180, v78, v79
	v_cvt_pk_bf16_f32 v181, v80, v81
	v_lshl_add_u64 v[190:191], s[42:43], 0, v[188:189]
	v_add_co_u32_e32 v70, vcc, s49, v190
	v_lshl_add_u64 v[196:197], s[42:43], 0, v[186:187]
	s_nop 0
	v_addc_co_u32_e32 v71, vcc, 0, v191, vcc
	v_add_co_u32_e32 v74, vcc, s28, v190
	s_nop 1
	v_addc_co_u32_e32 v75, vcc, 0, v191, vcc
	global_load_dwordx4 v[66:69], v[70:71], off offset:256
	s_nop 0
	global_load_dwordx4 v[70:73], v[70:71], off
	s_nop 0
	global_load_dwordx4 v[78:81], v[74:75], off offset:256
	s_nop 0
	global_load_dwordx4 v[74:77], v[74:75], off
	v_add_co_u32_e32 v162, vcc, s68, v196
	s_nop 1
	v_addc_co_u32_e32 v163, vcc, 0, v197, vcc
	global_load_dwordx4 v[162:165], v[162:163], off
	ds_read_b64_tr_b16 v[230:231], v201 offset:0
	ds_read_b64_tr_b16 v[232:233], v201 offset:0x800
	ds_read_b64_tr_b16 v[234:235], v201 offset:0x1000
	ds_read_b64_tr_b16 v[236:237], v201 offset:0x1800
	ds_read_b64_tr_b16 v[238:239], v201 offset:0x2000
	ds_read_b64_tr_b16 v[240:241], v201 offset:0x2800
	ds_read_b64_tr_b16 v[242:243], v201 offset:0x3000
	ds_read_b64_tr_b16 v[244:245], v201 offset:0x3800
	ds_read_b64_tr_b16 v[246:247], v201 offset:0x200
	ds_read_b64_tr_b16 v[248:249], v201 offset:0xa00
	s_waitcnt lgkmcnt(8)
; __device__ __forceinline__ void pv_d0(f32x16* o, int vb, bf16x8 pa0, bf16x8 pa1, bf16x8 pa2, bf16x8 pa3) {
;     ...
;   const s16x4 l0 = tr_read<v_rd_off(0, 0, 0)>(vb), h0 = tr_read<v_rd_off(0, 0, 1)>(vb);
;   const s16x4 l1 = tr_read<v_rd_off(0, 1, 0)>(vb), h1 = tr_read<v_rd_off(0, 1, 1)>(vb);
;   const s16x4 l2 = tr_read<v_rd_off(0, 2, 0)>(vb), h2 = tr_read<v_rd_off(0, 2, 1)>(vb);
;   const s16x4 l3 = tr_read<v_rd_off(0, 3, 0)>(vb), h3 = tr_read<v_rd_off(0, 3, 1)>(vb);
;   const s16x4 l4 = tr_read<v_rd_off(1, 0, 0)>(vb), h4 = tr_read<v_rd_off(1, 0, 1)>(vb);
;   asm volatile("s_waitcnt lgkmcnt(8)" ::: "memory"); SBAR();
;   o[0] = __builtin_amdgcn_mfma_f32_32x32x16_bf16(pa0, PK(l0, h0), o[0], 0, 0, 0);
;   const s16x4 l5 = tr_read<v_rd_off(1, 1, 0)>(vb), h5 = tr_read<v_rd_off(1, 1, 1)>(vb);
;   asm volatile("s_waitcnt lgkmcnt(8)" ::: "memory"); SBAR();
;   o[0] = __builtin_amdgcn_mfma_f32_32x32x16_bf16(pa1, PK(l1, h1), o[0], 0, 0, 0);
;   const s16x4 l6 = tr_read<v_rd_off(1, 2, 0)>(vb), h6 = tr_read<v_rd_off(1, 2, 1)>(vb);
;   asm volatile("s_waitcnt lgkmcnt(8)" ::: "memory"); SBAR();
;   o[0] = __builtin_amdgcn_mfma_f32_32x32x16_bf16(pa2, PK(l2, h2), o[0], 0, 0, 0);
;   const s16x4 l7 = tr_read<v_rd_off(1, 3, 0)>(vb), h7 = tr_read<v_rd_off(1, 3, 1)>(vb);
;   asm volatile("s_waitcnt lgkmcnt(8)" ::: "memory"); SBAR();
;   o[0] = __builtin_amdgcn_mfma_f32_32x32x16_bf16(pa3, PK(l3, h3), o[0], 0, 0, 0);
;   const s16x4 l8 = tr_read<v_rd_off(2, 0, 0)>(vb), h8 = tr_read<v_rd_off(2, 0, 1)>(vb);
;   asm volatile("s_waitcnt lgkmcnt(8)" ::: "memory"); SBAR();
;   o[1] = __builtin_amdgcn_mfma_f32_32x32x16_bf16(pa0, PK(l4, h4), o[1], 0, 0, 0);
;   const s16x4 l9 = tr_read<v_rd_off(2, 1, 0)>(vb), h9 = tr_read<v_rd_off(2, 1, 1)>(vb);
;   asm volatile("s_waitcnt lgkmcnt(8)" ::: "memory"); SBAR();
;   o[1] = __builtin_amdgcn_mfma_f32_32x32x16_bf16(pa1, PK(l5, h5), o[1], 0, 0, 0);
;   const s16x4 l10 = tr_read<v_rd_off(2, 2, 0)>(vb), h10 = tr_read<v_rd_off(2, 2, 1)>(vb);
;   asm volatile("s_waitcnt lgkmcnt(8)" ::: "memory"); SBAR();
;   o[1] = __builtin_amdgcn_mfma_f32_32x32x16_bf16(pa2, PK(l6, h6), o[1], 0, 0, 0);
;   const s16x4 l11 = tr_read<v_rd_off(2, 3, 0)>(vb), h11 = tr_read<v_rd_off(2, 3, 1)>(vb);
;   asm volatile("s_waitcnt lgkmcnt(8)" ::: "memory"); SBAR();
;   o[1] = __builtin_amdgcn_mfma_f32_32x32x16_bf16(pa3, PK(l7, h7), o[1], 0, 0, 0);
	s_nop 0
	v_mfma_f32_32x32x16_bf16 v[2:17], v[166:169], v[230:233], v[2:17]
	ds_read_b64_tr_b16 v[230:231], v201 offset:0x1200
	ds_read_b64_tr_b16 v[232:233], v201 offset:0x1a00
	s_waitcnt lgkmcnt(8)
	v_mfma_f32_32x32x16_bf16 v[2:17], v[170:173], v[234:237], v[2:17]
	ds_read_b64_tr_b16 v[234:235], v201 offset:0x2200
	ds_read_b64_tr_b16 v[236:237], v201 offset:0x2a00
	s_waitcnt lgkmcnt(8)
	v_mfma_f32_32x32x16_bf16 v[2:17], v[174:177], v[238:241], v[2:17]
	ds_read_b64_tr_b16 v[238:239], v201 offset:0x3200
	ds_read_b64_tr_b16 v[240:241], v201 offset:0x3a00
	s_waitcnt lgkmcnt(8)
	v_mfma_f32_32x32x16_bf16 v[2:17], v[178:181], v[242:245], v[2:17]
	ds_read_b64_tr_b16 v[242:243], v201 offset:0x400
	ds_read_b64_tr_b16 v[244:245], v201 offset:0xc00
	s_waitcnt lgkmcnt(8)
	v_mfma_f32_32x32x16_bf16 v[50:65], v[166:169], v[246:249], v[50:65]
	ds_read_b64_tr_b16 v[246:247], v201 offset:0x1400
	ds_read_b64_tr_b16 v[248:249], v201 offset:0x1c00
	s_waitcnt lgkmcnt(8)
	v_mfma_f32_32x32x16_bf16 v[50:65], v[170:173], v[230:233], v[50:65]
	ds_read_b64_tr_b16 v[230:231], v201 offset:0x2400
	ds_read_b64_tr_b16 v[232:233], v201 offset:0x2c00
	s_waitcnt lgkmcnt(8)
	v_mfma_f32_32x32x16_bf16 v[50:65], v[174:177], v[234:237], v[50:65]
	ds_read_b64_tr_b16 v[234:235], v201 offset:0x3400
	ds_read_b64_tr_b16 v[236:237], v201 offset:0x3c00
	s_waitcnt lgkmcnt(8)
	v_mfma_f32_32x32x16_bf16 v[50:65], v[178:181], v[238:241], v[50:65]
	ds_read_b64_tr_b16 v[238:239], v201 offset:0x600
	ds_read_b64_tr_b16 v[240:241], v201 offset:0xe00
	s_waitcnt lgkmcnt(8)
	v_mfma_f32_32x32x16_bf16 v[34:49], v[166:169], v[242:245], v[34:49]
	ds_read_b64_tr_b16 v[242:243], v201 offset:0x1600
	ds_read_b64_tr_b16 v[244:245], v201 offset:0x1e00
	s_waitcnt lgkmcnt(8)
	v_mfma_f32_32x32x16_bf16 v[34:49], v[170:173], v[246:249], v[34:49]
	ds_read_b64_tr_b16 v[246:247], v201 offset:0x2600
	ds_read_b64_tr_b16 v[248:249], v201 offset:0x2e00
	s_waitcnt lgkmcnt(8)
	v_mfma_f32_32x32x16_bf16 v[34:49], v[174:177], v[230:233], v[34:49]
	ds_read_b64_tr_b16 v[230:231], v201 offset:0x3600
	ds_read_b64_tr_b16 v[232:233], v201 offset:0x3e00
	s_waitcnt lgkmcnt(8)
	v_mfma_f32_32x32x16_bf16 v[34:49], v[178:181], v[234:237], v[34:49]
	s_waitcnt lgkmcnt(6)
	v_mfma_f32_32x32x16_bf16 v[18:33], v[166:169], v[238:241], v[18:33]
	s_waitcnt lgkmcnt(4)
	v_mfma_f32_32x32x16_bf16 v[18:33], v[170:173], v[242:245], v[18:33]
	s_waitcnt lgkmcnt(2)
	v_mfma_f32_32x32x16_bf16 v[18:33], v[174:177], v[246:249], v[18:33]
	s_waitcnt lgkmcnt(0)
	v_max_f32_e32 v166, v118, v118
	v_max_f32_e32 v167, v114, v114
	v_max_f32_e32 v166, v167, v166
	v_max_f32_e32 v167, v119, v119
	v_max_f32_e32 v168, v115, v115
	v_max_f32_e32 v167, v168, v167
	v_max_f32_e32 v168, v121, v121
	v_max_f32_e32 v169, v117, v117
	v_max_f32_e32 v168, v169, v168
	v_max3_f32 v169, v116, v120, v124
	v_max3_f32 v168, v168, v125, v129
	v_max3_f32 v166, v166, v122, v126
	v_max3_f32 v167, v167, v123, v127
	v_max3_f32 v169, v169, v128, v84
	v_max3_f32 v168, v168, v85, v89
	v_max3_f32 v166, v166, v82, v86
	v_max3_f32 v167, v167, v83, v87
	v_max3_f32 v169, v169, v88, v92
	v_max3_f32 v168, v168, v93, v97
	v_mfma_f32_32x32x16_bf16 v[18:33], v[178:181], v[230:233], v[18:33]
	v_max3_f32 v166, v166, v90, v94
	v_max3_f32 v167, v167, v91, v95
	v_max3_f32 v168, v169, v96, v168
	v_max3_f32 v166, v166, v167, v168
	v_mov_b32_e32 v167, v166
	s_nop 1
	v_permlane32_swap_b32_e32 v166, v167
	v_max_f32_e32 v167, v167, v167
	v_max_f32_e32 v166, v166, v166
	v_max_f32_e32 v166, v166, v167
	v_cmp_ge_f32_e32 vcc, s48, v166
	s_cmp_eq_u64 vcc, exec
	s_cbranch_scc0 .LBB0_400
	v_mov_b32_e32 v227, v225
	v_mov_b32_e32 v226, 1.0

; __device__ __forceinline__ void qkt12_roll(f32x16& p0, f32x16& p1, const f32x16& negm, int kb, int qa, const bf16x8* qr) {
;   const int a0 = kb ^ (0 << 5); const bf16x8 x0 = lds_rd128<0>(a0), y0 = lds_rd128<12288>(a0);
;   const int a1 = kb ^ (1 << 5); const bf16x8 x1 = lds_rd128<0>(a1), y1 = lds_rd128<12288>(a1);
;   asm volatile("s_waitcnt lgkmcnt(2)" ::: "memory"); SBAR();
;   p0 = __builtin_amdgcn_mfma_f32_32x32x16_bf16(x0, qr[0], negm, 0, 0, 0); p1 = __builtin_amdgcn_mfma_f32_32x32x16_bf16(y0, qr[0], negm, 0, 0, 0);
;   const int a2 = kb ^ (2 << 5); const bf16x8 x2 = lds_rd128<0>(a2), y2 = lds_rd128<12288>(a2);
;   asm volatile("s_waitcnt lgkmcnt(2)" ::: "memory"); SBAR();
;   p0 = __builtin_amdgcn_mfma_f32_32x32x16_bf16(x1, qr[1], p0, 0, 0, 0); p1 = __builtin_amdgcn_mfma_f32_32x32x16_bf16(y1, qr[1], p1, 0, 0, 0);
;   const int a3 = kb ^ (3 << 5); const bf16x8 x3 = lds_rd128<0>(a3), y3 = lds_rd128<12288>(a3);
;   asm volatile("s_waitcnt lgkmcnt(2)" ::: "memory"); SBAR();
;   p0 = __builtin_amdgcn_mfma_f32_32x32x16_bf16(x2, qr[2], p0, 0, 0, 0); p1 = __builtin_amdgcn_mfma_f32_32x32x16_bf16(y2, qr[2], p1, 0, 0, 0);
;   const int a4 = kb ^ (0 << 5); const bf16x8 x4 = lds_rd128<128>(a4), y4 = lds_rd128<12416>(a4);
;   asm volatile("s_waitcnt lgkmcnt(2)" ::: "memory"); SBAR();
;   p0 = __builtin_amdgcn_mfma_f32_32x32x16_bf16(x3, qr[3], p0, 0, 0, 0); p1 = __builtin_amdgcn_mfma_f32_32x32x16_bf16(y3, qr[3], p1, 0, 0, 0);
;   const int a5 = kb ^ (1 << 5); const bf16x8 x5 = lds_rd128<128>(a5), y5 = lds_rd128<12416>(a5);
;   asm volatile("s_waitcnt lgkmcnt(2)" ::: "memory"); SBAR();
;   p0 = __builtin_amdgcn_mfma_f32_32x32x16_bf16(x4, qr[4], p0, 0, 0, 0); p1 = __builtin_amdgcn_mfma_f32_32x32x16_bf16(y4, qr[4], p1, 0, 0, 0);
;   const int a6 = kb ^ (2 << 5); const bf16x8 x6 = lds_rd128<128>(a6), y6 = lds_rd128<12416>(a6);
;   asm volatile("s_waitcnt lgkmcnt(2)" ::: "memory"); SBAR();
;   p0 = __builtin_amdgcn_mfma_f32_32x32x16_bf16(x5, qr[5], p0, 0, 0, 0); p1 = __builtin_amdgcn_mfma_f32_32x32x16_bf16(y5, qr[5], p1, 0, 0, 0);
;   const int a7 = kb ^ (3 << 5); const bf16x8 x7 = lds_rd128<128>(a7), y7 = lds_rd128<12416>(a7);
;   asm volatile("s_waitcnt lgkmcnt(2)" ::: "memory"); SBAR();
;   p0 = __builtin_amdgcn_mfma_f32_32x32x16_bf16(x6, qr[6], p0, 0, 0, 0); p1 = __builtin_amdgcn_mfma_f32_32x32x16_bf16(y6, qr[6], p1, 0, 0, 0);
.LBB0_392:
	v_xor_b32_e32 v66, 0x80000000, v225
	v_cndmask_b32_e64 v228, v66, v228, s[6:7]
	v_exp_f32_e32 v166, v114
	v_exp_f32_e32 v167, v116
	v_exp_f32_e32 v165, v124
	v_exp_f32_e32 v163, v126
	v_exp_f32_e32 v162, v128
	v_exp_f32_e32 v164, v129
	v_cmp_neq_f32_e64 s[6:7], v228, -v227
	s_cmp_eq_u64 s[6:7], 0
	s_cselect_b64 s[6:7], -1, 0
	v_cndmask_b32_e64 v113, -v227, v113, s[6:7]
	v_cndmask_b32_e64 v112, -v227, v112, s[6:7]
	v_cndmask_b32_e64 v111, -v227, v111, s[6:7]
	v_cndmask_b32_e64 v110, -v227, v110, s[6:7]
	v_cndmask_b32_e64 v109, -v227, v109, s[6:7]
	v_cndmask_b32_e64 v108, -v227, v108, s[6:7]
	v_cndmask_b32_e64 v107, -v227, v107, s[6:7]
	v_cndmask_b32_e64 v106, -v227, v106, s[6:7]
	v_cndmask_b32_e64 v105, -v227, v105, s[6:7]
	v_cndmask_b32_e64 v104, -v227, v104, s[6:7]
	v_cndmask_b32_e64 v103, -v227, v103, s[6:7]
	v_cndmask_b32_e64 v102, -v227, v102, s[6:7]
	v_cndmask_b32_e64 v101, -v227, v101, s[6:7]
	v_cndmask_b32_e64 v100, -v227, v100, s[6:7]
	v_cndmask_b32_e64 v99, -v227, v99, s[6:7]
	v_cndmask_b32_e64 v98, -v227, v98, s[6:7]
	v_exp_f32_e32 v177, v115
	v_exp_f32_e32 v176, v117
	v_exp_f32_e32 v168, v118
	v_exp_f32_e32 v175, v119
	v_exp_f32_e32 v169, v120
	v_exp_f32_e32 v174, v121
	v_exp_f32_e32 v170, v122
	v_exp_f32_e32 v173, v123
	v_exp_f32_e32 v171, v125
	v_exp_f32_e32 v172, v127
	s_waitcnt lgkmcnt(0)
	s_barrier
	ds_read_b128 v[66:69], v209 offset:0
	ds_read_b128 v[178:181], v209 offset:0x3000
	ds_read_b128 v[230:233], v215 offset:0
	ds_read_b128 v[234:237], v215 offset:0x3000
	s_waitcnt lgkmcnt(2)
	s_nop 0
	v_mfma_f32_32x32x16_bf16 v[114:129], v[66:69], v[158:161], v[98:113]
	v_mfma_f32_32x32x16_bf16 v[66:81], v[178:181], v[158:161], v[98:113]
	ds_read_b128 v[178:181], v216 offset:0
	ds_read_b128 v[238:241], v216 offset:0x3000
	s_waitcnt lgkmcnt(2)
	v_mfma_f32_32x32x16_bf16 v[114:129], v[230:233], v[154:157], v[114:129]
	ds_read_b128 v[230:233], v217 offset:0
	v_mfma_f32_32x32x16_bf16 v[66:81], v[234:237], v[154:157], v[66:81]
	ds_read_b128 v[234:237], v217 offset:0x3000
	s_waitcnt lgkmcnt(2)
	v_mfma_f32_32x32x16_bf16 v[114:129], v[178:181], v[150:153], v[114:129]
	ds_read_b128 v[178:181], v209 offset:0x80
	v_mfma_f32_32x32x16_bf16 v[66:81], v[238:241], v[150:153], v[66:81]
	ds_read_b128 v[238:241], v209 offset:0x3080
	s_waitcnt lgkmcnt(2)
	v_mfma_f32_32x32x16_bf16 v[114:129], v[230:233], v[146:149], v[114:129]
	ds_read_b128 v[230:233], v215 offset:0x80
	v_mfma_f32_32x32x16_bf16 v[66:81], v[234:237], v[146:149], v[66:81]
	ds_read_b128 v[234:237], v215 offset:0x3080
	s_waitcnt lgkmcnt(2)
	v_mfma_f32_32x32x16_bf16 v[114:129], v[178:181], v[142:145], v[114:129]
	ds_read_b128 v[178:181], v216 offset:0x80
	v_mfma_f32_32x32x16_bf16 v[66:81], v[238:241], v[142:145], v[66:81]
	ds_read_b128 v[238:241], v216 offset:0x3080
	s_waitcnt lgkmcnt(2)
	v_mfma_f32_32x32x16_bf16 v[114:129], v[230:233], v[138:141], v[114:129]
	ds_read_b128 v[230:233], v217 offset:0x80
	v_mfma_f32_32x32x16_bf16 v[66:81], v[234:237], v[138:141], v[66:81]
	ds_read_b128 v[234:237], v217 offset:0x3080
	s_waitcnt lgkmcnt(2)
	v_mfma_f32_32x32x16_bf16 v[114:129], v[178:181], v[134:137], v[114:129]
	ds_read_b128 v[178:181], v209 offset:0x100
	v_mfma_f32_32x32x16_bf16 v[66:81], v[238:241], v[134:137], v[66:81]
	ds_read_b128 v[238:241], v209 offset:0x3100
	ds_read_b128 v[242:245], v199 offset:0
	s_waitcnt lgkmcnt(3)
	v_mfma_f32_32x32x16_bf16 v[114:129], v[230:233], v[130:133], v[114:129]
	ds_read_b128 v[230:233], v215 offset:0x100
	v_mfma_f32_32x32x16_bf16 v[66:81], v[234:237], v[130:133], v[66:81]
	ds_read_b128 v[234:237], v215 offset:0x3100
	ds_read_b128 v[246:249], v199 offset:0x400
	s_waitcnt lgkmcnt(3)
	v_mfma_f32_32x32x16_bf16 v[114:129], v[178:181], v[242:245], v[114:129]
	ds_read_b128 v[178:181], v216 offset:0x100
	v_mfma_f32_32x32x16_bf16 v[66:81], v[238:241], v[242:245], v[66:81]
	ds_read_b128 v[238:241], v216 offset:0x3100
	ds_read_b128 v[242:245], v199 offset:0x800
	s_waitcnt lgkmcnt(3)
	v_mfma_f32_32x32x16_bf16 v[114:129], v[230:233], v[246:249], v[114:129]
	ds_read_b128 v[230:233], v217 offset:0x100
	v_mfma_f32_32x32x16_bf16 v[66:81], v[234:237], v[246:249], v[66:81]
	ds_read_b128 v[234:237], v217 offset:0x3100
	ds_read_b128 v[246:249], v199 offset:0xc00
	s_waitcnt lgkmcnt(3)
	v_mfma_f32_32x32x16_bf16 v[114:129], v[178:181], v[242:245], v[114:129]
	s_waitcnt lgkmcnt(0)
; __device__ __forceinline__ void pv_d0(f32x16* o, int vb, bf16x8 pa0, bf16x8 pa1, bf16x8 pa2, bf16x8 pa3) {
;     ...
;   const s16x4 l0 = tr_read<v_rd_off(0, 0, 0)>(vb), h0 = tr_read<v_rd_off(0, 0, 1)>(vb);
;   const s16x4 l1 = tr_read<v_rd_off(0, 1, 0)>(vb), h1 = tr_read<v_rd_off(0, 1, 1)>(vb);
;   const s16x4 l2 = tr_read<v_rd_off(0, 2, 0)>(vb), h2 = tr_read<v_rd_off(0, 2, 1)>(vb);
;   const s16x4 l3 = tr_read<v_rd_off(0, 3, 0)>(vb), h3 = tr_read<v_rd_off(0, 3, 1)>(vb);
;   const s16x4 l4 = tr_read<v_rd_off(1, 0, 0)>(vb), h4 = tr_read<v_rd_off(1, 0, 1)>(vb);
;   asm volatile("s_waitcnt lgkmcnt(8)" ::: "memory"); SBAR();
;   o[0] = __builtin_amdgcn_mfma_f32_32x32x16_bf16(pa0, PK(l0, h0), o[0], 0, 0, 0);
;   const s16x4 l5 = tr_read<v_rd_off(1, 1, 0)>(vb), h5 = tr_read<v_rd_off(1, 1, 1)>(vb);
;   asm volatile("s_waitcnt lgkmcnt(8)" ::: "memory"); SBAR();
;   o[0] = __builtin_amdgcn_mfma_f32_32x32x16_bf16(pa1, PK(l1, h1), o[0], 0, 0, 0);
;   const s16x4 l6 = tr_read<v_rd_off(1, 2, 0)>(vb), h6 = tr_read<v_rd_off(1, 2, 1)>(vb);
;   asm volatile("s_waitcnt lgkmcnt(8)" ::: "memory"); SBAR();
;   o[0] = __builtin_amdgcn_mfma_f32_32x32x16_bf16(pa2, PK(l2, h2), o[0], 0, 0, 0);
;   const s16x4 l7 = tr_read<v_rd_off(1, 3, 0)>(vb), h7 = tr_read<v_rd_off(1, 3, 1)>(vb);
;   asm volatile("s_waitcnt lgkmcnt(8)" ::: "memory"); SBAR();
;   o[0] = __builtin_amdgcn_mfma_f32_32x32x16_bf16(pa3, PK(l3, h3), o[0], 0, 0, 0);
;   const s16x4 l8 = tr_read<v_rd_off(2, 0, 0)>(vb), h8 = tr_read<v_rd_off(2, 0, 1)>(vb);
;   asm volatile("s_waitcnt lgkmcnt(8)" ::: "memory"); SBAR();
;   o[1] = __builtin_amdgcn_mfma_f32_32x32x16_bf16(pa0, PK(l4, h4), o[1], 0, 0, 0);
;   const s16x4 l9 = tr_read<v_rd_off(2, 1, 0)>(vb), h9 = tr_read<v_rd_off(2, 1, 1)>(vb);
;   asm volatile("s_waitcnt lgkmcnt(8)" ::: "memory"); SBAR();
;   o[1] = __builtin_amdgcn_mfma_f32_32x32x16_bf16(pa1, PK(l5, h5), o[1], 0, 0, 0);
;   const s16x4 l10 = tr_read<v_rd_off(2, 2, 0)>(vb), h10 = tr_read<v_rd_off(2, 2, 1)>(vb);
;   asm volatile("s_waitcnt lgkmcnt(8)" ::: "memory"); SBAR();
;   o[1] = __builtin_amdgcn_mfma_f32_32x32x16_bf16(pa2, PK(l6, h6), o[1], 0, 0, 0);
;   const s16x4 l11 = tr_read<v_rd_off(2, 3, 0)>(vb), h11 = tr_read<v_rd_off(2, 3, 1)>(vb);
;   asm volatile("s_waitcnt lgkmcnt(8)" ::: "memory"); SBAR();
;   o[1] = __builtin_amdgcn_mfma_f32_32x32x16_bf16(pa3, PK(l7, h7), o[1], 0, 0, 0);
	v_mfma_f32_32x32x16_bf16 v[66:81], v[238:241], v[242:245], v[66:81]
	v_mfma_f32_32x32x16_bf16 v[114:129], v[230:233], v[246:249], v[114:129]
	v_mfma_f32_32x32x16_bf16 v[66:81], v[234:237], v[246:249], v[66:81]
	v_exp_f32_e32 v82, v82
	v_exp_f32_e32 v83, v83
	v_exp_f32_e32 v84, v84
	v_exp_f32_e32 v85, v85
	v_exp_f32_e32 v86, v86
	v_exp_f32_e32 v87, v87
	v_exp_f32_e32 v88, v88
	v_exp_f32_e32 v89, v89
	v_add_f32_e32 v178, v168, v166
	v_add_f32_e32 v179, v175, v177
	v_add_f32_e32 v180, v169, v167
	v_add_f32_e32 v181, v174, v176
	v_exp_f32_e32 v90, v90
	v_exp_f32_e32 v91, v91
	v_exp_f32_e32 v92, v92
	v_exp_f32_e32 v93, v93
	v_add_f32_e32 v178, v170, v178
	v_add_f32_e32 v179, v173, v179
	v_add_f32_e32 v180, v165, v180
	v_add_f32_e32 v181, v171, v181
	v_exp_f32_e32 v94, v94
	v_exp_f32_e32 v95, v95
	v_exp_f32_e32 v96, v96
	v_exp_f32_e32 v97, v97
	v_add_f32_e32 v178, v163, v178
	v_add_f32_e32 v179, v172, v179
	v_add_f32_e32 v180, v162, v180
	v_add_f32_e32 v181, v164, v181
	v_add_f32_e32 v178, v82, v178
	v_add_f32_e32 v179, v179, v83
	v_add_f32_e32 v180, v180, v84
	v_add_f32_e32 v181, v181, v85
	v_add_f32_e32 v178, v86, v178
	v_add_f32_e32 v179, v87, v179
	v_add_f32_e32 v180, v88, v180
	v_add_f32_e32 v181, v89, v181
	v_add_f32_e32 v178, v90, v178
	v_add_f32_e32 v179, v91, v179
	v_add_f32_e32 v180, v92, v180
	v_add_f32_e32 v181, v93, v181
	v_add_f32_e32 v178, v94, v178
	v_add_f32_e32 v179, v95, v179
	v_add_f32_e32 v180, v96, v180
	v_add_f32_e32 v181, v97, v181
	v_add_f32_e32 v178, v178, v179
	v_add_f32_e32 v179, v180, v181
	v_add_f32_e32 v229, v178, v179
	v_mov_b32_e32 v230, v229
	v_cvt_pk_bf16_f32 v166, v166, v177
	v_cvt_pk_bf16_f32 v167, v167, v176
	v_cvt_pk_bf16_f32 v168, v168, v175
	v_cvt_pk_bf16_f32 v169, v169, v174
	s_nop 1
	v_permlane32_swap_b32_e32 v229, v230
	v_cvt_pk_bf16_f32 v170, v170, v173
	v_cvt_pk_bf16_f32 v171, v165, v171
	v_cvt_pk_bf16_f32 v172, v163, v172
	v_cvt_pk_bf16_f32 v173, v162, v164
	v_cvt_pk_bf16_f32 v174, v82, v83
	v_cvt_pk_bf16_f32 v175, v84, v85
	v_cvt_pk_bf16_f32 v176, v86, v87
	v_cvt_pk_bf16_f32 v177, v88, v89
	v_cvt_pk_bf16_f32 v178, v90, v91
	v_cvt_pk_bf16_f32 v179, v92, v93
	v_cvt_pk_bf16_f32 v180, v94, v95
	v_cvt_pk_bf16_f32 v181, v96, v97
	s_nop 0
	v_add_co_u32_e32 v86, vcc, s69, v190
	s_nop 1
	v_addc_co_u32_e32 v87, vcc, 0, v191, vcc
	v_add_co_u32_e32 v90, vcc, s74, v190
	s_nop 1
	v_addc_co_u32_e32 v91, vcc, 0, v191, vcc
	global_load_dwordx4 v[82:85], v[86:87], off offset:256
	s_nop 0
	global_load_dwordx4 v[86:89], v[86:87], off
	s_nop 0
	global_load_dwordx4 v[94:97], v[90:91], off offset:256
	s_nop 0
	global_load_dwordx4 v[90:93], v[90:91], off
	v_add_co_u32_e32 v162, vcc, s75, v196
	s_nop 1
	v_addc_co_u32_e32 v163, vcc, 0, v197, vcc
	global_load_dwordx4 v[162:165], v[162:163], off
	ds_read_b64_tr_b16 v[232:233], v208 offset:0
	ds_read_b64_tr_b16 v[234:235], v208 offset:0x800
	ds_read_b64_tr_b16 v[236:237], v208 offset:0x1000
	ds_read_b64_tr_b16 v[238:239], v208 offset:0x1800
	ds_read_b64_tr_b16 v[240:241], v208 offset:0x2000
	ds_read_b64_tr_b16 v[242:243], v208 offset:0x2800
	ds_read_b64_tr_b16 v[244:245], v208 offset:0x3000
	ds_read_b64_tr_b16 v[246:247], v208 offset:0x3800
	ds_read_b64_tr_b16 v[248:249], v208 offset:0x200
	ds_read_b64_tr_b16 v[250:251], v208 offset:0xa00
	s_waitcnt lgkmcnt(8)
	s_nop 0
	v_mfma_f32_32x32x16_bf16 v[2:17], v[166:169], v[232:235], v[2:17]
	ds_read_b64_tr_b16 v[232:233], v208 offset:0x1200
	ds_read_b64_tr_b16 v[234:235], v208 offset:0x1a00
	s_waitcnt lgkmcnt(8)
	v_mfma_f32_32x32x16_bf16 v[2:17], v[170:173], v[236:239], v[2:17]
	ds_read_b64_tr_b16 v[236:237], v208 offset:0x2200
	ds_read_b64_tr_b16 v[238:239], v208 offset:0x2a00
	s_waitcnt lgkmcnt(8)
	v_mfma_f32_32x32x16_bf16 v[2:17], v[174:177], v[240:243], v[2:17]
	ds_read_b64_tr_b16 v[240:241], v208 offset:0x3200
	ds_read_b64_tr_b16 v[242:243], v208 offset:0x3a00
	s_waitcnt lgkmcnt(8)
	v_mfma_f32_32x32x16_bf16 v[2:17], v[178:181], v[244:247], v[2:17]
	ds_read_b64_tr_b16 v[244:245], v208 offset:0x400
	ds_read_b64_tr_b16 v[246:247], v208 offset:0xc00
	s_waitcnt lgkmcnt(8)
	v_mfma_f32_32x32x16_bf16 v[50:65], v[166:169], v[248:251], v[50:65]
	ds_read_b64_tr_b16 v[248:249], v208 offset:0x1400
	ds_read_b64_tr_b16 v[250:251], v208 offset:0x1c00
	s_waitcnt lgkmcnt(8)
	v_mfma_f32_32x32x16_bf16 v[50:65], v[170:173], v[232:235], v[50:65]
	ds_read_b64_tr_b16 v[232:233], v208 offset:0x2400
	ds_read_b64_tr_b16 v[234:235], v208 offset:0x2c00
	s_waitcnt lgkmcnt(8)
	v_mfma_f32_32x32x16_bf16 v[50:65], v[174:177], v[236:239], v[50:65]
	ds_read_b64_tr_b16 v[236:237], v208 offset:0x3400
	ds_read_b64_tr_b16 v[238:239], v208 offset:0x3c00
	s_waitcnt lgkmcnt(8)
	v_mfma_f32_32x32x16_bf16 v[50:65], v[178:181], v[240:243], v[50:65]
	ds_read_b64_tr_b16 v[240:241], v208 offset:0x600
	ds_read_b64_tr_b16 v[242:243], v208 offset:0xe00
	s_waitcnt lgkmcnt(8)
	v_mfma_f32_32x32x16_bf16 v[34:49], v[166:169], v[244:247], v[34:49]
	ds_read_b64_tr_b16 v[244:245], v208 offset:0x1600
	ds_read_b64_tr_b16 v[246:247], v208 offset:0x1e00
	s_waitcnt lgkmcnt(8)
	v_mfma_f32_32x32x16_bf16 v[34:49], v[170:173], v[248:251], v[34:49]
	ds_read_b64_tr_b16 v[248:249], v208 offset:0x2600
	ds_read_b64_tr_b16 v[250:251], v208 offset:0x2e00
	s_waitcnt lgkmcnt(8)
	v_mfma_f32_32x32x16_bf16 v[34:49], v[174:177], v[232:235], v[34:49]
	ds_read_b64_tr_b16 v[232:233], v208 offset:0x3600
	ds_read_b64_tr_b16 v[234:235], v208 offset:0x3e00
	s_waitcnt lgkmcnt(8)
	v_mfma_f32_32x32x16_bf16 v[34:49], v[178:181], v[236:239], v[34:49]
	s_waitcnt lgkmcnt(6)
	v_mfma_f32_32x32x16_bf16 v[18:33], v[166:169], v[240:243], v[18:33]
	s_waitcnt lgkmcnt(4)
	v_mfma_f32_32x32x16_bf16 v[18:33], v[170:173], v[244:247], v[18:33]
	s_waitcnt lgkmcnt(2)
	v_mfma_f32_32x32x16_bf16 v[18:33], v[174:177], v[248:251], v[18:33]
	s_waitcnt lgkmcnt(0)
	v_max_f32_e32 v166, v118, v118
	v_max_f32_e32 v167, v114, v114
	v_max_f32_e32 v166, v167, v166
	v_max_f32_e32 v167, v119, v119
	v_max_f32_e32 v168, v115, v115
	v_max_f32_e32 v167, v168, v167
	v_max_f32_e32 v168, v121, v121
	v_max_f32_e32 v169, v117, v117
	v_max_f32_e32 v168, v169, v168
	v_max3_f32 v169, v116, v120, v124
	v_max3_f32 v168, v168, v125, v129
	v_max3_f32 v166, v166, v122, v126
	v_max3_f32 v167, v167, v123, v127
	v_max3_f32 v169, v169, v128, v68
	v_max3_f32 v168, v168, v69, v73
	v_max3_f32 v166, v166, v66, v70
	v_max3_f32 v167, v167, v67, v71
	v_max3_f32 v169, v169, v72, v76
	v_max3_f32 v168, v168, v77, v81
	v_mfma_f32_32x32x16_bf16 v[18:33], v[178:181], v[232:235], v[18:33]
	v_max3_f32 v166, v166, v74, v78
	v_max3_f32 v167, v167, v75, v79
	v_max3_f32 v168, v169, v80, v168
	v_max3_f32 v166, v166, v167, v168
	v_mov_b32_e32 v167, v166
	s_nop 1
	v_permlane32_swap_b32_e32 v166, v167
	v_max_f32_e32 v167, v167, v167
	v_max_f32_e32 v166, v166, v166
	v_max_f32_e32 v167, v166, v167
	v_cmp_ge_f32_e32 vcc, s48, v167
	s_cmp_eq_u64 vcc, exec
	v_mov_b32_e32 v166, 1.0
	s_cbranch_scc0 .LBB0_401
	v_mov_b32_e32 v225, v227

; __device__ __forceinline__ void qkt12_roll(f32x16& p0, f32x16& p1, const f32x16& negm, int kb, int qa, const bf16x8* qr) {
;   const int a0 = kb ^ (0 << 5); const bf16x8 x0 = lds_rd128<0>(a0), y0 = lds_rd128<12288>(a0);
;   const int a1 = kb ^ (1 << 5); const bf16x8 x1 = lds_rd128<0>(a1), y1 = lds_rd128<12288>(a1);
;   asm volatile("s_waitcnt lgkmcnt(2)" ::: "memory"); SBAR();
;   p0 = __builtin_amdgcn_mfma_f32_32x32x16_bf16(x0, qr[0], negm, 0, 0, 0); p1 = __builtin_amdgcn_mfma_f32_32x32x16_bf16(y0, qr[0], negm, 0, 0, 0);
;   const int a2 = kb ^ (2 << 5); const bf16x8 x2 = lds_rd128<0>(a2), y2 = lds_rd128<12288>(a2);
;   asm volatile("s_waitcnt lgkmcnt(2)" ::: "memory"); SBAR();
;   p0 = __builtin_amdgcn_mfma_f32_32x32x16_bf16(x1, qr[1], p0, 0, 0, 0); p1 = __builtin_amdgcn_mfma_f32_32x32x16_bf16(y1, qr[1], p1, 0, 0, 0);
;   const int a3 = kb ^ (3 << 5); const bf16x8 x3 = lds_rd128<0>(a3), y3 = lds_rd128<12288>(a3);
;   asm volatile("s_waitcnt lgkmcnt(2)" ::: "memory"); SBAR();
;   p0 = __builtin_amdgcn_mfma_f32_32x32x16_bf16(x2, qr[2], p0, 0, 0, 0); p1 = __builtin_amdgcn_mfma_f32_32x32x16_bf16(y2, qr[2], p1, 0, 0, 0);
;   const int a4 = kb ^ (0 << 5); const bf16x8 x4 = lds_rd128<128>(a4), y4 = lds_rd128<12416>(a4);
;   asm volatile("s_waitcnt lgkmcnt(2)" ::: "memory"); SBAR();
;   p0 = __builtin_amdgcn_mfma_f32_32x32x16_bf16(x3, qr[3], p0, 0, 0, 0); p1 = __builtin_amdgcn_mfma_f32_32x32x16_bf16(y3, qr[3], p1, 0, 0, 0);
;   const int a5 = kb ^ (1 << 5); const bf16x8 x5 = lds_rd128<128>(a5), y5 = lds_rd128<12416>(a5);
;   asm volatile("s_waitcnt lgkmcnt(2)" ::: "memory"); SBAR();
;   p0 = __builtin_amdgcn_mfma_f32_32x32x16_bf16(x4, qr[4], p0, 0, 0, 0); p1 = __builtin_amdgcn_mfma_f32_32x32x16_bf16(y4, qr[4], p1, 0, 0, 0);
;   const int a6 = kb ^ (2 << 5); const bf16x8 x6 = lds_rd128<128>(a6), y6 = lds_rd128<12416>(a6);
;   asm volatile("s_waitcnt lgkmcnt(2)" ::: "memory"); SBAR();
;   p0 = __builtin_amdgcn_mfma_f32_32x32x16_bf16(x5, qr[5], p0, 0, 0, 0); p1 = __builtin_amdgcn_mfma_f32_32x32x16_bf16(y5, qr[5], p1, 0, 0, 0);
;   const int a7 = kb ^ (3 << 5); const bf16x8 x7 = lds_rd128<128>(a7), y7 = lds_rd128<12416>(a7);
;   asm volatile("s_waitcnt lgkmcnt(2)" ::: "memory"); SBAR();
;   p0 = __builtin_amdgcn_mfma_f32_32x32x16_bf16(x6, qr[6], p0, 0, 0, 0); p1 = __builtin_amdgcn_mfma_f32_32x32x16_bf16(y6, qr[6], p1, 0, 0, 0);
.LBB0_402:
	v_cmp_neq_f32_e64 s[6:7], v228, -v225
	s_cmp_eq_u64 s[6:7], 0
	s_cselect_b64 s[6:7], -1, 0
	v_cndmask_b32_e64 v97, -v225, v113, s[6:7]
	v_cndmask_b32_e64 v96, -v225, v112, s[6:7]
	v_cndmask_b32_e64 v95, -v225, v111, s[6:7]
	v_cndmask_b32_e64 v94, -v225, v110, s[6:7]
	v_cndmask_b32_e64 v93, -v225, v109, s[6:7]
	v_cndmask_b32_e64 v92, -v225, v108, s[6:7]
	v_cndmask_b32_e64 v91, -v225, v107, s[6:7]
	v_cndmask_b32_e64 v90, -v225, v106, s[6:7]
	v_cndmask_b32_e64 v89, -v225, v105, s[6:7]
	v_cndmask_b32_e64 v88, -v225, v104, s[6:7]
	v_cndmask_b32_e64 v87, -v225, v103, s[6:7]
	v_cndmask_b32_e64 v86, -v225, v102, s[6:7]
	v_cndmask_b32_e64 v85, -v225, v101, s[6:7]
	v_cndmask_b32_e64 v84, -v225, v100, s[6:7]
	v_cndmask_b32_e64 v83, -v225, v99, s[6:7]
	v_cndmask_b32_e64 v82, -v225, v98, s[6:7]
	ds_read_b128 v[114:117], v221 offset:0
	ds_read_b128 v[118:121], v221 offset:0x3000
	ds_read_b128 v[122:125], v220 offset:0
	ds_read_b128 v[126:129], v220 offset:0x3000
	s_waitcnt lgkmcnt(2)
	s_nop 1
	v_mfma_f32_32x32x16_bf16 v[98:113], v[114:117], v[158:161], v[82:97]
	ds_read_b128 v[114:117], v219 offset:0
	v_mfma_f32_32x32x16_bf16 v[82:97], v[118:121], v[158:161], v[82:97]
	ds_read_b128 v[118:121], v219 offset:0x3000
	s_waitcnt lgkmcnt(2)
	v_mfma_f32_32x32x16_bf16 v[98:113], v[122:125], v[154:157], v[98:113]
	ds_read_b128 v[122:125], v218 offset:0
	v_mfma_f32_32x32x16_bf16 v[82:97], v[126:129], v[154:157], v[82:97]
	ds_read_b128 v[126:129], v218 offset:0x3000
	s_waitcnt lgkmcnt(2)
	v_mfma_f32_32x32x16_bf16 v[98:113], v[114:117], v[150:153], v[98:113]
	ds_read_b128 v[114:117], v221 offset:0x80
	v_mfma_f32_32x32x16_bf16 v[82:97], v[118:121], v[150:153], v[82:97]
	ds_read_b128 v[118:121], v221 offset:0x3080
	s_waitcnt lgkmcnt(2)
	v_mfma_f32_32x32x16_bf16 v[98:113], v[122:125], v[146:149], v[98:113]
	ds_read_b128 v[122:125], v220 offset:0x80
	v_mfma_f32_32x32x16_bf16 v[82:97], v[126:129], v[146:149], v[82:97]
	ds_read_b128 v[126:129], v220 offset:0x3080
	s_waitcnt lgkmcnt(2)
	v_mfma_f32_32x32x16_bf16 v[98:113], v[114:117], v[142:145], v[98:113]
	ds_read_b128 v[114:117], v219 offset:0x80
	v_mfma_f32_32x32x16_bf16 v[82:97], v[118:121], v[142:145], v[82:97]
	ds_read_b128 v[118:121], v219 offset:0x3080
	s_waitcnt lgkmcnt(2)
	v_mfma_f32_32x32x16_bf16 v[98:113], v[122:125], v[138:141], v[98:113]
	ds_read_b128 v[122:125], v218 offset:0x80
	v_mfma_f32_32x32x16_bf16 v[82:97], v[126:129], v[138:141], v[82:97]
	ds_read_b128 v[126:129], v218 offset:0x3080
	s_waitcnt lgkmcnt(2)
	v_mfma_f32_32x32x16_bf16 v[98:113], v[114:117], v[134:137], v[98:113]
	ds_read_b128 v[114:117], v221 offset:0x100
	v_mfma_f32_32x32x16_bf16 v[82:97], v[118:121], v[134:137], v[82:97]
	ds_read_b128 v[118:121], v221 offset:0x3100
	ds_read_b128 v[134:137], v199 offset:0
	s_waitcnt lgkmcnt(3)
	v_mfma_f32_32x32x16_bf16 v[98:113], v[122:125], v[130:133], v[98:113]
	ds_read_b128 v[122:125], v220 offset:0x100
	v_mfma_f32_32x32x16_bf16 v[82:97], v[126:129], v[130:133], v[82:97]
	ds_read_b128 v[126:129], v220 offset:0x3100
	ds_read_b128 v[130:133], v199 offset:0x400
	s_waitcnt lgkmcnt(3)
	v_mfma_f32_32x32x16_bf16 v[98:113], v[114:117], v[134:137], v[98:113]
	ds_read_b128 v[114:117], v219 offset:0x100
	v_mfma_f32_32x32x16_bf16 v[82:97], v[118:121], v[134:137], v[82:97]
	ds_read_b128 v[118:121], v219 offset:0x3100
	ds_read_b128 v[134:137], v199 offset:0x800
	s_waitcnt lgkmcnt(3)
	v_mfma_f32_32x32x16_bf16 v[98:113], v[122:125], v[130:133], v[98:113]
	ds_read_b128 v[122:125], v218 offset:0x100
	v_mfma_f32_32x32x16_bf16 v[82:97], v[126:129], v[130:133], v[82:97]
	ds_read_b128 v[126:129], v218 offset:0x3100
	ds_read_b128 v[130:133], v199 offset:0xc00
	s_waitcnt lgkmcnt(3)
	v_mfma_f32_32x32x16_bf16 v[98:113], v[114:117], v[134:137], v[98:113]
	s_waitcnt lgkmcnt(0)
; template <bool EXP1 = true>
; __device__ __forceinline__ void finishSM(f32x16& p0, f32x16& p1, float alpha, float& l_reg, bf16x8& pa0, bf16x8& pa1, bf16x8& pa2, bf16x8& pa3) {
;   if constexpr (EXP1) {
; #pragma unroll
;   for (int r = 0; r < 16; ++r) p1[r] = __builtin_amdgcn_exp2f(p1[r]);
;   }
;   float sm_[4] = {p0[0], p0[1], p0[2], p0[3]};
; #pragma unroll
;   for (int r = 4; r < 16; ++r) sm_[r & 3] += p0[r];
; #pragma unroll
;   for (int r = 0; r < 16; ++r) sm_[r & 3] += p1[r];
;   float ps = (sm_[0] + sm_[1]) + (sm_[2] + sm_[3]);
;   { auto rr = __builtin_amdgcn_permlane32_swap(__float_as_uint(ps), __float_as_uint(ps), false, false);
;     ps = __uint_as_float(rr[0]) + __uint_as_float(rr[1]); }
;   l_reg = l_reg * alpha + ps;
;     ...
;   PK4(p0, 0, pa0); PK4(p0, 8, pa1); PK4(p1, 0, pa2); PK4(p1, 8, pa3);
;     ...
; }
; __device__ __forceinline__ void pv_d0(f32x16* o, int vb, bf16x8 pa0, bf16x8 pa1, bf16x8 pa2, bf16x8 pa3) {
;     ...
;   const s16x4 l0 = tr_read<v_rd_off(0, 0, 0)>(vb), h0 = tr_read<v_rd_off(0, 0, 1)>(vb);
;   const s16x4 l1 = tr_read<v_rd_off(0, 1, 0)>(vb), h1 = tr_read<v_rd_off(0, 1, 1)>(vb);
;   const s16x4 l2 = tr_read<v_rd_off(0, 2, 0)>(vb), h2 = tr_read<v_rd_off(0, 2, 1)>(vb);
;   const s16x4 l3 = tr_read<v_rd_off(0, 3, 0)>(vb), h3 = tr_read<v_rd_off(0, 3, 1)>(vb);
;   const s16x4 l4 = tr_read<v_rd_off(1, 0, 0)>(vb), h4 = tr_read<v_rd_off(1, 0, 1)>(vb);
;   asm volatile("s_waitcnt lgkmcnt(8)" ::: "memory"); SBAR();
;   o[0] = __builtin_amdgcn_mfma_f32_32x32x16_bf16(pa0, PK(l0, h0), o[0], 0, 0, 0);
;   const s16x4 l5 = tr_read<v_rd_off(1, 1, 0)>(vb), h5 = tr_read<v_rd_off(1, 1, 1)>(vb);
;   asm volatile("s_waitcnt lgkmcnt(8)" ::: "memory"); SBAR();
;   o[0] = __builtin_amdgcn_mfma_f32_32x32x16_bf16(pa1, PK(l1, h1), o[0], 0, 0, 0);
;   const s16x4 l6 = tr_read<v_rd_off(1, 2, 0)>(vb), h6 = tr_read<v_rd_off(1, 2, 1)>(vb);
;   asm volatile("s_waitcnt lgkmcnt(8)" ::: "memory"); SBAR();
;   o[0] = __builtin_amdgcn_mfma_f32_32x32x16_bf16(pa2, PK(l2, h2), o[0], 0, 0, 0);
;   const s16x4 l7 = tr_read<v_rd_off(1, 3, 0)>(vb), h7 = tr_read<v_rd_off(1, 3, 1)>(vb);
;   asm volatile("s_waitcnt lgkmcnt(8)" ::: "memory"); SBAR();
;   o[0] = __builtin_amdgcn_mfma_f32_32x32x16_bf16(pa3, PK(l3, h3), o[0], 0, 0, 0);
;   const s16x4 l8 = tr_read<v_rd_off(2, 0, 0)>(vb), h8 = tr_read<v_rd_off(2, 0, 1)>(vb);
;   asm volatile("s_waitcnt lgkmcnt(8)" ::: "memory"); SBAR();
	v_mfma_f32_32x32x16_bf16 v[82:97], v[118:121], v[134:137], v[82:97]
	v_mfma_f32_32x32x16_bf16 v[98:113], v[122:125], v[130:133], v[98:113]
	v_mfma_f32_32x32x16_bf16 v[82:97], v[126:129], v[130:133], v[82:97]
	v_exp_f32_e32 v116, v66
	v_exp_f32_e32 v117, v67
	v_exp_f32_e32 v118, v68
	v_exp_f32_e32 v119, v69
	v_exp_f32_e32 v120, v70
	v_exp_f32_e32 v121, v71
	v_exp_f32_e32 v122, v72
	v_exp_f32_e32 v123, v73
	v_add_f32_e32 v66, v168, v176
	v_add_f32_e32 v67, v175, v178
	v_add_f32_e32 v68, v169, v167
	v_add_f32_e32 v69, v174, v177
	v_exp_f32_e32 v124, v74
	v_exp_f32_e32 v125, v75
	v_exp_f32_e32 v126, v76
	v_exp_f32_e32 v127, v77
	v_add_f32_e32 v66, v170, v66
	v_add_f32_e32 v67, v173, v67
	v_add_f32_e32 v68, v165, v68
	v_add_f32_e32 v69, v171, v69
	v_exp_f32_e32 v128, v78
	v_exp_f32_e32 v129, v79
	v_exp_f32_e32 v130, v80
	v_exp_f32_e32 v81, v81
	v_add_f32_e32 v66, v163, v66
	v_add_f32_e32 v67, v172, v67
	v_add_f32_e32 v68, v162, v68
	v_add_f32_e32 v69, v164, v69
	v_add_f32_e32 v66, v66, v116
	v_add_f32_e32 v67, v67, v117
	v_add_f32_e32 v68, v68, v118
	v_add_f32_e32 v69, v69, v119
	v_add_f32_e32 v66, v120, v66
	v_add_f32_e32 v67, v121, v67
	v_add_f32_e32 v68, v122, v68
	v_add_f32_e32 v69, v123, v69
	v_add_f32_e32 v66, v124, v66
	v_add_f32_e32 v67, v125, v67
	v_add_f32_e32 v68, v126, v68
	v_add_f32_e32 v69, v127, v69
	v_add_f32_e32 v66, v128, v66
	v_add_f32_e32 v67, v129, v67
	v_add_f32_e32 v68, v130, v68
	v_add_f32_e32 v69, v81, v69
	v_add_f32_e32 v66, v66, v67
	v_add_f32_e32 v67, v68, v69
	v_add_f32_e32 v114, v66, v67
	v_mov_b32_e32 v115, v114
	v_cvt_pk_bf16_f32 v66, v176, v178
	v_cvt_pk_bf16_f32 v67, v167, v177
	v_cvt_pk_bf16_f32 v68, v168, v175
	s_nop 1
	v_permlane32_swap_b32_e32 v114, v115
	v_cvt_pk_bf16_f32 v69, v169, v174
	v_cvt_pk_bf16_f32 v70, v170, v173
	v_cvt_pk_bf16_f32 v71, v165, v171
	v_cvt_pk_bf16_f32 v72, v163, v172
	v_cvt_pk_bf16_f32 v73, v162, v164
	v_cvt_pk_bf16_f32 v74, v116, v117
	v_cvt_pk_bf16_f32 v75, v118, v119
	v_cvt_pk_bf16_f32 v76, v120, v121
	v_cvt_pk_bf16_f32 v77, v122, v123
	v_cvt_pk_bf16_f32 v78, v124, v125
	v_cvt_pk_bf16_f32 v79, v126, v127
	v_cvt_pk_bf16_f32 v80, v128, v129
	v_cvt_pk_bf16_f32 v81, v130, v81
	ds_read_b64_tr_b16 v[116:117], v201 offset:0
	ds_read_b64_tr_b16 v[118:119], v201 offset:0x800
	ds_read_b64_tr_b16 v[120:121], v201 offset:0x1000
	ds_read_b64_tr_b16 v[122:123], v201 offset:0x1800
	ds_read_b64_tr_b16 v[124:125], v201 offset:0x2000
	ds_read_b64_tr_b16 v[126:127], v201 offset:0x2800
	ds_read_b64_tr_b16 v[128:129], v201 offset:0x3000
	ds_read_b64_tr_b16 v[130:131], v201 offset:0x3800
	ds_read_b64_tr_b16 v[132:133], v201 offset:0x200
	ds_read_b64_tr_b16 v[134:135], v201 offset:0xa00
	s_waitcnt lgkmcnt(8)
	s_nop 0
	v_mfma_f32_32x32x16_bf16 v[2:17], v[66:69], v[116:119], v[2:17]
	ds_read_b64_tr_b16 v[116:117], v201 offset:0x1200
	ds_read_b64_tr_b16 v[118:119], v201 offset:0x1a00
	s_waitcnt lgkmcnt(8)
	v_mfma_f32_32x32x16_bf16 v[2:17], v[70:73], v[120:123], v[2:17]
	ds_read_b64_tr_b16 v[120:121], v201 offset:0x2200
	ds_read_b64_tr_b16 v[122:123], v201 offset:0x2a00
	s_waitcnt lgkmcnt(8)
	v_mfma_f32_32x32x16_bf16 v[2:17], v[74:77], v[124:127], v[2:17]
	ds_read_b64_tr_b16 v[124:125], v201 offset:0x3200
	ds_read_b64_tr_b16 v[126:127], v201 offset:0x3a00
	s_waitcnt lgkmcnt(8)
	v_mfma_f32_32x32x16_bf16 v[2:17], v[78:81], v[128:131], v[2:17]
	ds_read_b64_tr_b16 v[128:129], v201 offset:0x400
	ds_read_b64_tr_b16 v[130:131], v201 offset:0xc00
	s_waitcnt lgkmcnt(8)
	v_mfma_f32_32x32x16_bf16 v[50:65], v[66:69], v[132:135], v[50:65]
	ds_read_b64_tr_b16 v[132:133], v201 offset:0x1400
	ds_read_b64_tr_b16 v[134:135], v201 offset:0x1c00
	s_waitcnt lgkmcnt(8)
	v_mfma_f32_32x32x16_bf16 v[50:65], v[70:73], v[116:119], v[50:65]
	ds_read_b64_tr_b16 v[116:117], v201 offset:0x2400
	ds_read_b64_tr_b16 v[118:119], v201 offset:0x2c00
	s_waitcnt lgkmcnt(8)
	v_mfma_f32_32x32x16_bf16 v[50:65], v[74:77], v[120:123], v[50:65]
	ds_read_b64_tr_b16 v[120:121], v201 offset:0x3400
	ds_read_b64_tr_b16 v[122:123], v201 offset:0x3c00
	s_waitcnt lgkmcnt(8)
	v_mfma_f32_32x32x16_bf16 v[50:65], v[78:81], v[124:127], v[50:65]
	ds_read_b64_tr_b16 v[124:125], v201 offset:0x600
	ds_read_b64_tr_b16 v[126:127], v201 offset:0xe00
	s_waitcnt lgkmcnt(8)
	v_mfma_f32_32x32x16_bf16 v[34:49], v[66:69], v[128:131], v[34:49]
	ds_read_b64_tr_b16 v[128:129], v201 offset:0x1600
	ds_read_b64_tr_b16 v[130:131], v201 offset:0x1e00
	s_waitcnt lgkmcnt(8)
	v_mfma_f32_32x32x16_bf16 v[34:49], v[70:73], v[132:135], v[34:49]
	ds_read_b64_tr_b16 v[132:133], v201 offset:0x2600
	ds_read_b64_tr_b16 v[134:135], v201 offset:0x2e00
	s_waitcnt lgkmcnt(8)
	v_mfma_f32_32x32x16_bf16 v[34:49], v[74:77], v[116:119], v[34:49]
	ds_read_b64_tr_b16 v[116:117], v201 offset:0x3600
	ds_read_b64_tr_b16 v[118:119], v201 offset:0x3e00
	s_waitcnt lgkmcnt(8)
	v_mfma_f32_32x32x16_bf16 v[34:49], v[78:81], v[120:123], v[34:49]
	s_waitcnt lgkmcnt(6)
	v_mfma_f32_32x32x16_bf16 v[18:33], v[66:69], v[124:127], v[18:33]
	s_waitcnt lgkmcnt(4)
	v_mfma_f32_32x32x16_bf16 v[18:33], v[70:73], v[128:131], v[18:33]
	s_waitcnt lgkmcnt(2)
	v_mfma_f32_32x32x16_bf16 v[18:33], v[74:77], v[132:135], v[18:33]
	s_waitcnt lgkmcnt(0)
	v_max_f32_e32 v66, v102, v102
	v_max_f32_e32 v67, v98, v98
	v_max_f32_e32 v66, v67, v66
	v_max_f32_e32 v67, v103, v103
	v_max_f32_e32 v68, v99, v99
	v_max_f32_e32 v67, v68, v67
	v_max_f32_e32 v68, v105, v105
	v_max_f32_e32 v69, v101, v101
	v_max_f32_e32 v68, v69, v68
	v_max3_f32 v69, v100, v104, v108
	v_max3_f32 v68, v68, v109, v113
	v_max3_f32 v66, v66, v106, v110
	v_max3_f32 v67, v67, v107, v111
	v_max3_f32 v69, v69, v112, v84
	v_max3_f32 v68, v68, v85, v89
	v_max3_f32 v66, v66, v82, v86
	v_max3_f32 v67, v67, v83, v87
	v_max3_f32 v69, v69, v88, v92
	v_max3_f32 v68, v68, v93, v97
	v_mfma_f32_32x32x16_bf16 v[18:33], v[78:81], v[116:119], v[18:33]
	v_max3_f32 v66, v66, v90, v94
	v_max3_f32 v67, v67, v91, v95
	v_max3_f32 v68, v69, v96, v68
	v_max3_f32 v66, v66, v67, v68
	v_mov_b32_e32 v67, v66
	s_nop 1
	v_permlane32_swap_b32_e32 v66, v67
	v_max_f32_e32 v67, v67, v67
	v_max_f32_e32 v66, v66, v66
	v_max_f32_e32 v66, v66, v67
	v_cmp_ge_f32_e32 vcc, s48, v66
	s_cmp_lg_u64 vcc, exec
	v_mov_b32_e32 v116, 1.0
	s_cbranch_scc1 .LBB0_410

; template <bool EXP1 = true>
; __device__ __forceinline__ void finishSM(f32x16& p0, f32x16& p1, float alpha, float& l_reg, bf16x8& pa0, bf16x8& pa1, bf16x8& pa2, bf16x8& pa3) {
;   if constexpr (EXP1) {
; #pragma unroll
;   for (int r = 0; r < 16; ++r) p1[r] = __builtin_amdgcn_exp2f(p1[r]);
;   }
;   float sm_[4] = {p0[0], p0[1], p0[2], p0[3]};
; #pragma unroll
;   for (int r = 4; r < 16; ++r) sm_[r & 3] += p0[r];
; #pragma unroll
;   for (int r = 0; r < 16; ++r) sm_[r & 3] += p1[r];
;   float ps = (sm_[0] + sm_[1]) + (sm_[2] + sm_[3]);
;   { auto rr = __builtin_amdgcn_permlane32_swap(__float_as_uint(ps), __float_as_uint(ps), false, false);
;     ps = __uint_as_float(rr[0]) + __uint_as_float(rr[1]); }
;   l_reg = l_reg * alpha + ps;
;     ...
;   PK4(p0, 0, pa0); PK4(p0, 8, pa1); PK4(p1, 0, pa2); PK4(p1, 8, pa3);
;     ...
; }
; __device__ __forceinline__ void pv_d0(f32x16* o, int vb, bf16x8 pa0, bf16x8 pa1, bf16x8 pa2, bf16x8 pa3) {
;     ...
;   const s16x4 l0 = tr_read<v_rd_off(0, 0, 0)>(vb), h0 = tr_read<v_rd_off(0, 0, 1)>(vb);
;   const s16x4 l1 = tr_read<v_rd_off(0, 1, 0)>(vb), h1 = tr_read<v_rd_off(0, 1, 1)>(vb);
;   const s16x4 l2 = tr_read<v_rd_off(0, 2, 0)>(vb), h2 = tr_read<v_rd_off(0, 2, 1)>(vb);
;   const s16x4 l3 = tr_read<v_rd_off(0, 3, 0)>(vb), h3 = tr_read<v_rd_off(0, 3, 1)>(vb);
;   const s16x4 l4 = tr_read<v_rd_off(1, 0, 0)>(vb), h4 = tr_read<v_rd_off(1, 0, 1)>(vb);
;   asm volatile("s_waitcnt lgkmcnt(8)" ::: "memory"); SBAR();
;   o[0] = __builtin_amdgcn_mfma_f32_32x32x16_bf16(pa0, PK(l0, h0), o[0], 0, 0, 0);
;   const s16x4 l5 = tr_read<v_rd_off(1, 1, 0)>(vb), h5 = tr_read<v_rd_off(1, 1, 1)>(vb);
;   asm volatile("s_waitcnt lgkmcnt(8)" ::: "memory"); SBAR();
;   o[0] = __builtin_amdgcn_mfma_f32_32x32x16_bf16(pa1, PK(l1, h1), o[0], 0, 0, 0);
;   const s16x4 l6 = tr_read<v_rd_off(1, 2, 0)>(vb), h6 = tr_read<v_rd_off(1, 2, 1)>(vb);
;   asm volatile("s_waitcnt lgkmcnt(8)" ::: "memory"); SBAR();
;   o[0] = __builtin_amdgcn_mfma_f32_32x32x16_bf16(pa2, PK(l2, h2), o[0], 0, 0, 0);
;   const s16x4 l7 = tr_read<v_rd_off(1, 3, 0)>(vb), h7 = tr_read<v_rd_off(1, 3, 1)>(vb);
;   asm volatile("s_waitcnt lgkmcnt(8)" ::: "memory"); SBAR();
;   o[0] = __builtin_amdgcn_mfma_f32_32x32x16_bf16(pa3, PK(l3, h3), o[0], 0, 0, 0);
;   const s16x4 l8 = tr_read<v_rd_off(2, 0, 0)>(vb), h8 = tr_read<v_rd_off(2, 0, 1)>(vb);
;   asm volatile("s_waitcnt lgkmcnt(8)" ::: "memory"); SBAR();
.LBB0_407:
	v_exp_f32_e32 v66, v98
	v_exp_f32_e32 v81, v99
	v_exp_f32_e32 v67, v100
	v_exp_f32_e32 v80, v101
	v_exp_f32_e32 v68, v102
	v_exp_f32_e32 v79, v103
	v_exp_f32_e32 v69, v104
	v_exp_f32_e32 v78, v105
	v_exp_f32_e32 v70, v106
	v_exp_f32_e32 v77, v107
	v_exp_f32_e32 v71, v108
	v_exp_f32_e32 v76, v109
	v_exp_f32_e32 v72, v110
	v_exp_f32_e32 v75, v111
	v_exp_f32_e32 v73, v112
	v_exp_f32_e32 v74, v113
	v_exp_f32_e32 v98, v82
	v_exp_f32_e32 v99, v83
	v_exp_f32_e32 v84, v84
	v_exp_f32_e32 v85, v85
	v_exp_f32_e32 v86, v86
	v_exp_f32_e32 v87, v87
	v_exp_f32_e32 v88, v88
	v_exp_f32_e32 v89, v89
	v_add_f32_e32 v82, v68, v66
	v_add_f32_e32 v83, v79, v81
	v_add_f32_e32 v100, v69, v67
	v_add_f32_e32 v101, v78, v80
	v_exp_f32_e32 v90, v90
	v_exp_f32_e32 v91, v91
	v_exp_f32_e32 v92, v92
	v_exp_f32_e32 v93, v93
	v_add_f32_e32 v82, v70, v82
	v_add_f32_e32 v83, v77, v83
	v_add_f32_e32 v100, v71, v100
	v_add_f32_e32 v101, v76, v101
	v_exp_f32_e32 v94, v94
	v_exp_f32_e32 v95, v95
	v_exp_f32_e32 v96, v96
	v_exp_f32_e32 v97, v97
	v_add_f32_e32 v82, v72, v82
	v_add_f32_e32 v83, v75, v83
	v_add_f32_e32 v100, v73, v100
	v_add_f32_e32 v101, v74, v101
	v_add_f32_e32 v82, v98, v82
	v_add_f32_e32 v83, v99, v83
	v_add_f32_e32 v100, v100, v84
	v_add_f32_e32 v101, v101, v85
	v_add_f32_e32 v82, v86, v82
	v_add_f32_e32 v83, v87, v83
	v_add_f32_e32 v100, v88, v100
	v_add_f32_e32 v101, v89, v101
	v_add_f32_e32 v82, v90, v82
	v_add_f32_e32 v83, v91, v83
	v_add_f32_e32 v100, v92, v100
	v_add_f32_e32 v101, v93, v101
	v_add_f32_e32 v82, v94, v82
	v_add_f32_e32 v83, v95, v83
	v_add_f32_e32 v100, v96, v100
	v_add_f32_e32 v101, v97, v101
	v_add_f32_e32 v82, v83, v82
	v_add_f32_e32 v83, v100, v101
	v_add_f32_e32 v82, v83, v82
	v_mov_b32_e32 v83, v82
	s_nop 1
	v_permlane32_swap_b32_e32 v82, v83
	v_cvt_pk_bf16_f32 v66, v66, v81
	v_cvt_pk_bf16_f32 v67, v67, v80
	v_cvt_pk_bf16_f32 v68, v68, v79
	v_cvt_pk_bf16_f32 v69, v69, v78
	v_cvt_pk_bf16_f32 v70, v70, v77
	v_cvt_pk_bf16_f32 v71, v71, v76
	v_cvt_pk_bf16_f32 v72, v72, v75
	v_cvt_pk_bf16_f32 v73, v73, v74
	v_cvt_pk_bf16_f32 v74, v98, v99
	v_cvt_pk_bf16_f32 v75, v84, v85
	v_cvt_pk_bf16_f32 v76, v86, v87
	v_cvt_pk_bf16_f32 v77, v88, v89
	v_cvt_pk_bf16_f32 v78, v90, v91
	v_cvt_pk_bf16_f32 v79, v92, v93
	v_cvt_pk_bf16_f32 v80, v94, v95
	v_cvt_pk_bf16_f32 v81, v96, v97
	s_nop 0
	ds_read_b64_tr_b16 v[84:85], v208 offset:0
	ds_read_b64_tr_b16 v[86:87], v208 offset:0x800
	ds_read_b64_tr_b16 v[88:89], v208 offset:0x1000
	ds_read_b64_tr_b16 v[90:91], v208 offset:0x1800
	ds_read_b64_tr_b16 v[92:93], v208 offset:0x2000
	ds_read_b64_tr_b16 v[94:95], v208 offset:0x2800
	ds_read_b64_tr_b16 v[96:97], v208 offset:0x3000
	ds_read_b64_tr_b16 v[98:99], v208 offset:0x3800
	ds_read_b64_tr_b16 v[100:101], v208 offset:0x200
	ds_read_b64_tr_b16 v[102:103], v208 offset:0xa00
	s_waitcnt lgkmcnt(8)
	s_nop 0
	v_mfma_f32_32x32x16_bf16 v[2:17], v[66:69], v[84:87], v[2:17]
	ds_read_b64_tr_b16 v[84:85], v208 offset:0x1200
	ds_read_b64_tr_b16 v[86:87], v208 offset:0x1a00
	s_waitcnt lgkmcnt(8)
	v_mfma_f32_32x32x16_bf16 v[2:17], v[70:73], v[88:91], v[2:17]
	ds_read_b64_tr_b16 v[88:89], v208 offset:0x2200
	ds_read_b64_tr_b16 v[90:91], v208 offset:0x2a00
	s_waitcnt lgkmcnt(8)
	v_mfma_f32_32x32x16_bf16 v[2:17], v[74:77], v[92:95], v[2:17]
	ds_read_b64_tr_b16 v[92:93], v208 offset:0x3200
	ds_read_b64_tr_b16 v[94:95], v208 offset:0x3a00
	s_waitcnt lgkmcnt(8)
	v_mfma_f32_32x32x16_bf16 v[2:17], v[78:81], v[96:99], v[2:17]
	ds_read_b64_tr_b16 v[96:97], v208 offset:0x400
	ds_read_b64_tr_b16 v[98:99], v208 offset:0xc00
	s_waitcnt lgkmcnt(8)
	v_mfma_f32_32x32x16_bf16 v[50:65], v[66:69], v[100:103], v[50:65]
	ds_read_b64_tr_b16 v[100:101], v208 offset:0x1400
	ds_read_b64_tr_b16 v[102:103], v208 offset:0x1c00
	s_waitcnt lgkmcnt(8)
	v_mfma_f32_32x32x16_bf16 v[50:65], v[70:73], v[84:87], v[50:65]
	ds_read_b64_tr_b16 v[84:85], v208 offset:0x2400
	ds_read_b64_tr_b16 v[86:87], v208 offset:0x2c00
	s_waitcnt lgkmcnt(8)
	v_mfma_f32_32x32x16_bf16 v[50:65], v[74:77], v[88:91], v[50:65]
	ds_read_b64_tr_b16 v[88:89], v208 offset:0x3400
	ds_read_b64_tr_b16 v[90:91], v208 offset:0x3c00
	s_waitcnt lgkmcnt(8)
	v_mfma_f32_32x32x16_bf16 v[50:65], v[78:81], v[92:95], v[50:65]
	ds_read_b64_tr_b16 v[92:93], v208 offset:0x600
	ds_read_b64_tr_b16 v[94:95], v208 offset:0xe00
	s_waitcnt lgkmcnt(8)
	v_mfma_f32_32x32x16_bf16 v[34:49], v[66:69], v[96:99], v[34:49]
	ds_read_b64_tr_b16 v[96:97], v208 offset:0x1600
	ds_read_b64_tr_b16 v[98:99], v208 offset:0x1e00
	s_waitcnt lgkmcnt(8)
	v_mfma_f32_32x32x16_bf16 v[34:49], v[70:73], v[100:103], v[34:49]
	ds_read_b64_tr_b16 v[100:101], v208 offset:0x2600
	ds_read_b64_tr_b16 v[102:103], v208 offset:0x2e00
	s_waitcnt lgkmcnt(8)
	v_mfma_f32_32x32x16_bf16 v[34:49], v[74:77], v[84:87], v[34:49]
	ds_read_b64_tr_b16 v[84:85], v208 offset:0x3600
	ds_read_b64_tr_b16 v[86:87], v208 offset:0x3e00
	s_waitcnt lgkmcnt(8)
	v_mfma_f32_32x32x16_bf16 v[34:49], v[78:81], v[88:91], v[34:49]
	s_waitcnt lgkmcnt(6)
	v_mfma_f32_32x32x16_bf16 v[18:33], v[66:69], v[92:95], v[18:33]
	s_waitcnt lgkmcnt(4)
	v_mfma_f32_32x32x16_bf16 v[18:33], v[70:73], v[96:99], v[18:33]
	s_waitcnt lgkmcnt(2)
	v_mfma_f32_32x32x16_bf16 v[18:33], v[74:77], v[100:103], v[18:33]
	s_waitcnt lgkmcnt(0)
	v_mfma_f32_32x32x16_bf16 v[18:33], v[78:81], v[84:87], v[18:33]
	s_and_saveexec_b64 s[6:7], s[4:5]
	s_cbranch_execz .LBB0_356
	v_add_f32_e32 v66, v114, v115
	v_fmac_f32_e32 v66, v207, v166
	v_add_f32_e32 v67, v82, v83
	v_fmac_f32_e32 v67, v66, v116
	ds_write_b32 v200, v67
	s_branch .LBB0_356

; __device__ __forceinline__ int lane_id_v() { int l; asm volatile("v_mbcnt_lo_u32_b32 %0, -1, 0\n\tv_mbcnt_hi_u32_b32 %0, -1, %0" : "=v"(l)); return l; }
; __device__ __forceinline__ int v_st(int k, int c) { const int kk = (k & ~0xC) | ((k & 4) << 1) | ((k & 8) >> 1); return ((kk >> 3) * 4 + (c >> 5)) * 512 + ((kk & 7) * 32 + (c & 31)) * 2; }
; __device__ __forceinline__ int v_rd_base(int lane) { return ((lane & 3) << 3) | (((lane >> 2) & 3) << 6) | (((lane >> 4) & 1) << 5) | (((lane >> 5) & 1) << 8); }
;     ...
;   int tid_ = wave0 * 64 + lane_id_v();
;   const int tid = tid_, wid = tid >> 6, lane = tid & 63, r32 = lane & 31, hi = lane >> 5;
;   char* V_lds = lds; char* K_lds = lds + LDS_K_OFF;
;   float* ws = (float*)(lds + LDS_WS_OFF) + wid * 64; float* li_l = ws; float* al_l = ws + 32;
;   float* tbl_l = (float*)(lds + LDS_TBL_OFF);
;   __syncthreads();
;   if constexpr (BIAS) { for (int i = tid; i < TBLN; i += 512) tbl_l[i] = tblg[i]; }
;   float mC = 0.f, l_reg = 0, nm_cur = 0.f; f32x16 o[4] = {}; f32x16 negm = {}; bf16x8 qr[NDQ - NQL];
;   const bf16_t* Qw = Qb + (long)(wid * QBLK + r32) * ldq + hi * 8;
;   char* qls = lds + LDS_Q_OFF + wid * 8192 + lane * 16;
; #pragma unroll
;   for (int d0 = 0; d0 < NDQ - NQL; ++d0) qr[d0] = *reinterpret_cast<const bf16x8*>(Qw + d0 * 16);
;     ...
;   const int sr = tid >> 4, sc = (tid & 15) * 8, vst0 = v_st(sr, sc), vst1 = v_st(32 + sr, sc);
;   const int sr8 = tid >> 3, sc8 = (tid & 7) * 8;
;   const int vb0 = (int)(uintptr_t)V_lds + v_rd_base(lane);
;   const int qlane = q0 + wid * QBLK + r32;
;   struct { bf16x8 vs0, vs1, ks0, ks1, ks2; } sr_[SDEPTH];
;   constexpr int SWM = (NDQ == 8) ? 15 : 7;
;     ...
;   f32x16 pA0, pA1, pB0, pB1; float alA, alB; bf16x8 pa0, pa1, pa2, pa3; const int NT = nkeys / KVBLK;
;   const int kb0 = (int)(uintptr_t)K_lds + r32 * ROWB + (((r32 & SWM) << 4) ^ (hi << 4));
;   const int qa0 = (int)(uintptr_t)qls;
;     ...
;   constexpr int SE = 0, SO = SDEPTH - 1;
;   SLOAD(SE, kbeg); asm volatile("s_waitcnt vmcnt(0)" ::: "memory"); SWRITE(0, SE); __syncthreads();
.LBB0_419:
	s_lshl_b32 s4, s61, 7
	s_lshl_b32 s5, s62, 3
	s_and_b32 s64, s4, 0x100
	s_lshr_b32 s4, s62, 3
	s_and_b32 s5, s5, 32
	s_add_i32 s5, s5, s4
	s_lshl_b32 s8, s5, 8
	s_ashr_i32 s9, s8, 31
	s_and_b32 s63, s62, 3
	s_lshl_b64 s[4:5], s[8:9], 10
	s_add_u32 s4, s37, s4
	s_addc_u32 s5, s44, s5
	s_lshl_b32 s6, s63, 8
	s_add_u32 s56, s4, s6
	s_addc_u32 s57, s5, 0
	s_lshl_b32 s4, s62, 7
	s_and_b32 s4, s4, 0x100
	s_add_u32 s50, s45, s4
	s_addc_u32 s51, s46, 0
	v_readlane_b32 s6, v254, 19
	s_add_u32 s58, s47, s4
	v_readlane_b32 s7, v254, 20
	s_addc_u32 s59, s60, 0
	s_mov_b64 s[4:5], -1
	s_and_b64 vcc, exec, s[6:7]
	s_cbranch_vccz .LBB0_445
	v_readlane_b32 s4, v254, 8
	v_mbcnt_lo_u32_b32 v22, -1, 0
	v_mbcnt_hi_u32_b32 v22, -1, v22
	v_mov_b64_e32 v[54:55], s[58:59]
	v_lshlrev_b32_e32 v24, 3, v22
	v_add_u32_e32 v23, s4, v22
	v_ashrrev_i32_e32 v50, 4, v23
	v_and_b32_e32 v0, 0x78, v24
	v_lshlrev_b32_e32 v0, 1, v0
	v_mad_i64_i32 v[2:3], s[4:5], v50, s55, v[54:55]
	v_lshl_add_u64 v[2:3], v[2:3], 0, v[0:1]
	s_waitcnt vmcnt(63) expcnt(7) lgkmcnt(15)
	s_barrier
	v_add_u32_e32 v18, 32, v50
	global_load_dwordx4 v[2:5], v[2:3], off
	v_ashrrev_i32_e32 v51, 31, v50
	v_mad_i64_i32 v[6:7], s[4:5], v18, s55, v[54:55]
	v_ashrrev_i32_e32 v19, 31, v18
	v_lshlrev_b64 v[52:53], 9, v[50:51]
	v_lshlrev_b64 v[14:15], 9, v[18:19]
	v_ashrrev_i32_e32 v19, 1, v23
	s_movk_i32 s4, 0xffe0
	v_lshl_add_u64 v[10:11], s[50:51], 0, v[52:53]
	v_lshl_add_u64 v[14:15], s[50:51], 0, v[14:15]
	v_bfi_b32 v20, s4, v19, v22
	v_lshl_add_u64 v[6:7], v[6:7], 0, v[0:1]
	v_lshl_add_u64 v[10:11], v[10:11], 0, v[0:1]
	v_lshl_add_u64 v[14:15], v[14:15], 0, v[0:1]
	v_ashrrev_i32_e32 v21, 31, v20
	v_bfe_u32 v196, v22, 5, 1
	global_load_dwordx4 v[6:9], v[6:7], off
	v_lshlrev_b64 v[20:21], 10, v[20:21]
	global_load_dwordx4 v[10:13], v[10:11], off
	v_lshl_add_u64 v[20:21], s[56:57], 0, v[20:21]
	global_load_dwordx4 v[14:17], v[14:15], off
	v_lshlrev_b32_e32 v182, 4, v196
	v_mov_b32_e32 v183, v1
	v_lshl_add_u64 v[20:21], v[20:21], 0, v[182:183]
	global_load_dwordx4 v[142:145], v[20:21], off
	global_load_dwordx4 v[138:141], v[20:21], off offset:32
	global_load_dwordx4 v[134:137], v[20:21], off offset:64
	global_load_dwordx4 v[130:133], v[20:21], off offset:96
	global_load_dwordx4 v[126:129], v[20:21], off offset:128
	global_load_dwordx4 v[122:125], v[20:21], off offset:160
	global_load_dwordx4 v[118:121], v[20:21], off offset:192
	global_load_dwordx4 v[114:117], v[20:21], off offset:224
	v_and_b32_e32 v20, 0x3fffffc0, v23
	s_add_i32 s4, 0, 0x14000
	v_lshl_add_u32 v179, v20, 2, s4
	v_and_b32_e32 v180, 0xffffffe0, v19
	v_and_b32_e32 v19, 0xfffff0, v50
	v_lshlrev_b32_e32 v20, 1, v50
	v_and_or_b32 v19, v50, 8, v19
	v_lshrrev_b32_e32 v20, 1, v50
	v_lshrrev_b32_e32 v19, 1, v19
	v_bfe_u32 v21, v24, 5, 2
	v_and_b32_e32 v24, 3, v50
	v_or_b32_e32 v19, v19, v21
	v_and_or_b32 v20, v50, 4, v24
	v_and_b32_e32 v25, 0xfffff0, v18
	v_lshlrev_b32_e32 v26, 1, v18
	v_lshlrev_b32_e32 v19, 9, v19
	v_lshlrev_b32_e32 v20, 6, v20
	v_and_b32_e32 v24, 48, v0
	v_and_or_b32 v25, v18, 8, v25
	v_or3_b32 v19, v19, v20, v24
	v_lshrrev_b32_e32 v25, 1, v25
	v_or_b32_e32 v21, v25, v21
	v_add_u32_e32 v201, 0, v19
	v_lshlrev_b32_e32 v21, 9, v21
	s_waitcnt vmcnt(0)
	v_and_b32_e32 v51, 63, v22
	v_or3_b32 v20, v21, v20, v24
	v_lshlrev_b32_e32 v24, 4, v22
	s_cmp_lg_u32 0, -1
	v_lshlrev_b32_e32 v21, 3, v51
	v_and_b32_e32 v24, 0xc0, v24
	v_lshlrev_b32_e32 v25, 1, v22
	s_cselect_b32 s6, 0, 0
	s_add_i32 s4, 0, 0x8000
	v_and_b32_e32 v178, 31, v22
	v_and_or_b32 v24, v21, 24, v24
	v_and_b32_e32 v25, 32, v25
	v_and_b32_e32 v21, 0x100, v21
	s_cmp_lg_u32 s4, -1
	v_and_b32_e32 v87, 15, v22
	v_bitop3_b32 v22, v196, v22, 15 bitop3:0x78
	v_or3_b32 v86, v24, v25, v21
	v_lshlrev_b32_e32 v21, 8, v178
	s_cselect_b32 s4, s4, 0
	v_lshlrev_b32_e32 v22, 4, v22
	v_add_u32_e32 v207, 0, v20
	v_add3_u32 v200, v21, s4, v22
	v_xor_b32_e32 v210, 32, v200
	v_xor_b32_e32 v211, 64, v200
	s_mov_b32 s65, -1
	v_add_u32_e32 v199, s6, v86
	s_waitcnt vmcnt(11)
	ds_write_b128 v201, v[2:5]
	v_lshlrev_b32_e32 v2, 8, v50
	v_and_b32_e32 v3, 0xf0, v23
	v_bitop3_b32 v2, v0, v2, v3 bitop3:0xde
	v_add_u32_e32 v208, 0, v2
	v_lshlrev_b32_e32 v2, 8, v18
	v_bitop3_b32 v2, v2, v0, v3 bitop3:0xf6
	v_add_u32_e32 v209, 0, v2
	s_waitcnt vmcnt(10)
	ds_write_b128 v207, v[6:9]
	s_waitcnt vmcnt(9)
	ds_write_b128 v208, v[10:13] offset:32768
	s_waitcnt vmcnt(8)
	ds_write_b128 v209, v[14:17] offset:32768
	s_waitcnt lgkmcnt(0)
	s_barrier
; template <bool FIRST>
; __device__ __forceinline__ void partialSM(f32x16& p0, f32x16& p1, float& mC, float& alpha) {
;   float mx_[4] = {p0[0], p0[1], p0[2], p0[3]};
; #pragma unroll
;   for (int r = 4; r < 16; ++r) mx_[r & 3] = fmaxf(mx_[r & 3], p0[r]);
; #pragma unroll
;   for (int r = 0; r < 16; ++r) mx_[r & 3] = fmaxf(mx_[r & 3], p1[r]);
;   float pmax = fmaxf(fmaxf(mx_[0], mx_[1]), fmaxf(mx_[2], mx_[3]));
;   { auto rr = __builtin_amdgcn_permlane32_swap(__float_as_uint(pmax), __float_as_uint(pmax), false, false);
;     pmax = fmaxf(__uint_as_float(rr[0]), __uint_as_float(rr[1])); }
;   if (!FIRST && __builtin_expect(__all(pmax <= THR2), 1)) { alpha = 1.f; }
;   else { const float delta = FIRST ? fmaxf(pmax, -200.f) : fmaxf(pmax, 0.f); alpha = FIRST ? 1.f : __builtin_amdgcn_exp2f(-delta); mC += delta;
; #pragma unroll
;     for (int r = 0; r < 16; ++r) p0[r] -= delta;
; #pragma unroll
;     for (int r = 0; r < 16; ++r) p1[r] -= delta; }
; #pragma unroll
;   for (int r = 0; r < 16; ++r) p0[r] = __builtin_amdgcn_exp2f(p0[r]);
; }
; __device__ __forceinline__ void qkt8_roll(f32x16& p0, f32x16& p1, const f32x16& negm, int kb, const bf16x8* qr) {
;   const int a0 = kb ^ (0 << 5); const bf16x8 x0 = lds_rd128<0>(a0), y0 = lds_rd128<8192>(a0);
;   const int a1 = kb ^ (1 << 5); const bf16x8 x1 = lds_rd128<0>(a1), y1 = lds_rd128<8192>(a1);
;   const int a2 = kb ^ (2 << 5); const bf16x8 x2 = lds_rd128<0>(a2), y2 = lds_rd128<8192>(a2);
;   asm volatile("s_waitcnt lgkmcnt(4)" ::: "memory"); SBAR_M();
;   p0 = __builtin_amdgcn_mfma_f32_32x32x16_bf16(x0, qr[0], negm, 0, 0, 0); p1 = __builtin_amdgcn_mfma_f32_32x32x16_bf16(y0, qr[0], negm, 0, 0, 0);
;   const int a3 = kb ^ (3 << 5); const bf16x8 x3 = lds_rd128<0>(a3), y3 = lds_rd128<8192>(a3);
;   asm volatile("s_waitcnt lgkmcnt(4)" ::: "memory"); SBAR_M();
;   p0 = __builtin_amdgcn_mfma_f32_32x32x16_bf16(x1, qr[1], p0, 0, 0, 0); p1 = __builtin_amdgcn_mfma_f32_32x32x16_bf16(y1, qr[1], p1, 0, 0, 0);
;   const int a4 = kb ^ (4 << 5); const bf16x8 x4 = lds_rd128<0>(a4), y4 = lds_rd128<8192>(a4);
;   asm volatile("s_waitcnt lgkmcnt(4)" ::: "memory"); SBAR_M();
;   p0 = __builtin_amdgcn_mfma_f32_32x32x16_bf16(x2, qr[2], p0, 0, 0, 0); p1 = __builtin_amdgcn_mfma_f32_32x32x16_bf16(y2, qr[2], p1, 0, 0, 0);
;   const int a5 = kb ^ (5 << 5); const bf16x8 x5 = lds_rd128<0>(a5), y5 = lds_rd128<8192>(a5);
	ds_read_b128 v[2:5], v200 offset:0
	ds_read_b128 v[18:21], v200 offset:0x2000
	ds_read_b128 v[56:59], v210 offset:0
	ds_read_b128 v[60:63], v210 offset:0x2000
	ds_read_b128 v[64:67], v211 offset:0
	ds_read_b128 v[68:71], v211 offset:0x2000
	s_waitcnt lgkmcnt(4)
	s_waitcnt vmcnt(7)
	v_mfma_f32_32x32x16_bf16 v[34:49], v[2:5], v[142:145], 0
	v_xor_b32_e32 v212, 0x60, v200
	ds_read_b128 v[72:75], v212 offset:0
	ds_read_b128 v[76:79], v212 offset:0x2000
	s_mov_b32 s13, s12
	s_waitcnt lgkmcnt(4)
	s_mov_b32 s14, s12
	s_mov_b32 s15, s12
	v_mfma_f32_32x32x16_bf16 v[18:33], v[18:21], v[142:145], 0
	s_mov_b32 s16, s12
	s_mov_b32 s17, s12
	s_mov_b32 s18, s12
	s_mov_b32 s19, s12
	s_mov_b32 s20, s12
	s_mov_b32 s21, s12
	s_mov_b32 s22, s12
	s_mov_b32 s23, s12
	s_mov_b32 s24, s12
	s_mov_b32 s25, s12
	s_mov_b32 s26, s12
	s_mov_b32 s27, s12
	v_mov_b64_e32 v[2:3], s[12:13]
	v_mov_b64_e32 v[4:5], s[14:15]
	v_mov_b64_e32 v[6:7], s[16:17]
	v_mov_b64_e32 v[8:9], s[18:19]
	v_mov_b64_e32 v[10:11], s[20:21]
	v_mov_b64_e32 v[12:13], s[22:23]
	v_mov_b64_e32 v[14:15], s[24:25]
	v_mov_b64_e32 v[16:17], s[26:27]
	s_waitcnt vmcnt(6)
	v_mfma_f32_32x32x16_bf16 v[34:49], v[56:59], v[138:141], v[34:49]
	v_xor_b32_e32 v213, 0x80, v200
	ds_read_b128 v[56:59], v213 offset:0
	v_mfma_f32_32x32x16_bf16 v[18:33], v[60:63], v[138:141], v[18:33]
	ds_read_b128 v[60:63], v213 offset:0x2000
	s_waitcnt lgkmcnt(4)
	s_waitcnt vmcnt(5)
	v_mfma_f32_32x32x16_bf16 v[34:49], v[64:67], v[134:137], v[34:49]
	v_xor_b32_e32 v214, 0xa0, v200
	ds_read_b128 v[64:67], v214 offset:0
	v_mfma_f32_32x32x16_bf16 v[18:33], v[68:71], v[134:137], v[18:33]
	ds_read_b128 v[68:71], v214 offset:0x2000
	s_waitcnt lgkmcnt(4)
	s_waitcnt vmcnt(4)
	v_mfma_f32_32x32x16_bf16 v[34:49], v[72:75], v[130:133], v[34:49]
	v_xor_b32_e32 v215, 0xc0, v200
	ds_read_b128 v[72:75], v215 offset:0
	v_mfma_f32_32x32x16_bf16 v[18:33], v[76:79], v[130:133], v[18:33]
	ds_read_b128 v[76:79], v215 offset:0x2000
	s_waitcnt lgkmcnt(4)
	s_waitcnt vmcnt(3)
	v_mfma_f32_32x32x16_bf16 v[34:49], v[56:59], v[126:129], v[34:49]
	v_xor_b32_e32 v216, 0xe0, v200
	ds_read_b128 v[56:59], v216 offset:0
	v_mfma_f32_32x32x16_bf16 v[18:33], v[60:63], v[126:129], v[18:33]
	ds_read_b128 v[60:63], v216 offset:0x2000
	s_waitcnt lgkmcnt(4)
	s_waitcnt vmcnt(2)
	v_mfma_f32_32x32x16_bf16 v[34:49], v[64:67], v[122:125], v[34:49]
	s_waitcnt lgkmcnt(2)
	v_mfma_f32_32x32x16_bf16 v[18:33], v[68:71], v[122:125], v[18:33]
	s_waitcnt vmcnt(1)
	v_mfma_f32_32x32x16_bf16 v[34:49], v[72:75], v[118:121], v[34:49]
	s_waitcnt lgkmcnt(0)
	v_mfma_f32_32x32x16_bf16 v[18:33], v[76:79], v[118:121], v[18:33]
	v_add_u32_e32 v64, 64, v50
	v_add_u32_e32 v68, 0x60, v50
	v_mad_i64_i32 v[66:67], s[4:5], v64, s55, v[54:55]
	v_mad_i64_i32 v[54:55], s[4:5], v68, s55, v[54:55]
	v_ashrrev_i32_e32 v65, 31, v64
	v_ashrrev_i32_e32 v69, 31, v68
	s_waitcnt vmcnt(0)
	v_mfma_f32_32x32x16_bf16 v[34:49], v[56:59], v[114:117], v[34:49]
	v_lshl_add_u64 v[56:57], v[66:67], 0, v[0:1]
	v_lshl_add_u64 v[58:59], v[54:55], 0, v[0:1]
	global_load_dwordx4 v[54:57], v[56:57], off
	s_nop 0
	global_load_dwordx4 v[82:85], v[58:59], off
	v_lshlrev_b64 v[58:59], 9, v[64:65]
	v_lshl_add_u64 v[58:59], s[50:51], 0, v[58:59]
	v_lshl_add_u64 v[58:59], v[58:59], 0, v[0:1]
	s_mov_b32 s4, 0xc3480000
	v_mfma_f32_32x32x16_bf16 v[18:33], v[60:63], v[114:117], v[18:33]
	v_lshlrev_b64 v[60:61], 9, v[68:69]
	v_lshl_add_u64 v[60:61], s[50:51], 0, v[60:61]
	v_lshl_add_u64 v[62:63], v[60:61], 0, v[0:1]
	global_load_dwordx4 v[58:61], v[58:59], off
	s_nop 0
	global_load_dwordx4 v[62:65], v[62:63], off
	v_max_f32_e32 v66, v38, v38
	v_max_f32_e32 v0, v34, v34
	v_max_f32_e32 v0, v0, v66
	v_max_f32_e32 v66, v39, v39
	v_max_f32_e32 v67, v35, v35
	v_max_f32_e32 v66, v67, v66
	v_max_f32_e32 v67, v41, v41
	v_max_f32_e32 v68, v37, v37
	v_max_f32_e32 v67, v68, v67
	v_max3_f32 v68, v36, v40, v44
	v_max3_f32 v67, v67, v45, v49
	v_max3_f32 v0, v0, v42, v46
	v_max3_f32 v66, v66, v43, v47
	v_max3_f32 v68, v68, v48, v20
	v_max3_f32 v67, v67, v21, v25
	v_max3_f32 v0, v0, v18, v22
	v_max3_f32 v66, v66, v19, v23
	v_max3_f32 v68, v68, v24, v28
	v_max3_f32 v67, v67, v29, v33
	v_max3_f32 v0, v0, v26, v30
	v_max3_f32 v66, v66, v27, v31
	v_max3_f32 v67, v68, v32, v67
	v_max3_f32 v0, v0, v66, v67
	v_mov_b32_e32 v66, v0
	s_nop 1
	v_permlane32_swap_b32_e32 v0, v66
	v_max3_f32 v0, v0, v66, s4
	s_addk_i32 s6, 0x4000
	v_sub_f32_e32 v34, v34, v0
	v_sub_f32_e32 v35, v35, v0
	v_sub_f32_e32 v36, v36, v0
	v_sub_f32_e32 v37, v37, v0
	v_sub_f32_e32 v38, v38, v0
	v_sub_f32_e32 v39, v39, v0
	v_sub_f32_e32 v40, v40, v0
	v_sub_f32_e32 v41, v41, v0
	v_sub_f32_e32 v42, v42, v0
	v_sub_f32_e32 v43, v43, v0
	v_sub_f32_e32 v44, v44, v0
	v_sub_f32_e32 v45, v45, v0
	v_sub_f32_e32 v46, v46, v0
	v_sub_f32_e32 v47, v47, v0
	v_sub_f32_e32 v48, v48, v0
	v_sub_f32_e32 v49, v49, v0
	v_add_u32_e32 v198, s6, v86
	s_add_u32 s6, s42, s64
	v_exp_f32_e32 v146, v34
	v_exp_f32_e32 v161, v35
	v_exp_f32_e32 v147, v36
	v_exp_f32_e32 v160, v37
	v_exp_f32_e32 v148, v38
	v_exp_f32_e32 v159, v39
	v_exp_f32_e32 v149, v40
	v_exp_f32_e32 v158, v41
	v_exp_f32_e32 v150, v42
	v_exp_f32_e32 v157, v43
	v_exp_f32_e32 v151, v44
	v_exp_f32_e32 v156, v45
	v_exp_f32_e32 v152, v46
	v_exp_f32_e32 v155, v47
	v_exp_f32_e32 v153, v48
	v_exp_f32_e32 v154, v49
	s_addc_u32 s7, s43, 0
	v_sub_f32_e32 v67, v19, v0
	v_sub_f32_e32 v66, v18, v0
	s_waitcnt vmcnt(0)
	v_mov_b64_e32 v[18:19], s[6:7]
	v_sub_f32_e32 v81, v33, v0
	v_sub_f32_e32 v80, v32, v0
	v_sub_f32_e32 v79, v31, v0
	v_sub_f32_e32 v78, v30, v0
	v_sub_f32_e32 v77, v29, v0
	v_sub_f32_e32 v76, v28, v0
	v_sub_f32_e32 v75, v27, v0
	v_sub_f32_e32 v74, v26, v0
	v_sub_f32_e32 v73, v25, v0
	v_sub_f32_e32 v72, v24, v0
	v_sub_f32_e32 v71, v23, v0
	v_sub_f32_e32 v70, v22, v0
	v_sub_f32_e32 v69, v21, v0
	v_sub_f32_e32 v68, v20, v0
	s_waitcnt vmcnt(3)
; #define SWAIT() do { if constexpr (SDEPTH == 2) { if constexpr (NDQ == 4) asm volatile("s_waitcnt vmcnt(3)" ::: "memory"); else if constexpr (NDQ == 8) asm volatile("s_waitcnt vmcnt(4)" ::: "memory"); else asm volatile("s_waitcnt vmcnt(5)" ::: "memory"); } \
;     else asm volatile("s_waitcnt vmcnt(0)" ::: "memory"); } while (0)
; #define BIASADD(P0, P1, kt0) do { if constexpr (BIAS) { const int dlo_ = (kt0) - q0 - 255, dhi_ = (kt0) + 63 - q0; \
;     if (!(dlo_ >= 1024) && !(dhi_ <= -1024)) { const float* tb_ = tbl_l + ((kt0) - qlane + TOFF + 4 * hi); \
;       _Pragma("unroll") for (int r = 0; r < 16; ++r) { P0[r] += tb_[(r & 3) + 8 * (r >> 2)]; P1[r] += tb_[32 + (r & 3) + 8 * (r >> 2)]; } } } } while (0)
; #define NEGM_UPD(kt0) do { float nmj_ = -mC; if constexpr (BIAS) { const int dlo_ = (kt0) - q0 - 255, dhi_ = (kt0) + 63 - q0; if (dlo_ >= 1024) nmj_ += cb_hi; else if (dhi_ <= -1024) nmj_ += cb_lo; } \
;     if (__any(nmj_ != nm_cur)) { nm_cur = nmj_; _Pragma("unroll") for (int r = 0; r < 16; ++r) negm[r] = nmj_; } } while (0)
; #define QKT(P0, P1, KOFF) do { if constexpr (NDQ == 8 && NQL == 0) qkt8_roll(P0, P1, negm, kb0 + (KOFF), qr); \
;     else if constexpr (NDQ == 12 && NQL == 4) qkt12_roll(P0, P1, negm, kb0 + (KOFF), qa0, qr); else qkt<NDQ, NQL>(P0, P1, negm, K_lds + (KOFF), qr, qls, r32, hi); } while (0)
;     ...
;   f32x16 pA0, pA1, pB0, pB1; float alA, alB; bf16x8 pa0, pa1, pa2, pa3; const int NT = nkeys / KVBLK;
;   const int kb0 = (int)(uintptr_t)K_lds + r32 * ROWB + (((r32 & SWM) << 4) ^ (hi << 4));
;   const int qa0 = (int)(uintptr_t)qls;
;     ...
;   constexpr int SE = 0, SO = SDEPTH - 1;
;   SLOAD(SE, kbeg); asm volatile("s_waitcnt vmcnt(0)" ::: "memory"); SWRITE(0, SE); __syncthreads();
;   constexpr bool SLICED = (NDQ == 8 && NQL == 0 && BIAS == 1);
;   NEGM_UPD(kbeg); QKT(pA0, pA1, 0); BIASADD(pA0, pA1, kbeg); partialSM<true>(pA0, pA1, mC, alA);
;   if constexpr (SLICED) {
; #pragma unroll
;     for (int r = 0; r < 16; ++r) pA1[r] = __builtin_amdgcn_exp2f(pA1[r]); }
;   SLOAD(SO, kbeg + KVBLK); if constexpr (SDEPTH == 2) { if (2 < NT) SLOAD(SE, kbeg + 2 * KVBLK); }
;   SWAIT(); SWRITE(1, SO); __syncthreads();
	ds_write_b128 v201, v[54:57] offset:16384
	s_waitcnt vmcnt(2)
	ds_write_b128 v207, v[82:85] offset:16384
	s_waitcnt vmcnt(1)
	ds_write_b128 v208, v[58:61] offset:49152
	s_waitcnt vmcnt(0)
	ds_write_b128 v209, v[62:65] offset:49152
	v_add_u32_e32 v224, 0x4000, v200
	v_cmp_gt_u32_e64 s[4:5], 32, v51
	v_lshl_add_u64 v[184:185], s[6:7], 0, v[52:53]
	v_mad_i64_i32 v[186:187], s[6:7], v50, s55, v[18:19]
	v_mov_b32_e32 v232, 0
	v_mov_b64_e32 v[64:65], v[16:17]
	v_mov_b64_e32 v[48:49], v[16:17]
	v_mov_b64_e32 v[32:33], v[16:17]
	v_add_f32_e32 v227, 0, v0
	v_xor_b32_e32 v223, 32, v224
	v_xor_b32_e32 v222, 64, v224
	v_xor_b32_e32 v221, 0x60, v224
	v_xor_b32_e32 v220, 0x80, v224
	v_xor_b32_e32 v219, 0xa0, v224
	v_xor_b32_e32 v218, 0xc0, v224
	v_xor_b32_e32 v217, 0xe0, v224
	v_lshl_add_u32 v183, v178, 2, v179
	v_add_u32_e32 v181, v179, v182
	v_lshlrev_b32_e32 v0, 4, v87
	v_mov_b32_e32 v225, 1.0
	v_mov_b64_e32 v[62:63], v[14:15]
	v_mov_b64_e32 v[60:61], v[12:13]
	v_mov_b64_e32 v[58:59], v[10:11]
	v_mov_b64_e32 v[56:57], v[8:9]
	v_mov_b64_e32 v[54:55], v[6:7]
	v_mov_b64_e32 v[52:53], v[4:5]
	v_mov_b64_e32 v[50:51], v[2:3]
	v_mov_b64_e32 v[46:47], v[14:15]
	v_mov_b64_e32 v[44:45], v[12:13]
	v_mov_b64_e32 v[42:43], v[10:11]
	v_mov_b64_e32 v[40:41], v[8:9]
	v_mov_b64_e32 v[38:39], v[6:7]
	v_mov_b64_e32 v[36:37], v[4:5]
	v_mov_b64_e32 v[34:35], v[2:3]
	v_mov_b64_e32 v[30:31], v[14:15]
	v_mov_b64_e32 v[28:29], v[12:13]
	v_mov_b64_e32 v[26:27], v[10:11]
	v_mov_b64_e32 v[24:25], v[8:9]
	v_mov_b64_e32 v[22:23], v[6:7]
	v_mov_b64_e32 v[20:21], v[4:5]
	v_mov_b64_e32 v[18:19], v[2:3]
	v_mov_b32_e32 v197, 0
	v_mov_b32_e32 v82, 0
	v_mov_b32_e32 v83, v232
	v_mov_b32_e32 v84, v232
	v_mov_b32_e32 v85, v232
	v_mov_b32_e32 v86, v232
	v_mov_b32_e32 v87, v232
	v_mov_b32_e32 v88, v232
	v_mov_b32_e32 v89, v232
	v_mov_b32_e32 v90, v232
	v_mov_b32_e32 v91, v232
	v_mov_b32_e32 v92, v232
	v_mov_b32_e32 v93, v232
	v_mov_b32_e32 v94, v232
	v_mov_b32_e32 v95, v232
	v_mov_b32_e32 v96, v232
	v_mov_b32_e32 v97, v232
	s_waitcnt lgkmcnt(0)
	s_barrier
; #define SBAR_M() __builtin_amdgcn_sched_barrier(0)
; template <bool FIRST>
; __device__ __forceinline__ void partialSM(f32x16& p0, f32x16& p1, float& mC, float& alpha) {
;   float mx_[4] = {p0[0], p0[1], p0[2], p0[3]};
; #pragma unroll
;   for (int r = 4; r < 16; ++r) mx_[r & 3] = fmaxf(mx_[r & 3], p0[r]);
; #pragma unroll
;   for (int r = 0; r < 16; ++r) mx_[r & 3] = fmaxf(mx_[r & 3], p1[r]);
;   float pmax = fmaxf(fmaxf(mx_[0], mx_[1]), fmaxf(mx_[2], mx_[3]));
;   { auto rr = __builtin_amdgcn_permlane32_swap(__float_as_uint(pmax), __float_as_uint(pmax), false, false);
;     pmax = fmaxf(__uint_as_float(rr[0]), __uint_as_float(rr[1])); }
;   if (!FIRST && __builtin_expect(__all(pmax <= THR2), 1)) { alpha = 1.f; }
;   else { const float delta = FIRST ? fmaxf(pmax, -200.f) : fmaxf(pmax, 0.f); alpha = FIRST ? 1.f : __builtin_amdgcn_exp2f(-delta); mC += delta;
; #pragma unroll
;     for (int r = 0; r < 16; ++r) p0[r] -= delta;
; #pragma unroll
;     for (int r = 0; r < 16; ++r) p1[r] -= delta; }
; #pragma unroll
;   for (int r = 0; r < 16; ++r) p0[r] = __builtin_amdgcn_exp2f(p0[r]);
; }
; template <bool EXP1 = true>
; __device__ __forceinline__ void finishSM(f32x16& p0, f32x16& p1, float alpha, float& l_reg, bf16x8& pa0, bf16x8& pa1, bf16x8& pa2, bf16x8& pa3) {
;   if constexpr (EXP1) {
; #pragma unroll
;   for (int r = 0; r < 16; ++r) p1[r] = __builtin_amdgcn_exp2f(p1[r]);
;   }
;   float sm_[4] = {p0[0], p0[1], p0[2], p0[3]};
; #pragma unroll
;   for (int r = 4; r < 16; ++r) sm_[r & 3] += p0[r];
; #pragma unroll
;   for (int r = 0; r < 16; ++r) sm_[r & 3] += p1[r];
;   float ps = (sm_[0] + sm_[1]) + (sm_[2] + sm_[3]);
;   { auto rr = __builtin_amdgcn_permlane32_swap(__float_as_uint(ps), __float_as_uint(ps), false, false);
;     ps = __uint_as_float(rr[0]) + __uint_as_float(rr[1]); }
;   l_reg = l_reg * alpha + ps;
;     ...
;   PK4(p0, 0, pa0); PK4(p0, 8, pa1); PK4(p1, 0, pa2); PK4(p1, 8, pa3);
;     ...
; }
; __device__ __forceinline__ void qkt8_roll(f32x16& p0, f32x16& p1, const f32x16& negm, int kb, const bf16x8* qr) {
;   const int a0 = kb ^ (0 << 5); const bf16x8 x0 = lds_rd128<0>(a0), y0 = lds_rd128<8192>(a0);
;   const int a1 = kb ^ (1 << 5); const bf16x8 x1 = lds_rd128<0>(a1), y1 = lds_rd128<8192>(a1);
;   const int a2 = kb ^ (2 << 5); const bf16x8 x2 = lds_rd128<0>(a2), y2 = lds_rd128<8192>(a2);
;   asm volatile("s_waitcnt lgkmcnt(4)" ::: "memory"); SBAR_M();
.LBB0_421:
	v_exp_f32_e32 v66, v66
	v_exp_f32_e32 v67, v67
	v_exp_f32_e32 v68, v68
	v_exp_f32_e32 v69, v69
	v_exp_f32_e32 v70, v70
	v_exp_f32_e32 v71, v71
	v_exp_f32_e32 v72, v72
	v_exp_f32_e32 v73, v73
	v_add_f32_e32 v98, v148, v146
	v_add_f32_e32 v99, v159, v161
	v_add_f32_e32 v100, v149, v147
	v_add_f32_e32 v101, v158, v160
	v_exp_f32_e32 v74, v74
	v_exp_f32_e32 v75, v75
	v_exp_f32_e32 v76, v76
	v_exp_f32_e32 v77, v77
	v_add_f32_e32 v98, v150, v98
	v_add_f32_e32 v99, v157, v99
	v_add_f32_e32 v100, v151, v100
	v_add_f32_e32 v101, v156, v101
	v_exp_f32_e32 v78, v78
	v_exp_f32_e32 v79, v79
	v_exp_f32_e32 v80, v80
	v_exp_f32_e32 v81, v81
	v_add_f32_e32 v98, v152, v98
	v_add_f32_e32 v99, v155, v99
	v_add_f32_e32 v100, v153, v100
	v_add_f32_e32 v101, v154, v101
	v_add_f32_e32 v98, v66, v98
	v_add_f32_e32 v99, v67, v99
	v_add_f32_e32 v100, v68, v100
	v_add_f32_e32 v101, v69, v101
	v_add_f32_e32 v98, v70, v98
	v_add_f32_e32 v99, v71, v99
	v_add_f32_e32 v100, v72, v100
	v_add_f32_e32 v101, v73, v101
	v_add_f32_e32 v98, v74, v98
	v_add_f32_e32 v99, v75, v99
	v_add_f32_e32 v100, v76, v100
	v_add_f32_e32 v101, v77, v101
	v_add_f32_e32 v98, v78, v98
	v_add_f32_e32 v99, v79, v99
	v_add_f32_e32 v100, v80, v100
	v_add_f32_e32 v101, v81, v101
	v_add_f32_e32 v98, v98, v99
	v_add_f32_e32 v99, v100, v101
	v_add_f32_e32 v228, v98, v99
	v_mov_b32_e32 v229, v228
	v_cvt_pk_bf16_f32 v146, v146, v161
	v_cvt_pk_bf16_f32 v147, v147, v160
	v_cvt_pk_bf16_f32 v148, v148, v159
	v_cvt_pk_bf16_f32 v149, v149, v158
	v_cvt_pk_bf16_f32 v150, v150, v157
	v_cvt_pk_bf16_f32 v151, v151, v156
	v_cvt_pk_bf16_f32 v152, v152, v155
	v_cvt_pk_bf16_f32 v153, v153, v154
	v_cvt_pk_bf16_f32 v158, v66, v67
	v_cvt_pk_bf16_f32 v159, v68, v69
	v_cvt_pk_bf16_f32 v160, v70, v71
	v_cvt_pk_bf16_f32 v161, v72, v73
	v_cvt_pk_bf16_f32 v154, v74, v75
	v_cvt_pk_bf16_f32 v155, v76, v77
	v_cvt_pk_bf16_f32 v156, v78, v79
	v_cvt_pk_bf16_f32 v157, v80, v81
	s_nop 1
	v_permlane32_swap_b32_e32 v228, v229
	v_cmp_neq_f32_e64 s[6:7], v232, -v227
	s_cmp_eq_u64 s[6:7], 0
	s_cselect_b64 s[6:7], -1, 0
	v_cndmask_b32_e64 v81, -v227, v97, s[6:7]
	v_cndmask_b32_e64 v80, -v227, v96, s[6:7]
	v_cndmask_b32_e64 v79, -v227, v95, s[6:7]
	v_cndmask_b32_e64 v78, -v227, v94, s[6:7]
	v_cndmask_b32_e64 v77, -v227, v93, s[6:7]
	v_cndmask_b32_e64 v76, -v227, v92, s[6:7]
	v_cndmask_b32_e64 v75, -v227, v91, s[6:7]
	v_cndmask_b32_e64 v74, -v227, v90, s[6:7]
	v_cndmask_b32_e64 v73, -v227, v89, s[6:7]
	v_cndmask_b32_e64 v72, -v227, v88, s[6:7]
	v_cndmask_b32_e64 v71, -v227, v87, s[6:7]
	v_cndmask_b32_e64 v70, -v227, v86, s[6:7]
	v_cndmask_b32_e64 v69, -v227, v85, s[6:7]
	v_cndmask_b32_e64 v68, -v227, v84, s[6:7]
	v_cndmask_b32_e64 v67, -v227, v83, s[6:7]
	v_cndmask_b32_e64 v66, -v227, v82, s[6:7]
	ds_read_b128 v[82:85], v224 offset:0
	ds_read_b128 v[162:165], v224 offset:0x2000
	ds_read_b128 v[166:169], v223 offset:0
	ds_read_b128 v[170:173], v223 offset:0x2000
	ds_read_b128 v[174:177], v222 offset:0
	ds_read_b128 v[188:191], v222 offset:0x2000
	s_waitcnt lgkmcnt(4)
	s_nop 1
	v_mfma_f32_32x32x16_bf16 v[98:113], v[82:85], v[142:145], v[66:81]
	v_mfma_f32_32x32x16_bf16 v[82:97], v[162:165], v[142:145], v[66:81]
	ds_read_b128 v[162:165], v221 offset:0
	ds_read_b128 v[192:195], v221 offset:0x2000
	s_waitcnt lgkmcnt(4)
	v_mfma_f32_32x32x16_bf16 v[98:113], v[166:169], v[138:141], v[98:113]
	ds_read_b128 v[166:169], v220 offset:0
	v_mfma_f32_32x32x16_bf16 v[82:97], v[170:173], v[138:141], v[82:97]
	ds_read_b128 v[170:173], v220 offset:0x2000
	s_waitcnt lgkmcnt(4)
	v_mfma_f32_32x32x16_bf16 v[98:113], v[174:177], v[134:137], v[98:113]
	ds_read_b128 v[174:177], v219 offset:0
	v_mfma_f32_32x32x16_bf16 v[82:97], v[188:191], v[134:137], v[82:97]
	ds_read_b128 v[188:191], v219 offset:0x2000
	s_waitcnt lgkmcnt(4)
	v_mfma_f32_32x32x16_bf16 v[98:113], v[162:165], v[130:133], v[98:113]
	ds_read_b128 v[162:165], v218 offset:0
	v_mfma_f32_32x32x16_bf16 v[82:97], v[192:195], v[130:133], v[82:97]
	ds_read_b128 v[192:195], v218 offset:0x2000
	s_waitcnt lgkmcnt(4)
	v_mfma_f32_32x32x16_bf16 v[98:113], v[166:169], v[126:129], v[98:113]
	ds_read_b128 v[166:169], v217 offset:0
	v_mfma_f32_32x32x16_bf16 v[82:97], v[170:173], v[126:129], v[82:97]
	ds_read_b128 v[170:173], v217 offset:0x2000
	s_waitcnt lgkmcnt(4)
	v_mfma_f32_32x32x16_bf16 v[98:113], v[174:177], v[122:125], v[98:113]
	s_waitcnt lgkmcnt(2)
	v_mfma_f32_32x32x16_bf16 v[82:97], v[188:191], v[122:125], v[82:97]
	v_mfma_f32_32x32x16_bf16 v[98:113], v[162:165], v[118:121], v[98:113]
	s_waitcnt lgkmcnt(0)
	v_mfma_f32_32x32x16_bf16 v[82:97], v[192:195], v[118:121], v[82:97]
	v_mfma_f32_32x32x16_bf16 v[98:113], v[166:169], v[114:117], v[98:113]
	v_mfma_f32_32x32x16_bf16 v[82:97], v[170:173], v[114:117], v[82:97]
	s_nop 10
	v_max_f32_e32 v162, v102, v102
	v_max_f32_e32 v163, v98, v98
	v_max_f32_e32 v162, v163, v162
	v_max_f32_e32 v163, v103, v103
	v_max_f32_e32 v164, v99, v99
	v_max_f32_e32 v163, v164, v163
	v_max_f32_e32 v164, v105, v105
	v_max_f32_e32 v165, v101, v101
	v_max_f32_e32 v164, v165, v164
	v_max3_f32 v165, v100, v104, v108
	v_max3_f32 v164, v164, v109, v113
	v_max3_f32 v162, v162, v106, v110
	v_max3_f32 v163, v163, v107, v111
	v_max3_f32 v165, v165, v112, v84
	v_max3_f32 v164, v164, v85, v89
	v_max3_f32 v162, v162, v82, v86
	v_max3_f32 v163, v163, v83, v87
	v_max3_f32 v165, v165, v88, v92
	v_max3_f32 v164, v164, v93, v97
	v_max3_f32 v162, v162, v90, v94
	v_max3_f32 v163, v163, v91, v95
	v_max3_f32 v164, v165, v96, v164
	v_max3_f32 v162, v162, v163, v164
	v_mov_b32_e32 v163, v162
	s_nop 1
	v_permlane32_swap_b32_e32 v162, v163
	v_max_f32_e32 v163, v163, v163
	v_max_f32_e32 v162, v162, v162
	v_max_f32_e32 v162, v162, v163
	v_cmp_ge_f32_e32 vcc, s48, v162
	s_cmp_eq_u64 vcc, exec
	s_cbranch_scc0 .LBB0_435
	v_mov_b32_e32 v231, v227
	v_mov_b32_e32 v230, 1.0

; #define SBAR_M() __builtin_amdgcn_sched_barrier(0)
; template <bool FIRST>
; __device__ __forceinline__ void partialSM(f32x16& p0, f32x16& p1, float& mC, float& alpha) {
;   float mx_[4] = {p0[0], p0[1], p0[2], p0[3]};
; #pragma unroll
;   for (int r = 4; r < 16; ++r) mx_[r & 3] = fmaxf(mx_[r & 3], p0[r]);
; #pragma unroll
;   for (int r = 0; r < 16; ++r) mx_[r & 3] = fmaxf(mx_[r & 3], p1[r]);
;   float pmax = fmaxf(fmaxf(mx_[0], mx_[1]), fmaxf(mx_[2], mx_[3]));
;   { auto rr = __builtin_amdgcn_permlane32_swap(__float_as_uint(pmax), __float_as_uint(pmax), false, false);
;     pmax = fmaxf(__uint_as_float(rr[0]), __uint_as_float(rr[1])); }
;   if (!FIRST && __builtin_expect(__all(pmax <= THR2), 1)) { alpha = 1.f; }
;   else { const float delta = FIRST ? fmaxf(pmax, -200.f) : fmaxf(pmax, 0.f); alpha = FIRST ? 1.f : __builtin_amdgcn_exp2f(-delta); mC += delta;
; #pragma unroll
;     for (int r = 0; r < 16; ++r) p0[r] -= delta;
; #pragma unroll
;     for (int r = 0; r < 16; ++r) p1[r] -= delta; }
; #pragma unroll
;   for (int r = 0; r < 16; ++r) p0[r] = __builtin_amdgcn_exp2f(p0[r]);
; }
; template <bool EXP1 = true>
; __device__ __forceinline__ void finishSM(f32x16& p0, f32x16& p1, float alpha, float& l_reg, bf16x8& pa0, bf16x8& pa1, bf16x8& pa2, bf16x8& pa3) {
;   if constexpr (EXP1) {
; #pragma unroll
;   for (int r = 0; r < 16; ++r) p1[r] = __builtin_amdgcn_exp2f(p1[r]);
;   }
;   float sm_[4] = {p0[0], p0[1], p0[2], p0[3]};
; #pragma unroll
;   for (int r = 4; r < 16; ++r) sm_[r & 3] += p0[r];
; #pragma unroll
;   for (int r = 0; r < 16; ++r) sm_[r & 3] += p1[r];
;   float ps = (sm_[0] + sm_[1]) + (sm_[2] + sm_[3]);
;   { auto rr = __builtin_amdgcn_permlane32_swap(__float_as_uint(ps), __float_as_uint(ps), false, false);
;     ps = __uint_as_float(rr[0]) + __uint_as_float(rr[1]); }
;   l_reg = l_reg * alpha + ps;
;     ...
;   PK4(p0, 0, pa0); PK4(p0, 8, pa1); PK4(p1, 0, pa2); PK4(p1, 8, pa3);
;     ...
; }
; __device__ __forceinline__ void qkt8_roll(f32x16& p0, f32x16& p1, const f32x16& negm, int kb, const bf16x8* qr) {
;   const int a0 = kb ^ (0 << 5); const bf16x8 x0 = lds_rd128<0>(a0), y0 = lds_rd128<8192>(a0);
;   const int a1 = kb ^ (1 << 5); const bf16x8 x1 = lds_rd128<0>(a1), y1 = lds_rd128<8192>(a1);
;   const int a2 = kb ^ (2 << 5); const bf16x8 x2 = lds_rd128<0>(a2), y2 = lds_rd128<8192>(a2);
;   asm volatile("s_waitcnt lgkmcnt(4)" ::: "memory"); SBAR_M();
.LBB0_427:
	v_exp_f32_e32 v146, v98
	v_exp_f32_e32 v153, v99
	v_exp_f32_e32 v147, v100
	v_exp_f32_e32 v152, v101
	v_exp_f32_e32 v148, v102
	v_exp_f32_e32 v151, v103
	v_exp_f32_e32 v149, v104
	v_exp_f32_e32 v150, v105
	v_exp_f32_e32 v103, v106
	v_exp_f32_e32 v105, v107
	v_exp_f32_e32 v101, v108
	v_exp_f32_e32 v104, v109
	v_exp_f32_e32 v99, v110
	v_exp_f32_e32 v102, v111
	v_exp_f32_e32 v98, v112
	v_exp_f32_e32 v100, v113
	v_xor_b32_e32 v106, 0x80000000, v227
	v_exp_f32_e32 v82, v82
	v_exp_f32_e32 v83, v83
	v_exp_f32_e32 v84, v84
	v_exp_f32_e32 v85, v85
	v_cndmask_b32_e64 v232, v106, v232, s[6:7]
	v_exp_f32_e32 v86, v86
	v_exp_f32_e32 v87, v87
	v_exp_f32_e32 v88, v88
	v_exp_f32_e32 v89, v89
	v_add_f32_e32 v106, v148, v146
	v_add_f32_e32 v107, v151, v153
	v_add_f32_e32 v108, v149, v147
	v_add_f32_e32 v109, v150, v152
	v_exp_f32_e32 v90, v90
	v_exp_f32_e32 v91, v91
	v_exp_f32_e32 v92, v92
	v_exp_f32_e32 v93, v93
	v_add_f32_e32 v106, v103, v106
	v_add_f32_e32 v107, v105, v107
	v_add_f32_e32 v108, v101, v108
	v_add_f32_e32 v109, v104, v109
	v_exp_f32_e32 v94, v94
	v_exp_f32_e32 v95, v95
	v_exp_f32_e32 v96, v96
	v_exp_f32_e32 v97, v97
	v_add_f32_e32 v106, v99, v106
	v_add_f32_e32 v107, v102, v107
	v_add_f32_e32 v108, v98, v108
	v_add_f32_e32 v109, v100, v109
	v_add_f32_e32 v106, v82, v106
	v_add_f32_e32 v107, v107, v83
	v_add_f32_e32 v108, v108, v84
	v_add_f32_e32 v109, v109, v85
	v_add_f32_e32 v106, v86, v106
	v_add_f32_e32 v107, v87, v107
	v_add_f32_e32 v108, v88, v108
	v_add_f32_e32 v109, v89, v109
	v_add_f32_e32 v106, v90, v106
	v_add_f32_e32 v107, v91, v107
	v_add_f32_e32 v108, v92, v108
	v_add_f32_e32 v109, v93, v109
	v_add_f32_e32 v106, v94, v106
	v_add_f32_e32 v107, v95, v107
	v_add_f32_e32 v108, v96, v108
	v_add_f32_e32 v109, v97, v109
	v_add_f32_e32 v106, v106, v107
	v_add_f32_e32 v107, v108, v109
	v_add_f32_e32 v233, v106, v107
	s_waitcnt lgkmcnt(0)
	s_barrier
	v_mov_b32_e32 v234, v233
	v_cvt_pk_bf16_f32 v146, v146, v153
	v_cvt_pk_bf16_f32 v147, v147, v152
	v_cvt_pk_bf16_f32 v148, v148, v151
	v_cvt_pk_bf16_f32 v149, v149, v150
	v_cvt_pk_bf16_f32 v150, v103, v105
	v_cvt_pk_bf16_f32 v151, v101, v104
	v_cvt_pk_bf16_f32 v152, v99, v102
	v_cvt_pk_bf16_f32 v153, v98, v100
	v_cvt_pk_bf16_f32 v158, v82, v83
	v_cvt_pk_bf16_f32 v159, v84, v85
	v_cvt_pk_bf16_f32 v160, v86, v87
	v_cvt_pk_bf16_f32 v161, v88, v89
	v_cvt_pk_bf16_f32 v154, v90, v91
	v_cvt_pk_bf16_f32 v155, v92, v93
	v_cvt_pk_bf16_f32 v156, v94, v95
	v_cvt_pk_bf16_f32 v157, v96, v97
	s_nop 1
	v_permlane32_swap_b32_e32 v233, v234
	v_cmp_neq_f32_e64 s[6:7], v232, -v231
	s_cmp_eq_u64 s[6:7], 0
	s_cselect_b64 s[6:7], -1, 0
	v_cndmask_b32_e64 v97, -v231, v81, s[6:7]
	v_cndmask_b32_e64 v96, -v231, v80, s[6:7]
	v_cndmask_b32_e64 v95, -v231, v79, s[6:7]
	v_cndmask_b32_e64 v94, -v231, v78, s[6:7]
	v_cndmask_b32_e64 v93, -v231, v77, s[6:7]
	v_cndmask_b32_e64 v92, -v231, v76, s[6:7]
	v_cndmask_b32_e64 v91, -v231, v75, s[6:7]
	v_cndmask_b32_e64 v90, -v231, v74, s[6:7]
	v_cndmask_b32_e64 v89, -v231, v73, s[6:7]
	v_cndmask_b32_e64 v88, -v231, v72, s[6:7]
	v_cndmask_b32_e64 v87, -v231, v71, s[6:7]
	v_cndmask_b32_e64 v86, -v231, v70, s[6:7]
	v_cndmask_b32_e64 v85, -v231, v69, s[6:7]
	v_cndmask_b32_e64 v84, -v231, v68, s[6:7]
	v_cndmask_b32_e64 v83, -v231, v67, s[6:7]
	v_cndmask_b32_e64 v82, -v231, v66, s[6:7]
	ds_read_b128 v[66:69], v200 offset:0
	ds_read_b128 v[162:165], v200 offset:0x2000
	ds_read_b128 v[166:169], v210 offset:0
	ds_read_b128 v[170:173], v210 offset:0x2000
	ds_read_b128 v[174:177], v211 offset:0
	ds_read_b128 v[192:195], v211 offset:0x2000
	s_waitcnt lgkmcnt(4)
	s_nop 1
	v_mfma_f32_32x32x16_bf16 v[98:113], v[66:69], v[142:145], v[82:97]
	v_mfma_f32_32x32x16_bf16 v[66:81], v[162:165], v[142:145], v[82:97]
	ds_read_b128 v[162:165], v212 offset:0
	ds_read_b128 v[236:239], v212 offset:0x2000
	s_waitcnt lgkmcnt(4)
	v_mfma_f32_32x32x16_bf16 v[98:113], v[166:169], v[138:141], v[98:113]
	ds_read_b128 v[166:169], v213 offset:0
	v_mfma_f32_32x32x16_bf16 v[66:81], v[170:173], v[138:141], v[66:81]
	ds_read_b128 v[170:173], v213 offset:0x2000
	s_waitcnt lgkmcnt(4)
	v_mfma_f32_32x32x16_bf16 v[98:113], v[174:177], v[134:137], v[98:113]
	ds_read_b128 v[174:177], v214 offset:0
	v_mfma_f32_32x32x16_bf16 v[66:81], v[192:195], v[134:137], v[66:81]
	ds_read_b128 v[192:195], v214 offset:0x2000
	s_waitcnt lgkmcnt(4)
	v_mfma_f32_32x32x16_bf16 v[98:113], v[162:165], v[130:133], v[98:113]
	ds_read_b128 v[162:165], v215 offset:0
	v_mfma_f32_32x32x16_bf16 v[66:81], v[236:239], v[130:133], v[66:81]
	ds_read_b128 v[236:239], v215 offset:0x2000
	s_waitcnt lgkmcnt(4)
	v_mfma_f32_32x32x16_bf16 v[98:113], v[166:169], v[126:129], v[98:113]
	ds_read_b128 v[166:169], v216 offset:0
	v_mfma_f32_32x32x16_bf16 v[66:81], v[170:173], v[126:129], v[66:81]
	ds_read_b128 v[170:173], v216 offset:0x2000
	s_waitcnt lgkmcnt(4)
	v_mfma_f32_32x32x16_bf16 v[98:113], v[174:177], v[122:125], v[98:113]
	s_waitcnt lgkmcnt(2)
	v_mfma_f32_32x32x16_bf16 v[66:81], v[192:195], v[122:125], v[66:81]
	v_mfma_f32_32x32x16_bf16 v[98:113], v[162:165], v[118:121], v[98:113]
	s_waitcnt lgkmcnt(0)
	v_mfma_f32_32x32x16_bf16 v[66:81], v[236:239], v[118:121], v[66:81]
	v_mfma_f32_32x32x16_bf16 v[98:113], v[166:169], v[114:117], v[98:113]
	v_mfma_f32_32x32x16_bf16 v[66:81], v[170:173], v[114:117], v[66:81]
	s_nop 10
	v_max_f32_e32 v162, v102, v102
	v_max_f32_e32 v163, v98, v98
	v_max_f32_e32 v162, v163, v162
	v_max_f32_e32 v163, v103, v103
	v_max_f32_e32 v164, v99, v99
	v_max_f32_e32 v163, v164, v163
	v_max_f32_e32 v164, v105, v105
	v_max_f32_e32 v165, v101, v101
	v_max_f32_e32 v164, v165, v164
	v_max3_f32 v165, v100, v104, v108
	v_max3_f32 v164, v164, v109, v113
	v_max3_f32 v162, v162, v106, v110
	v_max3_f32 v163, v163, v107, v111
	v_max3_f32 v165, v165, v112, v68
	v_max3_f32 v164, v164, v69, v73
	v_max3_f32 v162, v162, v66, v70
	v_max3_f32 v163, v163, v67, v71
	v_max3_f32 v165, v165, v72, v76
	v_max3_f32 v164, v164, v77, v81
	v_max3_f32 v162, v162, v74, v78
	v_max3_f32 v163, v163, v75, v79
	v_max3_f32 v164, v165, v80, v164
	v_max3_f32 v162, v162, v163, v164
	v_mov_b32_e32 v163, v162
	s_nop 1
	v_permlane32_swap_b32_e32 v162, v163
	v_max_f32_e32 v163, v163, v163
	v_max_f32_e32 v162, v162, v162
	v_max_f32_e32 v162, v162, v163
	v_cmp_ge_f32_e32 vcc, s48, v162
	s_cmp_eq_u64 vcc, exec
	v_mov_b32_e32 v226, 1.0
	s_cbranch_scc0 .LBB0_436
	v_mov_b32_e32 v227, v231

; template <bool EXP1 = true>
; __device__ __forceinline__ void finishSM(f32x16& p0, f32x16& p1, float alpha, float& l_reg, bf16x8& pa0, bf16x8& pa1, bf16x8& pa2, bf16x8& pa3) {
;   if constexpr (EXP1) {
; #pragma unroll
;   for (int r = 0; r < 16; ++r) p1[r] = __builtin_amdgcn_exp2f(p1[r]);
;   }
;   float sm_[4] = {p0[0], p0[1], p0[2], p0[3]};
; #pragma unroll
;   for (int r = 4; r < 16; ++r) sm_[r & 3] += p0[r];
; #pragma unroll
;   for (int r = 0; r < 16; ++r) sm_[r & 3] += p1[r];
;   float ps = (sm_[0] + sm_[1]) + (sm_[2] + sm_[3]);
;   { auto rr = __builtin_amdgcn_permlane32_swap(__float_as_uint(ps), __float_as_uint(ps), false, false);
;     ps = __uint_as_float(rr[0]) + __uint_as_float(rr[1]); }
;   l_reg = l_reg * alpha + ps;
;     ...
;   PK4(p0, 0, pa0); PK4(p0, 8, pa1); PK4(p1, 0, pa2); PK4(p1, 8, pa3);
;     ...
; }
; __device__ __forceinline__ void qkt8_roll(f32x16& p0, f32x16& p1, const f32x16& negm, int kb, const bf16x8* qr) {
;   const int a0 = kb ^ (0 << 5); const bf16x8 x0 = lds_rd128<0>(a0), y0 = lds_rd128<8192>(a0);
;   const int a1 = kb ^ (1 << 5); const bf16x8 x1 = lds_rd128<0>(a1), y1 = lds_rd128<8192>(a1);
;   const int a2 = kb ^ (2 << 5); const bf16x8 x2 = lds_rd128<0>(a2), y2 = lds_rd128<8192>(a2);
;   asm volatile("s_waitcnt lgkmcnt(4)" ::: "memory"); SBAR_M();
;   p0 = __builtin_amdgcn_mfma_f32_32x32x16_bf16(x0, qr[0], negm, 0, 0, 0); p1 = __builtin_amdgcn_mfma_f32_32x32x16_bf16(y0, qr[0], negm, 0, 0, 0);
;   const int a3 = kb ^ (3 << 5); const bf16x8 x3 = lds_rd128<0>(a3), y3 = lds_rd128<8192>(a3);
;   asm volatile("s_waitcnt lgkmcnt(4)" ::: "memory"); SBAR_M();
;   p0 = __builtin_amdgcn_mfma_f32_32x32x16_bf16(x1, qr[1], p0, 0, 0, 0); p1 = __builtin_amdgcn_mfma_f32_32x32x16_bf16(y1, qr[1], p1, 0, 0, 0);
;   const int a4 = kb ^ (4 << 5); const bf16x8 x4 = lds_rd128<0>(a4), y4 = lds_rd128<8192>(a4);
;   asm volatile("s_waitcnt lgkmcnt(4)" ::: "memory"); SBAR_M();
;   p0 = __builtin_amdgcn_mfma_f32_32x32x16_bf16(x2, qr[2], p0, 0, 0, 0); p1 = __builtin_amdgcn_mfma_f32_32x32x16_bf16(y2, qr[2], p1, 0, 0, 0);
;   const int a5 = kb ^ (5 << 5); const bf16x8 x5 = lds_rd128<0>(a5), y5 = lds_rd128<8192>(a5);
;   asm volatile("s_waitcnt lgkmcnt(4)" ::: "memory"); SBAR_M();
;   p0 = __builtin_amdgcn_mfma_f32_32x32x16_bf16(x3, qr[3], p0, 0, 0, 0); p1 = __builtin_amdgcn_mfma_f32_32x32x16_bf16(y3, qr[3], p1, 0, 0, 0);
.LBB0_437:
	v_cmp_neq_f32_e64 s[6:7], v232, -v227
	s_cmp_eq_u64 s[6:7], 0
	s_cselect_b64 s[6:7], -1, 0
	v_cndmask_b32_e64 v97, -v227, v97, s[6:7]
	v_cndmask_b32_e64 v96, -v227, v96, s[6:7]
	v_cndmask_b32_e64 v95, -v227, v95, s[6:7]
	v_cndmask_b32_e64 v94, -v227, v94, s[6:7]
	v_cndmask_b32_e64 v93, -v227, v93, s[6:7]
	v_cndmask_b32_e64 v92, -v227, v92, s[6:7]
	v_cndmask_b32_e64 v91, -v227, v91, s[6:7]
	v_cndmask_b32_e64 v90, -v227, v90, s[6:7]
	v_cndmask_b32_e64 v89, -v227, v89, s[6:7]
	v_cndmask_b32_e64 v88, -v227, v88, s[6:7]
	v_cndmask_b32_e64 v87, -v227, v87, s[6:7]
	v_cndmask_b32_e64 v86, -v227, v86, s[6:7]
	v_cndmask_b32_e64 v85, -v227, v85, s[6:7]
	v_cndmask_b32_e64 v84, -v227, v84, s[6:7]
	v_cndmask_b32_e64 v83, -v227, v83, s[6:7]
	v_cndmask_b32_e64 v82, -v227, v82, s[6:7]
	ds_read_b128 v[162:165], v224 offset:0
	ds_read_b128 v[166:169], v224 offset:0x2000
	ds_read_b128 v[170:173], v223 offset:0
	ds_read_b128 v[174:177], v223 offset:0x2000
	ds_read_b128 v[184:187], v222 offset:0
	ds_read_b128 v[188:191], v222 offset:0x2000
	s_waitcnt lgkmcnt(4)
	s_nop 1
	v_mfma_f32_32x32x16_bf16 v[98:113], v[162:165], v[142:145], v[82:97]
	v_mfma_f32_32x32x16_bf16 v[82:97], v[166:169], v[142:145], v[82:97]
	ds_read_b128 v[142:145], v221 offset:0
	ds_read_b128 v[162:165], v221 offset:0x2000
	s_waitcnt lgkmcnt(4)
	v_mfma_f32_32x32x16_bf16 v[98:113], v[170:173], v[138:141], v[98:113]
	v_mfma_f32_32x32x16_bf16 v[82:97], v[174:177], v[138:141], v[82:97]
	ds_read_b128 v[138:141], v220 offset:0
	ds_read_b128 v[166:169], v220 offset:0x2000
	s_waitcnt lgkmcnt(4)
	v_mfma_f32_32x32x16_bf16 v[98:113], v[184:187], v[134:137], v[98:113]
	v_mfma_f32_32x32x16_bf16 v[82:97], v[188:191], v[134:137], v[82:97]
	ds_read_b128 v[134:137], v219 offset:0
	ds_read_b128 v[170:173], v219 offset:0x2000
	s_waitcnt lgkmcnt(4)
	v_mfma_f32_32x32x16_bf16 v[98:113], v[142:145], v[130:133], v[98:113]
	v_mfma_f32_32x32x16_bf16 v[82:97], v[162:165], v[130:133], v[82:97]
	ds_read_b128 v[130:133], v218 offset:0
	ds_read_b128 v[142:145], v218 offset:0x2000
	s_waitcnt lgkmcnt(4)
	v_mfma_f32_32x32x16_bf16 v[98:113], v[138:141], v[126:129], v[98:113]
	v_mfma_f32_32x32x16_bf16 v[82:97], v[166:169], v[126:129], v[82:97]
	ds_read_b128 v[126:129], v217 offset:0
	ds_read_b128 v[138:141], v217 offset:0x2000
	s_waitcnt lgkmcnt(4)
	v_mfma_f32_32x32x16_bf16 v[98:113], v[134:137], v[122:125], v[98:113]
	s_waitcnt lgkmcnt(2)
	v_mfma_f32_32x32x16_bf16 v[82:97], v[170:173], v[122:125], v[82:97]
	v_mfma_f32_32x32x16_bf16 v[98:113], v[130:133], v[118:121], v[98:113]
	s_waitcnt lgkmcnt(0)
	v_mfma_f32_32x32x16_bf16 v[82:97], v[142:145], v[118:121], v[82:97]
	v_mfma_f32_32x32x16_bf16 v[98:113], v[126:129], v[114:117], v[98:113]
	v_exp_f32_e32 v118, v69
	v_exp_f32_e32 v119, v70
	v_exp_f32_e32 v120, v71
	v_exp_f32_e32 v121, v72
	v_exp_f32_e32 v122, v73
	v_add_f32_e32 v0, v148, v146
	v_exp_f32_e32 v123, v74
	v_mfma_f32_32x32x16_bf16 v[82:97], v[138:141], v[114:117], v[82:97]
	v_exp_f32_e32 v115, v66
	v_exp_f32_e32 v116, v67
	v_exp_f32_e32 v117, v68
	v_add_f32_e32 v66, v159, v161
	v_add_f32_e32 v67, v149, v147
	v_add_f32_e32 v68, v158, v160
	v_exp_f32_e32 v124, v75
	v_exp_f32_e32 v125, v76
	v_exp_f32_e32 v126, v77
	v_add_f32_e32 v0, v150, v0
	v_add_f32_e32 v66, v157, v66
	v_add_f32_e32 v67, v151, v67
	v_add_f32_e32 v68, v156, v68
	v_exp_f32_e32 v127, v78
	v_exp_f32_e32 v128, v79
	v_exp_f32_e32 v129, v80
	v_exp_f32_e32 v81, v81
	v_add_f32_e32 v0, v152, v0
	v_add_f32_e32 v66, v155, v66
	v_add_f32_e32 v67, v153, v67
	v_add_f32_e32 v68, v154, v68
	v_add_f32_e32 v0, v0, v115
	v_add_f32_e32 v66, v66, v116
	v_add_f32_e32 v67, v67, v117
	v_add_f32_e32 v68, v68, v118
	v_add_f32_e32 v0, v119, v0
	v_add_f32_e32 v66, v120, v66
	v_add_f32_e32 v67, v121, v67
	v_add_f32_e32 v68, v122, v68
	v_add_f32_e32 v0, v123, v0
	v_add_f32_e32 v66, v124, v66
	v_add_f32_e32 v67, v125, v67
	v_add_f32_e32 v68, v126, v68
	v_add_f32_e32 v0, v127, v0
	v_add_f32_e32 v66, v128, v66
	v_add_f32_e32 v67, v129, v67
	v_add_f32_e32 v68, v81, v68
	v_add_f32_e32 v0, v0, v66
	v_add_f32_e32 v66, v67, v68
	v_add_f32_e32 v0, v0, v66
	v_mov_b32_e32 v114, v0
	v_cvt_pk_bf16_f32 v66, v146, v161
	v_cvt_pk_bf16_f32 v67, v147, v160
	v_cvt_pk_bf16_f32 v68, v148, v159
	s_nop 1
	v_permlane32_swap_b32_e32 v0, v114
	v_cvt_pk_bf16_f32 v69, v149, v158
	v_cvt_pk_bf16_f32 v70, v150, v157
	v_cvt_pk_bf16_f32 v71, v151, v156
	v_cvt_pk_bf16_f32 v72, v152, v155
	v_cvt_pk_bf16_f32 v73, v153, v154
	v_cvt_pk_bf16_f32 v74, v115, v116
	v_cvt_pk_bf16_f32 v75, v117, v118
	v_cvt_pk_bf16_f32 v76, v119, v120
	v_cvt_pk_bf16_f32 v77, v121, v122
	v_cvt_pk_bf16_f32 v78, v123, v124
	v_cvt_pk_bf16_f32 v79, v125, v126
	v_cvt_pk_bf16_f32 v80, v127, v128
	v_cvt_pk_bf16_f32 v81, v129, v81
	ds_read_b64_tr_b16 v[116:117], v199 offset:0
	ds_read_b64_tr_b16 v[118:119], v199 offset:0x800
	ds_read_b64_tr_b16 v[120:121], v199 offset:0x1000
	ds_read_b64_tr_b16 v[122:123], v199 offset:0x1800
	ds_read_b64_tr_b16 v[124:125], v199 offset:0x2000
	ds_read_b64_tr_b16 v[126:127], v199 offset:0x2800
	ds_read_b64_tr_b16 v[128:129], v199 offset:0x3000
	ds_read_b64_tr_b16 v[130:131], v199 offset:0x3800
	ds_read_b64_tr_b16 v[132:133], v199 offset:0x200
	ds_read_b64_tr_b16 v[134:135], v199 offset:0xa00
	s_waitcnt lgkmcnt(8)
; #define SBAR() __builtin_amdgcn_sched_barrier(0)
; template <bool FIRST>
; __device__ __forceinline__ void partialSM(f32x16& p0, f32x16& p1, float& mC, float& alpha) {
;   float mx_[4] = {p0[0], p0[1], p0[2], p0[3]};
; #pragma unroll
;   for (int r = 4; r < 16; ++r) mx_[r & 3] = fmaxf(mx_[r & 3], p0[r]);
; #pragma unroll
;   for (int r = 0; r < 16; ++r) mx_[r & 3] = fmaxf(mx_[r & 3], p1[r]);
;   float pmax = fmaxf(fmaxf(mx_[0], mx_[1]), fmaxf(mx_[2], mx_[3]));
;   { auto rr = __builtin_amdgcn_permlane32_swap(__float_as_uint(pmax), __float_as_uint(pmax), false, false);
;     pmax = fmaxf(__uint_as_float(rr[0]), __uint_as_float(rr[1])); }
;   if (!FIRST && __builtin_expect(__all(pmax <= THR2), 1)) { alpha = 1.f; }
; __device__ __forceinline__ void pv_d0(f32x16* o, int vb, bf16x8 pa0, bf16x8 pa1, bf16x8 pa2, bf16x8 pa3) {
;     ...
;   const s16x4 l0 = tr_read<v_rd_off(0, 0, 0)>(vb), h0 = tr_read<v_rd_off(0, 0, 1)>(vb);
;   const s16x4 l1 = tr_read<v_rd_off(0, 1, 0)>(vb), h1 = tr_read<v_rd_off(0, 1, 1)>(vb);
;   const s16x4 l2 = tr_read<v_rd_off(0, 2, 0)>(vb), h2 = tr_read<v_rd_off(0, 2, 1)>(vb);
;   const s16x4 l3 = tr_read<v_rd_off(0, 3, 0)>(vb), h3 = tr_read<v_rd_off(0, 3, 1)>(vb);
;   const s16x4 l4 = tr_read<v_rd_off(1, 0, 0)>(vb), h4 = tr_read<v_rd_off(1, 0, 1)>(vb);
;   asm volatile("s_waitcnt lgkmcnt(8)" ::: "memory"); SBAR();
;   o[0] = __builtin_amdgcn_mfma_f32_32x32x16_bf16(pa0, PK(l0, h0), o[0], 0, 0, 0);
;   const s16x4 l5 = tr_read<v_rd_off(1, 1, 0)>(vb), h5 = tr_read<v_rd_off(1, 1, 1)>(vb);
;   asm volatile("s_waitcnt lgkmcnt(8)" ::: "memory"); SBAR();
;   o[0] = __builtin_amdgcn_mfma_f32_32x32x16_bf16(pa1, PK(l1, h1), o[0], 0, 0, 0);
;   const s16x4 l6 = tr_read<v_rd_off(1, 2, 0)>(vb), h6 = tr_read<v_rd_off(1, 2, 1)>(vb);
;   asm volatile("s_waitcnt lgkmcnt(8)" ::: "memory"); SBAR();
;   o[0] = __builtin_amdgcn_mfma_f32_32x32x16_bf16(pa2, PK(l2, h2), o[0], 0, 0, 0);
;   const s16x4 l7 = tr_read<v_rd_off(1, 3, 0)>(vb), h7 = tr_read<v_rd_off(1, 3, 1)>(vb);
;   asm volatile("s_waitcnt lgkmcnt(8)" ::: "memory"); SBAR();
;   o[0] = __builtin_amdgcn_mfma_f32_32x32x16_bf16(pa3, PK(l3, h3), o[0], 0, 0, 0);
;   const s16x4 l8 = tr_read<v_rd_off(2, 0, 0)>(vb), h8 = tr_read<v_rd_off(2, 0, 1)>(vb);
;   asm volatile("s_waitcnt lgkmcnt(8)" ::: "memory"); SBAR();
;   o[1] = __builtin_amdgcn_mfma_f32_32x32x16_bf16(pa0, PK(l4, h4), o[1], 0, 0, 0);
	s_nop 0
	v_mfma_f32_32x32x16_bf16 v[2:17], v[66:69], v[116:119], v[2:17]
	ds_read_b64_tr_b16 v[116:117], v199 offset:0x1200
	ds_read_b64_tr_b16 v[118:119], v199 offset:0x1a00
	s_waitcnt lgkmcnt(8)
	v_mfma_f32_32x32x16_bf16 v[2:17], v[70:73], v[120:123], v[2:17]
	ds_read_b64_tr_b16 v[120:121], v199 offset:0x2200
	ds_read_b64_tr_b16 v[122:123], v199 offset:0x2a00
	s_waitcnt lgkmcnt(8)
	v_mfma_f32_32x32x16_bf16 v[2:17], v[74:77], v[124:127], v[2:17]
	ds_read_b64_tr_b16 v[124:125], v199 offset:0x3200
	ds_read_b64_tr_b16 v[126:127], v199 offset:0x3a00
	s_waitcnt lgkmcnt(8)
	v_mfma_f32_32x32x16_bf16 v[2:17], v[78:81], v[128:131], v[2:17]
	ds_read_b64_tr_b16 v[128:129], v199 offset:0x400
	ds_read_b64_tr_b16 v[130:131], v199 offset:0xc00
	s_waitcnt lgkmcnt(8)
	v_mfma_f32_32x32x16_bf16 v[50:65], v[66:69], v[132:135], v[50:65]
	ds_read_b64_tr_b16 v[132:133], v199 offset:0x1400
	ds_read_b64_tr_b16 v[134:135], v199 offset:0x1c00
	s_waitcnt lgkmcnt(8)
	v_mfma_f32_32x32x16_bf16 v[50:65], v[70:73], v[116:119], v[50:65]
	ds_read_b64_tr_b16 v[116:117], v199 offset:0x2400
	ds_read_b64_tr_b16 v[118:119], v199 offset:0x2c00
	s_waitcnt lgkmcnt(8)
	v_mfma_f32_32x32x16_bf16 v[50:65], v[74:77], v[120:123], v[50:65]
	ds_read_b64_tr_b16 v[120:121], v199 offset:0x3400
	ds_read_b64_tr_b16 v[122:123], v199 offset:0x3c00
	s_waitcnt lgkmcnt(8)
	v_mfma_f32_32x32x16_bf16 v[50:65], v[78:81], v[124:127], v[50:65]
	ds_read_b64_tr_b16 v[124:125], v199 offset:0x600
	ds_read_b64_tr_b16 v[126:127], v199 offset:0xe00
	s_waitcnt lgkmcnt(8)
	v_mfma_f32_32x32x16_bf16 v[34:49], v[66:69], v[128:131], v[34:49]
	ds_read_b64_tr_b16 v[128:129], v199 offset:0x1600
	ds_read_b64_tr_b16 v[130:131], v199 offset:0x1e00
	s_waitcnt lgkmcnt(8)
	v_mfma_f32_32x32x16_bf16 v[34:49], v[70:73], v[132:135], v[34:49]
	ds_read_b64_tr_b16 v[132:133], v199 offset:0x2600
	ds_read_b64_tr_b16 v[134:135], v199 offset:0x2e00
	s_waitcnt lgkmcnt(8)
	v_mfma_f32_32x32x16_bf16 v[34:49], v[74:77], v[116:119], v[34:49]
	ds_read_b64_tr_b16 v[116:117], v199 offset:0x3600
	ds_read_b64_tr_b16 v[118:119], v199 offset:0x3e00
	s_waitcnt lgkmcnt(8)
	v_mfma_f32_32x32x16_bf16 v[34:49], v[78:81], v[120:123], v[34:49]
	s_waitcnt lgkmcnt(6)
	v_mfma_f32_32x32x16_bf16 v[18:33], v[66:69], v[124:127], v[18:33]
	s_waitcnt lgkmcnt(4)
	v_mfma_f32_32x32x16_bf16 v[18:33], v[70:73], v[128:131], v[18:33]
	s_waitcnt lgkmcnt(2)
	v_mfma_f32_32x32x16_bf16 v[18:33], v[74:77], v[132:135], v[18:33]
	s_waitcnt lgkmcnt(0)
	v_max_f32_e32 v66, v102, v102
	v_max_f32_e32 v67, v98, v98
	v_max_f32_e32 v66, v67, v66
	v_max_f32_e32 v67, v103, v103
	v_max_f32_e32 v68, v99, v99
	v_max_f32_e32 v67, v68, v67
	v_max_f32_e32 v68, v105, v105
	v_max_f32_e32 v69, v101, v101
	v_max_f32_e32 v68, v69, v68
	v_max3_f32 v69, v100, v104, v108
	v_max3_f32 v68, v68, v109, v113
	v_max3_f32 v66, v66, v106, v110
	v_max3_f32 v67, v67, v107, v111
	v_max3_f32 v69, v69, v112, v84
	v_max3_f32 v68, v68, v85, v89
	v_max3_f32 v66, v66, v82, v86
	v_max3_f32 v67, v67, v83, v87
	v_max3_f32 v69, v69, v88, v92
	v_max3_f32 v68, v68, v93, v97
	v_mfma_f32_32x32x16_bf16 v[18:33], v[78:81], v[116:119], v[18:33]
	v_max3_f32 v66, v66, v90, v94
	v_max3_f32 v67, v67, v91, v95
	v_max3_f32 v68, v69, v96, v68
	v_max3_f32 v66, v66, v67, v68
	v_mov_b32_e32 v67, v66
	s_nop 1
	v_permlane32_swap_b32_e32 v66, v67
	v_max_f32_e32 v67, v67, v67
	v_max_f32_e32 v66, v66, v66
	v_max_f32_e32 v66, v66, v67
	v_cmp_ge_f32_e32 vcc, s48, v66
	s_cmp_lg_u64 vcc, exec
	v_mov_b32_e32 v115, 1.0
	s_cbranch_scc1 .LBB0_470

; template <bool EXP1 = true>
; __device__ __forceinline__ void finishSM(f32x16& p0, f32x16& p1, float alpha, float& l_reg, bf16x8& pa0, bf16x8& pa1, bf16x8& pa2, bf16x8& pa3) {
;   if constexpr (EXP1) {
; #pragma unroll
;   for (int r = 0; r < 16; ++r) p1[r] = __builtin_amdgcn_exp2f(p1[r]);
;   }
;   float sm_[4] = {p0[0], p0[1], p0[2], p0[3]};
; #pragma unroll
;   for (int r = 4; r < 16; ++r) sm_[r & 3] += p0[r];
; #pragma unroll
;   for (int r = 0; r < 16; ++r) sm_[r & 3] += p1[r];
;   float ps = (sm_[0] + sm_[1]) + (sm_[2] + sm_[3]);
;   { auto rr = __builtin_amdgcn_permlane32_swap(__float_as_uint(ps), __float_as_uint(ps), false, false);
;     ps = __uint_as_float(rr[0]) + __uint_as_float(rr[1]); }
;   l_reg = l_reg * alpha + ps;
;     ...
;   PK4(p0, 0, pa0); PK4(p0, 8, pa1); PK4(p1, 0, pa2); PK4(p1, 8, pa3);
;     ...
; }
; __device__ __forceinline__ void pv_d0(f32x16* o, int vb, bf16x8 pa0, bf16x8 pa1, bf16x8 pa2, bf16x8 pa3) {
;     ...
;   const s16x4 l0 = tr_read<v_rd_off(0, 0, 0)>(vb), h0 = tr_read<v_rd_off(0, 0, 1)>(vb);
;   const s16x4 l1 = tr_read<v_rd_off(0, 1, 0)>(vb), h1 = tr_read<v_rd_off(0, 1, 1)>(vb);
;   const s16x4 l2 = tr_read<v_rd_off(0, 2, 0)>(vb), h2 = tr_read<v_rd_off(0, 2, 1)>(vb);
;   const s16x4 l3 = tr_read<v_rd_off(0, 3, 0)>(vb), h3 = tr_read<v_rd_off(0, 3, 1)>(vb);
;   const s16x4 l4 = tr_read<v_rd_off(1, 0, 0)>(vb), h4 = tr_read<v_rd_off(1, 0, 1)>(vb);
;   asm volatile("s_waitcnt lgkmcnt(8)" ::: "memory"); SBAR();
;   o[0] = __builtin_amdgcn_mfma_f32_32x32x16_bf16(pa0, PK(l0, h0), o[0], 0, 0, 0);
;   const s16x4 l5 = tr_read<v_rd_off(1, 1, 0)>(vb), h5 = tr_read<v_rd_off(1, 1, 1)>(vb);
;   asm volatile("s_waitcnt lgkmcnt(8)" ::: "memory"); SBAR();
;   o[0] = __builtin_amdgcn_mfma_f32_32x32x16_bf16(pa1, PK(l1, h1), o[0], 0, 0, 0);
;   const s16x4 l6 = tr_read<v_rd_off(1, 2, 0)>(vb), h6 = tr_read<v_rd_off(1, 2, 1)>(vb);
;   asm volatile("s_waitcnt lgkmcnt(8)" ::: "memory"); SBAR();
;   o[0] = __builtin_amdgcn_mfma_f32_32x32x16_bf16(pa2, PK(l2, h2), o[0], 0, 0, 0);
;   const s16x4 l7 = tr_read<v_rd_off(1, 3, 0)>(vb), h7 = tr_read<v_rd_off(1, 3, 1)>(vb);
;   asm volatile("s_waitcnt lgkmcnt(8)" ::: "memory"); SBAR();
;   o[0] = __builtin_amdgcn_mfma_f32_32x32x16_bf16(pa3, PK(l3, h3), o[0], 0, 0, 0);
;   const s16x4 l8 = tr_read<v_rd_off(2, 0, 0)>(vb), h8 = tr_read<v_rd_off(2, 0, 1)>(vb);
;   asm volatile("s_waitcnt lgkmcnt(8)" ::: "memory"); SBAR();
.LBB0_442:
	v_exp_f32_e32 v66, v98
	v_exp_f32_e32 v81, v99
	v_exp_f32_e32 v67, v100
	v_exp_f32_e32 v80, v101
	v_exp_f32_e32 v68, v102
	v_exp_f32_e32 v79, v103
	v_exp_f32_e32 v69, v104
	v_exp_f32_e32 v78, v105
	v_exp_f32_e32 v70, v106
	v_exp_f32_e32 v77, v107
	v_exp_f32_e32 v71, v108
	v_exp_f32_e32 v76, v109
	v_exp_f32_e32 v72, v110
	v_exp_f32_e32 v75, v111
	v_exp_f32_e32 v73, v112
	v_exp_f32_e32 v74, v113
	v_exp_f32_e32 v98, v82
	v_exp_f32_e32 v99, v83
	v_exp_f32_e32 v84, v84
	v_exp_f32_e32 v85, v85
	v_exp_f32_e32 v86, v86
	v_exp_f32_e32 v87, v87
	v_exp_f32_e32 v88, v88
	v_exp_f32_e32 v89, v89
	v_add_f32_e32 v82, v68, v66
	v_add_f32_e32 v83, v79, v81
	v_add_f32_e32 v100, v69, v67
	v_add_f32_e32 v101, v78, v80
	v_exp_f32_e32 v90, v90
	v_exp_f32_e32 v91, v91
	v_exp_f32_e32 v92, v92
	v_exp_f32_e32 v93, v93
	v_add_f32_e32 v82, v70, v82
	v_add_f32_e32 v83, v77, v83
	v_add_f32_e32 v100, v71, v100
	v_add_f32_e32 v101, v76, v101
	v_exp_f32_e32 v94, v94
	v_exp_f32_e32 v95, v95
	v_exp_f32_e32 v96, v96
	v_exp_f32_e32 v97, v97
	v_add_f32_e32 v82, v72, v82
	v_add_f32_e32 v83, v75, v83
	v_add_f32_e32 v100, v73, v100
	v_add_f32_e32 v101, v74, v101
	v_add_f32_e32 v82, v98, v82
	v_add_f32_e32 v83, v99, v83
	v_add_f32_e32 v100, v100, v84
	v_add_f32_e32 v101, v101, v85
	v_add_f32_e32 v82, v86, v82
	v_add_f32_e32 v83, v87, v83
	v_add_f32_e32 v100, v88, v100
	v_add_f32_e32 v101, v89, v101
	v_add_f32_e32 v82, v90, v82
	v_add_f32_e32 v83, v91, v83
	v_add_f32_e32 v100, v92, v100
	v_add_f32_e32 v101, v93, v101
	v_add_f32_e32 v82, v94, v82
	v_add_f32_e32 v83, v95, v83
	v_add_f32_e32 v100, v96, v100
	v_add_f32_e32 v101, v97, v101
	v_add_f32_e32 v82, v83, v82
	v_add_f32_e32 v83, v100, v101
	v_add_f32_e32 v82, v83, v82
	v_mov_b32_e32 v83, v82
	s_nop 1
	v_permlane32_swap_b32_e32 v82, v83
	v_cvt_pk_bf16_f32 v66, v66, v81
	v_cvt_pk_bf16_f32 v67, v67, v80
	v_cvt_pk_bf16_f32 v68, v68, v79
	v_cvt_pk_bf16_f32 v69, v69, v78
	v_cvt_pk_bf16_f32 v70, v70, v77
	v_cvt_pk_bf16_f32 v71, v71, v76
	v_cvt_pk_bf16_f32 v72, v72, v75
	v_cvt_pk_bf16_f32 v73, v73, v74
	v_cvt_pk_bf16_f32 v74, v98, v99
	v_cvt_pk_bf16_f32 v75, v84, v85
	v_cvt_pk_bf16_f32 v76, v86, v87
	v_cvt_pk_bf16_f32 v77, v88, v89
	v_cvt_pk_bf16_f32 v78, v90, v91
	v_cvt_pk_bf16_f32 v79, v92, v93
	v_cvt_pk_bf16_f32 v80, v94, v95
	v_cvt_pk_bf16_f32 v81, v96, v97
	s_nop 0
	ds_read_b64_tr_b16 v[84:85], v198 offset:0
	ds_read_b64_tr_b16 v[86:87], v198 offset:0x800
	ds_read_b64_tr_b16 v[88:89], v198 offset:0x1000
	ds_read_b64_tr_b16 v[90:91], v198 offset:0x1800
	ds_read_b64_tr_b16 v[92:93], v198 offset:0x2000
	ds_read_b64_tr_b16 v[94:95], v198 offset:0x2800
	ds_read_b64_tr_b16 v[96:97], v198 offset:0x3000
	ds_read_b64_tr_b16 v[98:99], v198 offset:0x3800
	ds_read_b64_tr_b16 v[100:101], v198 offset:0x200
	ds_read_b64_tr_b16 v[102:103], v198 offset:0xa00
	s_waitcnt lgkmcnt(8)
	s_nop 0
	v_mfma_f32_32x32x16_bf16 v[2:17], v[66:69], v[84:87], v[2:17]
	ds_read_b64_tr_b16 v[84:85], v198 offset:0x1200
	ds_read_b64_tr_b16 v[86:87], v198 offset:0x1a00
	s_waitcnt lgkmcnt(8)
	v_mfma_f32_32x32x16_bf16 v[2:17], v[70:73], v[88:91], v[2:17]
	ds_read_b64_tr_b16 v[88:89], v198 offset:0x2200
	ds_read_b64_tr_b16 v[90:91], v198 offset:0x2a00
	s_waitcnt lgkmcnt(8)
	v_mfma_f32_32x32x16_bf16 v[2:17], v[74:77], v[92:95], v[2:17]
	ds_read_b64_tr_b16 v[92:93], v198 offset:0x3200
	ds_read_b64_tr_b16 v[94:95], v198 offset:0x3a00
	s_waitcnt lgkmcnt(8)
	v_mfma_f32_32x32x16_bf16 v[2:17], v[78:81], v[96:99], v[2:17]
	ds_read_b64_tr_b16 v[96:97], v198 offset:0x400
	ds_read_b64_tr_b16 v[98:99], v198 offset:0xc00
	s_waitcnt lgkmcnt(8)
	v_mfma_f32_32x32x16_bf16 v[50:65], v[66:69], v[100:103], v[50:65]
	ds_read_b64_tr_b16 v[100:101], v198 offset:0x1400
	ds_read_b64_tr_b16 v[102:103], v198 offset:0x1c00
	s_waitcnt lgkmcnt(8)
	v_mfma_f32_32x32x16_bf16 v[50:65], v[70:73], v[84:87], v[50:65]
	ds_read_b64_tr_b16 v[84:85], v198 offset:0x2400
	ds_read_b64_tr_b16 v[86:87], v198 offset:0x2c00
	s_waitcnt lgkmcnt(8)
	v_mfma_f32_32x32x16_bf16 v[50:65], v[74:77], v[88:91], v[50:65]
	ds_read_b64_tr_b16 v[88:89], v198 offset:0x3400
	ds_read_b64_tr_b16 v[90:91], v198 offset:0x3c00
	s_waitcnt lgkmcnt(8)
	v_mfma_f32_32x32x16_bf16 v[50:65], v[78:81], v[92:95], v[50:65]
	ds_read_b64_tr_b16 v[92:93], v198 offset:0x600
	ds_read_b64_tr_b16 v[94:95], v198 offset:0xe00
	s_waitcnt lgkmcnt(8)
	v_mfma_f32_32x32x16_bf16 v[34:49], v[66:69], v[96:99], v[34:49]
	ds_read_b64_tr_b16 v[96:97], v198 offset:0x1600
	ds_read_b64_tr_b16 v[98:99], v198 offset:0x1e00
	s_waitcnt lgkmcnt(8)
	v_mfma_f32_32x32x16_bf16 v[34:49], v[70:73], v[100:103], v[34:49]
	ds_read_b64_tr_b16 v[100:101], v198 offset:0x2600
	ds_read_b64_tr_b16 v[102:103], v198 offset:0x2e00
	s_waitcnt lgkmcnt(8)
	v_mfma_f32_32x32x16_bf16 v[34:49], v[74:77], v[84:87], v[34:49]
	ds_read_b64_tr_b16 v[84:85], v198 offset:0x3600
	ds_read_b64_tr_b16 v[86:87], v198 offset:0x3e00
	s_waitcnt lgkmcnt(8)
	v_mfma_f32_32x32x16_bf16 v[34:49], v[78:81], v[88:91], v[34:49]
	s_waitcnt lgkmcnt(6)
	v_mfma_f32_32x32x16_bf16 v[18:33], v[66:69], v[92:95], v[18:33]
	s_waitcnt lgkmcnt(4)
	v_mfma_f32_32x32x16_bf16 v[18:33], v[70:73], v[96:99], v[18:33]
	s_waitcnt lgkmcnt(2)
	v_mfma_f32_32x32x16_bf16 v[18:33], v[74:77], v[100:103], v[18:33]
	s_waitcnt lgkmcnt(0)
	v_mfma_f32_32x32x16_bf16 v[18:33], v[78:81], v[84:87], v[18:33]
	s_and_saveexec_b64 s[6:7], s[4:5]
	v_add_f32_e32 v0, v0, v114
	v_fmac_f32_e32 v0, v197, v226
	v_add_f32_e32 v66, v82, v83
	v_fmac_f32_e32 v66, v0, v115
	ds_write_b32 v183, v66
	s_or_b64 exec, exec, s[6:7]
	s_waitcnt lgkmcnt(0)
	s_mov_b64 s[4:5], 0
; __device__ __forceinline__ int lane_id_v() { int l; asm volatile("v_mbcnt_lo_u32_b32 %0, -1, 0\n\tv_mbcnt_hi_u32_b32 %0, -1, %0" : "=v"(l)); return l; }
; __device__ __forceinline__ int v_st(int k, int c) { const int kk = (k & ~0xC) | ((k & 4) << 1) | ((k & 8) >> 1); return ((kk >> 3) * 4 + (c >> 5)) * 512 + ((kk & 7) * 32 + (c & 31)) * 2; }
; __device__ __forceinline__ int v_rd_base(int lane) { return ((lane & 3) << 3) | (((lane >> 2) & 3) << 6) | (((lane >> 4) & 1) << 5) | (((lane >> 5) & 1) << 8); }
;     ...
;   int tid_ = wave0 * 64 + lane_id_v();
;   const int tid = tid_, wid = tid >> 6, lane = tid & 63, r32 = lane & 31, hi = lane >> 5;
;   char* V_lds = lds; char* K_lds = lds + LDS_K_OFF;
;   float* ws = (float*)(lds + LDS_WS_OFF) + wid * 64; float* li_l = ws; float* al_l = ws + 32;
;   float* tbl_l = (float*)(lds + LDS_TBL_OFF);
;   __syncthreads();
;   if constexpr (BIAS) { for (int i = tid; i < TBLN; i += 512) tbl_l[i] = tblg[i]; }
;   float mC = 0.f, l_reg = 0, nm_cur = 0.f; f32x16 o[4] = {}; f32x16 negm = {}; bf16x8 qr[NDQ - NQL];
;   const bf16_t* Qw = Qb + (long)(wid * QBLK + r32) * ldq + hi * 8;
;   char* qls = lds + LDS_Q_OFF + wid * 8192 + lane * 16;
; #pragma unroll
;   for (int d0 = 0; d0 < NDQ - NQL; ++d0) qr[d0] = *reinterpret_cast<const bf16x8*>(Qw + d0 * 16);
;     ...
;   const int sr = tid >> 4, sc = (tid & 15) * 8, vst0 = v_st(sr, sc), vst1 = v_st(32 + sr, sc);
;   const int sr8 = tid >> 3, sc8 = (tid & 7) * 8;
;   const int vb0 = (int)(uintptr_t)V_lds + v_rd_base(lane);
;   const int qlane = q0 + wid * QBLK + r32;
;   struct { bf16x8 vs0, vs1, ks0, ks1, ks2; } sr_[SDEPTH];
;   constexpr int SWM = (NDQ == 8) ? 15 : 7;
;     ...
;   f32x16 pA0, pA1, pB0, pB1; float alA, alB; bf16x8 pa0, pa1, pa2, pa3; const int NT = nkeys / KVBLK;
;   const int kb0 = (int)(uintptr_t)K_lds + r32 * ROWB + (((r32 & SWM) << 4) ^ (hi << 4));
;   const int qa0 = (int)(uintptr_t)qls;
;     ...
;   constexpr int SE = 0, SO = SDEPTH - 1;
;   SLOAD(SE, kbeg); asm volatile("s_waitcnt vmcnt(0)" ::: "memory"); SWRITE(0, SE); __syncthreads();
;   constexpr bool SLICED = (NDQ == 8 && NQL == 0 && BIAS == 1);
;   NEGM_UPD(kbeg); QKT(pA0, pA1, 0); BIASADD(pA0, pA1, kbeg); partialSM<true>(pA0, pA1, mC, alA);
.LBB0_445:
	s_and_b64 vcc, exec, s[4:5]
	s_cbranch_vccz .LBB0_418
	v_readlane_b32 s4, v254, 21
	v_mbcnt_lo_u32_b32 v22, -1, 0
	v_mbcnt_hi_u32_b32 v22, -1, v22
	v_mov_b64_e32 v[54:55], s[58:59]
	v_lshlrev_b32_e32 v24, 3, v22
	v_add_u32_e32 v23, s4, v22
	v_ashrrev_i32_e32 v50, 4, v23
	v_and_b32_e32 v0, 0x78, v24
	v_lshlrev_b32_e32 v0, 1, v0
	v_mad_i64_i32 v[2:3], s[4:5], v50, s55, v[54:55]
	v_lshl_add_u64 v[2:3], v[2:3], 0, v[0:1]
	s_waitcnt lgkmcnt(0)
	s_barrier
	v_add_u32_e32 v18, 32, v50
	global_load_dwordx4 v[2:5], v[2:3], off
	v_ashrrev_i32_e32 v51, 31, v50
	v_mad_i64_i32 v[6:7], s[4:5], v18, s55, v[54:55]
	v_ashrrev_i32_e32 v19, 31, v18
	v_lshlrev_b64 v[52:53], 9, v[50:51]
	v_lshlrev_b64 v[14:15], 9, v[18:19]
	v_ashrrev_i32_e32 v19, 1, v23
	s_movk_i32 s4, 0xffe0
	v_lshl_add_u64 v[10:11], s[50:51], 0, v[52:53]
	v_lshl_add_u64 v[14:15], s[50:51], 0, v[14:15]
	v_bfi_b32 v20, s4, v19, v22
	v_lshl_add_u64 v[6:7], v[6:7], 0, v[0:1]
	v_lshl_add_u64 v[10:11], v[10:11], 0, v[0:1]
	v_lshl_add_u64 v[14:15], v[14:15], 0, v[0:1]
	v_ashrrev_i32_e32 v21, 31, v20
	v_bfe_u32 v196, v22, 5, 1
	global_load_dwordx4 v[6:9], v[6:7], off
	v_lshlrev_b64 v[20:21], 10, v[20:21]
	global_load_dwordx4 v[10:13], v[10:11], off
	v_lshl_add_u64 v[20:21], s[56:57], 0, v[20:21]
	global_load_dwordx4 v[14:17], v[14:15], off
	v_lshlrev_b32_e32 v182, 4, v196
	v_mov_b32_e32 v183, v1
	v_lshl_add_u64 v[20:21], v[20:21], 0, v[182:183]
	global_load_dwordx4 v[158:161], v[20:21], off
	global_load_dwordx4 v[154:157], v[20:21], off offset:32
	global_load_dwordx4 v[150:153], v[20:21], off offset:64
	global_load_dwordx4 v[146:149], v[20:21], off offset:96
	global_load_dwordx4 v[142:145], v[20:21], off offset:128
	global_load_dwordx4 v[138:141], v[20:21], off offset:160
	global_load_dwordx4 v[134:137], v[20:21], off offset:192
	global_load_dwordx4 v[130:133], v[20:21], off offset:224
	v_and_b32_e32 v20, 0x3fffffc0, v23
	s_add_i32 s4, 0, 0x14000
	v_lshl_add_u32 v179, v20, 2, s4
	v_and_b32_e32 v180, 0xffffffe0, v19
	v_and_b32_e32 v19, 0xfffff0, v50
	v_lshlrev_b32_e32 v20, 1, v50
	v_and_or_b32 v19, v50, 8, v19
	v_lshrrev_b32_e32 v20, 1, v50
	v_lshrrev_b32_e32 v19, 1, v19
	v_bfe_u32 v21, v24, 5, 2
	v_and_b32_e32 v24, 3, v50
	v_or_b32_e32 v19, v19, v21
	v_and_or_b32 v20, v50, 4, v24
	v_and_b32_e32 v25, 0xfffff0, v18
	v_lshlrev_b32_e32 v26, 1, v18
	v_lshlrev_b32_e32 v19, 9, v19
	v_lshlrev_b32_e32 v20, 6, v20
	v_and_b32_e32 v24, 48, v0
	v_and_or_b32 v25, v18, 8, v25
	v_or3_b32 v19, v19, v20, v24
	v_lshrrev_b32_e32 v25, 1, v25
	v_or_b32_e32 v21, v25, v21
	v_add_u32_e32 v201, 0, v19
	v_lshlrev_b32_e32 v21, 9, v21
	s_waitcnt vmcnt(0)
	v_and_b32_e32 v51, 63, v22
	v_or3_b32 v20, v21, v20, v24
	v_lshlrev_b32_e32 v24, 4, v22
	s_cmp_lg_u32 0, -1
	v_lshlrev_b32_e32 v21, 3, v51
	v_and_b32_e32 v24, 0xc0, v24
	v_lshlrev_b32_e32 v25, 1, v22
	s_cselect_b32 s6, 0, 0
	s_add_i32 s4, 0, 0x8000
	v_and_b32_e32 v178, 31, v22
	v_and_or_b32 v24, v21, 24, v24
	v_and_b32_e32 v25, 32, v25
	v_and_b32_e32 v21, 0x100, v21
	s_cmp_lg_u32 s4, -1
	v_and_b32_e32 v87, 15, v22
	v_bitop3_b32 v22, v196, v22, 15 bitop3:0x78
	v_or3_b32 v86, v24, v25, v21
	v_lshlrev_b32_e32 v21, 8, v178
	s_cselect_b32 s4, s4, 0
	v_lshlrev_b32_e32 v22, 4, v22
	v_add_u32_e32 v207, 0, v20
	v_add3_u32 v200, v21, s4, v22
	v_xor_b32_e32 v210, 32, v200
	v_xor_b32_e32 v211, 64, v200
	s_mov_b32 s56, -1
	v_add_u32_e32 v199, s6, v86
	s_waitcnt vmcnt(11)
	ds_write_b128 v201, v[2:5]
	v_lshlrev_b32_e32 v2, 8, v50
	v_and_b32_e32 v3, 0xf0, v23
	v_bitop3_b32 v2, v0, v2, v3 bitop3:0xde
	v_add_u32_e32 v208, 0, v2
	v_lshlrev_b32_e32 v2, 8, v18
	v_bitop3_b32 v2, v2, v0, v3 bitop3:0xf6
	v_add_u32_e32 v209, 0, v2
	s_waitcnt vmcnt(10)
	ds_write_b128 v207, v[6:9]
	s_waitcnt vmcnt(9)
	ds_write_b128 v208, v[10:13] offset:32768
	s_waitcnt vmcnt(8)
	ds_write_b128 v209, v[14:17] offset:32768
	s_waitcnt lgkmcnt(0)
	s_barrier
	ds_read_b128 v[2:5], v200 offset:0
	ds_read_b128 v[18:21], v200 offset:0x2000
	ds_read_b128 v[56:59], v210 offset:0
	ds_read_b128 v[60:63], v210 offset:0x2000
	ds_read_b128 v[64:67], v211 offset:0
	ds_read_b128 v[68:71], v211 offset:0x2000
	s_waitcnt lgkmcnt(4)
	s_waitcnt vmcnt(7)
	v_mfma_f32_32x32x16_bf16 v[34:49], v[2:5], v[158:161], 0
	v_xor_b32_e32 v212, 0x60, v200
	ds_read_b128 v[72:75], v212 offset:0
	ds_read_b128 v[76:79], v212 offset:0x2000
	s_mov_b32 s13, s12
	s_waitcnt lgkmcnt(4)
	s_mov_b32 s14, s12
	s_mov_b32 s15, s12
	v_mfma_f32_32x32x16_bf16 v[18:33], v[18:21], v[158:161], 0
	s_mov_b32 s16, s12
	s_mov_b32 s17, s12
	s_mov_b32 s18, s12
	s_mov_b32 s19, s12
	s_mov_b32 s20, s12
	s_mov_b32 s21, s12
	s_mov_b32 s22, s12
	s_mov_b32 s23, s12
	s_mov_b32 s24, s12
	s_mov_b32 s25, s12
	s_mov_b32 s26, s12
	s_mov_b32 s27, s12
	v_mov_b64_e32 v[2:3], s[12:13]
	v_mov_b64_e32 v[4:5], s[14:15]
	v_mov_b64_e32 v[6:7], s[16:17]
	v_mov_b64_e32 v[8:9], s[18:19]
	v_mov_b64_e32 v[10:11], s[20:21]
	v_mov_b64_e32 v[12:13], s[22:23]
	v_mov_b64_e32 v[14:15], s[24:25]
	v_mov_b64_e32 v[16:17], s[26:27]
	s_waitcnt vmcnt(6)
	v_mfma_f32_32x32x16_bf16 v[34:49], v[56:59], v[154:157], v[34:49]
	v_xor_b32_e32 v213, 0x80, v200
	ds_read_b128 v[56:59], v213 offset:0
	v_mfma_f32_32x32x16_bf16 v[18:33], v[60:63], v[154:157], v[18:33]
	ds_read_b128 v[60:63], v213 offset:0x2000
	s_waitcnt lgkmcnt(4)
	s_waitcnt vmcnt(5)
	v_mfma_f32_32x32x16_bf16 v[34:49], v[64:67], v[150:153], v[34:49]
	v_xor_b32_e32 v214, 0xa0, v200
	ds_read_b128 v[64:67], v214 offset:0
	v_mfma_f32_32x32x16_bf16 v[18:33], v[68:71], v[150:153], v[18:33]
	ds_read_b128 v[68:71], v214 offset:0x2000
	s_waitcnt lgkmcnt(4)
	s_waitcnt vmcnt(4)
; template <bool FIRST>
; __device__ __forceinline__ void partialSM(f32x16& p0, f32x16& p1, float& mC, float& alpha) {
;   float mx_[4] = {p0[0], p0[1], p0[2], p0[3]};
; #pragma unroll
;   for (int r = 4; r < 16; ++r) mx_[r & 3] = fmaxf(mx_[r & 3], p0[r]);
; #pragma unroll
;   for (int r = 0; r < 16; ++r) mx_[r & 3] = fmaxf(mx_[r & 3], p1[r]);
;   float pmax = fmaxf(fmaxf(mx_[0], mx_[1]), fmaxf(mx_[2], mx_[3]));
;   { auto rr = __builtin_amdgcn_permlane32_swap(__float_as_uint(pmax), __float_as_uint(pmax), false, false);
;     pmax = fmaxf(__uint_as_float(rr[0]), __uint_as_float(rr[1])); }
;   if (!FIRST && __builtin_expect(__all(pmax <= THR2), 1)) { alpha = 1.f; }
;   else { const float delta = FIRST ? fmaxf(pmax, -200.f) : fmaxf(pmax, 0.f); alpha = FIRST ? 1.f : __builtin_amdgcn_exp2f(-delta); mC += delta;
; #pragma unroll
;     for (int r = 0; r < 16; ++r) p0[r] -= delta;
; #pragma unroll
;     for (int r = 0; r < 16; ++r) p1[r] -= delta; }
; #pragma unroll
;   for (int r = 0; r < 16; ++r) p0[r] = __builtin_amdgcn_exp2f(p0[r]);
; }
; __device__ __forceinline__ void qkt8_roll(f32x16& p0, f32x16& p1, const f32x16& negm, int kb, const bf16x8* qr) {
;   const int a0 = kb ^ (0 << 5); const bf16x8 x0 = lds_rd128<0>(a0), y0 = lds_rd128<8192>(a0);
;   const int a1 = kb ^ (1 << 5); const bf16x8 x1 = lds_rd128<0>(a1), y1 = lds_rd128<8192>(a1);
;   const int a2 = kb ^ (2 << 5); const bf16x8 x2 = lds_rd128<0>(a2), y2 = lds_rd128<8192>(a2);
;   asm volatile("s_waitcnt lgkmcnt(4)" ::: "memory"); SBAR_M();
;   p0 = __builtin_amdgcn_mfma_f32_32x32x16_bf16(x0, qr[0], negm, 0, 0, 0); p1 = __builtin_amdgcn_mfma_f32_32x32x16_bf16(y0, qr[0], negm, 0, 0, 0);
;   const int a3 = kb ^ (3 << 5); const bf16x8 x3 = lds_rd128<0>(a3), y3 = lds_rd128<8192>(a3);
;   asm volatile("s_waitcnt lgkmcnt(4)" ::: "memory"); SBAR_M();
;   p0 = __builtin_amdgcn_mfma_f32_32x32x16_bf16(x1, qr[1], p0, 0, 0, 0); p1 = __builtin_amdgcn_mfma_f32_32x32x16_bf16(y1, qr[1], p1, 0, 0, 0);
;   const int a4 = kb ^ (4 << 5); const bf16x8 x4 = lds_rd128<0>(a4), y4 = lds_rd128<8192>(a4);
;   asm volatile("s_waitcnt lgkmcnt(4)" ::: "memory"); SBAR_M();
;   p0 = __builtin_amdgcn_mfma_f32_32x32x16_bf16(x2, qr[2], p0, 0, 0, 0); p1 = __builtin_amdgcn_mfma_f32_32x32x16_bf16(y2, qr[2], p1, 0, 0, 0);
;   const int a5 = kb ^ (5 << 5); const bf16x8 x5 = lds_rd128<0>(a5), y5 = lds_rd128<8192>(a5);
	v_mfma_f32_32x32x16_bf16 v[34:49], v[72:75], v[146:149], v[34:49]
	v_xor_b32_e32 v215, 0xc0, v200
	ds_read_b128 v[72:75], v215 offset:0
	v_mfma_f32_32x32x16_bf16 v[18:33], v[76:79], v[146:149], v[18:33]
	ds_read_b128 v[76:79], v215 offset:0x2000
	s_waitcnt lgkmcnt(4)
	s_waitcnt vmcnt(3)
	v_mfma_f32_32x32x16_bf16 v[34:49], v[56:59], v[142:145], v[34:49]
	v_xor_b32_e32 v216, 0xe0, v200
	ds_read_b128 v[56:59], v216 offset:0
	v_mfma_f32_32x32x16_bf16 v[18:33], v[60:63], v[142:145], v[18:33]
	ds_read_b128 v[60:63], v216 offset:0x2000
	s_waitcnt lgkmcnt(4)
	s_waitcnt vmcnt(2)
	v_mfma_f32_32x32x16_bf16 v[34:49], v[64:67], v[138:141], v[34:49]
	s_waitcnt lgkmcnt(2)
	v_mfma_f32_32x32x16_bf16 v[18:33], v[68:71], v[138:141], v[18:33]
	s_waitcnt vmcnt(1)
	v_mfma_f32_32x32x16_bf16 v[34:49], v[72:75], v[134:137], v[34:49]
	s_waitcnt lgkmcnt(0)
	v_mfma_f32_32x32x16_bf16 v[18:33], v[76:79], v[134:137], v[18:33]
	v_add_u32_e32 v64, 64, v50
	v_add_u32_e32 v68, 0x60, v50
	v_mad_i64_i32 v[66:67], s[4:5], v64, s55, v[54:55]
	v_mad_i64_i32 v[54:55], s[4:5], v68, s55, v[54:55]
	v_ashrrev_i32_e32 v65, 31, v64
	v_ashrrev_i32_e32 v69, 31, v68
	s_waitcnt vmcnt(0)
	v_mfma_f32_32x32x16_bf16 v[34:49], v[56:59], v[130:133], v[34:49]
	v_lshl_add_u64 v[56:57], v[66:67], 0, v[0:1]
	v_lshl_add_u64 v[58:59], v[54:55], 0, v[0:1]
	global_load_dwordx4 v[54:57], v[56:57], off
	s_nop 0
	global_load_dwordx4 v[82:85], v[58:59], off
	v_lshlrev_b64 v[58:59], 9, v[64:65]
	v_lshl_add_u64 v[58:59], s[50:51], 0, v[58:59]
	v_lshl_add_u64 v[58:59], v[58:59], 0, v[0:1]
	s_mov_b32 s4, 0xc3480000
	v_mfma_f32_32x32x16_bf16 v[18:33], v[60:63], v[130:133], v[18:33]
	v_lshlrev_b64 v[60:61], 9, v[68:69]
	v_lshl_add_u64 v[60:61], s[50:51], 0, v[60:61]
	v_lshl_add_u64 v[62:63], v[60:61], 0, v[0:1]
	global_load_dwordx4 v[58:61], v[58:59], off
	s_nop 0
	global_load_dwordx4 v[62:65], v[62:63], off
	v_max_f32_e32 v66, v38, v38
	v_max_f32_e32 v0, v34, v34
	v_max_f32_e32 v0, v0, v66
	v_max_f32_e32 v66, v39, v39
	v_max_f32_e32 v67, v35, v35
	v_max_f32_e32 v66, v67, v66
	v_max_f32_e32 v67, v41, v41
	v_max_f32_e32 v68, v37, v37
	v_max_f32_e32 v67, v68, v67
	v_max3_f32 v68, v36, v40, v44
	v_max3_f32 v67, v67, v45, v49
	v_max3_f32 v0, v0, v42, v46
	v_max3_f32 v66, v66, v43, v47
	v_max3_f32 v68, v68, v48, v20
	v_max3_f32 v67, v67, v21, v25
	v_max3_f32 v0, v0, v18, v22
	v_max3_f32 v66, v66, v19, v23
	v_max3_f32 v68, v68, v24, v28
	v_max3_f32 v67, v67, v29, v33
	v_max3_f32 v0, v0, v26, v30
	v_max3_f32 v66, v66, v27, v31
	v_max3_f32 v67, v68, v32, v67
	v_max3_f32 v0, v0, v66, v67
	v_mov_b32_e32 v66, v0
	s_nop 1
	v_permlane32_swap_b32_e32 v0, v66
	v_max3_f32 v0, v0, v66, s4
	s_addk_i32 s6, 0x4000
	v_sub_f32_e32 v34, v34, v0
	v_sub_f32_e32 v35, v35, v0
	v_sub_f32_e32 v36, v36, v0
	v_sub_f32_e32 v37, v37, v0
	v_sub_f32_e32 v38, v38, v0
	v_sub_f32_e32 v39, v39, v0
	v_sub_f32_e32 v40, v40, v0
	v_sub_f32_e32 v41, v41, v0
	v_sub_f32_e32 v42, v42, v0
	v_sub_f32_e32 v43, v43, v0
	v_sub_f32_e32 v44, v44, v0
	v_sub_f32_e32 v45, v45, v0
	v_sub_f32_e32 v46, v46, v0
	v_sub_f32_e32 v47, v47, v0
	v_sub_f32_e32 v48, v48, v0
	v_sub_f32_e32 v49, v49, v0
	v_add_u32_e32 v198, s6, v86
	s_add_u32 s6, s42, s64
	v_exp_f32_e32 v176, v34
	v_exp_f32_e32 v188, v35
	v_exp_f32_e32 v163, v36
	v_exp_f32_e32 v177, v37
	v_exp_f32_e32 v164, v38
	v_exp_f32_e32 v175, v39
	v_exp_f32_e32 v165, v40
	v_exp_f32_e32 v174, v41
	v_exp_f32_e32 v166, v42
	v_exp_f32_e32 v173, v43
	v_exp_f32_e32 v167, v44
	v_exp_f32_e32 v172, v45
	v_exp_f32_e32 v168, v46
	v_exp_f32_e32 v171, v47
	v_exp_f32_e32 v169, v48
	v_exp_f32_e32 v170, v49
	s_addc_u32 s7, s43, 0
	v_sub_f32_e32 v67, v19, v0
	v_sub_f32_e32 v66, v18, v0
	s_waitcnt vmcnt(0)
	v_mov_b64_e32 v[18:19], s[6:7]
	v_sub_f32_e32 v81, v33, v0
	v_sub_f32_e32 v80, v32, v0
	v_sub_f32_e32 v79, v31, v0
	v_sub_f32_e32 v78, v30, v0
	v_sub_f32_e32 v77, v29, v0
	v_sub_f32_e32 v76, v28, v0
	v_sub_f32_e32 v75, v27, v0
	v_sub_f32_e32 v74, v26, v0
	v_sub_f32_e32 v73, v25, v0
	v_sub_f32_e32 v72, v24, v0
	v_sub_f32_e32 v71, v23, v0
	v_sub_f32_e32 v70, v22, v0
	v_sub_f32_e32 v69, v21, v0
	v_sub_f32_e32 v68, v20, v0
	s_waitcnt vmcnt(3)
	ds_write_b128 v201, v[54:57] offset:16384
	s_waitcnt vmcnt(2)
	ds_write_b128 v207, v[82:85] offset:16384
	s_waitcnt vmcnt(1)
	ds_write_b128 v208, v[58:61] offset:49152
	s_waitcnt vmcnt(0)
	ds_write_b128 v209, v[62:65] offset:49152
	v_add_u32_e32 v224, 0x4000, v200
	v_cmp_gt_u32_e64 s[4:5], 32, v51
	v_lshl_add_u64 v[184:185], s[6:7], 0, v[52:53]
	v_mad_i64_i32 v[186:187], s[6:7], v50, s55, v[18:19]
	v_mov_b32_e32 v231, 0
	v_mov_b64_e32 v[64:65], v[16:17]
	v_mov_b64_e32 v[48:49], v[16:17]
	v_mov_b64_e32 v[32:33], v[16:17]
	v_add_f32_e32 v228, 0, v0
	v_xor_b32_e32 v223, 32, v224
	v_xor_b32_e32 v222, 64, v224
	v_xor_b32_e32 v221, 0x60, v224
	v_xor_b32_e32 v220, 0x80, v224
	v_xor_b32_e32 v219, 0xa0, v224
	v_xor_b32_e32 v218, 0xc0, v224
	v_xor_b32_e32 v217, 0xe0, v224
	v_lshl_add_u32 v183, v178, 2, v179
	v_add_u32_e32 v181, v179, v182
	v_lshlrev_b32_e32 v0, 4, v87
	v_mov_b32_e32 v225, 1.0
	v_mov_b64_e32 v[62:63], v[14:15]
	v_mov_b64_e32 v[60:61], v[12:13]
	v_mov_b64_e32 v[58:59], v[10:11]
	v_mov_b64_e32 v[56:57], v[8:9]
	v_mov_b64_e32 v[54:55], v[6:7]
	v_mov_b64_e32 v[52:53], v[4:5]
	v_mov_b64_e32 v[50:51], v[2:3]
	v_mov_b64_e32 v[46:47], v[14:15]
	v_mov_b64_e32 v[44:45], v[12:13]
	v_mov_b64_e32 v[42:43], v[10:11]
	v_mov_b64_e32 v[40:41], v[8:9]
	v_mov_b64_e32 v[38:39], v[6:7]
	v_mov_b64_e32 v[36:37], v[4:5]
	v_mov_b64_e32 v[34:35], v[2:3]
	v_mov_b64_e32 v[30:31], v[14:15]
	v_mov_b64_e32 v[28:29], v[12:13]
	v_mov_b64_e32 v[26:27], v[10:11]
	v_mov_b64_e32 v[24:25], v[8:9]
	v_mov_b64_e32 v[22:23], v[6:7]
	v_mov_b64_e32 v[20:21], v[4:5]
	v_mov_b64_e32 v[18:19], v[2:3]
	v_mov_b32_e32 v197, 0
	v_mov_b32_e32 v82, 0
	v_mov_b32_e32 v83, v231
	v_mov_b32_e32 v84, v231
	v_mov_b32_e32 v85, v231
	v_mov_b32_e32 v86, v231
	v_mov_b32_e32 v87, v231
	v_mov_b32_e32 v88, v231
	v_mov_b32_e32 v89, v231
	v_mov_b32_e32 v90, v231
	v_mov_b32_e32 v91, v231
	v_mov_b32_e32 v92, v231
	v_mov_b32_e32 v93, v231
	v_mov_b32_e32 v94, v231
	v_mov_b32_e32 v95, v231
	v_mov_b32_e32 v96, v231
	v_mov_b32_e32 v97, v231
	s_waitcnt lgkmcnt(0)
	s_barrier
; template <bool EXP1 = true>
; __device__ __forceinline__ void finishSM(f32x16& p0, f32x16& p1, float alpha, float& l_reg, bf16x8& pa0, bf16x8& pa1, bf16x8& pa2, bf16x8& pa3) {
;   if constexpr (EXP1) {
; #pragma unroll
;   for (int r = 0; r < 16; ++r) p1[r] = __builtin_amdgcn_exp2f(p1[r]);
;   }
;   float sm_[4] = {p0[0], p0[1], p0[2], p0[3]};
; #pragma unroll
;   for (int r = 4; r < 16; ++r) sm_[r & 3] += p0[r];
; #pragma unroll
;   for (int r = 0; r < 16; ++r) sm_[r & 3] += p1[r];
;   float ps = (sm_[0] + sm_[1]) + (sm_[2] + sm_[3]);
;   { auto rr = __builtin_amdgcn_permlane32_swap(__float_as_uint(ps), __float_as_uint(ps), false, false);
;     ps = __uint_as_float(rr[0]) + __uint_as_float(rr[1]); }
;   l_reg = l_reg * alpha + ps;
;     ...
;   PK4(p0, 0, pa0); PK4(p0, 8, pa1); PK4(p1, 0, pa2); PK4(p1, 8, pa3);
;     ...
; }
; __device__ __forceinline__ void qkt8_roll(f32x16& p0, f32x16& p1, const f32x16& negm, int kb, const bf16x8* qr) {
;   const int a0 = kb ^ (0 << 5); const bf16x8 x0 = lds_rd128<0>(a0), y0 = lds_rd128<8192>(a0);
;   const int a1 = kb ^ (1 << 5); const bf16x8 x1 = lds_rd128<0>(a1), y1 = lds_rd128<8192>(a1);
;   const int a2 = kb ^ (2 << 5); const bf16x8 x2 = lds_rd128<0>(a2), y2 = lds_rd128<8192>(a2);
;   asm volatile("s_waitcnt lgkmcnt(4)" ::: "memory"); SBAR_M();
;   p0 = __builtin_amdgcn_mfma_f32_32x32x16_bf16(x0, qr[0], negm, 0, 0, 0); p1 = __builtin_amdgcn_mfma_f32_32x32x16_bf16(y0, qr[0], negm, 0, 0, 0);
;   const int a3 = kb ^ (3 << 5); const bf16x8 x3 = lds_rd128<0>(a3), y3 = lds_rd128<8192>(a3);
;   asm volatile("s_waitcnt lgkmcnt(4)" ::: "memory"); SBAR_M();
;   p0 = __builtin_amdgcn_mfma_f32_32x32x16_bf16(x1, qr[1], p0, 0, 0, 0); p1 = __builtin_amdgcn_mfma_f32_32x32x16_bf16(y1, qr[1], p1, 0, 0, 0);
;   const int a4 = kb ^ (4 << 5); const bf16x8 x4 = lds_rd128<0>(a4), y4 = lds_rd128<8192>(a4);
;   asm volatile("s_waitcnt lgkmcnt(4)" ::: "memory"); SBAR_M();
;   p0 = __builtin_amdgcn_mfma_f32_32x32x16_bf16(x2, qr[2], p0, 0, 0, 0); p1 = __builtin_amdgcn_mfma_f32_32x32x16_bf16(y2, qr[2], p1, 0, 0, 0);
;   const int a5 = kb ^ (5 << 5); const bf16x8 x5 = lds_rd128<0>(a5), y5 = lds_rd128<8192>(a5);
;   asm volatile("s_waitcnt lgkmcnt(4)" ::: "memory"); SBAR_M();
;   p0 = __builtin_amdgcn_mfma_f32_32x32x16_bf16(x3, qr[3], p0, 0, 0, 0); p1 = __builtin_amdgcn_mfma_f32_32x32x16_bf16(y3, qr[3], p1, 0, 0, 0);
.LBB0_447:
	v_cmp_neq_f32_e64 s[6:7], v231, -v228
	s_cmp_eq_u64 s[6:7], 0
	s_cselect_b64 s[6:7], -1, 0
	v_cndmask_b32_e64 v97, -v228, v97, s[6:7]
	v_cndmask_b32_e64 v96, -v228, v96, s[6:7]
	v_cndmask_b32_e64 v95, -v228, v95, s[6:7]
	v_cndmask_b32_e64 v94, -v228, v94, s[6:7]
	v_cndmask_b32_e64 v93, -v228, v93, s[6:7]
	v_cndmask_b32_e64 v92, -v228, v92, s[6:7]
	v_cndmask_b32_e64 v91, -v228, v91, s[6:7]
	v_cndmask_b32_e64 v90, -v228, v90, s[6:7]
	v_cndmask_b32_e64 v89, -v228, v89, s[6:7]
	v_cndmask_b32_e64 v88, -v228, v88, s[6:7]
	v_cndmask_b32_e64 v87, -v228, v87, s[6:7]
	v_cndmask_b32_e64 v86, -v228, v86, s[6:7]
	v_cndmask_b32_e64 v85, -v228, v85, s[6:7]
	v_cndmask_b32_e64 v84, -v228, v84, s[6:7]
	v_cndmask_b32_e64 v83, -v228, v83, s[6:7]
	v_cndmask_b32_e64 v82, -v228, v82, s[6:7]
	ds_read_b128 v[98:101], v224 offset:0
	ds_read_b128 v[232:235], v224 offset:0x2000
	ds_read_b128 v[236:239], v223 offset:0
	ds_read_b128 v[240:243], v223 offset:0x2000
	ds_read_b128 v[244:247], v222 offset:0
	ds_read_b128 v[248:251], v222 offset:0x2000
	s_waitcnt lgkmcnt(4)
	s_nop 1
	v_mfma_f32_32x32x16_bf16 v[114:129], v[98:101], v[158:161], v[82:97]
	v_mfma_f32_32x32x16_bf16 v[98:113], v[232:235], v[158:161], v[82:97]
	ds_read_b128 v[232:235], v221 offset:0
	ds_read_b128 v[190:193], v221 offset:0x2000
	s_waitcnt lgkmcnt(4)
	v_mfma_f32_32x32x16_bf16 v[114:129], v[236:239], v[154:157], v[114:129]
	ds_read_b128 v[236:239], v220 offset:0
	v_mfma_f32_32x32x16_bf16 v[98:113], v[240:243], v[154:157], v[98:113]
	ds_read_b128 v[240:243], v220 offset:0x2000
	s_waitcnt lgkmcnt(4)
	v_mfma_f32_32x32x16_bf16 v[114:129], v[244:247], v[150:153], v[114:129]
	ds_read_b128 v[244:247], v219 offset:0
	v_mfma_f32_32x32x16_bf16 v[98:113], v[248:251], v[150:153], v[98:113]
	ds_read_b128 v[248:251], v219 offset:0x2000
	s_waitcnt lgkmcnt(4)
	v_mfma_f32_32x32x16_bf16 v[114:129], v[232:235], v[146:149], v[114:129]
	v_mfma_f32_32x32x16_bf16 v[98:113], v[190:193], v[146:149], v[98:113]
	ds_read_b128 v[190:193], v218 offset:0
	ds_read_b128 v[232:235], v218 offset:0x2000
	s_waitcnt lgkmcnt(4)
	v_mfma_f32_32x32x16_bf16 v[114:129], v[236:239], v[142:145], v[114:129]
	ds_read_b128 v[236:239], v217 offset:0
	v_mfma_f32_32x32x16_bf16 v[98:113], v[240:243], v[142:145], v[98:113]
	ds_read_b128 v[240:243], v217 offset:0x2000
	s_waitcnt lgkmcnt(4)
	v_mfma_f32_32x32x16_bf16 v[114:129], v[244:247], v[138:141], v[114:129]
	s_waitcnt lgkmcnt(2)
	v_mfma_f32_32x32x16_bf16 v[98:113], v[248:251], v[138:141], v[98:113]
	v_mfma_f32_32x32x16_bf16 v[114:129], v[190:193], v[134:137], v[114:129]
	s_waitcnt lgkmcnt(0)
	v_mfma_f32_32x32x16_bf16 v[98:113], v[232:235], v[134:137], v[98:113]
	v_exp_f32_e32 v66, v66
	v_exp_f32_e32 v67, v67
	v_exp_f32_e32 v68, v68
	v_exp_f32_e32 v69, v69
	v_exp_f32_e32 v70, v70
	v_exp_f32_e32 v71, v71
	v_exp_f32_e32 v72, v72
	v_exp_f32_e32 v73, v73
	v_add_f32_e32 v162, v164, v176
	v_add_f32_e32 v189, v175, v188
	v_add_f32_e32 v190, v165, v163
	v_add_f32_e32 v191, v174, v177
	v_exp_f32_e32 v74, v74
	v_exp_f32_e32 v75, v75
	v_exp_f32_e32 v76, v76
	v_exp_f32_e32 v77, v77
	v_add_f32_e32 v162, v166, v162
	v_add_f32_e32 v189, v173, v189
	v_add_f32_e32 v190, v167, v190
	v_add_f32_e32 v191, v172, v191
	v_exp_f32_e32 v78, v78
	v_exp_f32_e32 v79, v79
	v_exp_f32_e32 v80, v80
	v_exp_f32_e32 v81, v81
	v_add_f32_e32 v162, v168, v162
	v_add_f32_e32 v189, v171, v189
	v_add_f32_e32 v190, v169, v190
	v_add_f32_e32 v191, v170, v191
	v_mfma_f32_32x32x16_bf16 v[114:129], v[236:239], v[130:133], v[114:129]
	v_add_f32_e32 v162, v66, v162
	v_add_f32_e32 v189, v67, v189
	v_add_f32_e32 v190, v68, v190
	v_add_f32_e32 v191, v69, v191
	v_add_f32_e32 v162, v70, v162
	v_add_f32_e32 v189, v71, v189
	v_add_f32_e32 v190, v72, v190
	v_mfma_f32_32x32x16_bf16 v[98:113], v[240:243], v[130:133], v[98:113]
	v_add_f32_e32 v191, v73, v191
	v_add_f32_e32 v162, v74, v162
	v_add_f32_e32 v189, v75, v189
	v_add_f32_e32 v190, v76, v190
	v_add_f32_e32 v191, v77, v191
	v_add_f32_e32 v162, v78, v162
	v_add_f32_e32 v189, v79, v189
	v_add_f32_e32 v190, v80, v190
	v_add_f32_e32 v191, v81, v191
	v_add_f32_e32 v162, v162, v189
	v_add_f32_e32 v189, v190, v191
	v_add_f32_e32 v226, v162, v189
	v_mov_b32_e32 v227, v226
	v_cvt_pk_bf16_f32 v162, v176, v188
	v_cvt_pk_bf16_f32 v163, v163, v177
	v_cvt_pk_bf16_f32 v164, v164, v175
	s_nop 1
	v_permlane32_swap_b32_e32 v226, v227
	v_cvt_pk_bf16_f32 v165, v165, v174
	v_cvt_pk_bf16_f32 v166, v166, v173
	v_cvt_pk_bf16_f32 v167, v167, v172
	v_cvt_pk_bf16_f32 v168, v168, v171
	v_cvt_pk_bf16_f32 v169, v169, v170
	v_cvt_pk_bf16_f32 v170, v66, v67
	v_cvt_pk_bf16_f32 v171, v68, v69
	v_cvt_pk_bf16_f32 v172, v70, v71
	v_cvt_pk_bf16_f32 v173, v72, v73
	v_cvt_pk_bf16_f32 v174, v74, v75
	v_cvt_pk_bf16_f32 v175, v76, v77
	v_cvt_pk_bf16_f32 v176, v78, v79
	v_cvt_pk_bf16_f32 v177, v80, v81
	v_lshl_add_u64 v[188:189], v[186:187], 0, v[0:1]
	v_add_co_u32_e32 v66, vcc, s78, v188
	v_lshl_add_u64 v[190:191], v[184:185], 0, v[0:1]
	s_nop 0
	v_addc_co_u32_e32 v67, vcc, 0, v189, vcc
	v_add_co_u32_e32 v70, vcc, s79, v188
	s_nop 1
	v_addc_co_u32_e32 v71, vcc, 0, v189, vcc
	v_add_co_u32_e32 v74, vcc, s70, v190
	global_load_dwordx4 v[66:69], v[66:67], off offset:2176
	s_nop 0
	global_load_dwordx4 v[70:73], v[70:71], off offset:2176
	v_addc_co_u32_e32 v75, vcc, 0, v191, vcc
	v_add_co_u32_e32 v78, vcc, s71, v190
	s_nop 1
	v_addc_co_u32_e32 v79, vcc, 0, v191, vcc
	global_load_dwordx4 v[74:77], v[74:75], off
	s_nop 0
	global_load_dwordx4 v[78:81], v[78:79], off
	ds_read_b64_tr_b16 v[232:233], v199 offset:0
	ds_read_b64_tr_b16 v[234:235], v199 offset:0x800
	ds_read_b64_tr_b16 v[236:237], v199 offset:0x1000
	ds_read_b64_tr_b16 v[238:239], v199 offset:0x1800
	ds_read_b64_tr_b16 v[240:241], v199 offset:0x2000
	ds_read_b64_tr_b16 v[242:243], v199 offset:0x2800
	ds_read_b64_tr_b16 v[244:245], v199 offset:0x3000
	ds_read_b64_tr_b16 v[246:247], v199 offset:0x3800
	ds_read_b64_tr_b16 v[248:249], v199 offset:0x200
	ds_read_b64_tr_b16 v[250:251], v199 offset:0xa00
	s_waitcnt lgkmcnt(8)
; #define SBAR() __builtin_amdgcn_sched_barrier(0)
; template <bool FIRST>
; __device__ __forceinline__ void partialSM(f32x16& p0, f32x16& p1, float& mC, float& alpha) {
;   float mx_[4] = {p0[0], p0[1], p0[2], p0[3]};
; #pragma unroll
;   for (int r = 4; r < 16; ++r) mx_[r & 3] = fmaxf(mx_[r & 3], p0[r]);
; #pragma unroll
;   for (int r = 0; r < 16; ++r) mx_[r & 3] = fmaxf(mx_[r & 3], p1[r]);
;   float pmax = fmaxf(fmaxf(mx_[0], mx_[1]), fmaxf(mx_[2], mx_[3]));
;   { auto rr = __builtin_amdgcn_permlane32_swap(__float_as_uint(pmax), __float_as_uint(pmax), false, false);
;     pmax = fmaxf(__uint_as_float(rr[0]), __uint_as_float(rr[1])); }
;   if (!FIRST && __builtin_expect(__all(pmax <= THR2), 1)) { alpha = 1.f; }
; __device__ __forceinline__ void pv_d0(f32x16* o, int vb, bf16x8 pa0, bf16x8 pa1, bf16x8 pa2, bf16x8 pa3) {
;     ...
;   const s16x4 l0 = tr_read<v_rd_off(0, 0, 0)>(vb), h0 = tr_read<v_rd_off(0, 0, 1)>(vb);
;   const s16x4 l1 = tr_read<v_rd_off(0, 1, 0)>(vb), h1 = tr_read<v_rd_off(0, 1, 1)>(vb);
;   const s16x4 l2 = tr_read<v_rd_off(0, 2, 0)>(vb), h2 = tr_read<v_rd_off(0, 2, 1)>(vb);
;   const s16x4 l3 = tr_read<v_rd_off(0, 3, 0)>(vb), h3 = tr_read<v_rd_off(0, 3, 1)>(vb);
;   const s16x4 l4 = tr_read<v_rd_off(1, 0, 0)>(vb), h4 = tr_read<v_rd_off(1, 0, 1)>(vb);
;   asm volatile("s_waitcnt lgkmcnt(8)" ::: "memory"); SBAR();
;   o[0] = __builtin_amdgcn_mfma_f32_32x32x16_bf16(pa0, PK(l0, h0), o[0], 0, 0, 0);
;   const s16x4 l5 = tr_read<v_rd_off(1, 1, 0)>(vb), h5 = tr_read<v_rd_off(1, 1, 1)>(vb);
;   asm volatile("s_waitcnt lgkmcnt(8)" ::: "memory"); SBAR();
;   o[0] = __builtin_amdgcn_mfma_f32_32x32x16_bf16(pa1, PK(l1, h1), o[0], 0, 0, 0);
;   const s16x4 l6 = tr_read<v_rd_off(1, 2, 0)>(vb), h6 = tr_read<v_rd_off(1, 2, 1)>(vb);
;   asm volatile("s_waitcnt lgkmcnt(8)" ::: "memory"); SBAR();
;   o[0] = __builtin_amdgcn_mfma_f32_32x32x16_bf16(pa2, PK(l2, h2), o[0], 0, 0, 0);
;   const s16x4 l7 = tr_read<v_rd_off(1, 3, 0)>(vb), h7 = tr_read<v_rd_off(1, 3, 1)>(vb);
;   asm volatile("s_waitcnt lgkmcnt(8)" ::: "memory"); SBAR();
;   o[0] = __builtin_amdgcn_mfma_f32_32x32x16_bf16(pa3, PK(l3, h3), o[0], 0, 0, 0);
;   const s16x4 l8 = tr_read<v_rd_off(2, 0, 0)>(vb), h8 = tr_read<v_rd_off(2, 0, 1)>(vb);
;   asm volatile("s_waitcnt lgkmcnt(8)" ::: "memory"); SBAR();
;   o[1] = __builtin_amdgcn_mfma_f32_32x32x16_bf16(pa0, PK(l4, h4), o[1], 0, 0, 0);
	s_nop 0
	v_mfma_f32_32x32x16_bf16 v[2:17], v[162:165], v[232:235], v[2:17]
	ds_read_b64_tr_b16 v[232:233], v199 offset:0x1200
	ds_read_b64_tr_b16 v[234:235], v199 offset:0x1a00
	s_waitcnt lgkmcnt(8)
	v_mfma_f32_32x32x16_bf16 v[2:17], v[166:169], v[236:239], v[2:17]
	ds_read_b64_tr_b16 v[236:237], v199 offset:0x2200
	ds_read_b64_tr_b16 v[238:239], v199 offset:0x2a00
	s_waitcnt lgkmcnt(8)
	v_mfma_f32_32x32x16_bf16 v[2:17], v[170:173], v[240:243], v[2:17]
	ds_read_b64_tr_b16 v[240:241], v199 offset:0x3200
	ds_read_b64_tr_b16 v[242:243], v199 offset:0x3a00
	s_waitcnt lgkmcnt(8)
	v_mfma_f32_32x32x16_bf16 v[2:17], v[174:177], v[244:247], v[2:17]
	ds_read_b64_tr_b16 v[244:245], v199 offset:0x400
	ds_read_b64_tr_b16 v[246:247], v199 offset:0xc00
	s_waitcnt lgkmcnt(8)
	v_mfma_f32_32x32x16_bf16 v[50:65], v[162:165], v[248:251], v[50:65]
	ds_read_b64_tr_b16 v[248:249], v199 offset:0x1400
	ds_read_b64_tr_b16 v[250:251], v199 offset:0x1c00
	s_waitcnt lgkmcnt(8)
	v_mfma_f32_32x32x16_bf16 v[50:65], v[166:169], v[232:235], v[50:65]
	ds_read_b64_tr_b16 v[232:233], v199 offset:0x2400
	ds_read_b64_tr_b16 v[234:235], v199 offset:0x2c00
	s_waitcnt lgkmcnt(8)
	v_mfma_f32_32x32x16_bf16 v[50:65], v[170:173], v[236:239], v[50:65]
	ds_read_b64_tr_b16 v[236:237], v199 offset:0x3400
	ds_read_b64_tr_b16 v[238:239], v199 offset:0x3c00
	s_waitcnt lgkmcnt(8)
	v_mfma_f32_32x32x16_bf16 v[50:65], v[174:177], v[240:243], v[50:65]
	ds_read_b64_tr_b16 v[240:241], v199 offset:0x600
	ds_read_b64_tr_b16 v[242:243], v199 offset:0xe00
	s_waitcnt lgkmcnt(8)
	v_mfma_f32_32x32x16_bf16 v[34:49], v[162:165], v[244:247], v[34:49]
	ds_read_b64_tr_b16 v[244:245], v199 offset:0x1600
	ds_read_b64_tr_b16 v[246:247], v199 offset:0x1e00
	s_waitcnt lgkmcnt(8)
	v_mfma_f32_32x32x16_bf16 v[34:49], v[166:169], v[248:251], v[34:49]
	ds_read_b64_tr_b16 v[248:249], v199 offset:0x2600
	ds_read_b64_tr_b16 v[250:251], v199 offset:0x2e00
	s_waitcnt lgkmcnt(8)
	v_mfma_f32_32x32x16_bf16 v[34:49], v[170:173], v[232:235], v[34:49]
	ds_read_b64_tr_b16 v[232:233], v199 offset:0x3600
	ds_read_b64_tr_b16 v[234:235], v199 offset:0x3e00
	s_waitcnt lgkmcnt(8)
	v_mfma_f32_32x32x16_bf16 v[34:49], v[174:177], v[236:239], v[34:49]
	s_waitcnt lgkmcnt(6)
	v_mfma_f32_32x32x16_bf16 v[18:33], v[162:165], v[240:243], v[18:33]
	s_waitcnt lgkmcnt(4)
	v_mfma_f32_32x32x16_bf16 v[18:33], v[166:169], v[244:247], v[18:33]
	s_waitcnt lgkmcnt(2)
	v_mfma_f32_32x32x16_bf16 v[18:33], v[170:173], v[248:251], v[18:33]
	s_waitcnt lgkmcnt(0)
	v_max_f32_e32 v162, v118, v118
	v_max_f32_e32 v163, v114, v114
	v_max_f32_e32 v162, v163, v162
	v_max_f32_e32 v163, v119, v119
	v_max_f32_e32 v164, v115, v115
	v_max_f32_e32 v163, v164, v163
	v_max_f32_e32 v164, v121, v121
	v_max_f32_e32 v165, v117, v117
	v_max_f32_e32 v164, v165, v164
	v_max3_f32 v165, v116, v120, v124
	v_max3_f32 v164, v164, v125, v129
	v_max3_f32 v162, v162, v122, v126
	v_max3_f32 v163, v163, v123, v127
	v_max3_f32 v165, v165, v128, v100
	v_max3_f32 v164, v164, v101, v105
	v_max3_f32 v162, v162, v98, v102
	v_max3_f32 v163, v163, v99, v103
	v_max3_f32 v165, v165, v104, v108
	v_max3_f32 v164, v164, v109, v113
	v_mfma_f32_32x32x16_bf16 v[18:33], v[174:177], v[232:235], v[18:33]
	v_max3_f32 v162, v162, v106, v110
	v_max3_f32 v163, v163, v107, v111
	v_max3_f32 v164, v165, v112, v164
	v_max3_f32 v162, v162, v163, v164
	v_mov_b32_e32 v163, v162
	s_nop 1
	v_permlane32_swap_b32_e32 v162, v163
	v_max_f32_e32 v163, v163, v163
	v_max_f32_e32 v162, v162, v162
	v_max_f32_e32 v162, v162, v163
	v_cmp_ge_f32_e32 vcc, s48, v162
	s_cmp_eq_u64 vcc, exec
	s_cbranch_scc0 .LBB0_461
	v_mov_b32_e32 v230, v228
	v_mov_b32_e32 v229, 1.0

; template <bool EXP1 = true>
; __device__ __forceinline__ void finishSM(f32x16& p0, f32x16& p1, float alpha, float& l_reg, bf16x8& pa0, bf16x8& pa1, bf16x8& pa2, bf16x8& pa3) {
;   if constexpr (EXP1) {
; #pragma unroll
;   for (int r = 0; r < 16; ++r) p1[r] = __builtin_amdgcn_exp2f(p1[r]);
;   }
;   float sm_[4] = {p0[0], p0[1], p0[2], p0[3]};
; #pragma unroll
;   for (int r = 4; r < 16; ++r) sm_[r & 3] += p0[r];
; #pragma unroll
;   for (int r = 0; r < 16; ++r) sm_[r & 3] += p1[r];
;   float ps = (sm_[0] + sm_[1]) + (sm_[2] + sm_[3]);
;   { auto rr = __builtin_amdgcn_permlane32_swap(__float_as_uint(ps), __float_as_uint(ps), false, false);
;     ps = __uint_as_float(rr[0]) + __uint_as_float(rr[1]); }
;   l_reg = l_reg * alpha + ps;
;     ...
;   PK4(p0, 0, pa0); PK4(p0, 8, pa1); PK4(p1, 0, pa2); PK4(p1, 8, pa3);
;     ...
; }
; __device__ __forceinline__ void qkt8_roll(f32x16& p0, f32x16& p1, const f32x16& negm, int kb, const bf16x8* qr) {
;   const int a0 = kb ^ (0 << 5); const bf16x8 x0 = lds_rd128<0>(a0), y0 = lds_rd128<8192>(a0);
;   const int a1 = kb ^ (1 << 5); const bf16x8 x1 = lds_rd128<0>(a1), y1 = lds_rd128<8192>(a1);
;   const int a2 = kb ^ (2 << 5); const bf16x8 x2 = lds_rd128<0>(a2), y2 = lds_rd128<8192>(a2);
;   asm volatile("s_waitcnt lgkmcnt(4)" ::: "memory"); SBAR_M();
;   p0 = __builtin_amdgcn_mfma_f32_32x32x16_bf16(x0, qr[0], negm, 0, 0, 0); p1 = __builtin_amdgcn_mfma_f32_32x32x16_bf16(y0, qr[0], negm, 0, 0, 0);
;   const int a3 = kb ^ (3 << 5); const bf16x8 x3 = lds_rd128<0>(a3), y3 = lds_rd128<8192>(a3);
;   asm volatile("s_waitcnt lgkmcnt(4)" ::: "memory"); SBAR_M();
;   p0 = __builtin_amdgcn_mfma_f32_32x32x16_bf16(x1, qr[1], p0, 0, 0, 0); p1 = __builtin_amdgcn_mfma_f32_32x32x16_bf16(y1, qr[1], p1, 0, 0, 0);
;   const int a4 = kb ^ (4 << 5); const bf16x8 x4 = lds_rd128<0>(a4), y4 = lds_rd128<8192>(a4);
;   asm volatile("s_waitcnt lgkmcnt(4)" ::: "memory"); SBAR_M();
;   p0 = __builtin_amdgcn_mfma_f32_32x32x16_bf16(x2, qr[2], p0, 0, 0, 0); p1 = __builtin_amdgcn_mfma_f32_32x32x16_bf16(y2, qr[2], p1, 0, 0, 0);
;   const int a5 = kb ^ (5 << 5); const bf16x8 x5 = lds_rd128<0>(a5), y5 = lds_rd128<8192>(a5);
;   asm volatile("s_waitcnt lgkmcnt(4)" ::: "memory"); SBAR_M();
;   p0 = __builtin_amdgcn_mfma_f32_32x32x16_bf16(x3, qr[3], p0, 0, 0, 0); p1 = __builtin_amdgcn_mfma_f32_32x32x16_bf16(y3, qr[3], p1, 0, 0, 0);
.LBB0_453:
	v_xor_b32_e32 v66, 0x80000000, v228
	v_cndmask_b32_e64 v231, v66, v231, s[6:7]
	v_exp_f32_e32 v162, v114
	v_exp_f32_e32 v163, v116
	v_cmp_neq_f32_e64 s[6:7], v231, -v230
	s_cmp_eq_u64 s[6:7], 0
	s_cselect_b64 s[6:7], -1, 0
	v_cndmask_b32_e64 v97, -v230, v97, s[6:7]
	v_cndmask_b32_e64 v96, -v230, v96, s[6:7]
	v_cndmask_b32_e64 v95, -v230, v95, s[6:7]
	v_cndmask_b32_e64 v94, -v230, v94, s[6:7]
	v_cndmask_b32_e64 v93, -v230, v93, s[6:7]
	v_cndmask_b32_e64 v92, -v230, v92, s[6:7]
	v_cndmask_b32_e64 v91, -v230, v91, s[6:7]
	v_cndmask_b32_e64 v90, -v230, v90, s[6:7]
	v_cndmask_b32_e64 v89, -v230, v89, s[6:7]
	v_cndmask_b32_e64 v88, -v230, v88, s[6:7]
	v_cndmask_b32_e64 v87, -v230, v87, s[6:7]
	v_cndmask_b32_e64 v86, -v230, v86, s[6:7]
	v_cndmask_b32_e64 v85, -v230, v85, s[6:7]
	v_cndmask_b32_e64 v84, -v230, v84, s[6:7]
	v_cndmask_b32_e64 v83, -v230, v83, s[6:7]
	v_cndmask_b32_e64 v82, -v230, v82, s[6:7]
	v_exp_f32_e32 v177, v115
	v_exp_f32_e32 v176, v117
	v_exp_f32_e32 v164, v118
	v_exp_f32_e32 v175, v119
	v_exp_f32_e32 v165, v120
	v_exp_f32_e32 v174, v121
	v_exp_f32_e32 v166, v122
	v_exp_f32_e32 v173, v123
	v_exp_f32_e32 v167, v124
	v_exp_f32_e32 v172, v125
	v_exp_f32_e32 v168, v126
	v_exp_f32_e32 v171, v127
	v_exp_f32_e32 v169, v128
	v_exp_f32_e32 v170, v129
	s_waitcnt lgkmcnt(0)
	s_barrier
	ds_read_b128 v[66:69], v200 offset:0
	ds_read_b128 v[232:235], v200 offset:0x2000
	ds_read_b128 v[236:239], v210 offset:0
	ds_read_b128 v[240:243], v210 offset:0x2000
	ds_read_b128 v[244:247], v211 offset:0
	ds_read_b128 v[248:251], v211 offset:0x2000
	s_waitcnt lgkmcnt(4)
	s_nop 0
	v_mfma_f32_32x32x16_bf16 v[114:129], v[66:69], v[158:161], v[82:97]
	v_mfma_f32_32x32x16_bf16 v[66:81], v[232:235], v[158:161], v[82:97]
	ds_read_b128 v[232:235], v212 offset:0
	ds_read_b128 v[192:195], v212 offset:0x2000
	s_waitcnt lgkmcnt(4)
	v_mfma_f32_32x32x16_bf16 v[114:129], v[236:239], v[154:157], v[114:129]
	ds_read_b128 v[236:239], v213 offset:0
	v_mfma_f32_32x32x16_bf16 v[66:81], v[240:243], v[154:157], v[66:81]
	ds_read_b128 v[240:243], v213 offset:0x2000
	s_waitcnt lgkmcnt(4)
	v_mfma_f32_32x32x16_bf16 v[114:129], v[244:247], v[150:153], v[114:129]
	ds_read_b128 v[244:247], v214 offset:0
	v_mfma_f32_32x32x16_bf16 v[66:81], v[248:251], v[150:153], v[66:81]
	ds_read_b128 v[248:251], v214 offset:0x2000
	s_waitcnt lgkmcnt(4)
	v_mfma_f32_32x32x16_bf16 v[114:129], v[232:235], v[146:149], v[114:129]
	v_mfma_f32_32x32x16_bf16 v[66:81], v[192:195], v[146:149], v[66:81]
	ds_read_b128 v[192:195], v215 offset:0
	ds_read_b128 v[232:235], v215 offset:0x2000
	s_waitcnt lgkmcnt(4)
	v_mfma_f32_32x32x16_bf16 v[114:129], v[236:239], v[142:145], v[114:129]
	ds_read_b128 v[236:239], v216 offset:0
	v_mfma_f32_32x32x16_bf16 v[66:81], v[240:243], v[142:145], v[66:81]
	ds_read_b128 v[240:243], v216 offset:0x2000
	s_waitcnt lgkmcnt(4)
	v_mfma_f32_32x32x16_bf16 v[114:129], v[244:247], v[138:141], v[114:129]
	s_waitcnt lgkmcnt(2)
	v_mfma_f32_32x32x16_bf16 v[66:81], v[248:251], v[138:141], v[66:81]
	v_mfma_f32_32x32x16_bf16 v[114:129], v[192:195], v[134:137], v[114:129]
	s_waitcnt lgkmcnt(0)
	v_mfma_f32_32x32x16_bf16 v[66:81], v[232:235], v[134:137], v[66:81]
	v_exp_f32_e32 v98, v98
	v_exp_f32_e32 v99, v99
	v_exp_f32_e32 v100, v100
	v_exp_f32_e32 v101, v101
	v_exp_f32_e32 v102, v102
	v_exp_f32_e32 v103, v103
	v_exp_f32_e32 v104, v104
	v_exp_f32_e32 v105, v105
	v_add_f32_e32 v192, v164, v162
	v_add_f32_e32 v193, v175, v177
	v_add_f32_e32 v194, v165, v163
	v_add_f32_e32 v195, v174, v176
	v_exp_f32_e32 v106, v106
	v_exp_f32_e32 v107, v107
	v_exp_f32_e32 v108, v108
	v_exp_f32_e32 v109, v109
	v_add_f32_e32 v192, v166, v192
	v_add_f32_e32 v193, v173, v193
	v_add_f32_e32 v194, v167, v194
	v_add_f32_e32 v195, v172, v195
	v_exp_f32_e32 v110, v110
	v_exp_f32_e32 v111, v111
	v_exp_f32_e32 v112, v112
	v_exp_f32_e32 v113, v113
	v_add_f32_e32 v192, v168, v192
	v_add_f32_e32 v193, v171, v193
	v_add_f32_e32 v194, v169, v194
	v_add_f32_e32 v195, v170, v195
	v_mfma_f32_32x32x16_bf16 v[114:129], v[236:239], v[130:133], v[114:129]
	v_add_f32_e32 v192, v98, v192
	v_add_f32_e32 v193, v193, v99
	v_add_f32_e32 v194, v194, v100
	v_add_f32_e32 v195, v195, v101
	v_add_f32_e32 v192, v102, v192
	v_add_f32_e32 v193, v103, v193
	v_add_f32_e32 v194, v104, v194
	v_mfma_f32_32x32x16_bf16 v[66:81], v[240:243], v[130:133], v[66:81]
	v_add_f32_e32 v195, v105, v195
	v_add_f32_e32 v192, v106, v192
	v_add_f32_e32 v193, v107, v193
	v_add_f32_e32 v194, v108, v194
	v_add_f32_e32 v195, v109, v195
	v_add_f32_e32 v192, v110, v192
	v_add_f32_e32 v193, v111, v193
	v_add_f32_e32 v194, v112, v194
	v_add_f32_e32 v195, v113, v195
	v_add_f32_e32 v192, v192, v193
	v_add_f32_e32 v193, v194, v195
	v_add_f32_e32 v232, v192, v193
	v_mov_b32_e32 v233, v232
	v_cvt_pk_bf16_f32 v162, v162, v177
	v_cvt_pk_bf16_f32 v163, v163, v176
	v_cvt_pk_bf16_f32 v164, v164, v175
	v_cvt_pk_bf16_f32 v165, v165, v174
	s_nop 1
	v_permlane32_swap_b32_e32 v232, v233
	v_cvt_pk_bf16_f32 v166, v166, v173
	v_cvt_pk_bf16_f32 v167, v167, v172
	v_cvt_pk_bf16_f32 v168, v168, v171
	v_cvt_pk_bf16_f32 v169, v169, v170
	v_cvt_pk_bf16_f32 v170, v98, v99
	v_cvt_pk_bf16_f32 v171, v100, v101
	v_cvt_pk_bf16_f32 v172, v102, v103
	v_cvt_pk_bf16_f32 v173, v104, v105
	v_cvt_pk_bf16_f32 v174, v106, v107
	v_cvt_pk_bf16_f32 v175, v108, v109
	v_cvt_pk_bf16_f32 v176, v110, v111
	v_cvt_pk_bf16_f32 v177, v112, v113
	s_nop 0
	v_add_co_u32_e32 v98, vcc, s72, v188
	s_nop 1
	v_addc_co_u32_e32 v99, vcc, 0, v189, vcc
	v_add_co_u32_e32 v102, vcc, s73, v188
	s_nop 1
	v_addc_co_u32_e32 v103, vcc, 0, v189, vcc
	v_add_co_u32_e32 v106, vcc, s33, v190
	global_load_dwordx4 v[98:101], v[98:99], off offset:2176
	s_nop 0
	global_load_dwordx4 v[102:105], v[102:103], off offset:2176
	v_addc_co_u32_e32 v107, vcc, 0, v191, vcc
	v_add_co_u32_e32 v110, vcc, s52, v190
	s_nop 1
	v_addc_co_u32_e32 v111, vcc, 0, v191, vcc
	global_load_dwordx4 v[106:109], v[106:107], off
	s_nop 0
	global_load_dwordx4 v[110:113], v[110:111], off
	ds_read_b64_tr_b16 v[188:189], v198 offset:0
	ds_read_b64_tr_b16 v[190:191], v198 offset:0x800
	ds_read_b64_tr_b16 v[192:193], v198 offset:0x1000
	ds_read_b64_tr_b16 v[194:195], v198 offset:0x1800
	ds_read_b64_tr_b16 v[234:235], v198 offset:0x2000
	ds_read_b64_tr_b16 v[236:237], v198 offset:0x2800
	ds_read_b64_tr_b16 v[238:239], v198 offset:0x3000
	ds_read_b64_tr_b16 v[240:241], v198 offset:0x3800
	ds_read_b64_tr_b16 v[242:243], v198 offset:0x200
	ds_read_b64_tr_b16 v[244:245], v198 offset:0xa00
	s_waitcnt lgkmcnt(8)
; #define SBAR() __builtin_amdgcn_sched_barrier(0)
; template <bool FIRST>
; __device__ __forceinline__ void partialSM(f32x16& p0, f32x16& p1, float& mC, float& alpha) {
;   float mx_[4] = {p0[0], p0[1], p0[2], p0[3]};
; #pragma unroll
;   for (int r = 4; r < 16; ++r) mx_[r & 3] = fmaxf(mx_[r & 3], p0[r]);
; #pragma unroll
;   for (int r = 0; r < 16; ++r) mx_[r & 3] = fmaxf(mx_[r & 3], p1[r]);
;   float pmax = fmaxf(fmaxf(mx_[0], mx_[1]), fmaxf(mx_[2], mx_[3]));
;   { auto rr = __builtin_amdgcn_permlane32_swap(__float_as_uint(pmax), __float_as_uint(pmax), false, false);
;     pmax = fmaxf(__uint_as_float(rr[0]), __uint_as_float(rr[1])); }
;   if (!FIRST && __builtin_expect(__all(pmax <= THR2), 1)) { alpha = 1.f; }
; __device__ __forceinline__ void pv_d0(f32x16* o, int vb, bf16x8 pa0, bf16x8 pa1, bf16x8 pa2, bf16x8 pa3) {
;     ...
;   const s16x4 l0 = tr_read<v_rd_off(0, 0, 0)>(vb), h0 = tr_read<v_rd_off(0, 0, 1)>(vb);
;   const s16x4 l1 = tr_read<v_rd_off(0, 1, 0)>(vb), h1 = tr_read<v_rd_off(0, 1, 1)>(vb);
;   const s16x4 l2 = tr_read<v_rd_off(0, 2, 0)>(vb), h2 = tr_read<v_rd_off(0, 2, 1)>(vb);
;   const s16x4 l3 = tr_read<v_rd_off(0, 3, 0)>(vb), h3 = tr_read<v_rd_off(0, 3, 1)>(vb);
;   const s16x4 l4 = tr_read<v_rd_off(1, 0, 0)>(vb), h4 = tr_read<v_rd_off(1, 0, 1)>(vb);
;   asm volatile("s_waitcnt lgkmcnt(8)" ::: "memory"); SBAR();
;   o[0] = __builtin_amdgcn_mfma_f32_32x32x16_bf16(pa0, PK(l0, h0), o[0], 0, 0, 0);
;   const s16x4 l5 = tr_read<v_rd_off(1, 1, 0)>(vb), h5 = tr_read<v_rd_off(1, 1, 1)>(vb);
;   asm volatile("s_waitcnt lgkmcnt(8)" ::: "memory"); SBAR();
;   o[0] = __builtin_amdgcn_mfma_f32_32x32x16_bf16(pa1, PK(l1, h1), o[0], 0, 0, 0);
;   const s16x4 l6 = tr_read<v_rd_off(1, 2, 0)>(vb), h6 = tr_read<v_rd_off(1, 2, 1)>(vb);
;   asm volatile("s_waitcnt lgkmcnt(8)" ::: "memory"); SBAR();
;   o[0] = __builtin_amdgcn_mfma_f32_32x32x16_bf16(pa2, PK(l2, h2), o[0], 0, 0, 0);
;   const s16x4 l7 = tr_read<v_rd_off(1, 3, 0)>(vb), h7 = tr_read<v_rd_off(1, 3, 1)>(vb);
;   asm volatile("s_waitcnt lgkmcnt(8)" ::: "memory"); SBAR();
;   o[0] = __builtin_amdgcn_mfma_f32_32x32x16_bf16(pa3, PK(l3, h3), o[0], 0, 0, 0);
;   const s16x4 l8 = tr_read<v_rd_off(2, 0, 0)>(vb), h8 = tr_read<v_rd_off(2, 0, 1)>(vb);
;   asm volatile("s_waitcnt lgkmcnt(8)" ::: "memory"); SBAR();
;   o[1] = __builtin_amdgcn_mfma_f32_32x32x16_bf16(pa0, PK(l4, h4), o[1], 0, 0, 0);
	s_nop 0
	v_mfma_f32_32x32x16_bf16 v[2:17], v[162:165], v[188:191], v[2:17]
	ds_read_b64_tr_b16 v[188:189], v198 offset:0x1200
	ds_read_b64_tr_b16 v[190:191], v198 offset:0x1a00
	s_waitcnt lgkmcnt(8)
	v_mfma_f32_32x32x16_bf16 v[2:17], v[166:169], v[192:195], v[2:17]
	ds_read_b64_tr_b16 v[192:193], v198 offset:0x2200
	ds_read_b64_tr_b16 v[194:195], v198 offset:0x2a00
	s_waitcnt lgkmcnt(8)
	v_mfma_f32_32x32x16_bf16 v[2:17], v[170:173], v[234:237], v[2:17]
	ds_read_b64_tr_b16 v[234:235], v198 offset:0x3200
	ds_read_b64_tr_b16 v[236:237], v198 offset:0x3a00
	s_waitcnt lgkmcnt(8)
	v_mfma_f32_32x32x16_bf16 v[2:17], v[174:177], v[238:241], v[2:17]
	ds_read_b64_tr_b16 v[238:239], v198 offset:0x400
	ds_read_b64_tr_b16 v[240:241], v198 offset:0xc00
	s_waitcnt lgkmcnt(8)
	v_mfma_f32_32x32x16_bf16 v[50:65], v[162:165], v[242:245], v[50:65]
	ds_read_b64_tr_b16 v[242:243], v198 offset:0x1400
	ds_read_b64_tr_b16 v[244:245], v198 offset:0x1c00
	s_waitcnt lgkmcnt(8)
	v_mfma_f32_32x32x16_bf16 v[50:65], v[166:169], v[188:191], v[50:65]
	ds_read_b64_tr_b16 v[188:189], v198 offset:0x2400
	ds_read_b64_tr_b16 v[190:191], v198 offset:0x2c00
	s_waitcnt lgkmcnt(8)
	v_mfma_f32_32x32x16_bf16 v[50:65], v[170:173], v[192:195], v[50:65]
	ds_read_b64_tr_b16 v[192:193], v198 offset:0x3400
	ds_read_b64_tr_b16 v[194:195], v198 offset:0x3c00
	s_waitcnt lgkmcnt(8)
	v_mfma_f32_32x32x16_bf16 v[50:65], v[174:177], v[234:237], v[50:65]
	ds_read_b64_tr_b16 v[234:235], v198 offset:0x600
	ds_read_b64_tr_b16 v[236:237], v198 offset:0xe00
	s_waitcnt lgkmcnt(8)
	v_mfma_f32_32x32x16_bf16 v[34:49], v[162:165], v[238:241], v[34:49]
	ds_read_b64_tr_b16 v[238:239], v198 offset:0x1600
	ds_read_b64_tr_b16 v[240:241], v198 offset:0x1e00
	s_waitcnt lgkmcnt(8)
	v_mfma_f32_32x32x16_bf16 v[34:49], v[166:169], v[242:245], v[34:49]
	ds_read_b64_tr_b16 v[242:243], v198 offset:0x2600
	ds_read_b64_tr_b16 v[244:245], v198 offset:0x2e00
	s_waitcnt lgkmcnt(8)
	v_mfma_f32_32x32x16_bf16 v[34:49], v[170:173], v[188:191], v[34:49]
	ds_read_b64_tr_b16 v[188:189], v198 offset:0x3600
	ds_read_b64_tr_b16 v[190:191], v198 offset:0x3e00
	s_waitcnt lgkmcnt(8)
	v_mfma_f32_32x32x16_bf16 v[34:49], v[174:177], v[192:195], v[34:49]
	s_waitcnt lgkmcnt(6)
	v_mfma_f32_32x32x16_bf16 v[18:33], v[162:165], v[234:237], v[18:33]
	s_waitcnt lgkmcnt(4)
	v_mfma_f32_32x32x16_bf16 v[18:33], v[166:169], v[238:241], v[18:33]
	s_waitcnt lgkmcnt(2)
	v_mfma_f32_32x32x16_bf16 v[18:33], v[170:173], v[242:245], v[18:33]
	s_waitcnt lgkmcnt(0)
	v_max_f32_e32 v162, v118, v118
	v_max_f32_e32 v163, v114, v114
	v_max_f32_e32 v162, v163, v162
	v_max_f32_e32 v163, v119, v119
	v_max_f32_e32 v164, v115, v115
	v_max_f32_e32 v163, v164, v163
	v_max_f32_e32 v164, v121, v121
	v_max_f32_e32 v165, v117, v117
	v_max_f32_e32 v164, v165, v164
	v_max3_f32 v165, v116, v120, v124
	v_max3_f32 v164, v164, v125, v129
	v_max3_f32 v162, v162, v122, v126
	v_max3_f32 v163, v163, v123, v127
	v_max3_f32 v165, v165, v128, v68
	v_max3_f32 v164, v164, v69, v73
	v_max3_f32 v162, v162, v66, v70
	v_max3_f32 v163, v163, v67, v71
	v_max3_f32 v165, v165, v72, v76
	v_max3_f32 v164, v164, v77, v81
	v_mfma_f32_32x32x16_bf16 v[18:33], v[174:177], v[188:191], v[18:33]
	v_max3_f32 v162, v162, v74, v78
	v_max3_f32 v163, v163, v75, v79
	v_max3_f32 v164, v165, v80, v164
	v_max3_f32 v162, v162, v163, v164
	v_mov_b32_e32 v163, v162
	s_nop 1
	v_permlane32_swap_b32_e32 v162, v163
	v_max_f32_e32 v163, v163, v163
	v_max_f32_e32 v162, v162, v162
	v_max_f32_e32 v163, v162, v163
	v_cmp_ge_f32_e32 vcc, s48, v163
	s_cmp_eq_u64 vcc, exec
	v_mov_b32_e32 v162, 1.0
	s_cbranch_scc0 .LBB0_462
	v_mov_b32_e32 v228, v230

; template <bool EXP1 = true>
; __device__ __forceinline__ void finishSM(f32x16& p0, f32x16& p1, float alpha, float& l_reg, bf16x8& pa0, bf16x8& pa1, bf16x8& pa2, bf16x8& pa3) {
;   if constexpr (EXP1) {
; #pragma unroll
;   for (int r = 0; r < 16; ++r) p1[r] = __builtin_amdgcn_exp2f(p1[r]);
;   }
;   float sm_[4] = {p0[0], p0[1], p0[2], p0[3]};
; #pragma unroll
;   for (int r = 4; r < 16; ++r) sm_[r & 3] += p0[r];
; #pragma unroll
;   for (int r = 0; r < 16; ++r) sm_[r & 3] += p1[r];
;   float ps = (sm_[0] + sm_[1]) + (sm_[2] + sm_[3]);
;   { auto rr = __builtin_amdgcn_permlane32_swap(__float_as_uint(ps), __float_as_uint(ps), false, false);
;     ps = __uint_as_float(rr[0]) + __uint_as_float(rr[1]); }
;   l_reg = l_reg * alpha + ps;
;     ...
;   PK4(p0, 0, pa0); PK4(p0, 8, pa1); PK4(p1, 0, pa2); PK4(p1, 8, pa3);
;     ...
; }
; __device__ __forceinline__ void qkt8_roll(f32x16& p0, f32x16& p1, const f32x16& negm, int kb, const bf16x8* qr) {
;   const int a0 = kb ^ (0 << 5); const bf16x8 x0 = lds_rd128<0>(a0), y0 = lds_rd128<8192>(a0);
;   const int a1 = kb ^ (1 << 5); const bf16x8 x1 = lds_rd128<0>(a1), y1 = lds_rd128<8192>(a1);
;   const int a2 = kb ^ (2 << 5); const bf16x8 x2 = lds_rd128<0>(a2), y2 = lds_rd128<8192>(a2);
;   asm volatile("s_waitcnt lgkmcnt(4)" ::: "memory"); SBAR_M();
;   p0 = __builtin_amdgcn_mfma_f32_32x32x16_bf16(x0, qr[0], negm, 0, 0, 0); p1 = __builtin_amdgcn_mfma_f32_32x32x16_bf16(y0, qr[0], negm, 0, 0, 0);
;   const int a3 = kb ^ (3 << 5); const bf16x8 x3 = lds_rd128<0>(a3), y3 = lds_rd128<8192>(a3);
;   asm volatile("s_waitcnt lgkmcnt(4)" ::: "memory"); SBAR_M();
;   p0 = __builtin_amdgcn_mfma_f32_32x32x16_bf16(x1, qr[1], p0, 0, 0, 0); p1 = __builtin_amdgcn_mfma_f32_32x32x16_bf16(y1, qr[1], p1, 0, 0, 0);
;   const int a4 = kb ^ (4 << 5); const bf16x8 x4 = lds_rd128<0>(a4), y4 = lds_rd128<8192>(a4);
;   asm volatile("s_waitcnt lgkmcnt(4)" ::: "memory"); SBAR_M();
;   p0 = __builtin_amdgcn_mfma_f32_32x32x16_bf16(x2, qr[2], p0, 0, 0, 0); p1 = __builtin_amdgcn_mfma_f32_32x32x16_bf16(y2, qr[2], p1, 0, 0, 0);
;   const int a5 = kb ^ (5 << 5); const bf16x8 x5 = lds_rd128<0>(a5), y5 = lds_rd128<8192>(a5);
;   asm volatile("s_waitcnt lgkmcnt(4)" ::: "memory"); SBAR_M();
;   p0 = __builtin_amdgcn_mfma_f32_32x32x16_bf16(x3, qr[3], p0, 0, 0, 0); p1 = __builtin_amdgcn_mfma_f32_32x32x16_bf16(y3, qr[3], p1, 0, 0, 0);
.LBB0_463:
	v_cmp_neq_f32_e64 s[6:7], v231, -v228
	s_cmp_eq_u64 s[6:7], 0
	s_cselect_b64 s[6:7], -1, 0
	v_cndmask_b32_e64 v97, -v228, v97, s[6:7]
	v_cndmask_b32_e64 v96, -v228, v96, s[6:7]
	v_cndmask_b32_e64 v95, -v228, v95, s[6:7]
	v_cndmask_b32_e64 v94, -v228, v94, s[6:7]
	v_cndmask_b32_e64 v93, -v228, v93, s[6:7]
	v_cndmask_b32_e64 v92, -v228, v92, s[6:7]
	v_cndmask_b32_e64 v91, -v228, v91, s[6:7]
	v_cndmask_b32_e64 v90, -v228, v90, s[6:7]
	v_cndmask_b32_e64 v89, -v228, v89, s[6:7]
	v_cndmask_b32_e64 v88, -v228, v88, s[6:7]
	v_cndmask_b32_e64 v87, -v228, v87, s[6:7]
	v_cndmask_b32_e64 v86, -v228, v86, s[6:7]
	v_cndmask_b32_e64 v85, -v228, v85, s[6:7]
	v_cndmask_b32_e64 v84, -v228, v84, s[6:7]
	v_cndmask_b32_e64 v83, -v228, v83, s[6:7]
	v_cndmask_b32_e64 v82, -v228, v82, s[6:7]
	ds_read_b128 v[114:117], v224 offset:0
	ds_read_b128 v[118:121], v224 offset:0x2000
	ds_read_b128 v[122:125], v223 offset:0
	ds_read_b128 v[126:129], v223 offset:0x2000
	ds_read_b128 v[184:187], v222 offset:0
	ds_read_b128 v[208:211], v222 offset:0x2000
	s_waitcnt lgkmcnt(4)
	s_nop 1
	v_mfma_f32_32x32x16_bf16 v[98:113], v[114:117], v[158:161], v[82:97]
	ds_read_b128 v[114:117], v221 offset:0
	v_mfma_f32_32x32x16_bf16 v[82:97], v[118:121], v[158:161], v[82:97]
	ds_read_b128 v[118:121], v221 offset:0x2000
	s_waitcnt lgkmcnt(4)
	v_mfma_f32_32x32x16_bf16 v[98:113], v[122:125], v[154:157], v[98:113]
	ds_read_b128 v[122:125], v220 offset:0
	v_mfma_f32_32x32x16_bf16 v[82:97], v[126:129], v[154:157], v[82:97]
	ds_read_b128 v[126:129], v220 offset:0x2000
	s_waitcnt lgkmcnt(4)
	v_mfma_f32_32x32x16_bf16 v[98:113], v[184:187], v[150:153], v[98:113]
	v_mfma_f32_32x32x16_bf16 v[82:97], v[208:211], v[150:153], v[82:97]
	ds_read_b128 v[150:153], v219 offset:0
	ds_read_b128 v[154:157], v219 offset:0x2000
	s_waitcnt lgkmcnt(4)
	v_mfma_f32_32x32x16_bf16 v[98:113], v[114:117], v[146:149], v[98:113]
	ds_read_b128 v[114:117], v218 offset:0
	v_mfma_f32_32x32x16_bf16 v[82:97], v[118:121], v[146:149], v[82:97]
	ds_read_b128 v[118:121], v218 offset:0x2000
	s_waitcnt lgkmcnt(4)
	v_mfma_f32_32x32x16_bf16 v[98:113], v[122:125], v[142:145], v[98:113]
	ds_read_b128 v[122:125], v217 offset:0
	v_mfma_f32_32x32x16_bf16 v[82:97], v[126:129], v[142:145], v[82:97]
	ds_read_b128 v[126:129], v217 offset:0x2000
	s_waitcnt lgkmcnt(4)
	v_mfma_f32_32x32x16_bf16 v[98:113], v[150:153], v[138:141], v[98:113]
	s_waitcnt lgkmcnt(2)
	v_mfma_f32_32x32x16_bf16 v[82:97], v[154:157], v[138:141], v[82:97]
	v_mfma_f32_32x32x16_bf16 v[98:113], v[114:117], v[134:137], v[98:113]
	s_waitcnt lgkmcnt(0)
	v_mfma_f32_32x32x16_bf16 v[82:97], v[118:121], v[134:137], v[82:97]
	v_exp_f32_e32 v115, v66
	v_exp_f32_e32 v116, v67
	v_exp_f32_e32 v117, v68
	v_exp_f32_e32 v118, v69
	v_mfma_f32_32x32x16_bf16 v[98:113], v[122:125], v[130:133], v[98:113]
	v_exp_f32_e32 v119, v70
	v_exp_f32_e32 v120, v71
	v_exp_f32_e32 v121, v72
	v_exp_f32_e32 v122, v73
	v_add_f32_e32 v0, v164, v176
	v_add_f32_e32 v66, v175, v188
	v_add_f32_e32 v67, v165, v163
	v_add_f32_e32 v68, v174, v177
	v_mfma_f32_32x32x16_bf16 v[82:97], v[126:129], v[130:133], v[82:97]
	v_exp_f32_e32 v123, v74
	v_exp_f32_e32 v124, v75
	v_exp_f32_e32 v125, v76
	v_exp_f32_e32 v126, v77
	v_add_f32_e32 v0, v166, v0
	v_add_f32_e32 v66, v173, v66
	v_add_f32_e32 v67, v167, v67
	v_add_f32_e32 v68, v172, v68
	v_exp_f32_e32 v127, v78
	v_exp_f32_e32 v128, v79
	v_exp_f32_e32 v129, v80
	v_exp_f32_e32 v81, v81
	v_add_f32_e32 v0, v168, v0
	v_add_f32_e32 v66, v171, v66
	v_add_f32_e32 v67, v169, v67
	v_add_f32_e32 v68, v170, v68
	v_add_f32_e32 v0, v0, v115
	v_add_f32_e32 v66, v66, v116
	v_add_f32_e32 v67, v67, v117
	v_add_f32_e32 v68, v68, v118
	v_add_f32_e32 v0, v119, v0
	v_add_f32_e32 v66, v120, v66
	v_add_f32_e32 v67, v121, v67
	v_add_f32_e32 v68, v122, v68
	v_add_f32_e32 v0, v123, v0
	v_add_f32_e32 v66, v124, v66
	v_add_f32_e32 v67, v125, v67
	v_add_f32_e32 v68, v126, v68
	v_add_f32_e32 v0, v127, v0
	v_add_f32_e32 v66, v128, v66
	v_add_f32_e32 v67, v129, v67
	v_add_f32_e32 v68, v81, v68
	v_add_f32_e32 v0, v0, v66
	v_add_f32_e32 v66, v67, v68
	v_add_f32_e32 v0, v0, v66
	v_mov_b32_e32 v114, v0
	v_cvt_pk_bf16_f32 v66, v176, v188
	v_cvt_pk_bf16_f32 v67, v163, v177
	v_cvt_pk_bf16_f32 v68, v164, v175
	s_nop 1
	v_permlane32_swap_b32_e32 v0, v114
	v_cvt_pk_bf16_f32 v69, v165, v174
	v_cvt_pk_bf16_f32 v70, v166, v173
	v_cvt_pk_bf16_f32 v71, v167, v172
	v_cvt_pk_bf16_f32 v72, v168, v171
	v_cvt_pk_bf16_f32 v73, v169, v170
	v_cvt_pk_bf16_f32 v74, v115, v116
	v_cvt_pk_bf16_f32 v75, v117, v118
	v_cvt_pk_bf16_f32 v76, v119, v120
	v_cvt_pk_bf16_f32 v77, v121, v122
	v_cvt_pk_bf16_f32 v78, v123, v124
	v_cvt_pk_bf16_f32 v79, v125, v126
	v_cvt_pk_bf16_f32 v80, v127, v128
	v_cvt_pk_bf16_f32 v81, v129, v81
	ds_read_b64_tr_b16 v[116:117], v199 offset:0
	ds_read_b64_tr_b16 v[118:119], v199 offset:0x800
	ds_read_b64_tr_b16 v[120:121], v199 offset:0x1000
	ds_read_b64_tr_b16 v[122:123], v199 offset:0x1800
	ds_read_b64_tr_b16 v[124:125], v199 offset:0x2000
	ds_read_b64_tr_b16 v[126:127], v199 offset:0x2800
	ds_read_b64_tr_b16 v[128:129], v199 offset:0x3000
	ds_read_b64_tr_b16 v[130:131], v199 offset:0x3800
	ds_read_b64_tr_b16 v[132:133], v199 offset:0x200
	ds_read_b64_tr_b16 v[134:135], v199 offset:0xa00
	s_waitcnt lgkmcnt(8)
; #define SBAR() __builtin_amdgcn_sched_barrier(0)
; template <bool FIRST>
; __device__ __forceinline__ void partialSM(f32x16& p0, f32x16& p1, float& mC, float& alpha) {
;   float mx_[4] = {p0[0], p0[1], p0[2], p0[3]};
; #pragma unroll
;   for (int r = 4; r < 16; ++r) mx_[r & 3] = fmaxf(mx_[r & 3], p0[r]);
; #pragma unroll
;   for (int r = 0; r < 16; ++r) mx_[r & 3] = fmaxf(mx_[r & 3], p1[r]);
;   float pmax = fmaxf(fmaxf(mx_[0], mx_[1]), fmaxf(mx_[2], mx_[3]));
;   { auto rr = __builtin_amdgcn_permlane32_swap(__float_as_uint(pmax), __float_as_uint(pmax), false, false);
;     pmax = fmaxf(__uint_as_float(rr[0]), __uint_as_float(rr[1])); }
;   if (!FIRST && __builtin_expect(__all(pmax <= THR2), 1)) { alpha = 1.f; }
; __device__ __forceinline__ void pv_d0(f32x16* o, int vb, bf16x8 pa0, bf16x8 pa1, bf16x8 pa2, bf16x8 pa3) {
;     ...
;   const s16x4 l0 = tr_read<v_rd_off(0, 0, 0)>(vb), h0 = tr_read<v_rd_off(0, 0, 1)>(vb);
;   const s16x4 l1 = tr_read<v_rd_off(0, 1, 0)>(vb), h1 = tr_read<v_rd_off(0, 1, 1)>(vb);
;   const s16x4 l2 = tr_read<v_rd_off(0, 2, 0)>(vb), h2 = tr_read<v_rd_off(0, 2, 1)>(vb);
;   const s16x4 l3 = tr_read<v_rd_off(0, 3, 0)>(vb), h3 = tr_read<v_rd_off(0, 3, 1)>(vb);
;   const s16x4 l4 = tr_read<v_rd_off(1, 0, 0)>(vb), h4 = tr_read<v_rd_off(1, 0, 1)>(vb);
;   asm volatile("s_waitcnt lgkmcnt(8)" ::: "memory"); SBAR();
;   o[0] = __builtin_amdgcn_mfma_f32_32x32x16_bf16(pa0, PK(l0, h0), o[0], 0, 0, 0);
;   const s16x4 l5 = tr_read<v_rd_off(1, 1, 0)>(vb), h5 = tr_read<v_rd_off(1, 1, 1)>(vb);
;   asm volatile("s_waitcnt lgkmcnt(8)" ::: "memory"); SBAR();
;   o[0] = __builtin_amdgcn_mfma_f32_32x32x16_bf16(pa1, PK(l1, h1), o[0], 0, 0, 0);
;   const s16x4 l6 = tr_read<v_rd_off(1, 2, 0)>(vb), h6 = tr_read<v_rd_off(1, 2, 1)>(vb);
;   asm volatile("s_waitcnt lgkmcnt(8)" ::: "memory"); SBAR();
;   o[0] = __builtin_amdgcn_mfma_f32_32x32x16_bf16(pa2, PK(l2, h2), o[0], 0, 0, 0);
;   const s16x4 l7 = tr_read<v_rd_off(1, 3, 0)>(vb), h7 = tr_read<v_rd_off(1, 3, 1)>(vb);
;   asm volatile("s_waitcnt lgkmcnt(8)" ::: "memory"); SBAR();
;   o[0] = __builtin_amdgcn_mfma_f32_32x32x16_bf16(pa3, PK(l3, h3), o[0], 0, 0, 0);
;   const s16x4 l8 = tr_read<v_rd_off(2, 0, 0)>(vb), h8 = tr_read<v_rd_off(2, 0, 1)>(vb);
;   asm volatile("s_waitcnt lgkmcnt(8)" ::: "memory"); SBAR();
;   o[1] = __builtin_amdgcn_mfma_f32_32x32x16_bf16(pa0, PK(l4, h4), o[1], 0, 0, 0);
	s_nop 0
	v_mfma_f32_32x32x16_bf16 v[2:17], v[66:69], v[116:119], v[2:17]
	ds_read_b64_tr_b16 v[116:117], v199 offset:0x1200
	ds_read_b64_tr_b16 v[118:119], v199 offset:0x1a00
	s_waitcnt lgkmcnt(8)
	v_mfma_f32_32x32x16_bf16 v[2:17], v[70:73], v[120:123], v[2:17]
	ds_read_b64_tr_b16 v[120:121], v199 offset:0x2200
	ds_read_b64_tr_b16 v[122:123], v199 offset:0x2a00
	s_waitcnt lgkmcnt(8)
	v_mfma_f32_32x32x16_bf16 v[2:17], v[74:77], v[124:127], v[2:17]
	ds_read_b64_tr_b16 v[124:125], v199 offset:0x3200
	ds_read_b64_tr_b16 v[126:127], v199 offset:0x3a00
	s_waitcnt lgkmcnt(8)
	v_mfma_f32_32x32x16_bf16 v[2:17], v[78:81], v[128:131], v[2:17]
	ds_read_b64_tr_b16 v[128:129], v199 offset:0x400
	ds_read_b64_tr_b16 v[130:131], v199 offset:0xc00
	s_waitcnt lgkmcnt(8)
	v_mfma_f32_32x32x16_bf16 v[50:65], v[66:69], v[132:135], v[50:65]
	ds_read_b64_tr_b16 v[132:133], v199 offset:0x1400
	ds_read_b64_tr_b16 v[134:135], v199 offset:0x1c00
	s_waitcnt lgkmcnt(8)
	v_mfma_f32_32x32x16_bf16 v[50:65], v[70:73], v[116:119], v[50:65]
	ds_read_b64_tr_b16 v[116:117], v199 offset:0x2400
	ds_read_b64_tr_b16 v[118:119], v199 offset:0x2c00
	s_waitcnt lgkmcnt(8)
	v_mfma_f32_32x32x16_bf16 v[50:65], v[74:77], v[120:123], v[50:65]
	ds_read_b64_tr_b16 v[120:121], v199 offset:0x3400
	ds_read_b64_tr_b16 v[122:123], v199 offset:0x3c00
	s_waitcnt lgkmcnt(8)
	v_mfma_f32_32x32x16_bf16 v[50:65], v[78:81], v[124:127], v[50:65]
	ds_read_b64_tr_b16 v[124:125], v199 offset:0x600
	ds_read_b64_tr_b16 v[126:127], v199 offset:0xe00
	s_waitcnt lgkmcnt(8)
	v_mfma_f32_32x32x16_bf16 v[34:49], v[66:69], v[128:131], v[34:49]
	ds_read_b64_tr_b16 v[128:129], v199 offset:0x1600
	ds_read_b64_tr_b16 v[130:131], v199 offset:0x1e00
	s_waitcnt lgkmcnt(8)
	v_mfma_f32_32x32x16_bf16 v[34:49], v[70:73], v[132:135], v[34:49]
	ds_read_b64_tr_b16 v[132:133], v199 offset:0x2600
	ds_read_b64_tr_b16 v[134:135], v199 offset:0x2e00
	s_waitcnt lgkmcnt(8)
	v_mfma_f32_32x32x16_bf16 v[34:49], v[74:77], v[116:119], v[34:49]
	ds_read_b64_tr_b16 v[116:117], v199 offset:0x3600
	ds_read_b64_tr_b16 v[118:119], v199 offset:0x3e00
	s_waitcnt lgkmcnt(8)
	v_mfma_f32_32x32x16_bf16 v[34:49], v[78:81], v[120:123], v[34:49]
	s_waitcnt lgkmcnt(6)
	v_mfma_f32_32x32x16_bf16 v[18:33], v[66:69], v[124:127], v[18:33]
	s_waitcnt lgkmcnt(4)
	v_mfma_f32_32x32x16_bf16 v[18:33], v[70:73], v[128:131], v[18:33]
	s_waitcnt lgkmcnt(2)
	v_mfma_f32_32x32x16_bf16 v[18:33], v[74:77], v[132:135], v[18:33]
	s_waitcnt lgkmcnt(0)
	v_max_f32_e32 v66, v102, v102
	v_max_f32_e32 v67, v98, v98
	v_max_f32_e32 v66, v67, v66
	v_max_f32_e32 v67, v103, v103
	v_max_f32_e32 v68, v99, v99
	v_max_f32_e32 v67, v68, v67
	v_max_f32_e32 v68, v105, v105
	v_max_f32_e32 v69, v101, v101
	v_max_f32_e32 v68, v69, v68
	v_max3_f32 v69, v100, v104, v108
	v_max3_f32 v68, v68, v109, v113
	v_max3_f32 v66, v66, v106, v110
	v_max3_f32 v67, v67, v107, v111
	v_max3_f32 v69, v69, v112, v84
	v_max3_f32 v68, v68, v85, v89
	v_max3_f32 v66, v66, v82, v86
	v_max3_f32 v67, v67, v83, v87
	v_max3_f32 v69, v69, v88, v92
	v_max3_f32 v68, v68, v93, v97
	v_mfma_f32_32x32x16_bf16 v[18:33], v[78:81], v[116:119], v[18:33]
	v_max3_f32 v66, v66, v90, v94
	v_max3_f32 v67, v67, v91, v95
	v_max3_f32 v68, v69, v96, v68
	v_max3_f32 v66, v66, v67, v68
	v_mov_b32_e32 v67, v66
	s_nop 1
	v_permlane32_swap_b32_e32 v66, v67
	v_max_f32_e32 v67, v67, v67
	v_max_f32_e32 v66, v66, v66
	v_max_f32_e32 v66, v66, v67
	v_cmp_ge_f32_e32 vcc, s48, v66
	s_cmp_lg_u64 vcc, exec
	v_mov_b32_e32 v115, 1.0
	s_cbranch_scc1 .LBB0_471

; template <bool EXP1 = true>
; __device__ __forceinline__ void finishSM(f32x16& p0, f32x16& p1, float alpha, float& l_reg, bf16x8& pa0, bf16x8& pa1, bf16x8& pa2, bf16x8& pa3) {
;   if constexpr (EXP1) {
; #pragma unroll
;   for (int r = 0; r < 16; ++r) p1[r] = __builtin_amdgcn_exp2f(p1[r]);
;   }
;   float sm_[4] = {p0[0], p0[1], p0[2], p0[3]};
; #pragma unroll
;   for (int r = 4; r < 16; ++r) sm_[r & 3] += p0[r];
; #pragma unroll
;   for (int r = 0; r < 16; ++r) sm_[r & 3] += p1[r];
;   float ps = (sm_[0] + sm_[1]) + (sm_[2] + sm_[3]);
;   { auto rr = __builtin_amdgcn_permlane32_swap(__float_as_uint(ps), __float_as_uint(ps), false, false);
;     ps = __uint_as_float(rr[0]) + __uint_as_float(rr[1]); }
;   l_reg = l_reg * alpha + ps;
;     ...
;   PK4(p0, 0, pa0); PK4(p0, 8, pa1); PK4(p1, 0, pa2); PK4(p1, 8, pa3);
;     ...
; }
; __device__ __forceinline__ void pv_d0(f32x16* o, int vb, bf16x8 pa0, bf16x8 pa1, bf16x8 pa2, bf16x8 pa3) {
;     ...
;   const s16x4 l0 = tr_read<v_rd_off(0, 0, 0)>(vb), h0 = tr_read<v_rd_off(0, 0, 1)>(vb);
;   const s16x4 l1 = tr_read<v_rd_off(0, 1, 0)>(vb), h1 = tr_read<v_rd_off(0, 1, 1)>(vb);
;   const s16x4 l2 = tr_read<v_rd_off(0, 2, 0)>(vb), h2 = tr_read<v_rd_off(0, 2, 1)>(vb);
;   const s16x4 l3 = tr_read<v_rd_off(0, 3, 0)>(vb), h3 = tr_read<v_rd_off(0, 3, 1)>(vb);
;   const s16x4 l4 = tr_read<v_rd_off(1, 0, 0)>(vb), h4 = tr_read<v_rd_off(1, 0, 1)>(vb);
;   asm volatile("s_waitcnt lgkmcnt(8)" ::: "memory"); SBAR();
;   o[0] = __builtin_amdgcn_mfma_f32_32x32x16_bf16(pa0, PK(l0, h0), o[0], 0, 0, 0);
;   const s16x4 l5 = tr_read<v_rd_off(1, 1, 0)>(vb), h5 = tr_read<v_rd_off(1, 1, 1)>(vb);
;   asm volatile("s_waitcnt lgkmcnt(8)" ::: "memory"); SBAR();
;   o[0] = __builtin_amdgcn_mfma_f32_32x32x16_bf16(pa1, PK(l1, h1), o[0], 0, 0, 0);
;   const s16x4 l6 = tr_read<v_rd_off(1, 2, 0)>(vb), h6 = tr_read<v_rd_off(1, 2, 1)>(vb);
;   asm volatile("s_waitcnt lgkmcnt(8)" ::: "memory"); SBAR();
;   o[0] = __builtin_amdgcn_mfma_f32_32x32x16_bf16(pa2, PK(l2, h2), o[0], 0, 0, 0);
;   const s16x4 l7 = tr_read<v_rd_off(1, 3, 0)>(vb), h7 = tr_read<v_rd_off(1, 3, 1)>(vb);
;   asm volatile("s_waitcnt lgkmcnt(8)" ::: "memory"); SBAR();
;   o[0] = __builtin_amdgcn_mfma_f32_32x32x16_bf16(pa3, PK(l3, h3), o[0], 0, 0, 0);
;   const s16x4 l8 = tr_read<v_rd_off(2, 0, 0)>(vb), h8 = tr_read<v_rd_off(2, 0, 1)>(vb);
;   asm volatile("s_waitcnt lgkmcnt(8)" ::: "memory"); SBAR();
.LBB0_468:
	v_exp_f32_e32 v66, v98
	v_exp_f32_e32 v81, v99
	v_exp_f32_e32 v67, v100
	v_exp_f32_e32 v80, v101
	v_exp_f32_e32 v68, v102
	v_exp_f32_e32 v79, v103
	v_exp_f32_e32 v69, v104
	v_exp_f32_e32 v78, v105
	v_exp_f32_e32 v70, v106
	v_exp_f32_e32 v77, v107
	v_exp_f32_e32 v71, v108
	v_exp_f32_e32 v76, v109
	v_exp_f32_e32 v72, v110
	v_exp_f32_e32 v75, v111
	v_exp_f32_e32 v73, v112
	v_exp_f32_e32 v74, v113
	v_exp_f32_e32 v98, v82
	v_exp_f32_e32 v99, v83
	v_exp_f32_e32 v84, v84
	v_exp_f32_e32 v85, v85
	v_exp_f32_e32 v86, v86
	v_exp_f32_e32 v87, v87
	v_exp_f32_e32 v88, v88
	v_exp_f32_e32 v89, v89
	v_add_f32_e32 v82, v68, v66
	v_add_f32_e32 v83, v79, v81
	v_add_f32_e32 v100, v69, v67
	v_add_f32_e32 v101, v78, v80
	v_exp_f32_e32 v90, v90
	v_exp_f32_e32 v91, v91
	v_exp_f32_e32 v92, v92
	v_exp_f32_e32 v93, v93
	v_add_f32_e32 v82, v70, v82
	v_add_f32_e32 v83, v77, v83
	v_add_f32_e32 v100, v71, v100
	v_add_f32_e32 v101, v76, v101
	v_exp_f32_e32 v94, v94
	v_exp_f32_e32 v95, v95
	v_exp_f32_e32 v96, v96
	v_exp_f32_e32 v97, v97
	v_add_f32_e32 v82, v72, v82
	v_add_f32_e32 v83, v75, v83
	v_add_f32_e32 v100, v73, v100
	v_add_f32_e32 v101, v74, v101
	v_add_f32_e32 v82, v98, v82
	v_add_f32_e32 v83, v99, v83
	v_add_f32_e32 v100, v100, v84
	v_add_f32_e32 v101, v101, v85
	v_add_f32_e32 v82, v86, v82
	v_add_f32_e32 v83, v87, v83
	v_add_f32_e32 v100, v88, v100
	v_add_f32_e32 v101, v89, v101
	v_add_f32_e32 v82, v90, v82
	v_add_f32_e32 v83, v91, v83
	v_add_f32_e32 v100, v92, v100
	v_add_f32_e32 v101, v93, v101
	v_add_f32_e32 v82, v94, v82
	v_add_f32_e32 v83, v95, v83
	v_add_f32_e32 v100, v96, v100
	v_add_f32_e32 v101, v97, v101
	v_add_f32_e32 v82, v83, v82
	v_add_f32_e32 v83, v100, v101
	v_add_f32_e32 v82, v83, v82
	v_mov_b32_e32 v83, v82
	s_nop 1
	v_permlane32_swap_b32_e32 v82, v83
	v_cvt_pk_bf16_f32 v66, v66, v81
	v_cvt_pk_bf16_f32 v67, v67, v80
	v_cvt_pk_bf16_f32 v68, v68, v79
	v_cvt_pk_bf16_f32 v69, v69, v78
	v_cvt_pk_bf16_f32 v70, v70, v77
	v_cvt_pk_bf16_f32 v71, v71, v76
	v_cvt_pk_bf16_f32 v72, v72, v75
	v_cvt_pk_bf16_f32 v73, v73, v74
	v_cvt_pk_bf16_f32 v74, v98, v99
	v_cvt_pk_bf16_f32 v75, v84, v85
	v_cvt_pk_bf16_f32 v76, v86, v87
	v_cvt_pk_bf16_f32 v77, v88, v89
	v_cvt_pk_bf16_f32 v78, v90, v91
	v_cvt_pk_bf16_f32 v79, v92, v93
	v_cvt_pk_bf16_f32 v80, v94, v95
	v_cvt_pk_bf16_f32 v81, v96, v97
	s_nop 0
	ds_read_b64_tr_b16 v[84:85], v198 offset:0
	ds_read_b64_tr_b16 v[86:87], v198 offset:0x800
	ds_read_b64_tr_b16 v[88:89], v198 offset:0x1000
	ds_read_b64_tr_b16 v[90:91], v198 offset:0x1800
	ds_read_b64_tr_b16 v[92:93], v198 offset:0x2000
	ds_read_b64_tr_b16 v[94:95], v198 offset:0x2800
	ds_read_b64_tr_b16 v[96:97], v198 offset:0x3000
	ds_read_b64_tr_b16 v[98:99], v198 offset:0x3800
	ds_read_b64_tr_b16 v[100:101], v198 offset:0x200
	ds_read_b64_tr_b16 v[102:103], v198 offset:0xa00
	s_waitcnt lgkmcnt(8)
	s_nop 0
	v_mfma_f32_32x32x16_bf16 v[2:17], v[66:69], v[84:87], v[2:17]
	ds_read_b64_tr_b16 v[84:85], v198 offset:0x1200
	ds_read_b64_tr_b16 v[86:87], v198 offset:0x1a00
	s_waitcnt lgkmcnt(8)
	v_mfma_f32_32x32x16_bf16 v[2:17], v[70:73], v[88:91], v[2:17]
	ds_read_b64_tr_b16 v[88:89], v198 offset:0x2200
	ds_read_b64_tr_b16 v[90:91], v198 offset:0x2a00
	s_waitcnt lgkmcnt(8)
	v_mfma_f32_32x32x16_bf16 v[2:17], v[74:77], v[92:95], v[2:17]
	ds_read_b64_tr_b16 v[92:93], v198 offset:0x3200
	ds_read_b64_tr_b16 v[94:95], v198 offset:0x3a00
	s_waitcnt lgkmcnt(8)
	v_mfma_f32_32x32x16_bf16 v[2:17], v[78:81], v[96:99], v[2:17]
	ds_read_b64_tr_b16 v[96:97], v198 offset:0x400
	ds_read_b64_tr_b16 v[98:99], v198 offset:0xc00
	s_waitcnt lgkmcnt(8)
	v_mfma_f32_32x32x16_bf16 v[50:65], v[66:69], v[100:103], v[50:65]
	ds_read_b64_tr_b16 v[100:101], v198 offset:0x1400
	ds_read_b64_tr_b16 v[102:103], v198 offset:0x1c00
	s_waitcnt lgkmcnt(8)
	v_mfma_f32_32x32x16_bf16 v[50:65], v[70:73], v[84:87], v[50:65]
	ds_read_b64_tr_b16 v[84:85], v198 offset:0x2400
	ds_read_b64_tr_b16 v[86:87], v198 offset:0x2c00
	s_waitcnt lgkmcnt(8)
	v_mfma_f32_32x32x16_bf16 v[50:65], v[74:77], v[88:91], v[50:65]
	ds_read_b64_tr_b16 v[88:89], v198 offset:0x3400
	ds_read_b64_tr_b16 v[90:91], v198 offset:0x3c00
	s_waitcnt lgkmcnt(8)
	v_mfma_f32_32x32x16_bf16 v[50:65], v[78:81], v[92:95], v[50:65]
	ds_read_b64_tr_b16 v[92:93], v198 offset:0x600
	ds_read_b64_tr_b16 v[94:95], v198 offset:0xe00
	s_waitcnt lgkmcnt(8)
	v_mfma_f32_32x32x16_bf16 v[34:49], v[66:69], v[96:99], v[34:49]
	ds_read_b64_tr_b16 v[96:97], v198 offset:0x1600
	ds_read_b64_tr_b16 v[98:99], v198 offset:0x1e00
	s_waitcnt lgkmcnt(8)
	v_mfma_f32_32x32x16_bf16 v[34:49], v[70:73], v[100:103], v[34:49]
	ds_read_b64_tr_b16 v[100:101], v198 offset:0x2600
	ds_read_b64_tr_b16 v[102:103], v198 offset:0x2e00
	s_waitcnt lgkmcnt(8)
	v_mfma_f32_32x32x16_bf16 v[34:49], v[74:77], v[84:87], v[34:49]
	ds_read_b64_tr_b16 v[84:85], v198 offset:0x3600
	ds_read_b64_tr_b16 v[86:87], v198 offset:0x3e00
	s_waitcnt lgkmcnt(8)
	v_mfma_f32_32x32x16_bf16 v[34:49], v[78:81], v[88:91], v[34:49]
	s_waitcnt lgkmcnt(6)
	v_mfma_f32_32x32x16_bf16 v[18:33], v[66:69], v[92:95], v[18:33]
	s_waitcnt lgkmcnt(4)
	v_mfma_f32_32x32x16_bf16 v[18:33], v[70:73], v[96:99], v[18:33]
	s_waitcnt lgkmcnt(2)
	v_mfma_f32_32x32x16_bf16 v[18:33], v[74:77], v[100:103], v[18:33]
	s_waitcnt lgkmcnt(0)
	v_mfma_f32_32x32x16_bf16 v[18:33], v[78:81], v[84:87], v[18:33]
	s_and_saveexec_b64 s[6:7], s[4:5]
	s_cbranch_execz .LBB0_417
	v_add_f32_e32 v0, v0, v114
	v_fmac_f32_e32 v0, v197, v162
	v_add_f32_e32 v66, v82, v83
	v_fmac_f32_e32 v66, v0, v115
	ds_write_b32 v183, v66
	s_branch .LBB0_417

; __device__ __forceinline__ int lane_id_v() { int l; asm volatile("v_mbcnt_lo_u32_b32 %0, -1, 0\n\tv_mbcnt_hi_u32_b32 %0, -1, %0" : "=v"(l)); return l; }
; __device__ __forceinline__ int v_st(int k, int c) { const int kk = (k & ~0xC) | ((k & 4) << 1) | ((k & 8) >> 1); return ((kk >> 3) * 4 + (c >> 5)) * 512 + ((kk & 7) * 32 + (c & 31)) * 2; }
; __device__ __forceinline__ int v_rd_base(int lane) { return ((lane & 3) << 3) | (((lane >> 2) & 3) << 6) | (((lane >> 4) & 1) << 5) | (((lane >> 5) & 1) << 8); }
;     ...
;   int tid_ = wave0 * 64 + lane_id_v();
;   const int tid = tid_, wid = tid >> 6, lane = tid & 63, r32 = lane & 31, hi = lane >> 5;
;   char* V_lds = lds; char* K_lds = lds + LDS_K_OFF;
;   float* ws = (float*)(lds + LDS_WS_OFF) + wid * 64; float* li_l = ws; float* al_l = ws + 32;
;   float* tbl_l = (float*)(lds + LDS_TBL_OFF);
;   __syncthreads();
;   if constexpr (BIAS) { for (int i = tid; i < TBLN; i += 512) tbl_l[i] = tblg[i]; }
;   float mC = 0.f, l_reg = 0, nm_cur = 0.f; f32x16 o[4] = {}; f32x16 negm = {}; bf16x8 qr[NDQ - NQL];
;   const bf16_t* Qw = Qb + (long)(wid * QBLK + r32) * ldq + hi * 8;
;   char* qls = lds + LDS_Q_OFF + wid * 8192 + lane * 16;
; #pragma unroll
;   for (int d0 = 0; d0 < NDQ - NQL; ++d0) qr[d0] = *reinterpret_cast<const bf16x8*>(Qw + d0 * 16);
;     ...
;   const int sr = tid >> 4, sc = (tid & 15) * 8, vst0 = v_st(sr, sc), vst1 = v_st(32 + sr, sc);
;   const int sr8 = tid >> 3, sc8 = (tid & 7) * 8;
;   const int vb0 = (int)(uintptr_t)V_lds + v_rd_base(lane);
;   const int qlane = q0 + wid * QBLK + r32;
;   struct { bf16x8 vs0, vs1, ks0, ks1, ks2; } sr_[SDEPTH];
;   constexpr int SWM = (NDQ == 8) ? 15 : 7;
;     ...
;   f32x16 pA0, pA1, pB0, pB1; float alA, alB; bf16x8 pa0, pa1, pa2, pa3; const int NT = nkeys / KVBLK;
;   const int kb0 = (int)(uintptr_t)K_lds + r32 * ROWB + (((r32 & SWM) << 4) ^ (hi << 4));
;   const int qa0 = (int)(uintptr_t)qls;
;     ...
;   constexpr int SE = 0, SO = SDEPTH - 1;
;   SLOAD(SE, kbeg); asm volatile("s_waitcnt vmcnt(0)" ::: "memory"); SWRITE(0, SE); __syncthreads();
.LBB0_482:
	s_or_b64 exec, exec, s[4:5]
	s_add_i32 s27, s25, 0xfffffc00
	s_mul_i32 s5, s22, 0x2800
	s_mul_hi_i32 s4, s22, 0x2800
	s_add_u32 s23, s42, s5
	s_addc_u32 s24, s43, s4
	s_lshl_b32 s8, s26, 8
	s_add_u32 s4, s23, s8
	s_addc_u32 s5, s24, 0
	s_add_u32 s4, s4, 0x1c801a80
	s_addc_u32 s5, s5, 0
	v_ashrrev_i32_e32 v35, 1, v34
	s_movk_i32 s10, 0xffe0
	v_bfe_u32 v208, v36, 5, 1
	v_bfi_b32 v0, s10, v35, v36
	v_mov_b64_e32 v[2:3], s[4:5]
	v_mad_i64_i32 v[2:3], s[4:5], v0, s55, v[2:3]
	v_lshlrev_b32_e32 v196, 4, v208
	v_mov_b32_e32 v197, v1
	v_lshl_add_u64 v[2:3], v[2:3], 0, v[196:197]
	v_ashrrev_i32_e32 v212, 4, v34
	global_load_dwordx4 v[142:145], v[2:3], off
	global_load_dwordx4 v[138:141], v[2:3], off offset:32
	global_load_dwordx4 v[134:137], v[2:3], off offset:64
	global_load_dwordx4 v[130:133], v[2:3], off offset:96
	global_load_dwordx4 v[126:129], v[2:3], off offset:128
	global_load_dwordx4 v[122:125], v[2:3], off offset:160
	global_load_dwordx4 v[118:121], v[2:3], off offset:192
	global_load_dwordx4 v[114:117], v[2:3], off offset:224
	v_and_b32_e32 v3, 0xfffff0, v212
	v_lshlrev_b32_e32 v4, 1, v212
	v_lshlrev_b32_e32 v0, 3, v36
	v_and_or_b32 v3, v212, 8, v3
	v_lshrrev_b32_e32 v3, 1, v3
	v_bfe_u32 v5, v0, 5, 2
	v_and_b32_e32 v2, 0x78, v0
	v_or_b32_e32 v0, v3, v5
	v_lshrrev_b32_e32 v4, 1, v212
	v_lshlrev_b32_e32 v3, 9, v0
	v_and_b32_e32 v0, 3, v212
	v_and_or_b32 v0, v212, 4, v0
	v_lshlrev_b32_e32 v4, 6, v0
	v_lshlrev_b32_e32 v0, 1, v2
	v_and_b32_e32 v2, 48, v0
	v_add_u32_e32 v19, 32, v212
	v_or3_b32 v18, v3, v4, v2
	v_and_b32_e32 v3, 0xfffff0, v19
	v_lshlrev_b32_e32 v6, 1, v19
	s_add_u32 s6, s13, s8
	v_and_or_b32 v3, v19, 8, v3
	s_addc_u32 s7, s14, 0
	v_lshrrev_b32_e32 v3, 1, v3
	s_add_u32 s8, s15, s8
	v_or_b32_e32 v3, v3, v5
	s_addc_u32 s9, s16, 0
	v_and_b32_e32 v207, 31, v36
	v_lshlrev_b32_e32 v3, 9, v3
	s_add_i32 s4, 0, 0x8000
	v_and_b32_e32 v190, 0xffffffe0, v35
	v_or3_b32 v20, v3, v4, v2
	v_or_b32_e32 v2, s22, v207
	s_cmp_lg_u32 s4, -1
	v_bitop3_b32 v3, v208, v36, 15 bitop3:0x78
	v_add_u32_e32 v210, v190, v2
	v_lshlrev_b32_e32 v2, 8, v207
	s_cselect_b32 s4, s4, 0
	v_lshlrev_b32_e32 v3, 4, v3
	v_add_u32_e32 v10, s27, v212
	v_mov_b64_e32 v[6:7], s[8:9]
	v_add3_u32 v213, v2, s4, v3
	v_mad_i64_i32 v[2:3], s[4:5], v10, s55, v[6:7]
	v_lshl_add_u64 v[2:3], v[2:3], 0, v[0:1]
	global_load_dwordx4 v[2:5], v[2:3], off
	s_add_i32 s4, s25, 0xfffffc20
	v_add_u32_e32 v16, s4, v212
	v_mov_b64_e32 v[14:15], s[6:7]
	v_mad_i64_i32 v[6:7], s[4:5], v16, s55, v[6:7]
	v_mad_i64_i32 v[10:11], s[4:5], v10, s55, v[14:15]
	v_mad_i64_i32 v[14:15], s[4:5], v16, s55, v[14:15]
	v_lshl_add_u64 v[6:7], v[6:7], 0, v[0:1]
	v_lshl_add_u64 v[10:11], v[10:11], 0, v[0:1]
	v_lshl_add_u64 v[14:15], v[14:15], 0, v[0:1]
	global_load_dwordx4 v[6:9], v[6:7], off
	v_add_u32_e32 v214, 0, v18
	global_load_dwordx4 v[10:13], v[10:11], off
	v_add_u32_e32 v215, 0, v20
	global_load_dwordx4 v[14:17], v[14:15], off
	s_waitcnt vmcnt(0)
	v_xor_b32_e32 v218, 32, v213
	v_xor_b32_e32 v219, 64, v213
	s_sub_i32 s5, s25, s22
	s_sub_i32 s4, s27, s22
	s_add_i32 s10, s5, 0xfffffc3f
	s_cmpk_gt_i32 s4, 0x4fe
	s_cselect_b64 s[4:5], -1, 0
	s_cmpk_lt_i32 s10, 0xfc01
	s_cselect_b64 s[10:11], -1, 0
	s_waitcnt vmcnt(3)
	ds_write_b128 v214, v[2:5]
	v_lshlrev_b32_e32 v2, 8, v212
	v_and_b32_e32 v3, 0xf0, v34
	v_bitop3_b32 v2, v0, v2, v3 bitop3:0xde
	v_add_u32_e32 v216, 0, v2
	v_lshlrev_b32_e32 v2, 8, v19
	v_bitop3_b32 v2, v2, v0, v3 bitop3:0xf6
	v_add_u32_e32 v217, 0, v2
	s_waitcnt vmcnt(2)
	ds_write_b128 v215, v[6:9]
	s_waitcnt vmcnt(1)
	ds_write_b128 v216, v[10:13] offset:32768
	s_waitcnt vmcnt(0)
	ds_write_b128 v217, v[14:17] offset:32768
	s_waitcnt lgkmcnt(0)
	s_barrier
; __device__ __forceinline__ void qkt8_roll(f32x16& p0, f32x16& p1, const f32x16& negm, int kb, const bf16x8* qr) {
;   const int a0 = kb ^ (0 << 5); const bf16x8 x0 = lds_rd128<0>(a0), y0 = lds_rd128<8192>(a0);
;   const int a1 = kb ^ (1 << 5); const bf16x8 x1 = lds_rd128<0>(a1), y1 = lds_rd128<8192>(a1);
;   const int a2 = kb ^ (2 << 5); const bf16x8 x2 = lds_rd128<0>(a2), y2 = lds_rd128<8192>(a2);
;   asm volatile("s_waitcnt lgkmcnt(4)" ::: "memory"); SBAR_M();
;   p0 = __builtin_amdgcn_mfma_f32_32x32x16_bf16(x0, qr[0], negm, 0, 0, 0); p1 = __builtin_amdgcn_mfma_f32_32x32x16_bf16(y0, qr[0], negm, 0, 0, 0);
;   const int a3 = kb ^ (3 << 5); const bf16x8 x3 = lds_rd128<0>(a3), y3 = lds_rd128<8192>(a3);
;   asm volatile("s_waitcnt lgkmcnt(4)" ::: "memory"); SBAR_M();
;   p0 = __builtin_amdgcn_mfma_f32_32x32x16_bf16(x1, qr[1], p0, 0, 0, 0); p1 = __builtin_amdgcn_mfma_f32_32x32x16_bf16(y1, qr[1], p1, 0, 0, 0);
;   const int a4 = kb ^ (4 << 5); const bf16x8 x4 = lds_rd128<0>(a4), y4 = lds_rd128<8192>(a4);
;   asm volatile("s_waitcnt lgkmcnt(4)" ::: "memory"); SBAR_M();
;   p0 = __builtin_amdgcn_mfma_f32_32x32x16_bf16(x2, qr[2], p0, 0, 0, 0); p1 = __builtin_amdgcn_mfma_f32_32x32x16_bf16(y2, qr[2], p1, 0, 0, 0);
;   const int a5 = kb ^ (5 << 5); const bf16x8 x5 = lds_rd128<0>(a5), y5 = lds_rd128<8192>(a5);
;   asm volatile("s_waitcnt lgkmcnt(4)" ::: "memory"); SBAR_M();
;   p0 = __builtin_amdgcn_mfma_f32_32x32x16_bf16(x3, qr[3], p0, 0, 0, 0); p1 = __builtin_amdgcn_mfma_f32_32x32x16_bf16(y3, qr[3], p1, 0, 0, 0);
;   const int a6 = kb ^ (6 << 5); const bf16x8 x6 = lds_rd128<0>(a6), y6 = lds_rd128<8192>(a6);
;   asm volatile("s_waitcnt lgkmcnt(4)" ::: "memory"); SBAR_M();
;   p0 = __builtin_amdgcn_mfma_f32_32x32x16_bf16(x4, qr[4], p0, 0, 0, 0); p1 = __builtin_amdgcn_mfma_f32_32x32x16_bf16(y4, qr[4], p1, 0, 0, 0);
;   const int a7 = kb ^ (7 << 5); const bf16x8 x7 = lds_rd128<0>(a7), y7 = lds_rd128<8192>(a7);
;   asm volatile("s_waitcnt lgkmcnt(4)" ::: "memory"); SBAR_M();
;   p0 = __builtin_amdgcn_mfma_f32_32x32x16_bf16(x5, qr[5], p0, 0, 0, 0); p1 = __builtin_amdgcn_mfma_f32_32x32x16_bf16(y5, qr[5], p1, 0, 0, 0);
;   asm volatile("s_waitcnt lgkmcnt(2)" ::: "memory"); SBAR_M();
;   p0 = __builtin_amdgcn_mfma_f32_32x32x16_bf16(x6, qr[6], p0, 0, 0, 0); p1 = __builtin_amdgcn_mfma_f32_32x32x16_bf16(y6, qr[6], p1, 0, 0, 0);
	ds_read_b128 v[2:5], v213 offset:0
	ds_read_b128 v[6:9], v213 offset:0x2000
	ds_read_b128 v[38:41], v218 offset:0
	ds_read_b128 v[42:45], v218 offset:0x2000
	ds_read_b128 v[46:49], v219 offset:0
	ds_read_b128 v[50:53], v219 offset:0x2000
	s_waitcnt lgkmcnt(4)
	s_nop 0
	v_mfma_f32_32x32x16_bf16 v[18:33], v[2:5], v[142:145], 0
	v_xor_b32_e32 v220, 0x60, v213
	ds_read_b128 v[54:57], v220 offset:0
	ds_read_b128 v[58:61], v220 offset:0x2000
	s_waitcnt lgkmcnt(4)
	v_mfma_f32_32x32x16_bf16 v[2:17], v[6:9], v[142:145], 0
	v_mfma_f32_32x32x16_bf16 v[18:33], v[38:41], v[138:141], v[18:33]
	v_xor_b32_e32 v221, 0x80, v213
	ds_read_b128 v[38:41], v221 offset:0
	v_mfma_f32_32x32x16_bf16 v[2:17], v[42:45], v[138:141], v[2:17]
	ds_read_b128 v[42:45], v221 offset:0x2000
	s_waitcnt lgkmcnt(4)
	v_mfma_f32_32x32x16_bf16 v[18:33], v[46:49], v[134:137], v[18:33]
	v_xor_b32_e32 v223, 0xa0, v213
	ds_read_b128 v[46:49], v223 offset:0
	v_mfma_f32_32x32x16_bf16 v[2:17], v[50:53], v[134:137], v[2:17]
	ds_read_b128 v[50:53], v223 offset:0x2000
	s_waitcnt lgkmcnt(4)
	v_mfma_f32_32x32x16_bf16 v[18:33], v[54:57], v[130:133], v[18:33]
	v_xor_b32_e32 v224, 0xc0, v213
	ds_read_b128 v[54:57], v224 offset:0
	v_mfma_f32_32x32x16_bf16 v[2:17], v[58:61], v[130:133], v[2:17]
	ds_read_b128 v[58:61], v224 offset:0x2000
	s_waitcnt lgkmcnt(4)
	v_mfma_f32_32x32x16_bf16 v[18:33], v[38:41], v[126:129], v[18:33]
	v_xor_b32_e32 v225, 0xe0, v213
	ds_read_b128 v[38:41], v225 offset:0
	v_mfma_f32_32x32x16_bf16 v[2:17], v[42:45], v[126:129], v[2:17]
	ds_read_b128 v[42:45], v225 offset:0x2000
	s_waitcnt lgkmcnt(4)
	v_mfma_f32_32x32x16_bf16 v[18:33], v[46:49], v[122:125], v[18:33]
	s_waitcnt lgkmcnt(2)
	v_mfma_f32_32x32x16_bf16 v[2:17], v[50:53], v[122:125], v[2:17]
	v_mfma_f32_32x32x16_bf16 v[18:33], v[54:57], v[118:121], v[18:33]
	s_waitcnt lgkmcnt(0)
	v_mfma_f32_32x32x16_bf16 v[2:17], v[58:61], v[118:121], v[2:17]
	v_mfma_f32_32x32x16_bf16 v[18:33], v[38:41], v[114:117], v[18:33]
	s_or_b64 s[4:5], s[4:5], s[10:11]
	s_andn2_b64 vcc, exec, s[4:5]
	v_mfma_f32_32x32x16_bf16 v[2:17], v[42:45], v[114:117], v[2:17]
	s_cbranch_vccz .LBB0_484
	v_sub_u32_e32 v37, s27, v210
	v_lshlrev_b32_e32 v37, 2, v37
	v_readlane_b32 s4, v254, 59
	s_nop 1
	v_add3_u32 v37, s4, v37, v196
	v_add_u32_e32 v38, 0x1600, v37
	v_add_u32_e32 v40, 0x1680, v37
	ds_read2_b32 v[38:39], v38 offset1:1
	ds_read2_b32 v[40:41], v40 offset1:1
	v_add_u32_e32 v42, 0x1608, v37
	v_add_u32_e32 v44, 0x1688, v37
	v_add_u32_e32 v46, 0x1620, v37
	v_add_u32_e32 v48, 0x16a0, v37
	v_add_u32_e32 v50, 0x1628, v37
	v_add_u32_e32 v52, 0x16a8, v37
	v_add_u32_e32 v54, 0x1640, v37
	v_add_u32_e32 v56, 0x16c0, v37
	v_add_u32_e32 v58, 0x1648, v37
	v_add_u32_e32 v60, 0x16c8, v37
	v_add_u32_e32 v62, 0x1660, v37
	v_add_u32_e32 v64, 0x16e0, v37
	v_add_u32_e32 v66, 0x1668, v37
	v_add_u32_e32 v37, 0x16e8, v37
	ds_read2_b32 v[42:43], v42 offset1:1
	ds_read2_b32 v[44:45], v44 offset1:1
	ds_read2_b32 v[46:47], v46 offset1:1
	ds_read2_b32 v[48:49], v48 offset1:1
	ds_read2_b32 v[50:51], v50 offset1:1
	ds_read2_b32 v[52:53], v52 offset1:1
	ds_read2_b32 v[54:55], v54 offset1:1
	ds_read2_b32 v[56:57], v56 offset1:1
	ds_read2_b32 v[58:59], v58 offset1:1
	ds_read2_b32 v[60:61], v60 offset1:1
	ds_read2_b32 v[62:63], v62 offset1:1
	ds_read2_b32 v[64:65], v64 offset1:1
	ds_read2_b32 v[66:67], v66 offset1:1
	s_waitcnt lgkmcnt(14)
	v_pk_add_f32 v[18:19], v[18:19], v[38:39]
	ds_read2_b32 v[38:39], v37 offset1:1
	s_waitcnt lgkmcnt(3)
	v_pk_add_f32 v[30:31], v[30:31], v[62:63]
	v_pk_add_f32 v[28:29], v[28:29], v[58:59]
	s_waitcnt lgkmcnt(1)
	v_pk_add_f32 v[32:33], v[32:33], v[66:67]
	v_pk_add_f32 v[26:27], v[26:27], v[54:55]
	v_pk_add_f32 v[24:25], v[24:25], v[50:51]
	v_pk_add_f32 v[22:23], v[22:23], v[46:47]
	v_pk_add_f32 v[20:21], v[20:21], v[42:43]
	s_waitcnt lgkmcnt(0)
	v_pk_add_f32 v[16:17], v[16:17], v[38:39]
	v_pk_add_f32 v[14:15], v[14:15], v[64:65]
	v_pk_add_f32 v[12:13], v[12:13], v[60:61]
	v_pk_add_f32 v[10:11], v[10:11], v[56:57]
	v_pk_add_f32 v[8:9], v[8:9], v[52:53]
	v_pk_add_f32 v[6:7], v[6:7], v[48:49]
	v_pk_add_f32 v[4:5], v[4:5], v[44:45]
	v_pk_add_f32 v[2:3], v[2:3], v[40:41]

; #define SBAR() __builtin_amdgcn_sched_barrier(0)
; template <int K>
; __device__ __forceinline__ void fsm_slice(f32x16& p0, f32x16& p1, float alpha, float& l_reg, bf16x8& pa0, bf16x8& pa1, bf16x8& pa2, bf16x8& pa3, float (&sm)[4]) {
;   if constexpr (K == 2) {
;     sm[0] = p0[0]; sm[1] = p0[1]; sm[2] = p0[2]; sm[3] = p0[3];
; #pragma unroll
;     for (int r = 4; r < 16; ++r) sm[r & 3] += p0[r];
;   } else if constexpr (K == 3) {
; #pragma unroll
;     for (int r = 0; r < 16; ++r) sm[r & 3] += p1[r];
;   } else if constexpr (K == 4) {
;     float ps = (sm[0] + sm[1]) + (sm[2] + sm[3]);
;     { auto rr = __builtin_amdgcn_permlane32_swap(__float_as_uint(ps), __float_as_uint(ps), false, false);
;       ps = __uint_as_float(rr[0]) + __uint_as_float(rr[1]); }
;     l_reg = l_reg * alpha + ps;
;     PK4S(p0, 0, pa0);
;   } else if constexpr (K == 5) { PK4S(p0, 8, pa1);
;   } else if constexpr (K == 6) { PK4S(p1, 0, pa2);
;   } else if constexpr (K == 7) { PK4S(p1, 8, pa3); }
; }
; __device__ __forceinline__ void qkt8_fsm(f32x16& p0, f32x16& p1, const f32x16& negm, int kb, const bf16x8* qr, f32x16& q0p, f32x16& q1p, float alpha, float& l_reg, bf16x8& pa0, bf16x8& pa1, bf16x8& pa2, bf16x8& pa3) {
;   float sm[4];
;   const int a0 = kb ^ (0 << 5); const bf16x8 x0 = lds_rd128<0>(a0), y0 = lds_rd128<8192>(a0);
;   const int a1 = kb ^ (1 << 5); const bf16x8 x1 = lds_rd128<0>(a1), y1 = lds_rd128<8192>(a1);
;   const int a2 = kb ^ (2 << 5); const bf16x8 x2 = lds_rd128<0>(a2), y2 = lds_rd128<8192>(a2);
;   asm volatile("s_waitcnt lgkmcnt(4)" ::: "memory"); SBAR();
;   p0 = __builtin_amdgcn_mfma_f32_32x32x16_bf16(x0, qr[0], negm, 0, 0, 0); p1 = __builtin_amdgcn_mfma_f32_32x32x16_bf16(y0, qr[0], negm, 0, 0, 0);
;   fsm_slice<0>(q0p, q1p, alpha, l_reg, pa0, pa1, pa2, pa3, sm); SBAR();
;   const int a3 = kb ^ (3 << 5); const bf16x8 x3 = lds_rd128<0>(a3), y3 = lds_rd128<8192>(a3);
;   asm volatile("s_waitcnt lgkmcnt(4)" ::: "memory"); SBAR();
;   p0 = __builtin_amdgcn_mfma_f32_32x32x16_bf16(x1, qr[1], p0, 0, 0, 0); p1 = __builtin_amdgcn_mfma_f32_32x32x16_bf16(y1, qr[1], p1, 0, 0, 0);
;   fsm_slice<1>(q0p, q1p, alpha, l_reg, pa0, pa1, pa2, pa3, sm); SBAR();
;   const int a4 = kb ^ (4 << 5); const bf16x8 x4 = lds_rd128<0>(a4), y4 = lds_rd128<8192>(a4);
;   asm volatile("s_waitcnt lgkmcnt(4)" ::: "memory"); SBAR();
.LBB0_486:
	s_add_i32 s46, s44, s45
	s_cmp_gt_i32 s45, s11
	s_cselect_b64 s[6:7], -1, 0
	s_cmpk_lt_i32 s46, 0xfbc2
	s_cselect_b64 s[8:9], -1, 0
	v_sub_f32_e32 v82, 0, v222
	s_or_b64 s[8:9], s[6:7], s[8:9]
	v_cndmask_b32_e64 v243, -v222, v82, s[8:9]
	v_cmp_neq_f32_e32 vcc, v243, v241
	s_cmp_eq_u64 vcc, 0
	s_cselect_b64 s[6:7], -1, 0
	v_cndmask_b32_e64 v81, v243, v81, s[6:7]
	v_cndmask_b32_e64 v80, v243, v80, s[6:7]
	v_cndmask_b32_e64 v79, v243, v79, s[6:7]
	v_cndmask_b32_e64 v78, v243, v78, s[6:7]
	v_cndmask_b32_e64 v77, v243, v77, s[6:7]
	v_cndmask_b32_e64 v76, v243, v76, s[6:7]
	v_cndmask_b32_e64 v75, v243, v75, s[6:7]
	v_cndmask_b32_e64 v74, v243, v74, s[6:7]
	v_cndmask_b32_e64 v73, v243, v73, s[6:7]
	v_cndmask_b32_e64 v72, v243, v72, s[6:7]
	v_cndmask_b32_e64 v71, v243, v71, s[6:7]
	v_cndmask_b32_e64 v70, v243, v70, s[6:7]
	v_cndmask_b32_e64 v69, v243, v69, s[6:7]
	v_cndmask_b32_e64 v68, v243, v68, s[6:7]
	v_cndmask_b32_e64 v67, v243, v67, s[6:7]
	v_cndmask_b32_e64 v66, v243, v66, s[6:7]
	ds_read_b128 v[82:85], v233 offset:0
	ds_read_b128 v[178:181], v233 offset:0x2000
	ds_read_b128 v[182:185], v232 offset:0
	ds_read_b128 v[186:189], v232 offset:0x2000
	ds_read_b128 v[192:195], v231 offset:0
	ds_read_b128 v[244:247], v231 offset:0x2000
	s_waitcnt lgkmcnt(4)
	s_nop 1
	v_mfma_f32_32x32x16_bf16 v[98:113], v[82:85], v[142:145], v[66:81]
	v_mfma_f32_32x32x16_bf16 v[82:97], v[178:181], v[142:145], v[66:81]
	ds_read_b128 v[178:181], v230 offset:0
	ds_read_b128 v[248:251], v230 offset:0x2000
	s_waitcnt lgkmcnt(4)
	v_mfma_f32_32x32x16_bf16 v[98:113], v[182:185], v[138:141], v[98:113]
	v_mfma_f32_32x32x16_bf16 v[82:97], v[186:189], v[138:141], v[82:97]
	ds_read_b128 v[182:185], v229 offset:0
	ds_read_b128 v[186:189], v229 offset:0x2000
	s_waitcnt lgkmcnt(4)
	v_mfma_f32_32x32x16_bf16 v[98:113], v[192:195], v[134:137], v[98:113]
	v_add_f32_e32 v192, v146, v148
	v_add_f32_e32 v193, v177, v175
	v_add_f32_e32 v194, v147, v149
	v_add_f32_e32 v195, v176, v174
	v_add_f32_e32 v192, v150, v192
	v_add_f32_e32 v193, v173, v193
	v_add_f32_e32 v194, v151, v194
	v_mfma_f32_32x32x16_bf16 v[82:97], v[244:247], v[134:137], v[82:97]
	v_add_f32_e32 v195, v172, v195
	v_add_f32_e32 v202, v152, v192
	v_add_f32_e32 v203, v171, v193
	v_add_f32_e32 v204, v153, v194
	v_add_f32_e32 v205, v170, v195
	ds_read_b128 v[192:195], v228 offset:0
	ds_read_b128 v[244:247], v228 offset:0x2000
	s_waitcnt lgkmcnt(4)
	v_mfma_f32_32x32x16_bf16 v[98:113], v[178:181], v[130:133], v[98:113]
	v_add_f32_e32 v178, v154, v202
	v_add_f32_e32 v179, v169, v203
	v_add_f32_e32 v180, v155, v204
	v_add_f32_e32 v181, v168, v205
	v_add_f32_e32 v178, v156, v178
	v_add_f32_e32 v179, v167, v179
	v_add_f32_e32 v180, v157, v180
	v_mfma_f32_32x32x16_bf16 v[82:97], v[248:251], v[130:133], v[82:97]
	v_add_f32_e32 v181, v166, v181
	v_add_f32_e32 v178, v158, v178
	v_add_f32_e32 v179, v165, v179
	v_add_f32_e32 v180, v159, v180
	v_add_f32_e32 v181, v164, v181
	v_add_f32_e32 v202, v160, v178
	v_add_f32_e32 v203, v163, v179
	v_add_f32_e32 v204, v161, v180
	v_add_f32_e32 v205, v162, v181
	ds_read_b128 v[178:181], v227 offset:0
	ds_read_b128 v[248:251], v227 offset:0x2000
	s_waitcnt lgkmcnt(4)
	v_mfma_f32_32x32x16_bf16 v[98:113], v[182:185], v[126:129], v[98:113]
	v_add_f32_e32 v182, v202, v203
	v_add_f32_e32 v183, v204, v205
	v_add_f32_e32 v239, v182, v183
	v_mov_b32_e32 v240, v239
	v_cvt_pk_bf16_f32 v146, v146, v177
	v_cvt_pk_bf16_f32 v147, v147, v176
	v_cvt_pk_bf16_f32 v148, v148, v175
	v_mfma_f32_32x32x16_bf16 v[82:97], v[186:189], v[126:129], v[82:97]
	v_cvt_pk_bf16_f32 v149, v149, v174
	s_nop 0
	v_permlane32_swap_b32_e32 v239, v240
	ds_read_b128 v[174:177], v226 offset:0
	ds_read_b128 v[182:185], v226 offset:0x2000
	s_waitcnt lgkmcnt(4)
	v_mfma_f32_32x32x16_bf16 v[98:113], v[192:195], v[122:125], v[98:113]
	v_cvt_pk_bf16_f32 v150, v150, v173
	v_cvt_pk_bf16_f32 v151, v151, v172
	v_cvt_pk_bf16_f32 v152, v152, v171
	v_cvt_pk_bf16_f32 v153, v153, v170
	s_nop 0
	v_mfma_f32_32x32x16_bf16 v[82:97], v[244:247], v[122:125], v[82:97]
	s_waitcnt lgkmcnt(2)
	v_mfma_f32_32x32x16_bf16 v[98:113], v[178:181], v[118:121], v[98:113]
	v_cvt_pk_bf16_f32 v154, v154, v169
	v_cvt_pk_bf16_f32 v155, v155, v168
	v_cvt_pk_bf16_f32 v156, v156, v167
	v_cvt_pk_bf16_f32 v157, v157, v166
	s_nop 0
	v_mfma_f32_32x32x16_bf16 v[82:97], v[248:251], v[118:121], v[82:97]
	s_waitcnt lgkmcnt(0)
	v_mfma_f32_32x32x16_bf16 v[98:113], v[174:177], v[114:117], v[98:113]
	v_cvt_pk_bf16_f32 v158, v158, v165
	v_cvt_pk_bf16_f32 v159, v159, v164
	v_cvt_pk_bf16_f32 v160, v160, v163
	v_cvt_pk_bf16_f32 v161, v161, v162
	s_nop 0
	v_mfma_f32_32x32x16_bf16 v[82:97], v[182:185], v[114:117], v[82:97]
	v_add_u32_e32 v238, s45, v212
	v_add_u32_e32 v170, 64, v238
	v_add_u32_e32 v172, 0x60, v238
	v_mad_i64_i32 v[162:163], s[50:51], v170, s55, v[198:199]
	v_mad_i64_i32 v[166:167], s[50:51], v172, s55, v[198:199]
	v_mad_i64_i32 v[170:171], s[50:51], v170, s55, v[200:201]
	v_mad_i64_i32 v[174:175], s[50:51], v172, s55, v[200:201]
	global_load_dwordx4 v[162:165], v[162:163], off
	s_nop 0
	global_load_dwordx4 v[166:169], v[166:167], off
	s_nop 0
	global_load_dwordx4 v[170:173], v[170:171], off
	s_nop 0
	global_load_dwordx4 v[174:177], v[174:175], off
	s_and_b64 vcc, exec, s[8:9]
	s_cbranch_vccnz .LBB0_488
	ds_read2_b32 v[178:179], v236 offset1:1
	ds_read2_b32 v[180:181], v236 offset0:2 offset1:3
	ds_read2_b32 v[182:183], v236 offset0:8 offset1:9
	ds_read2_b32 v[184:185], v236 offset0:10 offset1:11
	ds_read2_b32 v[186:187], v236 offset0:16 offset1:17
	ds_read2_b32 v[188:189], v236 offset0:18 offset1:19
	ds_read2_b32 v[192:193], v236 offset0:24 offset1:25
	ds_read2_b32 v[194:195], v236 offset0:26 offset1:27
	ds_read2_b32 v[202:203], v236 offset0:32 offset1:33
	ds_read2_b32 v[204:205], v236 offset0:34 offset1:35
	ds_read2_b32 v[244:245], v236 offset0:40 offset1:41
	ds_read2_b32 v[246:247], v236 offset0:42 offset1:43
	s_waitcnt lgkmcnt(11)
	v_add_f32_e32 v98, v98, v178
	v_add_f32_e32 v99, v99, v179
	s_waitcnt lgkmcnt(5)
	v_add_f32_e32 v110, v110, v192
	v_add_f32_e32 v111, v111, v193
	v_add_f32_e32 v108, v108, v188
	v_add_f32_e32 v109, v109, v189
	v_add_f32_e32 v106, v106, v186
	v_add_f32_e32 v107, v107, v187
	ds_read2_b32 v[178:179], v236 offset0:48 offset1:49
	ds_read2_b32 v[186:187], v236 offset0:50 offset1:51
	ds_read2_b32 v[188:189], v236 offset0:56 offset1:57
	ds_read2_b32 v[192:193], v236 offset0:58 offset1:59
	s_waitcnt lgkmcnt(8)
	v_add_f32_e32 v112, v112, v194
	v_add_f32_e32 v113, v113, v195
	v_add_f32_e32 v104, v104, v184
	v_add_f32_e32 v105, v105, v185
	v_add_f32_e32 v102, v102, v182
	v_add_f32_e32 v103, v103, v183
	v_add_f32_e32 v100, v100, v180
	v_add_f32_e32 v101, v101, v181
	s_waitcnt lgkmcnt(7)
	v_add_f32_e32 v82, v82, v202
	v_add_f32_e32 v83, v83, v203
	s_waitcnt lgkmcnt(0)
	v_add_f32_e32 v96, v96, v192
	v_add_f32_e32 v97, v97, v193
	v_add_f32_e32 v94, v94, v188
	v_add_f32_e32 v95, v95, v189
	v_add_f32_e32 v92, v92, v186
	v_add_f32_e32 v93, v93, v187
	v_add_f32_e32 v90, v90, v178
	v_add_f32_e32 v91, v91, v179
	v_add_f32_e32 v88, v88, v246
	v_add_f32_e32 v89, v89, v247
	v_add_f32_e32 v86, v86, v244
	v_add_f32_e32 v87, v87, v245
	v_add_f32_e32 v84, v84, v204
	v_add_f32_e32 v85, v85, v205

; #define SBAR() __builtin_amdgcn_sched_barrier(0)
; __device__ __forceinline__ void qkt8_fsm(f32x16& p0, f32x16& p1, const f32x16& negm, int kb, const bf16x8* qr, f32x16& q0p, f32x16& q1p, float alpha, float& l_reg, bf16x8& pa0, bf16x8& pa1, bf16x8& pa2, bf16x8& pa3) {
;   float sm[4];
;   const int a0 = kb ^ (0 << 5); const bf16x8 x0 = lds_rd128<0>(a0), y0 = lds_rd128<8192>(a0);
;   const int a1 = kb ^ (1 << 5); const bf16x8 x1 = lds_rd128<0>(a1), y1 = lds_rd128<8192>(a1);
;   const int a2 = kb ^ (2 << 5); const bf16x8 x2 = lds_rd128<0>(a2), y2 = lds_rd128<8192>(a2);
;   asm volatile("s_waitcnt lgkmcnt(4)" ::: "memory"); SBAR();
;   p0 = __builtin_amdgcn_mfma_f32_32x32x16_bf16(x0, qr[0], negm, 0, 0, 0); p1 = __builtin_amdgcn_mfma_f32_32x32x16_bf16(y0, qr[0], negm, 0, 0, 0);
;   fsm_slice<0>(q0p, q1p, alpha, l_reg, pa0, pa1, pa2, pa3, sm); SBAR();
;   const int a3 = kb ^ (3 << 5); const bf16x8 x3 = lds_rd128<0>(a3), y3 = lds_rd128<8192>(a3);
;   asm volatile("s_waitcnt lgkmcnt(4)" ::: "memory"); SBAR();
;   p0 = __builtin_amdgcn_mfma_f32_32x32x16_bf16(x1, qr[1], p0, 0, 0, 0); p1 = __builtin_amdgcn_mfma_f32_32x32x16_bf16(y1, qr[1], p1, 0, 0, 0);
;   fsm_slice<1>(q0p, q1p, alpha, l_reg, pa0, pa1, pa2, pa3, sm); SBAR();
;   const int a4 = kb ^ (4 << 5); const bf16x8 x4 = lds_rd128<0>(a4), y4 = lds_rd128<8192>(a4);
;   asm volatile("s_waitcnt lgkmcnt(4)" ::: "memory"); SBAR();
;   p0 = __builtin_amdgcn_mfma_f32_32x32x16_bf16(x2, qr[2], p0, 0, 0, 0); p1 = __builtin_amdgcn_mfma_f32_32x32x16_bf16(y2, qr[2], p1, 0, 0, 0);
;   fsm_slice<2>(q0p, q1p, alpha, l_reg, pa0, pa1, pa2, pa3, sm); SBAR();
;   const int a5 = kb ^ (5 << 5); const bf16x8 x5 = lds_rd128<0>(a5), y5 = lds_rd128<8192>(a5);
;   asm volatile("s_waitcnt lgkmcnt(4)" ::: "memory"); SBAR();
;   p0 = __builtin_amdgcn_mfma_f32_32x32x16_bf16(x3, qr[3], p0, 0, 0, 0); p1 = __builtin_amdgcn_mfma_f32_32x32x16_bf16(y3, qr[3], p1, 0, 0, 0);
;   fsm_slice<3>(q0p, q1p, alpha, l_reg, pa0, pa1, pa2, pa3, sm); SBAR();
;   const int a6 = kb ^ (6 << 5); const bf16x8 x6 = lds_rd128<0>(a6), y6 = lds_rd128<8192>(a6);
;   asm volatile("s_waitcnt lgkmcnt(4)" ::: "memory"); SBAR();
;   p0 = __builtin_amdgcn_mfma_f32_32x32x16_bf16(x4, qr[4], p0, 0, 0, 0); p1 = __builtin_amdgcn_mfma_f32_32x32x16_bf16(y4, qr[4], p1, 0, 0, 0);
;   fsm_slice<4>(q0p, q1p, alpha, l_reg, pa0, pa1, pa2, pa3, sm); SBAR();
.LBB0_493:
	v_cndmask_b32_e64 v241, v243, v241, s[6:7]
	s_add_i32 s6, s45, 64
	s_add_i32 s46, s46, 64
	s_cmp_gt_i32 s6, s11
	s_cselect_b64 s[6:7], -1, 0
	s_cmpk_lt_i32 s46, 0xfbc2
	s_cselect_b64 s[8:9], -1, 0
	v_exp_f32_e32 v154, v82
	v_sub_f32_e32 v82, 0, v222
	s_or_b64 s[8:9], s[6:7], s[8:9]
	v_cndmask_b32_e64 v243, -v222, v82, s[8:9]
	v_exp_f32_e32 v146, v98
	v_exp_f32_e32 v177, v99
	v_exp_f32_e32 v147, v100
	v_exp_f32_e32 v176, v101
	v_exp_f32_e32 v148, v102
	v_exp_f32_e32 v175, v103
	v_exp_f32_e32 v149, v104
	v_exp_f32_e32 v174, v105
	v_exp_f32_e32 v150, v106
	v_exp_f32_e32 v173, v107
	v_exp_f32_e32 v151, v108
	v_exp_f32_e32 v172, v109
	v_exp_f32_e32 v152, v110
	v_exp_f32_e32 v171, v111
	v_exp_f32_e32 v153, v112
	v_exp_f32_e32 v170, v113
	v_exp_f32_e32 v169, v83
	v_exp_f32_e32 v155, v84
	v_exp_f32_e32 v168, v85
	v_exp_f32_e32 v156, v86
	v_exp_f32_e32 v167, v87
	v_exp_f32_e32 v157, v88
	v_exp_f32_e32 v166, v89
	v_exp_f32_e32 v158, v90
	v_exp_f32_e32 v165, v91
	v_exp_f32_e32 v159, v92
	v_exp_f32_e32 v164, v93
	v_exp_f32_e32 v160, v94
	v_exp_f32_e32 v163, v95
	v_exp_f32_e32 v161, v96
	v_exp_f32_e32 v162, v97
	v_cmp_neq_f32_e32 vcc, v243, v241
	s_cmp_eq_u64 vcc, 0
	s_cselect_b64 s[6:7], -1, 0
	v_cndmask_b32_e64 v81, v243, v81, s[6:7]
	v_cndmask_b32_e64 v80, v243, v80, s[6:7]
	v_cndmask_b32_e64 v79, v243, v79, s[6:7]
	v_cndmask_b32_e64 v78, v243, v78, s[6:7]
	v_cndmask_b32_e64 v77, v243, v77, s[6:7]
	v_cndmask_b32_e64 v76, v243, v76, s[6:7]
	v_cndmask_b32_e64 v75, v243, v75, s[6:7]
	v_cndmask_b32_e64 v74, v243, v74, s[6:7]
	v_cndmask_b32_e64 v73, v243, v73, s[6:7]
	v_cndmask_b32_e64 v72, v243, v72, s[6:7]
	v_cndmask_b32_e64 v71, v243, v71, s[6:7]
	v_cndmask_b32_e64 v70, v243, v70, s[6:7]
	v_cndmask_b32_e64 v69, v243, v69, s[6:7]
	v_cndmask_b32_e64 v68, v243, v68, s[6:7]
	v_cndmask_b32_e64 v67, v243, v67, s[6:7]
	v_cndmask_b32_e64 v66, v243, v66, s[6:7]
	s_waitcnt lgkmcnt(0)
	s_barrier
	ds_read_b128 v[82:85], v213 offset:0
	ds_read_b128 v[178:181], v213 offset:0x2000
	ds_read_b128 v[182:185], v218 offset:0
	ds_read_b128 v[186:189], v218 offset:0x2000
	ds_read_b128 v[192:195], v219 offset:0
	ds_read_b128 v[244:247], v219 offset:0x2000
	s_waitcnt lgkmcnt(4)
	s_nop 0
	v_mfma_f32_32x32x16_bf16 v[98:113], v[82:85], v[142:145], v[66:81]
	v_mfma_f32_32x32x16_bf16 v[82:97], v[178:181], v[142:145], v[66:81]
	ds_read_b128 v[178:181], v220 offset:0
	ds_read_b128 v[248:251], v220 offset:0x2000
	s_waitcnt lgkmcnt(4)
	v_mfma_f32_32x32x16_bf16 v[98:113], v[182:185], v[138:141], v[98:113]
	v_mfma_f32_32x32x16_bf16 v[82:97], v[186:189], v[138:141], v[82:97]
	ds_read_b128 v[182:185], v221 offset:0
	ds_read_b128 v[186:189], v221 offset:0x2000
	s_waitcnt lgkmcnt(4)
	v_mfma_f32_32x32x16_bf16 v[98:113], v[192:195], v[134:137], v[98:113]
	v_add_f32_e32 v192, v148, v146
	v_add_f32_e32 v193, v175, v177
	v_add_f32_e32 v194, v149, v147
	v_add_f32_e32 v195, v174, v176
	v_add_f32_e32 v192, v150, v192
	v_add_f32_e32 v193, v173, v193
	v_add_f32_e32 v194, v151, v194
	v_mfma_f32_32x32x16_bf16 v[82:97], v[244:247], v[134:137], v[82:97]
	v_add_f32_e32 v195, v172, v195
	v_add_f32_e32 v244, v152, v192
	v_add_f32_e32 v245, v171, v193
	v_add_f32_e32 v246, v153, v194
	v_add_f32_e32 v247, v170, v195
	ds_read_b128 v[192:195], v223 offset:0
	ds_read_b128 v[202:205], v223 offset:0x2000
	s_waitcnt lgkmcnt(4)
	v_mfma_f32_32x32x16_bf16 v[98:113], v[178:181], v[130:133], v[98:113]
	v_add_f32_e32 v178, v154, v244
	v_add_f32_e32 v179, v169, v245
	v_add_f32_e32 v180, v155, v246
	v_add_f32_e32 v181, v168, v247
	v_add_f32_e32 v178, v156, v178
	v_add_f32_e32 v179, v167, v179
	v_add_f32_e32 v180, v157, v180
	v_mfma_f32_32x32x16_bf16 v[82:97], v[248:251], v[130:133], v[82:97]
	v_add_f32_e32 v181, v166, v181
	v_add_f32_e32 v178, v158, v178
	v_add_f32_e32 v179, v165, v179
	v_add_f32_e32 v180, v159, v180
	v_add_f32_e32 v181, v164, v181
	v_add_f32_e32 v244, v160, v178
	v_add_f32_e32 v245, v163, v179
	v_add_f32_e32 v250, v161, v180
	v_add_f32_e32 v251, v162, v181
	ds_read_b128 v[178:181], v224 offset:0
	ds_read_b128 v[246:249], v224 offset:0x2000
	s_waitcnt lgkmcnt(4)
	v_mfma_f32_32x32x16_bf16 v[98:113], v[182:185], v[126:129], v[98:113]
	v_add_f32_e32 v182, v245, v244
	v_add_f32_e32 v183, v251, v250
	v_add_f32_e32 v244, v183, v182
	v_mov_b32_e32 v245, v244
	v_cvt_pk_bf16_f32 v146, v146, v177
	v_cvt_pk_bf16_f32 v147, v147, v176
	v_cvt_pk_bf16_f32 v148, v148, v175
	v_mfma_f32_32x32x16_bf16 v[82:97], v[186:189], v[126:129], v[82:97]
	v_cvt_pk_bf16_f32 v149, v149, v174
	s_nop 0
	v_permlane32_swap_b32_e32 v244, v245
	ds_read_b128 v[174:177], v225 offset:0
	ds_read_b128 v[182:185], v225 offset:0x2000
	s_waitcnt lgkmcnt(4)
	v_mfma_f32_32x32x16_bf16 v[98:113], v[192:195], v[122:125], v[98:113]
	v_cvt_pk_bf16_f32 v150, v150, v173
	v_cvt_pk_bf16_f32 v151, v151, v172
	v_cvt_pk_bf16_f32 v152, v152, v171
	v_cvt_pk_bf16_f32 v153, v153, v170
	s_nop 0
	v_mfma_f32_32x32x16_bf16 v[82:97], v[202:205], v[122:125], v[82:97]
	s_waitcnt lgkmcnt(2)
	v_mfma_f32_32x32x16_bf16 v[98:113], v[178:181], v[118:121], v[98:113]
	v_cvt_pk_bf16_f32 v154, v154, v169
	v_cvt_pk_bf16_f32 v155, v155, v168
	v_cvt_pk_bf16_f32 v156, v156, v167
	v_cvt_pk_bf16_f32 v157, v157, v166
	s_nop 0
	v_mfma_f32_32x32x16_bf16 v[82:97], v[246:249], v[118:121], v[82:97]
	s_waitcnt lgkmcnt(0)
	v_mfma_f32_32x32x16_bf16 v[98:113], v[174:177], v[114:117], v[98:113]
	v_cvt_pk_bf16_f32 v158, v158, v165
	v_cvt_pk_bf16_f32 v159, v159, v164
	v_cvt_pk_bf16_f32 v160, v160, v163
	v_cvt_pk_bf16_f32 v161, v161, v162
	s_nop 0
	v_mfma_f32_32x32x16_bf16 v[82:97], v[182:185], v[114:117], v[82:97]
	v_add_u32_e32 v170, 0x80, v238
	v_add_u32_e32 v172, 0xa0, v238
	v_mad_i64_i32 v[162:163], s[46:47], v170, s55, v[198:199]
	v_mad_i64_i32 v[166:167], s[46:47], v172, s55, v[198:199]
	v_mad_i64_i32 v[170:171], s[46:47], v170, s55, v[200:201]
	v_mad_i64_i32 v[174:175], s[46:47], v172, s55, v[200:201]
	global_load_dwordx4 v[162:165], v[162:163], off
	s_nop 0
	global_load_dwordx4 v[166:169], v[166:167], off
	s_nop 0
	global_load_dwordx4 v[170:173], v[170:171], off
	s_nop 0
	global_load_dwordx4 v[174:177], v[174:175], off
	s_and_b64 vcc, exec, s[8:9]
	s_cbranch_vccnz .LBB0_495
	ds_read2_b32 v[178:179], v236 offset0:64 offset1:65
	ds_read2_b32 v[180:181], v236 offset0:66 offset1:67
	ds_read2_b32 v[182:183], v236 offset0:72 offset1:73
	ds_read2_b32 v[184:185], v236 offset0:74 offset1:75
	ds_read2_b32 v[186:187], v236 offset0:80 offset1:81
	ds_read2_b32 v[188:189], v236 offset0:82 offset1:83
	ds_read2_b32 v[192:193], v236 offset0:88 offset1:89
	ds_read2_b32 v[194:195], v236 offset0:90 offset1:91
	ds_read2_b32 v[202:203], v236 offset0:96 offset1:97
	ds_read2_b32 v[204:205], v236 offset0:98 offset1:99
	ds_read2_b32 v[246:247], v236 offset0:104 offset1:105
	ds_read2_b32 v[248:249], v236 offset0:106 offset1:107
	s_waitcnt lgkmcnt(11)
	v_add_f32_e32 v98, v98, v178
	v_add_f32_e32 v99, v99, v179
	s_waitcnt lgkmcnt(5)
	v_add_f32_e32 v110, v110, v192
	v_add_f32_e32 v111, v111, v193
	v_add_f32_e32 v108, v108, v188
	v_add_f32_e32 v109, v109, v189
	v_add_f32_e32 v106, v106, v186
	v_add_f32_e32 v107, v107, v187
	ds_read2_b32 v[178:179], v236 offset0:112 offset1:113
	ds_read2_b32 v[186:187], v236 offset0:114 offset1:115
	ds_read2_b32 v[188:189], v236 offset0:120 offset1:121
	ds_read2_b32 v[192:193], v236 offset0:122 offset1:123
	s_waitcnt lgkmcnt(8)
	v_add_f32_e32 v112, v112, v194
	v_add_f32_e32 v113, v113, v195
	v_add_f32_e32 v104, v104, v184
	v_add_f32_e32 v105, v105, v185
	v_add_f32_e32 v102, v102, v182
	v_add_f32_e32 v103, v103, v183
	v_add_f32_e32 v100, v100, v180
	v_add_f32_e32 v101, v101, v181
	s_waitcnt lgkmcnt(7)
	v_add_f32_e32 v82, v82, v202
	v_add_f32_e32 v83, v83, v203
	s_waitcnt lgkmcnt(0)
	v_add_f32_e32 v96, v96, v192
	v_add_f32_e32 v97, v97, v193
	v_add_f32_e32 v94, v94, v188
	v_add_f32_e32 v95, v95, v189
	v_add_f32_e32 v92, v92, v186
	v_add_f32_e32 v93, v93, v187
	v_add_f32_e32 v90, v90, v178
	v_add_f32_e32 v91, v91, v179
	v_add_f32_e32 v88, v88, v248
	v_add_f32_e32 v89, v89, v249
	v_add_f32_e32 v86, v86, v246
	v_add_f32_e32 v87, v87, v247
	v_add_f32_e32 v84, v84, v204
	v_add_f32_e32 v85, v85, v205

; #define SBAR() __builtin_amdgcn_sched_barrier(0)
; #define BIASADD(P0, P1, kt0) do { if constexpr (BIAS) { const int dlo_ = (kt0) - q0 - 255, dhi_ = (kt0) + 63 - q0; \
;     if (!(dlo_ >= 1024) && !(dhi_ <= -1024)) { const float* tb_ = tbl_l + ((kt0) - qlane + TOFF + 4 * hi); \
;       _Pragma("unroll") for (int r = 0; r < 16; ++r) { P0[r] += tb_[(r & 3) + 8 * (r >> 2)]; P1[r] += tb_[32 + (r & 3) + 8 * (r >> 2)]; } } } } while (0)
; #define NEGM_UPD(kt0) do { float nmj_ = -mC; if constexpr (BIAS) { const int dlo_ = (kt0) - q0 - 255, dhi_ = (kt0) + 63 - q0; if (dlo_ >= 1024) nmj_ += cb_hi; else if (dhi_ <= -1024) nmj_ += cb_lo; } \
;     if (__any(nmj_ != nm_cur)) { nm_cur = nmj_; _Pragma("unroll") for (int r = 0; r < 16; ++r) negm[r] = nmj_; } } while (0)
; #define QKT(P0, P1, KOFF) do { if constexpr (NDQ == 8 && NQL == 0) qkt8_roll(P0, P1, negm, kb0 + (KOFF), qr); \
;     else if constexpr (NDQ == 12 && NQL == 4) qkt12_roll(P0, P1, negm, kb0 + (KOFF), qa0, qr); else qkt<NDQ, NQL>(P0, P1, negm, K_lds + (KOFF), qr, qls, r32, hi); } while (0)
; template <bool EXP1 = true>
; __device__ __forceinline__ void finishSM(f32x16& p0, f32x16& p1, float alpha, float& l_reg, bf16x8& pa0, bf16x8& pa1, bf16x8& pa2, bf16x8& pa3) {
;   if constexpr (EXP1) {
; #pragma unroll
;   for (int r = 0; r < 16; ++r) p1[r] = __builtin_amdgcn_exp2f(p1[r]);
;   }
;   float sm_[4] = {p0[0], p0[1], p0[2], p0[3]};
; #pragma unroll
;   for (int r = 4; r < 16; ++r) sm_[r & 3] += p0[r];
; #pragma unroll
;   for (int r = 0; r < 16; ++r) sm_[r & 3] += p1[r];
;   float ps = (sm_[0] + sm_[1]) + (sm_[2] + sm_[3]);
;   { auto rr = __builtin_amdgcn_permlane32_swap(__float_as_uint(ps), __float_as_uint(ps), false, false);
;     ps = __uint_as_float(rr[0]) + __uint_as_float(rr[1]); }
;   l_reg = l_reg * alpha + ps;
;     ...
;   PK4(p0, 0, pa0); PK4(p0, 8, pa1); PK4(p1, 0, pa2); PK4(p1, 8, pa3);
;     ...
; }
;     ...
;   NEGM_UPD(kbeg + (NT - 1) * KVBLK); SBAR(); QKT(pB0, pB1, SHM_K);
;   finishSM<!SLICED>(pA0, pA1, alA, l_reg, pa0, pa1, pa2, pa3); SBAR();
;   pv_d0(o, vb0, pa0, pa1, pa2, pa3); BIASADD(pB0, pB1, kbeg + (NT - 1) * KVBLK); partialSM<false>(pB0, pB1, mC, alB);
.LBB0_506:
	s_lshl_b32 s6, s26, 7
	s_add_i32 s4, s25, s10
	s_addk_i32 s4, 0xfbc0
	s_sub_i32 s5, s4, s22
	s_addk_i32 s5, 0xfb01
	s_cmp_lt_u32 s5, 0xfffff6c3
	v_sub_f32_e32 v82, 0, v222
	s_cselect_b64 s[8:9], -1, 0
	v_cndmask_b32_e64 v82, -v222, v82, s[8:9]
	v_cmp_neq_f32_e32 vcc, v82, v241
	s_cmp_eq_u64 vcc, 0
	s_cselect_b64 vcc, -1, 0
	v_cndmask_b32_e32 v81, v82, v81, vcc
	v_cndmask_b32_e32 v80, v82, v80, vcc
	v_cndmask_b32_e32 v79, v82, v79, vcc
	v_cndmask_b32_e32 v78, v82, v78, vcc
	v_cndmask_b32_e32 v77, v82, v77, vcc
	v_cndmask_b32_e32 v76, v82, v76, vcc
	v_cndmask_b32_e32 v75, v82, v75, vcc
	v_cndmask_b32_e32 v74, v82, v74, vcc
	v_cndmask_b32_e32 v73, v82, v73, vcc
	v_cndmask_b32_e32 v72, v82, v72, vcc
	v_cndmask_b32_e32 v71, v82, v71, vcc
	v_cndmask_b32_e32 v70, v82, v70, vcc
	v_cndmask_b32_e32 v69, v82, v69, vcc
	v_cndmask_b32_e32 v68, v82, v68, vcc
	v_cndmask_b32_e32 v67, v82, v67, vcc
	v_cndmask_b32_e32 v66, v82, v66, vcc
	s_cmp_gt_u32 s5, 0xfffff6c2
	ds_read_b128 v[98:101], v233 offset:0
	ds_read_b128 v[102:105], v233 offset:0x2000
	ds_read_b128 v[106:109], v232 offset:0
	ds_read_b128 v[110:113], v232 offset:0x2000
	ds_read_b128 v[178:181], v231 offset:0
	ds_read_b128 v[182:185], v231 offset:0x2000
	s_waitcnt lgkmcnt(4)
	s_nop 0
	v_mfma_f32_32x32x16_bf16 v[82:97], v[98:101], v[142:145], v[66:81]
	ds_read_b128 v[98:101], v230 offset:0
	v_mfma_f32_32x32x16_bf16 v[66:81], v[102:105], v[142:145], v[66:81]
	ds_read_b128 v[102:105], v230 offset:0x2000
	s_waitcnt lgkmcnt(4)
	v_mfma_f32_32x32x16_bf16 v[82:97], v[106:109], v[138:141], v[82:97]
	ds_read_b128 v[106:109], v229 offset:0
	v_mfma_f32_32x32x16_bf16 v[66:81], v[110:113], v[138:141], v[66:81]
	ds_read_b128 v[110:113], v229 offset:0x2000
	s_waitcnt lgkmcnt(4)
	v_mfma_f32_32x32x16_bf16 v[82:97], v[178:181], v[134:137], v[82:97]
	v_mfma_f32_32x32x16_bf16 v[66:81], v[182:185], v[134:137], v[66:81]
	ds_read_b128 v[134:137], v228 offset:0
	ds_read_b128 v[138:141], v228 offset:0x2000
	s_waitcnt lgkmcnt(4)
	v_mfma_f32_32x32x16_bf16 v[82:97], v[98:101], v[130:133], v[82:97]
	ds_read_b128 v[98:101], v227 offset:0
	v_mfma_f32_32x32x16_bf16 v[66:81], v[102:105], v[130:133], v[66:81]
	ds_read_b128 v[102:105], v227 offset:0x2000
	s_waitcnt lgkmcnt(4)
	v_mfma_f32_32x32x16_bf16 v[82:97], v[106:109], v[126:129], v[82:97]
	ds_read_b128 v[106:109], v226 offset:0
	v_mfma_f32_32x32x16_bf16 v[66:81], v[110:113], v[126:129], v[66:81]
	ds_read_b128 v[110:113], v226 offset:0x2000
	s_waitcnt lgkmcnt(4)
	v_mfma_f32_32x32x16_bf16 v[82:97], v[134:137], v[122:125], v[82:97]
	s_waitcnt lgkmcnt(2)
	v_mfma_f32_32x32x16_bf16 v[66:81], v[138:141], v[122:125], v[66:81]
	v_mfma_f32_32x32x16_bf16 v[82:97], v[98:101], v[118:121], v[82:97]
	s_waitcnt lgkmcnt(0)
	v_mfma_f32_32x32x16_bf16 v[66:81], v[102:105], v[118:121], v[66:81]
	v_add_f32_e32 v98, v148, v146
	v_add_f32_e32 v99, v175, v177
	v_add_f32_e32 v100, v149, v147
	v_add_f32_e32 v101, v174, v176
	v_add_f32_e32 v98, v150, v98
	v_add_f32_e32 v99, v173, v99
	v_add_f32_e32 v100, v151, v100
	v_add_f32_e32 v101, v172, v101
	v_add_f32_e32 v98, v152, v98
	v_add_f32_e32 v99, v171, v99
	v_add_f32_e32 v100, v153, v100
	v_add_f32_e32 v101, v170, v101
	v_mfma_f32_32x32x16_bf16 v[82:97], v[106:109], v[114:117], v[82:97]
	v_add_f32_e32 v98, v154, v98
	v_add_f32_e32 v99, v169, v99
	v_add_f32_e32 v100, v155, v100
	v_add_f32_e32 v101, v168, v101
	v_add_f32_e32 v98, v156, v98
	v_add_f32_e32 v99, v167, v99
	v_add_f32_e32 v100, v157, v100
	v_mfma_f32_32x32x16_bf16 v[66:81], v[110:113], v[114:117], v[66:81]
	v_add_f32_e32 v101, v166, v101
	v_add_f32_e32 v98, v158, v98
	v_add_f32_e32 v99, v165, v99
	v_add_f32_e32 v100, v159, v100
	v_add_f32_e32 v101, v164, v101
	v_add_f32_e32 v98, v160, v98
	v_add_f32_e32 v99, v163, v99
	v_add_f32_e32 v100, v161, v100
	v_add_f32_e32 v101, v162, v101
	v_add_f32_e32 v98, v98, v99
	v_add_f32_e32 v99, v100, v101
	v_add_f32_e32 v114, v98, v99
	v_mov_b32_e32 v115, v114
	s_nop 1
	v_permlane32_swap_b32_e32 v114, v115
	v_cvt_pk_bf16_f32 v98, v146, v177
	v_cvt_pk_bf16_f32 v99, v147, v176
	v_cvt_pk_bf16_f32 v100, v148, v175
	v_cvt_pk_bf16_f32 v101, v149, v174
	v_cvt_pk_bf16_f32 v102, v150, v173
	v_cvt_pk_bf16_f32 v103, v151, v172
	v_cvt_pk_bf16_f32 v104, v152, v171
	v_cvt_pk_bf16_f32 v105, v153, v170
	v_cvt_pk_bf16_f32 v106, v154, v169
	v_cvt_pk_bf16_f32 v107, v155, v168
	v_cvt_pk_bf16_f32 v108, v156, v167
	v_cvt_pk_bf16_f32 v109, v157, v166
	v_cvt_pk_bf16_f32 v110, v158, v165
	v_cvt_pk_bf16_f32 v111, v159, v164
	v_cvt_pk_bf16_f32 v112, v160, v163
	v_cvt_pk_bf16_f32 v113, v161, v162
	s_nop 0
	ds_read_b64_tr_b16 v[116:117], v211 offset:0
	ds_read_b64_tr_b16 v[118:119], v211 offset:0x800
	ds_read_b64_tr_b16 v[120:121], v211 offset:0x1000
	ds_read_b64_tr_b16 v[122:123], v211 offset:0x1800
	ds_read_b64_tr_b16 v[124:125], v211 offset:0x2000
	ds_read_b64_tr_b16 v[126:127], v211 offset:0x2800
	ds_read_b64_tr_b16 v[128:129], v211 offset:0x3000
	ds_read_b64_tr_b16 v[130:131], v211 offset:0x3800
	ds_read_b64_tr_b16 v[132:133], v211 offset:0x200
	ds_read_b64_tr_b16 v[134:135], v211 offset:0xa00
	s_waitcnt lgkmcnt(8)
; __device__ __forceinline__ void pv_d0(f32x16* o, int vb, bf16x8 pa0, bf16x8 pa1, bf16x8 pa2, bf16x8 pa3) {
;     ...
;   const s16x4 l0 = tr_read<v_rd_off(0, 0, 0)>(vb), h0 = tr_read<v_rd_off(0, 0, 1)>(vb);
;   const s16x4 l1 = tr_read<v_rd_off(0, 1, 0)>(vb), h1 = tr_read<v_rd_off(0, 1, 1)>(vb);
;   const s16x4 l2 = tr_read<v_rd_off(0, 2, 0)>(vb), h2 = tr_read<v_rd_off(0, 2, 1)>(vb);
;   const s16x4 l3 = tr_read<v_rd_off(0, 3, 0)>(vb), h3 = tr_read<v_rd_off(0, 3, 1)>(vb);
;   const s16x4 l4 = tr_read<v_rd_off(1, 0, 0)>(vb), h4 = tr_read<v_rd_off(1, 0, 1)>(vb);
;   asm volatile("s_waitcnt lgkmcnt(8)" ::: "memory"); SBAR();
;   o[0] = __builtin_amdgcn_mfma_f32_32x32x16_bf16(pa0, PK(l0, h0), o[0], 0, 0, 0);
;   const s16x4 l5 = tr_read<v_rd_off(1, 1, 0)>(vb), h5 = tr_read<v_rd_off(1, 1, 1)>(vb);
;   asm volatile("s_waitcnt lgkmcnt(8)" ::: "memory"); SBAR();
;   o[0] = __builtin_amdgcn_mfma_f32_32x32x16_bf16(pa1, PK(l1, h1), o[0], 0, 0, 0);
;   const s16x4 l6 = tr_read<v_rd_off(1, 2, 0)>(vb), h6 = tr_read<v_rd_off(1, 2, 1)>(vb);
;   asm volatile("s_waitcnt lgkmcnt(8)" ::: "memory"); SBAR();
;   o[0] = __builtin_amdgcn_mfma_f32_32x32x16_bf16(pa2, PK(l2, h2), o[0], 0, 0, 0);
;   const s16x4 l7 = tr_read<v_rd_off(1, 3, 0)>(vb), h7 = tr_read<v_rd_off(1, 3, 1)>(vb);
;   asm volatile("s_waitcnt lgkmcnt(8)" ::: "memory"); SBAR();
;   o[0] = __builtin_amdgcn_mfma_f32_32x32x16_bf16(pa3, PK(l3, h3), o[0], 0, 0, 0);
;   const s16x4 l8 = tr_read<v_rd_off(2, 0, 0)>(vb), h8 = tr_read<v_rd_off(2, 0, 1)>(vb);
;   asm volatile("s_waitcnt lgkmcnt(8)" ::: "memory"); SBAR();
;   o[1] = __builtin_amdgcn_mfma_f32_32x32x16_bf16(pa0, PK(l4, h4), o[1], 0, 0, 0);
;   const s16x4 l9 = tr_read<v_rd_off(2, 1, 0)>(vb), h9 = tr_read<v_rd_off(2, 1, 1)>(vb);
;   asm volatile("s_waitcnt lgkmcnt(8)" ::: "memory"); SBAR();
;   o[1] = __builtin_amdgcn_mfma_f32_32x32x16_bf16(pa1, PK(l5, h5), o[1], 0, 0, 0);
;   const s16x4 l10 = tr_read<v_rd_off(2, 2, 0)>(vb), h10 = tr_read<v_rd_off(2, 2, 1)>(vb);
;   asm volatile("s_waitcnt lgkmcnt(8)" ::: "memory"); SBAR();
;   o[1] = __builtin_amdgcn_mfma_f32_32x32x16_bf16(pa2, PK(l6, h6), o[1], 0, 0, 0);
;   const s16x4 l11 = tr_read<v_rd_off(2, 3, 0)>(vb), h11 = tr_read<v_rd_off(2, 3, 1)>(vb);
;   asm volatile("s_waitcnt lgkmcnt(8)" ::: "memory"); SBAR();
;   o[1] = __builtin_amdgcn_mfma_f32_32x32x16_bf16(pa3, PK(l7, h7), o[1], 0, 0, 0);
	s_nop 0
	v_mfma_f32_32x32x16_bf16 v[50:65], v[98:101], v[116:119], v[50:65]
	ds_read_b64_tr_b16 v[116:117], v211 offset:0x1200
	ds_read_b64_tr_b16 v[118:119], v211 offset:0x1a00
	s_waitcnt lgkmcnt(8)
	v_mfma_f32_32x32x16_bf16 v[50:65], v[102:105], v[120:123], v[50:65]
	ds_read_b64_tr_b16 v[120:121], v211 offset:0x2200
	ds_read_b64_tr_b16 v[122:123], v211 offset:0x2a00
	s_waitcnt lgkmcnt(8)
	v_mfma_f32_32x32x16_bf16 v[50:65], v[106:109], v[124:127], v[50:65]
	ds_read_b64_tr_b16 v[124:125], v211 offset:0x3200
	ds_read_b64_tr_b16 v[126:127], v211 offset:0x3a00
	s_waitcnt lgkmcnt(8)
	v_mfma_f32_32x32x16_bf16 v[50:65], v[110:113], v[128:131], v[50:65]
	ds_read_b64_tr_b16 v[128:129], v211 offset:0x400
	ds_read_b64_tr_b16 v[130:131], v211 offset:0xc00
	s_waitcnt lgkmcnt(8)
	v_mfma_f32_32x32x16_bf16 v[34:49], v[98:101], v[132:135], v[34:49]
	ds_read_b64_tr_b16 v[132:133], v211 offset:0x1400
	ds_read_b64_tr_b16 v[134:135], v211 offset:0x1c00
	s_waitcnt lgkmcnt(8)
	v_mfma_f32_32x32x16_bf16 v[34:49], v[102:105], v[116:119], v[34:49]
	ds_read_b64_tr_b16 v[116:117], v211 offset:0x2400
	ds_read_b64_tr_b16 v[118:119], v211 offset:0x2c00
	s_waitcnt lgkmcnt(8)
	v_mfma_f32_32x32x16_bf16 v[34:49], v[106:109], v[120:123], v[34:49]
	ds_read_b64_tr_b16 v[120:121], v211 offset:0x3400
	ds_read_b64_tr_b16 v[122:123], v211 offset:0x3c00
	s_waitcnt lgkmcnt(8)
	v_mfma_f32_32x32x16_bf16 v[34:49], v[110:113], v[124:127], v[34:49]
	ds_read_b64_tr_b16 v[124:125], v211 offset:0x600
	ds_read_b64_tr_b16 v[126:127], v211 offset:0xe00
	s_waitcnt lgkmcnt(8)
	v_mfma_f32_32x32x16_bf16 v[18:33], v[98:101], v[128:131], v[18:33]
	ds_read_b64_tr_b16 v[128:129], v211 offset:0x1600
	ds_read_b64_tr_b16 v[130:131], v211 offset:0x1e00
	s_waitcnt lgkmcnt(8)
	v_mfma_f32_32x32x16_bf16 v[18:33], v[102:105], v[132:135], v[18:33]
	ds_read_b64_tr_b16 v[132:133], v211 offset:0x2600
	ds_read_b64_tr_b16 v[134:135], v211 offset:0x2e00
	s_waitcnt lgkmcnt(8)
	v_mfma_f32_32x32x16_bf16 v[18:33], v[106:109], v[116:119], v[18:33]
	ds_read_b64_tr_b16 v[116:117], v211 offset:0x3600
	ds_read_b64_tr_b16 v[118:119], v211 offset:0x3e00
	s_waitcnt lgkmcnt(8)
	v_mfma_f32_32x32x16_bf16 v[18:33], v[110:113], v[120:123], v[18:33]
	s_waitcnt lgkmcnt(6)
	v_mfma_f32_32x32x16_bf16 v[2:17], v[98:101], v[124:127], v[2:17]
	s_waitcnt lgkmcnt(4)
	v_mfma_f32_32x32x16_bf16 v[2:17], v[102:105], v[128:131], v[2:17]
	s_waitcnt lgkmcnt(2)
	v_mfma_f32_32x32x16_bf16 v[2:17], v[106:109], v[132:135], v[2:17]
	s_waitcnt lgkmcnt(0)
	v_mfma_f32_32x32x16_bf16 v[2:17], v[110:113], v[116:119], v[2:17]
	s_cbranch_scc0 .LBB0_508
	v_sub_u32_e32 v98, s4, v210
	v_lshlrev_b32_e32 v98, 2, v98
	v_readlane_b32 s4, v254, 59
	s_nop 1
	v_add3_u32 v128, s4, v98, v196
	v_add_u32_e32 v98, 0x1600, v128
	v_add_u32_e32 v100, 0x1680, v128
	ds_read2_b32 v[98:99], v98 offset1:1
	ds_read2_b32 v[100:101], v100 offset1:1
	v_add_u32_e32 v102, 0x1608, v128
	v_add_u32_e32 v104, 0x1688, v128
	v_add_u32_e32 v106, 0x1620, v128
	v_add_u32_e32 v108, 0x16a0, v128
	v_add_u32_e32 v110, 0x1628, v128
	v_add_u32_e32 v112, 0x16a8, v128
	v_add_u32_e32 v116, 0x1640, v128
	v_add_u32_e32 v118, 0x16c0, v128
	v_add_u32_e32 v120, 0x1648, v128
	v_add_u32_e32 v122, 0x16c8, v128
	v_add_u32_e32 v124, 0x1660, v128
	v_add_u32_e32 v126, 0x16e0, v128
	v_add_u32_e32 v129, 0x1668, v128
	v_add_u32_e32 v130, 0x16e8, v128
	ds_read2_b32 v[102:103], v102 offset1:1
	ds_read2_b32 v[104:105], v104 offset1:1
	ds_read2_b32 v[106:107], v106 offset1:1
	ds_read2_b32 v[108:109], v108 offset1:1
	ds_read2_b32 v[110:111], v110 offset1:1
	ds_read2_b32 v[112:113], v112 offset1:1
	ds_read2_b32 v[116:117], v116 offset1:1
	ds_read2_b32 v[118:119], v118 offset1:1
	ds_read2_b32 v[120:121], v120 offset1:1
	ds_read2_b32 v[122:123], v122 offset1:1
	ds_read2_b32 v[124:125], v124 offset1:1
	ds_read2_b32 v[126:127], v126 offset1:1
	ds_read2_b32 v[128:129], v129 offset1:1
	s_waitcnt lgkmcnt(14)
	v_pk_add_f32 v[82:83], v[82:83], v[98:99]
	ds_read2_b32 v[98:99], v130 offset1:1
	s_waitcnt lgkmcnt(3)
	v_pk_add_f32 v[94:95], v[94:95], v[124:125]
	v_pk_add_f32 v[92:93], v[92:93], v[120:121]
	s_waitcnt lgkmcnt(1)
	v_pk_add_f32 v[96:97], v[96:97], v[128:129]
	v_pk_add_f32 v[90:91], v[90:91], v[116:117]
	v_pk_add_f32 v[88:89], v[88:89], v[110:111]
	v_pk_add_f32 v[86:87], v[86:87], v[106:107]
	v_pk_add_f32 v[84:85], v[84:85], v[102:103]
	s_waitcnt lgkmcnt(0)
	v_pk_add_f32 v[80:81], v[80:81], v[98:99]
	v_pk_add_f32 v[78:79], v[78:79], v[126:127]
	v_pk_add_f32 v[76:77], v[76:77], v[122:123]
	v_pk_add_f32 v[74:75], v[74:75], v[118:119]
	v_pk_add_f32 v[72:73], v[72:73], v[112:113]
	v_pk_add_f32 v[70:71], v[70:71], v[108:109]
	v_pk_add_f32 v[68:69], v[68:69], v[104:105]
	v_pk_add_f32 v[66:67], v[66:67], v[100:101]

; #define SBAR() __builtin_amdgcn_sched_barrier(0)
; #define RESC(a) do { if (__any((a) < 1.f)) { if (hi == 0) al_l[r32] = (a); asm volatile("s_waitcnt lgkmcnt(0)" ::: "memory"); \
;     _Pragma("unroll") for (int d = 0; d < 4; ++d) _Pragma("unroll") for (int r = 0; r < 16; ++r) o[d][r] *= al_l[crow(r, hi)]; } } while (0)
; template <bool EXP1 = true>
; __device__ __forceinline__ void finishSM(f32x16& p0, f32x16& p1, float alpha, float& l_reg, bf16x8& pa0, bf16x8& pa1, bf16x8& pa2, bf16x8& pa3) {
;   if constexpr (EXP1) {
; #pragma unroll
;   for (int r = 0; r < 16; ++r) p1[r] = __builtin_amdgcn_exp2f(p1[r]);
;   }
;   float sm_[4] = {p0[0], p0[1], p0[2], p0[3]};
; #pragma unroll
;   for (int r = 4; r < 16; ++r) sm_[r & 3] += p0[r];
; #pragma unroll
;   for (int r = 0; r < 16; ++r) sm_[r & 3] += p1[r];
;   float ps = (sm_[0] + sm_[1]) + (sm_[2] + sm_[3]);
;   { auto rr = __builtin_amdgcn_permlane32_swap(__float_as_uint(ps), __float_as_uint(ps), false, false);
;     ps = __uint_as_float(rr[0]) + __uint_as_float(rr[1]); }
;   l_reg = l_reg * alpha + ps;
;     ...
;   PK4(p0, 0, pa0); PK4(p0, 8, pa1); PK4(p1, 0, pa2); PK4(p1, 8, pa3);
;     ...
; }
;     ...
;   __syncthreads(); RESC(alB);
;   finishSM(pB0, pB1, alB, l_reg, pa0, pa1, pa2, pa3); SBAR();
;   pv_d0(o, vb0 + (int)SHM_V, pa0, pa1, pa2, pa3);
;   if (hi == 0) li_l[r32] = l_reg; asm volatile("s_waitcnt lgkmcnt(0)" ::: "memory");
.LBB0_513:
	v_exp_f32_e32 v104, v82
	v_exp_f32_e32 v106, v83
	v_exp_f32_e32 v102, v84
	v_exp_f32_e32 v105, v85
	v_exp_f32_e32 v100, v86
	v_exp_f32_e32 v103, v87
	v_exp_f32_e32 v99, v88
	v_exp_f32_e32 v101, v89
	v_exp_f32_e32 v89, v90
	v_exp_f32_e32 v91, v91
	v_exp_f32_e32 v87, v92
	v_exp_f32_e32 v90, v93
	v_exp_f32_e32 v85, v94
	v_exp_f32_e32 v88, v95
	v_exp_f32_e32 v84, v96
	v_exp_f32_e32 v86, v97
	v_exp_f32_e32 v92, v66
	v_exp_f32_e32 v93, v67
	v_exp_f32_e32 v94, v68
	v_exp_f32_e32 v95, v69
	v_exp_f32_e32 v96, v70
	v_exp_f32_e32 v97, v71
	v_exp_f32_e32 v107, v72
	v_exp_f32_e32 v108, v73
	v_add_f32_e32 v66, v100, v104
	v_add_f32_e32 v67, v103, v106
	v_add_f32_e32 v68, v99, v102
	v_add_f32_e32 v69, v101, v105
	v_exp_f32_e32 v109, v74
	v_exp_f32_e32 v110, v75
	v_exp_f32_e32 v111, v76
	v_exp_f32_e32 v112, v77
	v_add_f32_e32 v66, v89, v66
	v_add_f32_e32 v67, v91, v67
	v_add_f32_e32 v68, v87, v68
	v_add_f32_e32 v69, v90, v69
	v_exp_f32_e32 v113, v78
	v_exp_f32_e32 v116, v79
	v_exp_f32_e32 v117, v80
	v_exp_f32_e32 v81, v81
	v_add_f32_e32 v66, v85, v66
	v_add_f32_e32 v67, v88, v67
	v_add_f32_e32 v68, v84, v68
	v_add_f32_e32 v69, v86, v69
	v_add_f32_e32 v66, v92, v66
	v_add_f32_e32 v67, v93, v67
	v_add_f32_e32 v68, v68, v94
	v_add_f32_e32 v69, v69, v95
	v_add_f32_e32 v66, v96, v66
	v_add_f32_e32 v67, v97, v67
	v_add_f32_e32 v68, v107, v68
	v_add_f32_e32 v69, v108, v69
	v_add_f32_e32 v66, v109, v66
	v_add_f32_e32 v67, v110, v67
	v_add_f32_e32 v68, v111, v68
	v_add_f32_e32 v69, v112, v69
	v_add_f32_e32 v66, v113, v66
	v_add_f32_e32 v67, v116, v67
	v_add_f32_e32 v68, v117, v68
	v_add_f32_e32 v69, v81, v69
	v_add_f32_e32 v66, v67, v66
	v_add_f32_e32 v67, v68, v69
	v_add_f32_e32 v82, v67, v66
	v_mov_b32_e32 v83, v82
	s_nop 1
	v_permlane32_swap_b32_e32 v82, v83
	v_cvt_pk_bf16_f32 v66, v104, v106
	v_cvt_pk_bf16_f32 v67, v102, v105
	v_cvt_pk_bf16_f32 v68, v100, v103
	v_cvt_pk_bf16_f32 v69, v99, v101
	v_cvt_pk_bf16_f32 v70, v89, v91
	v_cvt_pk_bf16_f32 v71, v87, v90
	v_cvt_pk_bf16_f32 v72, v85, v88
	v_cvt_pk_bf16_f32 v73, v84, v86
	v_cvt_pk_bf16_f32 v74, v92, v93
	v_cvt_pk_bf16_f32 v75, v94, v95
	v_cvt_pk_bf16_f32 v76, v96, v97
	v_cvt_pk_bf16_f32 v77, v107, v108
	v_cvt_pk_bf16_f32 v78, v109, v110
	v_cvt_pk_bf16_f32 v79, v111, v112
	v_cvt_pk_bf16_f32 v80, v113, v116
	v_cvt_pk_bf16_f32 v81, v117, v81
	s_nop 0
	s_cmp_lg_u32 0, -1
	s_cselect_b32 s4, 0, 0
	s_addk_i32 s4, 0x4000
	v_add_u32_e32 v96, s4, v209
	ds_read_b64_tr_b16 v[84:85], v96 offset:0
	ds_read_b64_tr_b16 v[86:87], v96 offset:0x800
	ds_read_b64_tr_b16 v[88:89], v96 offset:0x1000
	ds_read_b64_tr_b16 v[90:91], v96 offset:0x1800
	ds_read_b64_tr_b16 v[92:93], v96 offset:0x2000
	ds_read_b64_tr_b16 v[94:95], v96 offset:0x2800
	ds_read_b64_tr_b16 v[100:101], v96 offset:0x3000
	ds_read_b64_tr_b16 v[102:103], v96 offset:0x3800
	ds_read_b64_tr_b16 v[104:105], v96 offset:0x200
	ds_read_b64_tr_b16 v[106:107], v96 offset:0xa00
	s_waitcnt lgkmcnt(8)
	s_nop 0
	v_mfma_f32_32x32x16_bf16 v[50:65], v[66:69], v[84:87], v[50:65]
	ds_read_b64_tr_b16 v[84:85], v96 offset:0x1200
	ds_read_b64_tr_b16 v[86:87], v96 offset:0x1a00
	s_waitcnt lgkmcnt(8)
	v_mfma_f32_32x32x16_bf16 v[50:65], v[70:73], v[88:91], v[50:65]
	ds_read_b64_tr_b16 v[88:89], v96 offset:0x2200
	ds_read_b64_tr_b16 v[90:91], v96 offset:0x2a00
	s_waitcnt lgkmcnt(8)
	v_mfma_f32_32x32x16_bf16 v[50:65], v[74:77], v[92:95], v[50:65]
	ds_read_b64_tr_b16 v[92:93], v96 offset:0x3200
	ds_read_b64_tr_b16 v[94:95], v96 offset:0x3a00
	s_waitcnt lgkmcnt(8)
	v_mfma_f32_32x32x16_bf16 v[50:65], v[78:81], v[100:103], v[50:65]
	ds_read_b64_tr_b16 v[100:101], v96 offset:0x400
	ds_read_b64_tr_b16 v[102:103], v96 offset:0xc00
	s_waitcnt lgkmcnt(8)
	v_mfma_f32_32x32x16_bf16 v[34:49], v[66:69], v[104:107], v[34:49]
	ds_read_b64_tr_b16 v[104:105], v96 offset:0x1400
	ds_read_b64_tr_b16 v[106:107], v96 offset:0x1c00
	s_waitcnt lgkmcnt(8)
	v_mfma_f32_32x32x16_bf16 v[34:49], v[70:73], v[84:87], v[34:49]
	ds_read_b64_tr_b16 v[84:85], v96 offset:0x2400
	ds_read_b64_tr_b16 v[86:87], v96 offset:0x2c00
	s_waitcnt lgkmcnt(8)
	v_mfma_f32_32x32x16_bf16 v[34:49], v[74:77], v[88:91], v[34:49]
	ds_read_b64_tr_b16 v[88:89], v96 offset:0x3400
	ds_read_b64_tr_b16 v[90:91], v96 offset:0x3c00
	s_waitcnt lgkmcnt(8)
	v_mfma_f32_32x32x16_bf16 v[34:49], v[78:81], v[92:95], v[34:49]
	ds_read_b64_tr_b16 v[92:93], v96 offset:0x600
	ds_read_b64_tr_b16 v[94:95], v96 offset:0xe00
	s_waitcnt lgkmcnt(8)
	v_mfma_f32_32x32x16_bf16 v[18:33], v[66:69], v[100:103], v[18:33]
	ds_read_b64_tr_b16 v[100:101], v96 offset:0x1600
	ds_read_b64_tr_b16 v[102:103], v96 offset:0x1e00
	s_waitcnt lgkmcnt(8)
	v_mfma_f32_32x32x16_bf16 v[18:33], v[70:73], v[104:107], v[18:33]
	ds_read_b64_tr_b16 v[104:105], v96 offset:0x2600
	ds_read_b64_tr_b16 v[106:107], v96 offset:0x2e00
	s_waitcnt lgkmcnt(8)
	v_mfma_f32_32x32x16_bf16 v[18:33], v[74:77], v[84:87], v[18:33]
	ds_read_b64_tr_b16 v[84:85], v96 offset:0x3600
	ds_read_b64_tr_b16 v[86:87], v96 offset:0x3e00
	s_waitcnt lgkmcnt(8)
	v_mfma_f32_32x32x16_bf16 v[18:33], v[78:81], v[88:91], v[18:33]
	s_waitcnt lgkmcnt(6)
	v_mfma_f32_32x32x16_bf16 v[2:17], v[66:69], v[92:95], v[2:17]
	s_waitcnt lgkmcnt(4)
	v_mfma_f32_32x32x16_bf16 v[2:17], v[70:73], v[100:103], v[2:17]
	s_waitcnt lgkmcnt(2)
	v_mfma_f32_32x32x16_bf16 v[2:17], v[74:77], v[104:107], v[2:17]
	s_waitcnt lgkmcnt(0)
	v_mfma_f32_32x32x16_bf16 v[2:17], v[78:81], v[84:87], v[2:17]
	v_cmp_gt_u32_e32 vcc, 32, v197
	s_and_saveexec_b64 s[4:5], vcc
	s_cbranch_execz .LBB0_473
	v_add_f32_e32 v66, v114, v115
	v_fmac_f32_e32 v66, v0, v238
	v_add_f32_e32 v0, v82, v83
	v_fmac_f32_e32 v0, v66, v98
	v_lshl_add_u32 v66, v207, 2, v191
	ds_write_b32 v66, v0
	s_branch .LBB0_473
